# non-temporal hint on the streaming f32 row loads of the norm phases (1 6 10 17 22) and on the final output stores
# speedup vs baseline: 1.0161x; 1.0161x over previous
.LBB0_94:
	s_cmp_gt_i32 s44, 1
	s_cselect_b64 s[2:3], -1, 0
	s_cmp_lt_i32 s45, 2
	s_cselect_b64 s[4:5], -1, 0
	s_or_b64 s[2:3], s[2:3], s[4:5]
	s_and_b64 vcc, exec, s[2:3]
	s_cbranch_vccnz .LBB0_295
	s_lshl_b32 s96, s22, 3
	s_lshr_b32 s97, s70, 6
	s_add_u32 s96, s96, s97
	s_lshl_b32 s97, s96, 4
	s_cmpk_ge_u32 s97, 0x8000
	s_cbranch_scc1 .Lnp1_done
	s_load_dwordx2 s[88:89], s[0:1], 0x0
	s_load_dwordx2 s[90:91], s[0:1], 0x18
	s_load_dwordx2 s[92:93], s[0:1], 0x140
	s_load_dwordx2 s[94:95], s[0:1], 0x158
	v_mbcnt_hi_u32_b32 v0, -1, v210
	v_lshlrev_b32_e32 v1, 4, v0
	s_waitcnt lgkmcnt(0)
	s_add_u32 s90, s90, 0
	s_addc_u32 s91, s91, 0
	global_load_dwordx4 v[112:115], v1, s[90:91] nt
	global_load_dwordx4 v[116:119], v1, s[90:91] offset:1024 nt
	global_load_dwordx4 v[120:123], v1, s[90:91] offset:2048 nt
	global_load_dwordx4 v[124:127], v1, s[90:91] offset:3072 nt
	s_lshr_b32 s98, s97, 12
	s_add_u32 s98, s98, 0
	s_mul_i32 s98, s98, 0x3000
	s_add_u32 s92, s92, s98
	s_addc_u32 s93, s93, 0
	global_load_dwordx4 v[144:147], v1, s[92:93] nt
	global_load_dwordx4 v[148:151], v1, s[92:93] offset:1024 nt
	global_load_dwordx4 v[152:155], v1, s[92:93] offset:2048 nt
	global_load_dwordx4 v[156:159], v1, s[92:93] offset:3072 nt
	s_add_u32 s92, s92, 0x1000
	s_addc_u32 s93, s93, 0
	global_load_dwordx4 v[128:131], v1, s[92:93] nt
	global_load_dwordx4 v[132:135], v1, s[92:93] offset:1024 nt
	global_load_dwordx4 v[136:139], v1, s[92:93] offset:2048 nt
	global_load_dwordx4 v[140:143], v1, s[92:93] offset:3072 nt
	s_load_dwordx2 s[90:91], s[0:1], 0x210
	s_load_dwordx2 s[92:93], s[0:1], 0x218
	s_waitcnt vmcnt(0) lgkmcnt(0)
	v_pk_add_f32 v[128:129], v[128:129], 1.0 op_sel_hi:[1,0]
	v_pk_add_f32 v[130:131], v[130:131], 1.0 op_sel_hi:[1,0]
	v_pk_add_f32 v[132:133], v[132:133], 1.0 op_sel_hi:[1,0]
	v_pk_add_f32 v[134:135], v[134:135], 1.0 op_sel_hi:[1,0]
	v_pk_add_f32 v[136:137], v[136:137], 1.0 op_sel_hi:[1,0]
	v_pk_add_f32 v[138:139], v[138:139], 1.0 op_sel_hi:[1,0]
	v_pk_add_f32 v[140:141], v[140:141], 1.0 op_sel_hi:[1,0]
	v_pk_add_f32 v[142:143], v[142:143], 1.0 op_sel_hi:[1,0]
	s_add_u32 s98, s97, 0
	s_lshl_b32 s98, s98, 12
	v_add_u32_e32 v3, s98, v1
	global_load_dwordx4 v[16:19], v3, s[88:89] nt
	global_load_dwordx4 v[20:23], v3, s[88:89] offset:1024 nt
	global_load_dwordx4 v[24:27], v3, s[88:89] offset:2048 nt
	global_load_dwordx4 v[28:31], v3, s[88:89] offset:3072 nt
	s_add_u32 s98, s97, 1
	s_lshl_b32 s98, s98, 12
	v_add_u32_e32 v3, s98, v1
	global_load_dwordx4 v[32:35], v3, s[88:89] nt
	global_load_dwordx4 v[36:39], v3, s[88:89] offset:1024 nt
	global_load_dwordx4 v[40:43], v3, s[88:89] offset:2048 nt
	global_load_dwordx4 v[44:47], v3, s[88:89] offset:3072 nt
	s_add_u32 s98, s97, 2
	s_lshl_b32 s98, s98, 12
	v_add_u32_e32 v3, s98, v1
	global_load_dwordx4 v[48:51], v3, s[88:89] nt
	global_load_dwordx4 v[52:55], v3, s[88:89] offset:1024 nt
	global_load_dwordx4 v[56:59], v3, s[88:89] offset:2048 nt
	global_load_dwordx4 v[60:63], v3, s[88:89] offset:3072 nt
	s_add_u32 s98, s97, 3
	s_lshl_b32 s98, s98, 12
	v_add_u32_e32 v3, s98, v1
	global_load_dwordx4 v[64:67], v3, s[88:89] nt
	global_load_dwordx4 v[68:71], v3, s[88:89] offset:1024 nt
	global_load_dwordx4 v[72:75], v3, s[88:89] offset:2048 nt
	global_load_dwordx4 v[76:79], v3, s[88:89] offset:3072 nt
	s_add_u32 s98, s97, 4
	s_lshl_b32 s98, s98, 12
	v_add_u32_e32 v3, s98, v1
	global_load_dwordx4 v[80:83], v3, s[88:89] nt
	global_load_dwordx4 v[84:87], v3, s[88:89] offset:1024 nt
	global_load_dwordx4 v[88:91], v3, s[88:89] offset:2048 nt
	global_load_dwordx4 v[92:95], v3, s[88:89] offset:3072 nt
	s_add_u32 s98, s97, 5
	s_lshl_b32 s98, s98, 12
	v_add_u32_e32 v3, s98, v1
	global_load_dwordx4 v[96:99], v3, s[88:89] nt
	global_load_dwordx4 v[100:103], v3, s[88:89] offset:1024 nt
	global_load_dwordx4 v[104:107], v3, s[88:89] offset:2048 nt
	global_load_dwordx4 v[108:111], v3, s[88:89] offset:3072 nt
	s_waitcnt vmcnt(20)
	v_mul_f32_e32 v4, v16, v16
	v_fma_f32 v4, v17, v17, v4
	v_fma_f32 v4, v18, v18, v4
	v_fma_f32 v4, v19, v19, v4
	v_fma_f32 v4, v20, v20, v4
	v_fma_f32 v4, v21, v21, v4
	v_fma_f32 v4, v22, v22, v4
	v_fma_f32 v4, v23, v23, v4
	v_fma_f32 v4, v24, v24, v4
	v_fma_f32 v4, v25, v25, v4
	v_fma_f32 v4, v26, v26, v4
	v_fma_f32 v4, v27, v27, v4
	v_fma_f32 v4, v28, v28, v4
	v_fma_f32 v4, v29, v29, v4
	v_fma_f32 v4, v30, v30, v4
	v_fma_f32 v4, v31, v31, v4
	s_nop 1
	v_add_f32_dpp v5, v4, v4 quad_perm:[1,0,3,2] row_mask:0xf bank_mask:0xf
	s_nop 1
	v_add_f32_dpp v4, v5, v5 quad_perm:[2,3,0,1] row_mask:0xf bank_mask:0xf
	s_nop 1
	v_add_f32_dpp v5, v4, v4 row_half_mirror row_mask:0xf bank_mask:0xf
	s_nop 1
	v_add_f32_dpp v4, v5, v5 row_mirror row_mask:0xf bank_mask:0xf
	s_nop 1
	v_readlane_b32 s98, v4, 0
	v_readlane_b32 s99, v4, 16
	s_nop 3
	v_mov_b32_e32 v5, s98
	v_add_f32_e32 v5, s99, v5
	v_readlane_b32 s98, v4, 32
	v_readlane_b32 s99, v4, 48
	s_nop 3
	v_add_f32_e32 v5, s98, v5
	v_add_f32_e32 v5, s99, v5
	v_mul_f32_e32 v5, 0x3a800000, v5
	v_add_f32_e32 v5, 0x358637bd, v5
	v_rsq_f32_e32 v6, v5
	s_nop 0
	s_add_u32 s98, s97, 0
	v_pk_mul_f32 v[16:17], v[16:17], v[6:7] op_sel_hi:[1,0]
	v_pk_mul_f32 v[18:19], v[18:19], v[6:7] op_sel_hi:[1,0]
	v_pk_mul_f32 v[20:21], v[20:21], v[6:7] op_sel_hi:[1,0]
	v_pk_mul_f32 v[22:23], v[22:23], v[6:7] op_sel_hi:[1,0]
	v_pk_mul_f32 v[24:25], v[24:25], v[6:7] op_sel_hi:[1,0]
	v_pk_mul_f32 v[26:27], v[26:27], v[6:7] op_sel_hi:[1,0]
	v_pk_mul_f32 v[28:29], v[28:29], v[6:7] op_sel_hi:[1,0]
	v_pk_mul_f32 v[30:31], v[30:31], v[6:7] op_sel_hi:[1,0]
	v_pk_mul_f32 v[16:17], v[16:17], v[112:113]
	v_pk_mul_f32 v[18:19], v[18:19], v[114:115]
	v_pk_mul_f32 v[20:21], v[20:21], v[116:117]
	v_pk_mul_f32 v[22:23], v[22:23], v[118:119]
	v_pk_mul_f32 v[24:25], v[24:25], v[120:121]
	v_pk_mul_f32 v[26:27], v[26:27], v[122:123]
	v_pk_mul_f32 v[28:29], v[28:29], v[124:125]
	v_pk_mul_f32 v[30:31], v[30:31], v[126:127]
	v_pk_fma_f32 v[16:17], v[16:17], v[128:129], v[144:145]
	v_pk_fma_f32 v[18:19], v[18:19], v[130:131], v[146:147]
	v_pk_fma_f32 v[20:21], v[20:21], v[132:133], v[148:149]
	v_pk_fma_f32 v[22:23], v[22:23], v[134:135], v[150:151]
	v_pk_fma_f32 v[24:25], v[24:25], v[136:137], v[152:153]
	v_pk_fma_f32 v[26:27], v[26:27], v[138:139], v[154:155]
	v_pk_fma_f32 v[28:29], v[28:29], v[140:141], v[156:157]
	v_pk_fma_f32 v[30:31], v[30:31], v[142:143], v[158:159]
	v_cvt_pk_bf16_f32 v16, v16, v17
	v_cvt_pk_bf16_f32 v17, v18, v19
	v_cvt_pk_bf16_f32 v18, v20, v21
	v_cvt_pk_bf16_f32 v19, v22, v23
	v_cvt_pk_bf16_f32 v20, v24, v25
	v_cvt_pk_bf16_f32 v21, v26, v27
	v_cvt_pk_bf16_f32 v22, v28, v29
	v_cvt_pk_bf16_f32 v23, v30, v31
	s_lshl_b32 s99, s98, 11
	v_lshl_add_u32 v8, v0, 3, s99
	global_store_dwordx2 v8, v[16:17], s[94:95]
	global_store_dwordx2 v8, v[18:19], s[94:95] offset:512
	global_store_dwordx2 v8, v[20:21], s[94:95] offset:1024
	global_store_dwordx2 v8, v[22:23], s[94:95] offset:1536
	s_lshl_b32 s99, s98, 2
	v_mov_b32_e32 v9, s99
	v_mov_b32_e32 v10, 0
	v_cmp_eq_u32_e32 vcc, 0, v0
	s_and_saveexec_b64 s[98:99], vcc
	global_store_dword v9, v10, s[90:91]
	global_store_dword v9, v10, s[92:93]
	s_or_b64 exec, exec, s[98:99]
	s_add_u32 s98, s97, 6
	s_lshl_b32 s98, s98, 12
	v_add_u32_e32 v3, s98, v1
	global_load_dwordx4 v[16:19], v3, s[88:89] nt
	global_load_dwordx4 v[20:23], v3, s[88:89] offset:1024 nt
	global_load_dwordx4 v[24:27], v3, s[88:89] offset:2048 nt
	global_load_dwordx4 v[28:31], v3, s[88:89] offset:3072 nt
	s_waitcnt vmcnt(26)
	v_mul_f32_e32 v4, v32, v32
	v_fma_f32 v4, v33, v33, v4
	v_fma_f32 v4, v34, v34, v4
	v_fma_f32 v4, v35, v35, v4
	v_fma_f32 v4, v36, v36, v4
	v_fma_f32 v4, v37, v37, v4
	v_fma_f32 v4, v38, v38, v4
	v_fma_f32 v4, v39, v39, v4
	v_fma_f32 v4, v40, v40, v4
	v_fma_f32 v4, v41, v41, v4
	v_fma_f32 v4, v42, v42, v4
	v_fma_f32 v4, v43, v43, v4
	v_fma_f32 v4, v44, v44, v4
	v_fma_f32 v4, v45, v45, v4
	v_fma_f32 v4, v46, v46, v4
	v_fma_f32 v4, v47, v47, v4
	s_nop 1
	v_add_f32_dpp v5, v4, v4 quad_perm:[1,0,3,2] row_mask:0xf bank_mask:0xf
	s_nop 1
	v_add_f32_dpp v4, v5, v5 quad_perm:[2,3,0,1] row_mask:0xf bank_mask:0xf
	s_nop 1
	v_add_f32_dpp v5, v4, v4 row_half_mirror row_mask:0xf bank_mask:0xf
	s_nop 1
	v_add_f32_dpp v4, v5, v5 row_mirror row_mask:0xf bank_mask:0xf
	s_nop 1
	v_readlane_b32 s98, v4, 0
	v_readlane_b32 s99, v4, 16
	s_nop 3
	v_mov_b32_e32 v5, s98
	v_add_f32_e32 v5, s99, v5
	v_readlane_b32 s98, v4, 32
	v_readlane_b32 s99, v4, 48
	s_nop 3
	v_add_f32_e32 v5, s98, v5
	v_add_f32_e32 v5, s99, v5
	v_mul_f32_e32 v5, 0x3a800000, v5
	v_add_f32_e32 v5, 0x358637bd, v5
	v_rsq_f32_e32 v6, v5
	s_nop 0
	s_add_u32 s98, s97, 1
	v_pk_mul_f32 v[32:33], v[32:33], v[6:7] op_sel_hi:[1,0]
	v_pk_mul_f32 v[34:35], v[34:35], v[6:7] op_sel_hi:[1,0]
	v_pk_mul_f32 v[36:37], v[36:37], v[6:7] op_sel_hi:[1,0]
	v_pk_mul_f32 v[38:39], v[38:39], v[6:7] op_sel_hi:[1,0]
	v_pk_mul_f32 v[40:41], v[40:41], v[6:7] op_sel_hi:[1,0]
	v_pk_mul_f32 v[42:43], v[42:43], v[6:7] op_sel_hi:[1,0]
	v_pk_mul_f32 v[44:45], v[44:45], v[6:7] op_sel_hi:[1,0]
	v_pk_mul_f32 v[46:47], v[46:47], v[6:7] op_sel_hi:[1,0]
	v_pk_mul_f32 v[32:33], v[32:33], v[112:113]
	v_pk_mul_f32 v[34:35], v[34:35], v[114:115]
	v_pk_mul_f32 v[36:37], v[36:37], v[116:117]
	v_pk_mul_f32 v[38:39], v[38:39], v[118:119]
	v_pk_mul_f32 v[40:41], v[40:41], v[120:121]
	v_pk_mul_f32 v[42:43], v[42:43], v[122:123]
	v_pk_mul_f32 v[44:45], v[44:45], v[124:125]
	v_pk_mul_f32 v[46:47], v[46:47], v[126:127]
	v_pk_fma_f32 v[32:33], v[32:33], v[128:129], v[144:145]
	v_pk_fma_f32 v[34:35], v[34:35], v[130:131], v[146:147]
	v_pk_fma_f32 v[36:37], v[36:37], v[132:133], v[148:149]
	v_pk_fma_f32 v[38:39], v[38:39], v[134:135], v[150:151]
	v_pk_fma_f32 v[40:41], v[40:41], v[136:137], v[152:153]
	v_pk_fma_f32 v[42:43], v[42:43], v[138:139], v[154:155]
	v_pk_fma_f32 v[44:45], v[44:45], v[140:141], v[156:157]
	v_pk_fma_f32 v[46:47], v[46:47], v[142:143], v[158:159]
	v_cvt_pk_bf16_f32 v32, v32, v33
	v_cvt_pk_bf16_f32 v33, v34, v35
	v_cvt_pk_bf16_f32 v34, v36, v37
	v_cvt_pk_bf16_f32 v35, v38, v39
	v_cvt_pk_bf16_f32 v36, v40, v41
	v_cvt_pk_bf16_f32 v37, v42, v43
	v_cvt_pk_bf16_f32 v38, v44, v45
	v_cvt_pk_bf16_f32 v39, v46, v47
	s_lshl_b32 s99, s98, 11
	v_lshl_add_u32 v8, v0, 3, s99
	global_store_dwordx2 v8, v[32:33], s[94:95]
	global_store_dwordx2 v8, v[34:35], s[94:95] offset:512
	global_store_dwordx2 v8, v[36:37], s[94:95] offset:1024
	global_store_dwordx2 v8, v[38:39], s[94:95] offset:1536
	s_lshl_b32 s99, s98, 2
	v_mov_b32_e32 v9, s99
	v_mov_b32_e32 v10, 0
	v_cmp_eq_u32_e32 vcc, 0, v0
	s_and_saveexec_b64 s[98:99], vcc
	global_store_dword v9, v10, s[90:91]
	global_store_dword v9, v10, s[92:93]
	s_or_b64 exec, exec, s[98:99]
	s_add_u32 s98, s97, 7
	s_lshl_b32 s98, s98, 12
	v_add_u32_e32 v3, s98, v1
	global_load_dwordx4 v[32:35], v3, s[88:89] nt
	global_load_dwordx4 v[36:39], v3, s[88:89] offset:1024 nt
	global_load_dwordx4 v[40:43], v3, s[88:89] offset:2048 nt
	global_load_dwordx4 v[44:47], v3, s[88:89] offset:3072 nt
	s_waitcnt vmcnt(32)
	v_mul_f32_e32 v4, v48, v48
	v_fma_f32 v4, v49, v49, v4
	v_fma_f32 v4, v50, v50, v4
	v_fma_f32 v4, v51, v51, v4
	v_fma_f32 v4, v52, v52, v4
	v_fma_f32 v4, v53, v53, v4
	v_fma_f32 v4, v54, v54, v4
	v_fma_f32 v4, v55, v55, v4
	v_fma_f32 v4, v56, v56, v4
	v_fma_f32 v4, v57, v57, v4
	v_fma_f32 v4, v58, v58, v4
	v_fma_f32 v4, v59, v59, v4
	v_fma_f32 v4, v60, v60, v4
	v_fma_f32 v4, v61, v61, v4
	v_fma_f32 v4, v62, v62, v4
	v_fma_f32 v4, v63, v63, v4
	s_nop 1
	v_add_f32_dpp v5, v4, v4 quad_perm:[1,0,3,2] row_mask:0xf bank_mask:0xf
	s_nop 1
	v_add_f32_dpp v4, v5, v5 quad_perm:[2,3,0,1] row_mask:0xf bank_mask:0xf
	s_nop 1
	v_add_f32_dpp v5, v4, v4 row_half_mirror row_mask:0xf bank_mask:0xf
	s_nop 1
	v_add_f32_dpp v4, v5, v5 row_mirror row_mask:0xf bank_mask:0xf
	s_nop 1
	v_readlane_b32 s98, v4, 0
	v_readlane_b32 s99, v4, 16
	s_nop 3
	v_mov_b32_e32 v5, s98
	v_add_f32_e32 v5, s99, v5
	v_readlane_b32 s98, v4, 32
	v_readlane_b32 s99, v4, 48
	s_nop 3
	v_add_f32_e32 v5, s98, v5
	v_add_f32_e32 v5, s99, v5
	v_mul_f32_e32 v5, 0x3a800000, v5
	v_add_f32_e32 v5, 0x358637bd, v5
	v_rsq_f32_e32 v6, v5
	s_nop 0
	s_add_u32 s98, s97, 2
	v_pk_mul_f32 v[48:49], v[48:49], v[6:7] op_sel_hi:[1,0]
	v_pk_mul_f32 v[50:51], v[50:51], v[6:7] op_sel_hi:[1,0]
	v_pk_mul_f32 v[52:53], v[52:53], v[6:7] op_sel_hi:[1,0]
	v_pk_mul_f32 v[54:55], v[54:55], v[6:7] op_sel_hi:[1,0]
	v_pk_mul_f32 v[56:57], v[56:57], v[6:7] op_sel_hi:[1,0]
	v_pk_mul_f32 v[58:59], v[58:59], v[6:7] op_sel_hi:[1,0]
	v_pk_mul_f32 v[60:61], v[60:61], v[6:7] op_sel_hi:[1,0]
	v_pk_mul_f32 v[62:63], v[62:63], v[6:7] op_sel_hi:[1,0]
	v_pk_mul_f32 v[48:49], v[48:49], v[112:113]
	v_pk_mul_f32 v[50:51], v[50:51], v[114:115]
	v_pk_mul_f32 v[52:53], v[52:53], v[116:117]
	v_pk_mul_f32 v[54:55], v[54:55], v[118:119]
	v_pk_mul_f32 v[56:57], v[56:57], v[120:121]
	v_pk_mul_f32 v[58:59], v[58:59], v[122:123]
	v_pk_mul_f32 v[60:61], v[60:61], v[124:125]
	v_pk_mul_f32 v[62:63], v[62:63], v[126:127]
	v_pk_fma_f32 v[48:49], v[48:49], v[128:129], v[144:145]
	v_pk_fma_f32 v[50:51], v[50:51], v[130:131], v[146:147]
	v_pk_fma_f32 v[52:53], v[52:53], v[132:133], v[148:149]
	v_pk_fma_f32 v[54:55], v[54:55], v[134:135], v[150:151]
	v_pk_fma_f32 v[56:57], v[56:57], v[136:137], v[152:153]
	v_pk_fma_f32 v[58:59], v[58:59], v[138:139], v[154:155]
	v_pk_fma_f32 v[60:61], v[60:61], v[140:141], v[156:157]
	v_pk_fma_f32 v[62:63], v[62:63], v[142:143], v[158:159]
	v_cvt_pk_bf16_f32 v48, v48, v49
	v_cvt_pk_bf16_f32 v49, v50, v51
	v_cvt_pk_bf16_f32 v50, v52, v53
	v_cvt_pk_bf16_f32 v51, v54, v55
	v_cvt_pk_bf16_f32 v52, v56, v57
	v_cvt_pk_bf16_f32 v53, v58, v59
	v_cvt_pk_bf16_f32 v54, v60, v61
	v_cvt_pk_bf16_f32 v55, v62, v63
	s_lshl_b32 s99, s98, 11
	v_lshl_add_u32 v8, v0, 3, s99
	global_store_dwordx2 v8, v[48:49], s[94:95]
	global_store_dwordx2 v8, v[50:51], s[94:95] offset:512
	global_store_dwordx2 v8, v[52:53], s[94:95] offset:1024
	global_store_dwordx2 v8, v[54:55], s[94:95] offset:1536
	s_lshl_b32 s99, s98, 2
	v_mov_b32_e32 v9, s99
	v_mov_b32_e32 v10, 0
	v_cmp_eq_u32_e32 vcc, 0, v0
	s_and_saveexec_b64 s[98:99], vcc
	global_store_dword v9, v10, s[90:91]
	global_store_dword v9, v10, s[92:93]
	s_or_b64 exec, exec, s[98:99]
	s_add_u32 s98, s97, 8
	s_lshl_b32 s98, s98, 12
	v_add_u32_e32 v3, s98, v1
	global_load_dwordx4 v[48:51], v3, s[88:89] nt
	global_load_dwordx4 v[52:55], v3, s[88:89] offset:1024 nt
	global_load_dwordx4 v[56:59], v3, s[88:89] offset:2048 nt
	global_load_dwordx4 v[60:63], v3, s[88:89] offset:3072 nt
	s_waitcnt vmcnt(38)
	v_mul_f32_e32 v4, v64, v64
	v_fma_f32 v4, v65, v65, v4
	v_fma_f32 v4, v66, v66, v4
	v_fma_f32 v4, v67, v67, v4
	v_fma_f32 v4, v68, v68, v4
	v_fma_f32 v4, v69, v69, v4
	v_fma_f32 v4, v70, v70, v4
	v_fma_f32 v4, v71, v71, v4
	v_fma_f32 v4, v72, v72, v4
	v_fma_f32 v4, v73, v73, v4
	v_fma_f32 v4, v74, v74, v4
	v_fma_f32 v4, v75, v75, v4
	v_fma_f32 v4, v76, v76, v4
	v_fma_f32 v4, v77, v77, v4
	v_fma_f32 v4, v78, v78, v4
	v_fma_f32 v4, v79, v79, v4
	s_nop 1
	v_add_f32_dpp v5, v4, v4 quad_perm:[1,0,3,2] row_mask:0xf bank_mask:0xf
	s_nop 1
	v_add_f32_dpp v4, v5, v5 quad_perm:[2,3,0,1] row_mask:0xf bank_mask:0xf
	s_nop 1
	v_add_f32_dpp v5, v4, v4 row_half_mirror row_mask:0xf bank_mask:0xf
	s_nop 1
	v_add_f32_dpp v4, v5, v5 row_mirror row_mask:0xf bank_mask:0xf
	s_nop 1
	v_readlane_b32 s98, v4, 0
	v_readlane_b32 s99, v4, 16
	s_nop 3
	v_mov_b32_e32 v5, s98
	v_add_f32_e32 v5, s99, v5
	v_readlane_b32 s98, v4, 32
	v_readlane_b32 s99, v4, 48
	s_nop 3
	v_add_f32_e32 v5, s98, v5
	v_add_f32_e32 v5, s99, v5
	v_mul_f32_e32 v5, 0x3a800000, v5
	v_add_f32_e32 v5, 0x358637bd, v5
	v_rsq_f32_e32 v6, v5
	s_nop 0
	s_add_u32 s98, s97, 3
	v_pk_mul_f32 v[64:65], v[64:65], v[6:7] op_sel_hi:[1,0]
	v_pk_mul_f32 v[66:67], v[66:67], v[6:7] op_sel_hi:[1,0]
	v_pk_mul_f32 v[68:69], v[68:69], v[6:7] op_sel_hi:[1,0]
	v_pk_mul_f32 v[70:71], v[70:71], v[6:7] op_sel_hi:[1,0]
	v_pk_mul_f32 v[72:73], v[72:73], v[6:7] op_sel_hi:[1,0]
	v_pk_mul_f32 v[74:75], v[74:75], v[6:7] op_sel_hi:[1,0]
	v_pk_mul_f32 v[76:77], v[76:77], v[6:7] op_sel_hi:[1,0]
	v_pk_mul_f32 v[78:79], v[78:79], v[6:7] op_sel_hi:[1,0]
	v_pk_mul_f32 v[64:65], v[64:65], v[112:113]
	v_pk_mul_f32 v[66:67], v[66:67], v[114:115]
	v_pk_mul_f32 v[68:69], v[68:69], v[116:117]
	v_pk_mul_f32 v[70:71], v[70:71], v[118:119]
	v_pk_mul_f32 v[72:73], v[72:73], v[120:121]
	v_pk_mul_f32 v[74:75], v[74:75], v[122:123]
	v_pk_mul_f32 v[76:77], v[76:77], v[124:125]
	v_pk_mul_f32 v[78:79], v[78:79], v[126:127]
	v_pk_fma_f32 v[64:65], v[64:65], v[128:129], v[144:145]
	v_pk_fma_f32 v[66:67], v[66:67], v[130:131], v[146:147]
	v_pk_fma_f32 v[68:69], v[68:69], v[132:133], v[148:149]
	v_pk_fma_f32 v[70:71], v[70:71], v[134:135], v[150:151]
	v_pk_fma_f32 v[72:73], v[72:73], v[136:137], v[152:153]
	v_pk_fma_f32 v[74:75], v[74:75], v[138:139], v[154:155]
	v_pk_fma_f32 v[76:77], v[76:77], v[140:141], v[156:157]
	v_pk_fma_f32 v[78:79], v[78:79], v[142:143], v[158:159]
	v_cvt_pk_bf16_f32 v64, v64, v65
	v_cvt_pk_bf16_f32 v65, v66, v67
	v_cvt_pk_bf16_f32 v66, v68, v69
	v_cvt_pk_bf16_f32 v67, v70, v71
	v_cvt_pk_bf16_f32 v68, v72, v73
	v_cvt_pk_bf16_f32 v69, v74, v75
	v_cvt_pk_bf16_f32 v70, v76, v77
	v_cvt_pk_bf16_f32 v71, v78, v79
	s_lshl_b32 s99, s98, 11
	v_lshl_add_u32 v8, v0, 3, s99
	global_store_dwordx2 v8, v[64:65], s[94:95]
	global_store_dwordx2 v8, v[66:67], s[94:95] offset:512
	global_store_dwordx2 v8, v[68:69], s[94:95] offset:1024
	global_store_dwordx2 v8, v[70:71], s[94:95] offset:1536
	s_lshl_b32 s99, s98, 2
	v_mov_b32_e32 v9, s99
	v_mov_b32_e32 v10, 0
	v_cmp_eq_u32_e32 vcc, 0, v0
	s_and_saveexec_b64 s[98:99], vcc
	global_store_dword v9, v10, s[90:91]
	global_store_dword v9, v10, s[92:93]
	s_or_b64 exec, exec, s[98:99]
	s_add_u32 s98, s97, 9
	s_lshl_b32 s98, s98, 12
	v_add_u32_e32 v3, s98, v1
	global_load_dwordx4 v[64:67], v3, s[88:89] nt
	global_load_dwordx4 v[68:71], v3, s[88:89] offset:1024 nt
	global_load_dwordx4 v[72:75], v3, s[88:89] offset:2048 nt
	global_load_dwordx4 v[76:79], v3, s[88:89] offset:3072 nt
	s_waitcnt vmcnt(44)
	v_mul_f32_e32 v4, v80, v80
	v_fma_f32 v4, v81, v81, v4
	v_fma_f32 v4, v82, v82, v4
	v_fma_f32 v4, v83, v83, v4
	v_fma_f32 v4, v84, v84, v4
	v_fma_f32 v4, v85, v85, v4
	v_fma_f32 v4, v86, v86, v4
	v_fma_f32 v4, v87, v87, v4
	v_fma_f32 v4, v88, v88, v4
	v_fma_f32 v4, v89, v89, v4
	v_fma_f32 v4, v90, v90, v4
	v_fma_f32 v4, v91, v91, v4
	v_fma_f32 v4, v92, v92, v4
	v_fma_f32 v4, v93, v93, v4
	v_fma_f32 v4, v94, v94, v4
	v_fma_f32 v4, v95, v95, v4
	s_nop 1
	v_add_f32_dpp v5, v4, v4 quad_perm:[1,0,3,2] row_mask:0xf bank_mask:0xf
	s_nop 1
	v_add_f32_dpp v4, v5, v5 quad_perm:[2,3,0,1] row_mask:0xf bank_mask:0xf
	s_nop 1
	v_add_f32_dpp v5, v4, v4 row_half_mirror row_mask:0xf bank_mask:0xf
	s_nop 1
	v_add_f32_dpp v4, v5, v5 row_mirror row_mask:0xf bank_mask:0xf
	s_nop 1
	v_readlane_b32 s98, v4, 0
	v_readlane_b32 s99, v4, 16
	s_nop 3
	v_mov_b32_e32 v5, s98
	v_add_f32_e32 v5, s99, v5
	v_readlane_b32 s98, v4, 32
	v_readlane_b32 s99, v4, 48
	s_nop 3
	v_add_f32_e32 v5, s98, v5
	v_add_f32_e32 v5, s99, v5
	v_mul_f32_e32 v5, 0x3a800000, v5
	v_add_f32_e32 v5, 0x358637bd, v5
	v_rsq_f32_e32 v6, v5
	s_nop 0
	s_add_u32 s98, s97, 4
	v_pk_mul_f32 v[80:81], v[80:81], v[6:7] op_sel_hi:[1,0]
	v_pk_mul_f32 v[82:83], v[82:83], v[6:7] op_sel_hi:[1,0]
	v_pk_mul_f32 v[84:85], v[84:85], v[6:7] op_sel_hi:[1,0]
	v_pk_mul_f32 v[86:87], v[86:87], v[6:7] op_sel_hi:[1,0]
	v_pk_mul_f32 v[88:89], v[88:89], v[6:7] op_sel_hi:[1,0]
	v_pk_mul_f32 v[90:91], v[90:91], v[6:7] op_sel_hi:[1,0]
	v_pk_mul_f32 v[92:93], v[92:93], v[6:7] op_sel_hi:[1,0]
	v_pk_mul_f32 v[94:95], v[94:95], v[6:7] op_sel_hi:[1,0]
	v_pk_mul_f32 v[80:81], v[80:81], v[112:113]
	v_pk_mul_f32 v[82:83], v[82:83], v[114:115]
	v_pk_mul_f32 v[84:85], v[84:85], v[116:117]
	v_pk_mul_f32 v[86:87], v[86:87], v[118:119]
	v_pk_mul_f32 v[88:89], v[88:89], v[120:121]
	v_pk_mul_f32 v[90:91], v[90:91], v[122:123]
	v_pk_mul_f32 v[92:93], v[92:93], v[124:125]
	v_pk_mul_f32 v[94:95], v[94:95], v[126:127]
	v_pk_fma_f32 v[80:81], v[80:81], v[128:129], v[144:145]
	v_pk_fma_f32 v[82:83], v[82:83], v[130:131], v[146:147]
	v_pk_fma_f32 v[84:85], v[84:85], v[132:133], v[148:149]
	v_pk_fma_f32 v[86:87], v[86:87], v[134:135], v[150:151]
	v_pk_fma_f32 v[88:89], v[88:89], v[136:137], v[152:153]
	v_pk_fma_f32 v[90:91], v[90:91], v[138:139], v[154:155]
	v_pk_fma_f32 v[92:93], v[92:93], v[140:141], v[156:157]
	v_pk_fma_f32 v[94:95], v[94:95], v[142:143], v[158:159]
	v_cvt_pk_bf16_f32 v80, v80, v81
	v_cvt_pk_bf16_f32 v81, v82, v83
	v_cvt_pk_bf16_f32 v82, v84, v85
	v_cvt_pk_bf16_f32 v83, v86, v87
	v_cvt_pk_bf16_f32 v84, v88, v89
	v_cvt_pk_bf16_f32 v85, v90, v91
	v_cvt_pk_bf16_f32 v86, v92, v93
	v_cvt_pk_bf16_f32 v87, v94, v95
	s_lshl_b32 s99, s98, 11
	v_lshl_add_u32 v8, v0, 3, s99
	global_store_dwordx2 v8, v[80:81], s[94:95]
	global_store_dwordx2 v8, v[82:83], s[94:95] offset:512
	global_store_dwordx2 v8, v[84:85], s[94:95] offset:1024
	global_store_dwordx2 v8, v[86:87], s[94:95] offset:1536
	s_lshl_b32 s99, s98, 2
	v_mov_b32_e32 v9, s99
	v_mov_b32_e32 v10, 0
	v_cmp_eq_u32_e32 vcc, 0, v0
	s_and_saveexec_b64 s[98:99], vcc
	global_store_dword v9, v10, s[90:91]
	global_store_dword v9, v10, s[92:93]
	s_or_b64 exec, exec, s[98:99]
	s_add_u32 s98, s97, 10
	s_lshl_b32 s98, s98, 12
	v_add_u32_e32 v3, s98, v1
	global_load_dwordx4 v[80:83], v3, s[88:89] nt
	global_load_dwordx4 v[84:87], v3, s[88:89] offset:1024 nt
	global_load_dwordx4 v[88:91], v3, s[88:89] offset:2048 nt
	global_load_dwordx4 v[92:95], v3, s[88:89] offset:3072 nt
	s_waitcnt vmcnt(50)
	v_mul_f32_e32 v4, v96, v96
	v_fma_f32 v4, v97, v97, v4
	v_fma_f32 v4, v98, v98, v4
	v_fma_f32 v4, v99, v99, v4
	v_fma_f32 v4, v100, v100, v4
	v_fma_f32 v4, v101, v101, v4
	v_fma_f32 v4, v102, v102, v4
	v_fma_f32 v4, v103, v103, v4
	v_fma_f32 v4, v104, v104, v4
	v_fma_f32 v4, v105, v105, v4
	v_fma_f32 v4, v106, v106, v4
	v_fma_f32 v4, v107, v107, v4
	v_fma_f32 v4, v108, v108, v4
	v_fma_f32 v4, v109, v109, v4
	v_fma_f32 v4, v110, v110, v4
	v_fma_f32 v4, v111, v111, v4
	s_nop 1
	v_add_f32_dpp v5, v4, v4 quad_perm:[1,0,3,2] row_mask:0xf bank_mask:0xf
	s_nop 1
	v_add_f32_dpp v4, v5, v5 quad_perm:[2,3,0,1] row_mask:0xf bank_mask:0xf
	s_nop 1
	v_add_f32_dpp v5, v4, v4 row_half_mirror row_mask:0xf bank_mask:0xf
	s_nop 1
	v_add_f32_dpp v4, v5, v5 row_mirror row_mask:0xf bank_mask:0xf
	s_nop 1
	v_readlane_b32 s98, v4, 0
	v_readlane_b32 s99, v4, 16
	s_nop 3
	v_mov_b32_e32 v5, s98
	v_add_f32_e32 v5, s99, v5
	v_readlane_b32 s98, v4, 32
	v_readlane_b32 s99, v4, 48
	s_nop 3
	v_add_f32_e32 v5, s98, v5
	v_add_f32_e32 v5, s99, v5
	v_mul_f32_e32 v5, 0x3a800000, v5
	v_add_f32_e32 v5, 0x358637bd, v5
	v_rsq_f32_e32 v6, v5
	s_nop 0
	s_add_u32 s98, s97, 5
	v_pk_mul_f32 v[96:97], v[96:97], v[6:7] op_sel_hi:[1,0]
	v_pk_mul_f32 v[98:99], v[98:99], v[6:7] op_sel_hi:[1,0]
	v_pk_mul_f32 v[100:101], v[100:101], v[6:7] op_sel_hi:[1,0]
	v_pk_mul_f32 v[102:103], v[102:103], v[6:7] op_sel_hi:[1,0]
	v_pk_mul_f32 v[104:105], v[104:105], v[6:7] op_sel_hi:[1,0]
	v_pk_mul_f32 v[106:107], v[106:107], v[6:7] op_sel_hi:[1,0]
	v_pk_mul_f32 v[108:109], v[108:109], v[6:7] op_sel_hi:[1,0]
	v_pk_mul_f32 v[110:111], v[110:111], v[6:7] op_sel_hi:[1,0]
	v_pk_mul_f32 v[96:97], v[96:97], v[112:113]
	v_pk_mul_f32 v[98:99], v[98:99], v[114:115]
	v_pk_mul_f32 v[100:101], v[100:101], v[116:117]
	v_pk_mul_f32 v[102:103], v[102:103], v[118:119]
	v_pk_mul_f32 v[104:105], v[104:105], v[120:121]
	v_pk_mul_f32 v[106:107], v[106:107], v[122:123]
	v_pk_mul_f32 v[108:109], v[108:109], v[124:125]
	v_pk_mul_f32 v[110:111], v[110:111], v[126:127]
	v_pk_fma_f32 v[96:97], v[96:97], v[128:129], v[144:145]
	v_pk_fma_f32 v[98:99], v[98:99], v[130:131], v[146:147]
	v_pk_fma_f32 v[100:101], v[100:101], v[132:133], v[148:149]
	v_pk_fma_f32 v[102:103], v[102:103], v[134:135], v[150:151]
	v_pk_fma_f32 v[104:105], v[104:105], v[136:137], v[152:153]
	v_pk_fma_f32 v[106:107], v[106:107], v[138:139], v[154:155]
	v_pk_fma_f32 v[108:109], v[108:109], v[140:141], v[156:157]
	v_pk_fma_f32 v[110:111], v[110:111], v[142:143], v[158:159]
	v_cvt_pk_bf16_f32 v96, v96, v97
	v_cvt_pk_bf16_f32 v97, v98, v99
	v_cvt_pk_bf16_f32 v98, v100, v101
	v_cvt_pk_bf16_f32 v99, v102, v103
	v_cvt_pk_bf16_f32 v100, v104, v105
	v_cvt_pk_bf16_f32 v101, v106, v107
	v_cvt_pk_bf16_f32 v102, v108, v109
	v_cvt_pk_bf16_f32 v103, v110, v111
	s_lshl_b32 s99, s98, 11
	v_lshl_add_u32 v8, v0, 3, s99
	global_store_dwordx2 v8, v[96:97], s[94:95]
	global_store_dwordx2 v8, v[98:99], s[94:95] offset:512
	global_store_dwordx2 v8, v[100:101], s[94:95] offset:1024
	global_store_dwordx2 v8, v[102:103], s[94:95] offset:1536
	s_lshl_b32 s99, s98, 2
	v_mov_b32_e32 v9, s99
	v_mov_b32_e32 v10, 0
	v_cmp_eq_u32_e32 vcc, 0, v0
	s_and_saveexec_b64 s[98:99], vcc
	global_store_dword v9, v10, s[90:91]
	global_store_dword v9, v10, s[92:93]
	s_or_b64 exec, exec, s[98:99]
	s_add_u32 s98, s97, 11
	s_lshl_b32 s98, s98, 12
	v_add_u32_e32 v3, s98, v1
	global_load_dwordx4 v[96:99], v3, s[88:89] nt
	global_load_dwordx4 v[100:103], v3, s[88:89] offset:1024 nt
	global_load_dwordx4 v[104:107], v3, s[88:89] offset:2048 nt
	global_load_dwordx4 v[108:111], v3, s[88:89] offset:3072 nt
	s_waitcnt vmcnt(50)
	v_mul_f32_e32 v4, v16, v16
	v_fma_f32 v4, v17, v17, v4
	v_fma_f32 v4, v18, v18, v4
	v_fma_f32 v4, v19, v19, v4
	v_fma_f32 v4, v20, v20, v4
	v_fma_f32 v4, v21, v21, v4
	v_fma_f32 v4, v22, v22, v4
	v_fma_f32 v4, v23, v23, v4
	v_fma_f32 v4, v24, v24, v4
	v_fma_f32 v4, v25, v25, v4
	v_fma_f32 v4, v26, v26, v4
	v_fma_f32 v4, v27, v27, v4
	v_fma_f32 v4, v28, v28, v4
	v_fma_f32 v4, v29, v29, v4
	v_fma_f32 v4, v30, v30, v4
	v_fma_f32 v4, v31, v31, v4
	s_nop 1
	v_add_f32_dpp v5, v4, v4 quad_perm:[1,0,3,2] row_mask:0xf bank_mask:0xf
	s_nop 1
	v_add_f32_dpp v4, v5, v5 quad_perm:[2,3,0,1] row_mask:0xf bank_mask:0xf
	s_nop 1
	v_add_f32_dpp v5, v4, v4 row_half_mirror row_mask:0xf bank_mask:0xf
	s_nop 1
	v_add_f32_dpp v4, v5, v5 row_mirror row_mask:0xf bank_mask:0xf
	s_nop 1
	v_readlane_b32 s98, v4, 0
	v_readlane_b32 s99, v4, 16
	s_nop 3
	v_mov_b32_e32 v5, s98
	v_add_f32_e32 v5, s99, v5
	v_readlane_b32 s98, v4, 32
	v_readlane_b32 s99, v4, 48
	s_nop 3
	v_add_f32_e32 v5, s98, v5
	v_add_f32_e32 v5, s99, v5
	v_mul_f32_e32 v5, 0x3a800000, v5
	v_add_f32_e32 v5, 0x358637bd, v5
	v_rsq_f32_e32 v6, v5
	s_nop 0
	s_add_u32 s98, s97, 6
	v_pk_mul_f32 v[16:17], v[16:17], v[6:7] op_sel_hi:[1,0]
	v_pk_mul_f32 v[18:19], v[18:19], v[6:7] op_sel_hi:[1,0]
	v_pk_mul_f32 v[20:21], v[20:21], v[6:7] op_sel_hi:[1,0]
	v_pk_mul_f32 v[22:23], v[22:23], v[6:7] op_sel_hi:[1,0]
	v_pk_mul_f32 v[24:25], v[24:25], v[6:7] op_sel_hi:[1,0]
	v_pk_mul_f32 v[26:27], v[26:27], v[6:7] op_sel_hi:[1,0]
	v_pk_mul_f32 v[28:29], v[28:29], v[6:7] op_sel_hi:[1,0]
	v_pk_mul_f32 v[30:31], v[30:31], v[6:7] op_sel_hi:[1,0]
	v_pk_mul_f32 v[16:17], v[16:17], v[112:113]
	v_pk_mul_f32 v[18:19], v[18:19], v[114:115]
	v_pk_mul_f32 v[20:21], v[20:21], v[116:117]
	v_pk_mul_f32 v[22:23], v[22:23], v[118:119]
	v_pk_mul_f32 v[24:25], v[24:25], v[120:121]
	v_pk_mul_f32 v[26:27], v[26:27], v[122:123]
	v_pk_mul_f32 v[28:29], v[28:29], v[124:125]
	v_pk_mul_f32 v[30:31], v[30:31], v[126:127]
	v_pk_fma_f32 v[16:17], v[16:17], v[128:129], v[144:145]
	v_pk_fma_f32 v[18:19], v[18:19], v[130:131], v[146:147]
	v_pk_fma_f32 v[20:21], v[20:21], v[132:133], v[148:149]
	v_pk_fma_f32 v[22:23], v[22:23], v[134:135], v[150:151]
	v_pk_fma_f32 v[24:25], v[24:25], v[136:137], v[152:153]
	v_pk_fma_f32 v[26:27], v[26:27], v[138:139], v[154:155]
	v_pk_fma_f32 v[28:29], v[28:29], v[140:141], v[156:157]
	v_pk_fma_f32 v[30:31], v[30:31], v[142:143], v[158:159]
	v_cvt_pk_bf16_f32 v16, v16, v17
	v_cvt_pk_bf16_f32 v17, v18, v19
	v_cvt_pk_bf16_f32 v18, v20, v21
	v_cvt_pk_bf16_f32 v19, v22, v23
	v_cvt_pk_bf16_f32 v20, v24, v25
	v_cvt_pk_bf16_f32 v21, v26, v27
	v_cvt_pk_bf16_f32 v22, v28, v29
	v_cvt_pk_bf16_f32 v23, v30, v31
	s_lshl_b32 s99, s98, 11
	v_lshl_add_u32 v8, v0, 3, s99
	global_store_dwordx2 v8, v[16:17], s[94:95]
	global_store_dwordx2 v8, v[18:19], s[94:95] offset:512
	global_store_dwordx2 v8, v[20:21], s[94:95] offset:1024
	global_store_dwordx2 v8, v[22:23], s[94:95] offset:1536
	s_lshl_b32 s99, s98, 2
	v_mov_b32_e32 v9, s99
	v_mov_b32_e32 v10, 0
	v_cmp_eq_u32_e32 vcc, 0, v0
	s_and_saveexec_b64 s[98:99], vcc
	global_store_dword v9, v10, s[90:91]
	global_store_dword v9, v10, s[92:93]
	s_or_b64 exec, exec, s[98:99]
	s_add_u32 s98, s97, 12
	s_lshl_b32 s98, s98, 12
	v_add_u32_e32 v3, s98, v1
	global_load_dwordx4 v[16:19], v3, s[88:89] nt
	global_load_dwordx4 v[20:23], v3, s[88:89] offset:1024 nt
	global_load_dwordx4 v[24:27], v3, s[88:89] offset:2048 nt
	global_load_dwordx4 v[28:31], v3, s[88:89] offset:3072 nt
	s_waitcnt vmcnt(50)
	v_mul_f32_e32 v4, v32, v32
	v_fma_f32 v4, v33, v33, v4
	v_fma_f32 v4, v34, v34, v4
	v_fma_f32 v4, v35, v35, v4
	v_fma_f32 v4, v36, v36, v4
	v_fma_f32 v4, v37, v37, v4
	v_fma_f32 v4, v38, v38, v4
	v_fma_f32 v4, v39, v39, v4
	v_fma_f32 v4, v40, v40, v4
	v_fma_f32 v4, v41, v41, v4
	v_fma_f32 v4, v42, v42, v4
	v_fma_f32 v4, v43, v43, v4
	v_fma_f32 v4, v44, v44, v4
	v_fma_f32 v4, v45, v45, v4
	v_fma_f32 v4, v46, v46, v4
	v_fma_f32 v4, v47, v47, v4
	s_nop 1
	v_add_f32_dpp v5, v4, v4 quad_perm:[1,0,3,2] row_mask:0xf bank_mask:0xf
	s_nop 1
	v_add_f32_dpp v4, v5, v5 quad_perm:[2,3,0,1] row_mask:0xf bank_mask:0xf
	s_nop 1
	v_add_f32_dpp v5, v4, v4 row_half_mirror row_mask:0xf bank_mask:0xf
	s_nop 1
	v_add_f32_dpp v4, v5, v5 row_mirror row_mask:0xf bank_mask:0xf
	s_nop 1
	v_readlane_b32 s98, v4, 0
	v_readlane_b32 s99, v4, 16
	s_nop 3
	v_mov_b32_e32 v5, s98
	v_add_f32_e32 v5, s99, v5
	v_readlane_b32 s98, v4, 32
	v_readlane_b32 s99, v4, 48
	s_nop 3
	v_add_f32_e32 v5, s98, v5
	v_add_f32_e32 v5, s99, v5
	v_mul_f32_e32 v5, 0x3a800000, v5
	v_add_f32_e32 v5, 0x358637bd, v5
	v_rsq_f32_e32 v6, v5
	s_nop 0
	s_add_u32 s98, s97, 7
	v_pk_mul_f32 v[32:33], v[32:33], v[6:7] op_sel_hi:[1,0]
	v_pk_mul_f32 v[34:35], v[34:35], v[6:7] op_sel_hi:[1,0]
	v_pk_mul_f32 v[36:37], v[36:37], v[6:7] op_sel_hi:[1,0]
	v_pk_mul_f32 v[38:39], v[38:39], v[6:7] op_sel_hi:[1,0]
	v_pk_mul_f32 v[40:41], v[40:41], v[6:7] op_sel_hi:[1,0]
	v_pk_mul_f32 v[42:43], v[42:43], v[6:7] op_sel_hi:[1,0]
	v_pk_mul_f32 v[44:45], v[44:45], v[6:7] op_sel_hi:[1,0]
	v_pk_mul_f32 v[46:47], v[46:47], v[6:7] op_sel_hi:[1,0]
	v_pk_mul_f32 v[32:33], v[32:33], v[112:113]
	v_pk_mul_f32 v[34:35], v[34:35], v[114:115]
	v_pk_mul_f32 v[36:37], v[36:37], v[116:117]
	v_pk_mul_f32 v[38:39], v[38:39], v[118:119]
	v_pk_mul_f32 v[40:41], v[40:41], v[120:121]
	v_pk_mul_f32 v[42:43], v[42:43], v[122:123]
	v_pk_mul_f32 v[44:45], v[44:45], v[124:125]
	v_pk_mul_f32 v[46:47], v[46:47], v[126:127]
	v_pk_fma_f32 v[32:33], v[32:33], v[128:129], v[144:145]
	v_pk_fma_f32 v[34:35], v[34:35], v[130:131], v[146:147]
	v_pk_fma_f32 v[36:37], v[36:37], v[132:133], v[148:149]
	v_pk_fma_f32 v[38:39], v[38:39], v[134:135], v[150:151]
	v_pk_fma_f32 v[40:41], v[40:41], v[136:137], v[152:153]
	v_pk_fma_f32 v[42:43], v[42:43], v[138:139], v[154:155]
	v_pk_fma_f32 v[44:45], v[44:45], v[140:141], v[156:157]
	v_pk_fma_f32 v[46:47], v[46:47], v[142:143], v[158:159]
	v_cvt_pk_bf16_f32 v32, v32, v33
	v_cvt_pk_bf16_f32 v33, v34, v35
	v_cvt_pk_bf16_f32 v34, v36, v37
	v_cvt_pk_bf16_f32 v35, v38, v39
	v_cvt_pk_bf16_f32 v36, v40, v41
	v_cvt_pk_bf16_f32 v37, v42, v43
	v_cvt_pk_bf16_f32 v38, v44, v45
	v_cvt_pk_bf16_f32 v39, v46, v47
	s_lshl_b32 s99, s98, 11
	v_lshl_add_u32 v8, v0, 3, s99
	global_store_dwordx2 v8, v[32:33], s[94:95]
	global_store_dwordx2 v8, v[34:35], s[94:95] offset:512
	global_store_dwordx2 v8, v[36:37], s[94:95] offset:1024
	global_store_dwordx2 v8, v[38:39], s[94:95] offset:1536
	s_lshl_b32 s99, s98, 2
	v_mov_b32_e32 v9, s99
	v_mov_b32_e32 v10, 0
	v_cmp_eq_u32_e32 vcc, 0, v0
	s_and_saveexec_b64 s[98:99], vcc
	global_store_dword v9, v10, s[90:91]
	global_store_dword v9, v10, s[92:93]
	s_or_b64 exec, exec, s[98:99]
	s_add_u32 s98, s97, 13
	s_lshl_b32 s98, s98, 12
	v_add_u32_e32 v3, s98, v1
	global_load_dwordx4 v[32:35], v3, s[88:89] nt
	global_load_dwordx4 v[36:39], v3, s[88:89] offset:1024 nt
	global_load_dwordx4 v[40:43], v3, s[88:89] offset:2048 nt
	global_load_dwordx4 v[44:47], v3, s[88:89] offset:3072 nt
	s_waitcnt vmcnt(50)
	v_mul_f32_e32 v4, v48, v48
	v_fma_f32 v4, v49, v49, v4
	v_fma_f32 v4, v50, v50, v4
	v_fma_f32 v4, v51, v51, v4
	v_fma_f32 v4, v52, v52, v4
	v_fma_f32 v4, v53, v53, v4
	v_fma_f32 v4, v54, v54, v4
	v_fma_f32 v4, v55, v55, v4
	v_fma_f32 v4, v56, v56, v4
	v_fma_f32 v4, v57, v57, v4
	v_fma_f32 v4, v58, v58, v4
	v_fma_f32 v4, v59, v59, v4
	v_fma_f32 v4, v60, v60, v4
	v_fma_f32 v4, v61, v61, v4
	v_fma_f32 v4, v62, v62, v4
	v_fma_f32 v4, v63, v63, v4
	s_nop 1
	v_add_f32_dpp v5, v4, v4 quad_perm:[1,0,3,2] row_mask:0xf bank_mask:0xf
	s_nop 1
	v_add_f32_dpp v4, v5, v5 quad_perm:[2,3,0,1] row_mask:0xf bank_mask:0xf
	s_nop 1
	v_add_f32_dpp v5, v4, v4 row_half_mirror row_mask:0xf bank_mask:0xf
	s_nop 1
	v_add_f32_dpp v4, v5, v5 row_mirror row_mask:0xf bank_mask:0xf
	s_nop 1
	v_readlane_b32 s98, v4, 0
	v_readlane_b32 s99, v4, 16
	s_nop 3
	v_mov_b32_e32 v5, s98
	v_add_f32_e32 v5, s99, v5
	v_readlane_b32 s98, v4, 32
	v_readlane_b32 s99, v4, 48
	s_nop 3
	v_add_f32_e32 v5, s98, v5
	v_add_f32_e32 v5, s99, v5
	v_mul_f32_e32 v5, 0x3a800000, v5
	v_add_f32_e32 v5, 0x358637bd, v5
	v_rsq_f32_e32 v6, v5
	s_nop 0
	s_add_u32 s98, s97, 8
	v_pk_mul_f32 v[48:49], v[48:49], v[6:7] op_sel_hi:[1,0]
	v_pk_mul_f32 v[50:51], v[50:51], v[6:7] op_sel_hi:[1,0]
	v_pk_mul_f32 v[52:53], v[52:53], v[6:7] op_sel_hi:[1,0]
	v_pk_mul_f32 v[54:55], v[54:55], v[6:7] op_sel_hi:[1,0]
	v_pk_mul_f32 v[56:57], v[56:57], v[6:7] op_sel_hi:[1,0]
	v_pk_mul_f32 v[58:59], v[58:59], v[6:7] op_sel_hi:[1,0]
	v_pk_mul_f32 v[60:61], v[60:61], v[6:7] op_sel_hi:[1,0]
	v_pk_mul_f32 v[62:63], v[62:63], v[6:7] op_sel_hi:[1,0]
	v_pk_mul_f32 v[48:49], v[48:49], v[112:113]
	v_pk_mul_f32 v[50:51], v[50:51], v[114:115]
	v_pk_mul_f32 v[52:53], v[52:53], v[116:117]
	v_pk_mul_f32 v[54:55], v[54:55], v[118:119]
	v_pk_mul_f32 v[56:57], v[56:57], v[120:121]
	v_pk_mul_f32 v[58:59], v[58:59], v[122:123]
	v_pk_mul_f32 v[60:61], v[60:61], v[124:125]
	v_pk_mul_f32 v[62:63], v[62:63], v[126:127]
	v_pk_fma_f32 v[48:49], v[48:49], v[128:129], v[144:145]
	v_pk_fma_f32 v[50:51], v[50:51], v[130:131], v[146:147]
	v_pk_fma_f32 v[52:53], v[52:53], v[132:133], v[148:149]
	v_pk_fma_f32 v[54:55], v[54:55], v[134:135], v[150:151]
	v_pk_fma_f32 v[56:57], v[56:57], v[136:137], v[152:153]
	v_pk_fma_f32 v[58:59], v[58:59], v[138:139], v[154:155]
	v_pk_fma_f32 v[60:61], v[60:61], v[140:141], v[156:157]
	v_pk_fma_f32 v[62:63], v[62:63], v[142:143], v[158:159]
	v_cvt_pk_bf16_f32 v48, v48, v49
	v_cvt_pk_bf16_f32 v49, v50, v51
	v_cvt_pk_bf16_f32 v50, v52, v53
	v_cvt_pk_bf16_f32 v51, v54, v55
	v_cvt_pk_bf16_f32 v52, v56, v57
	v_cvt_pk_bf16_f32 v53, v58, v59
	v_cvt_pk_bf16_f32 v54, v60, v61
	v_cvt_pk_bf16_f32 v55, v62, v63
	s_lshl_b32 s99, s98, 11
	v_lshl_add_u32 v8, v0, 3, s99
	global_store_dwordx2 v8, v[48:49], s[94:95]
	global_store_dwordx2 v8, v[50:51], s[94:95] offset:512
	global_store_dwordx2 v8, v[52:53], s[94:95] offset:1024
	global_store_dwordx2 v8, v[54:55], s[94:95] offset:1536
	s_lshl_b32 s99, s98, 2
	v_mov_b32_e32 v9, s99
	v_mov_b32_e32 v10, 0
	v_cmp_eq_u32_e32 vcc, 0, v0
	s_and_saveexec_b64 s[98:99], vcc
	global_store_dword v9, v10, s[90:91]
	global_store_dword v9, v10, s[92:93]
	s_or_b64 exec, exec, s[98:99]
	s_add_u32 s98, s97, 14
	s_lshl_b32 s98, s98, 12
	v_add_u32_e32 v3, s98, v1
	global_load_dwordx4 v[48:51], v3, s[88:89] nt
	global_load_dwordx4 v[52:55], v3, s[88:89] offset:1024 nt
	global_load_dwordx4 v[56:59], v3, s[88:89] offset:2048 nt
	global_load_dwordx4 v[60:63], v3, s[88:89] offset:3072 nt
	s_waitcnt vmcnt(50)
	v_mul_f32_e32 v4, v64, v64
	v_fma_f32 v4, v65, v65, v4
	v_fma_f32 v4, v66, v66, v4
	v_fma_f32 v4, v67, v67, v4
	v_fma_f32 v4, v68, v68, v4
	v_fma_f32 v4, v69, v69, v4
	v_fma_f32 v4, v70, v70, v4
	v_fma_f32 v4, v71, v71, v4
	v_fma_f32 v4, v72, v72, v4
	v_fma_f32 v4, v73, v73, v4
	v_fma_f32 v4, v74, v74, v4
	v_fma_f32 v4, v75, v75, v4
	v_fma_f32 v4, v76, v76, v4
	v_fma_f32 v4, v77, v77, v4
	v_fma_f32 v4, v78, v78, v4
	v_fma_f32 v4, v79, v79, v4
	s_nop 1
	v_add_f32_dpp v5, v4, v4 quad_perm:[1,0,3,2] row_mask:0xf bank_mask:0xf
	s_nop 1
	v_add_f32_dpp v4, v5, v5 quad_perm:[2,3,0,1] row_mask:0xf bank_mask:0xf
	s_nop 1
	v_add_f32_dpp v5, v4, v4 row_half_mirror row_mask:0xf bank_mask:0xf
	s_nop 1
	v_add_f32_dpp v4, v5, v5 row_mirror row_mask:0xf bank_mask:0xf
	s_nop 1
	v_readlane_b32 s98, v4, 0
	v_readlane_b32 s99, v4, 16
	s_nop 3
	v_mov_b32_e32 v5, s98
	v_add_f32_e32 v5, s99, v5
	v_readlane_b32 s98, v4, 32
	v_readlane_b32 s99, v4, 48
	s_nop 3
	v_add_f32_e32 v5, s98, v5
	v_add_f32_e32 v5, s99, v5
	v_mul_f32_e32 v5, 0x3a800000, v5
	v_add_f32_e32 v5, 0x358637bd, v5
	v_rsq_f32_e32 v6, v5
	s_nop 0
	s_add_u32 s98, s97, 9
	v_pk_mul_f32 v[64:65], v[64:65], v[6:7] op_sel_hi:[1,0]
	v_pk_mul_f32 v[66:67], v[66:67], v[6:7] op_sel_hi:[1,0]
	v_pk_mul_f32 v[68:69], v[68:69], v[6:7] op_sel_hi:[1,0]
	v_pk_mul_f32 v[70:71], v[70:71], v[6:7] op_sel_hi:[1,0]
	v_pk_mul_f32 v[72:73], v[72:73], v[6:7] op_sel_hi:[1,0]
	v_pk_mul_f32 v[74:75], v[74:75], v[6:7] op_sel_hi:[1,0]
	v_pk_mul_f32 v[76:77], v[76:77], v[6:7] op_sel_hi:[1,0]
	v_pk_mul_f32 v[78:79], v[78:79], v[6:7] op_sel_hi:[1,0]
	v_pk_mul_f32 v[64:65], v[64:65], v[112:113]
	v_pk_mul_f32 v[66:67], v[66:67], v[114:115]
	v_pk_mul_f32 v[68:69], v[68:69], v[116:117]
	v_pk_mul_f32 v[70:71], v[70:71], v[118:119]
	v_pk_mul_f32 v[72:73], v[72:73], v[120:121]
	v_pk_mul_f32 v[74:75], v[74:75], v[122:123]
	v_pk_mul_f32 v[76:77], v[76:77], v[124:125]
	v_pk_mul_f32 v[78:79], v[78:79], v[126:127]
	v_pk_fma_f32 v[64:65], v[64:65], v[128:129], v[144:145]
	v_pk_fma_f32 v[66:67], v[66:67], v[130:131], v[146:147]
	v_pk_fma_f32 v[68:69], v[68:69], v[132:133], v[148:149]
	v_pk_fma_f32 v[70:71], v[70:71], v[134:135], v[150:151]
	v_pk_fma_f32 v[72:73], v[72:73], v[136:137], v[152:153]
	v_pk_fma_f32 v[74:75], v[74:75], v[138:139], v[154:155]
	v_pk_fma_f32 v[76:77], v[76:77], v[140:141], v[156:157]
	v_pk_fma_f32 v[78:79], v[78:79], v[142:143], v[158:159]
	v_cvt_pk_bf16_f32 v64, v64, v65
	v_cvt_pk_bf16_f32 v65, v66, v67
	v_cvt_pk_bf16_f32 v66, v68, v69
	v_cvt_pk_bf16_f32 v67, v70, v71
	v_cvt_pk_bf16_f32 v68, v72, v73
	v_cvt_pk_bf16_f32 v69, v74, v75
	v_cvt_pk_bf16_f32 v70, v76, v77
	v_cvt_pk_bf16_f32 v71, v78, v79
	s_lshl_b32 s99, s98, 11
	v_lshl_add_u32 v8, v0, 3, s99
	global_store_dwordx2 v8, v[64:65], s[94:95]
	global_store_dwordx2 v8, v[66:67], s[94:95] offset:512
	global_store_dwordx2 v8, v[68:69], s[94:95] offset:1024
	global_store_dwordx2 v8, v[70:71], s[94:95] offset:1536
	s_lshl_b32 s99, s98, 2
	v_mov_b32_e32 v9, s99
	v_mov_b32_e32 v10, 0
	v_cmp_eq_u32_e32 vcc, 0, v0
	s_and_saveexec_b64 s[98:99], vcc
	global_store_dword v9, v10, s[90:91]
	global_store_dword v9, v10, s[92:93]
	s_or_b64 exec, exec, s[98:99]
	s_add_u32 s98, s97, 15
	s_lshl_b32 s98, s98, 12
	v_add_u32_e32 v3, s98, v1
	global_load_dwordx4 v[64:67], v3, s[88:89] nt
	global_load_dwordx4 v[68:71], v3, s[88:89] offset:1024 nt
	global_load_dwordx4 v[72:75], v3, s[88:89] offset:2048 nt
	global_load_dwordx4 v[76:79], v3, s[88:89] offset:3072 nt
	s_waitcnt vmcnt(50)
	v_mul_f32_e32 v4, v80, v80
	v_fma_f32 v4, v81, v81, v4
	v_fma_f32 v4, v82, v82, v4
	v_fma_f32 v4, v83, v83, v4
	v_fma_f32 v4, v84, v84, v4
	v_fma_f32 v4, v85, v85, v4
	v_fma_f32 v4, v86, v86, v4
	v_fma_f32 v4, v87, v87, v4
	v_fma_f32 v4, v88, v88, v4
	v_fma_f32 v4, v89, v89, v4
	v_fma_f32 v4, v90, v90, v4
	v_fma_f32 v4, v91, v91, v4
	v_fma_f32 v4, v92, v92, v4
	v_fma_f32 v4, v93, v93, v4
	v_fma_f32 v4, v94, v94, v4
	v_fma_f32 v4, v95, v95, v4
	s_nop 1
	v_add_f32_dpp v5, v4, v4 quad_perm:[1,0,3,2] row_mask:0xf bank_mask:0xf
	s_nop 1
	v_add_f32_dpp v4, v5, v5 quad_perm:[2,3,0,1] row_mask:0xf bank_mask:0xf
	s_nop 1
	v_add_f32_dpp v5, v4, v4 row_half_mirror row_mask:0xf bank_mask:0xf
	s_nop 1
	v_add_f32_dpp v4, v5, v5 row_mirror row_mask:0xf bank_mask:0xf
	s_nop 1
	v_readlane_b32 s98, v4, 0
	v_readlane_b32 s99, v4, 16
	s_nop 3
	v_mov_b32_e32 v5, s98
	v_add_f32_e32 v5, s99, v5
	v_readlane_b32 s98, v4, 32
	v_readlane_b32 s99, v4, 48
	s_nop 3
	v_add_f32_e32 v5, s98, v5
	v_add_f32_e32 v5, s99, v5
	v_mul_f32_e32 v5, 0x3a800000, v5
	v_add_f32_e32 v5, 0x358637bd, v5
	v_rsq_f32_e32 v6, v5
	s_nop 0
	s_add_u32 s98, s97, 10
	v_pk_mul_f32 v[80:81], v[80:81], v[6:7] op_sel_hi:[1,0]
	v_pk_mul_f32 v[82:83], v[82:83], v[6:7] op_sel_hi:[1,0]
	v_pk_mul_f32 v[84:85], v[84:85], v[6:7] op_sel_hi:[1,0]
	v_pk_mul_f32 v[86:87], v[86:87], v[6:7] op_sel_hi:[1,0]
	v_pk_mul_f32 v[88:89], v[88:89], v[6:7] op_sel_hi:[1,0]
	v_pk_mul_f32 v[90:91], v[90:91], v[6:7] op_sel_hi:[1,0]
	v_pk_mul_f32 v[92:93], v[92:93], v[6:7] op_sel_hi:[1,0]
	v_pk_mul_f32 v[94:95], v[94:95], v[6:7] op_sel_hi:[1,0]
	v_pk_mul_f32 v[80:81], v[80:81], v[112:113]
	v_pk_mul_f32 v[82:83], v[82:83], v[114:115]
	v_pk_mul_f32 v[84:85], v[84:85], v[116:117]
	v_pk_mul_f32 v[86:87], v[86:87], v[118:119]
	v_pk_mul_f32 v[88:89], v[88:89], v[120:121]
	v_pk_mul_f32 v[90:91], v[90:91], v[122:123]
	v_pk_mul_f32 v[92:93], v[92:93], v[124:125]
	v_pk_mul_f32 v[94:95], v[94:95], v[126:127]
	v_pk_fma_f32 v[80:81], v[80:81], v[128:129], v[144:145]
	v_pk_fma_f32 v[82:83], v[82:83], v[130:131], v[146:147]
	v_pk_fma_f32 v[84:85], v[84:85], v[132:133], v[148:149]
	v_pk_fma_f32 v[86:87], v[86:87], v[134:135], v[150:151]
	v_pk_fma_f32 v[88:89], v[88:89], v[136:137], v[152:153]
	v_pk_fma_f32 v[90:91], v[90:91], v[138:139], v[154:155]
	v_pk_fma_f32 v[92:93], v[92:93], v[140:141], v[156:157]
	v_pk_fma_f32 v[94:95], v[94:95], v[142:143], v[158:159]
	v_cvt_pk_bf16_f32 v80, v80, v81
	v_cvt_pk_bf16_f32 v81, v82, v83
	v_cvt_pk_bf16_f32 v82, v84, v85
	v_cvt_pk_bf16_f32 v83, v86, v87
	v_cvt_pk_bf16_f32 v84, v88, v89
	v_cvt_pk_bf16_f32 v85, v90, v91
	v_cvt_pk_bf16_f32 v86, v92, v93
	v_cvt_pk_bf16_f32 v87, v94, v95
	s_lshl_b32 s99, s98, 11
	v_lshl_add_u32 v8, v0, 3, s99
	global_store_dwordx2 v8, v[80:81], s[94:95]
	global_store_dwordx2 v8, v[82:83], s[94:95] offset:512
	global_store_dwordx2 v8, v[84:85], s[94:95] offset:1024
	global_store_dwordx2 v8, v[86:87], s[94:95] offset:1536
	s_lshl_b32 s99, s98, 2
	v_mov_b32_e32 v9, s99
	v_mov_b32_e32 v10, 0
	v_cmp_eq_u32_e32 vcc, 0, v0
	s_and_saveexec_b64 s[98:99], vcc
	global_store_dword v9, v10, s[90:91]
	global_store_dword v9, v10, s[92:93]
	s_or_b64 exec, exec, s[98:99]
	s_waitcnt vmcnt(46)
	v_mul_f32_e32 v4, v96, v96
	v_fma_f32 v4, v97, v97, v4
	v_fma_f32 v4, v98, v98, v4
	v_fma_f32 v4, v99, v99, v4
	v_fma_f32 v4, v100, v100, v4
	v_fma_f32 v4, v101, v101, v4
	v_fma_f32 v4, v102, v102, v4
	v_fma_f32 v4, v103, v103, v4
	v_fma_f32 v4, v104, v104, v4
	v_fma_f32 v4, v105, v105, v4
	v_fma_f32 v4, v106, v106, v4
	v_fma_f32 v4, v107, v107, v4
	v_fma_f32 v4, v108, v108, v4
	v_fma_f32 v4, v109, v109, v4
	v_fma_f32 v4, v110, v110, v4
	v_fma_f32 v4, v111, v111, v4
	s_nop 1
	v_add_f32_dpp v5, v4, v4 quad_perm:[1,0,3,2] row_mask:0xf bank_mask:0xf
	s_nop 1
	v_add_f32_dpp v4, v5, v5 quad_perm:[2,3,0,1] row_mask:0xf bank_mask:0xf
	s_nop 1
	v_add_f32_dpp v5, v4, v4 row_half_mirror row_mask:0xf bank_mask:0xf
	s_nop 1
	v_add_f32_dpp v4, v5, v5 row_mirror row_mask:0xf bank_mask:0xf
	s_nop 1
	v_readlane_b32 s98, v4, 0
	v_readlane_b32 s99, v4, 16
	s_nop 3
	v_mov_b32_e32 v5, s98
	v_add_f32_e32 v5, s99, v5
	v_readlane_b32 s98, v4, 32
	v_readlane_b32 s99, v4, 48
	s_nop 3
	v_add_f32_e32 v5, s98, v5
	v_add_f32_e32 v5, s99, v5
	v_mul_f32_e32 v5, 0x3a800000, v5
	v_add_f32_e32 v5, 0x358637bd, v5
	v_rsq_f32_e32 v6, v5
	s_nop 0
	s_add_u32 s98, s97, 11
	v_pk_mul_f32 v[96:97], v[96:97], v[6:7] op_sel_hi:[1,0]
	v_pk_mul_f32 v[98:99], v[98:99], v[6:7] op_sel_hi:[1,0]
	v_pk_mul_f32 v[100:101], v[100:101], v[6:7] op_sel_hi:[1,0]
	v_pk_mul_f32 v[102:103], v[102:103], v[6:7] op_sel_hi:[1,0]
	v_pk_mul_f32 v[104:105], v[104:105], v[6:7] op_sel_hi:[1,0]
	v_pk_mul_f32 v[106:107], v[106:107], v[6:7] op_sel_hi:[1,0]
	v_pk_mul_f32 v[108:109], v[108:109], v[6:7] op_sel_hi:[1,0]
	v_pk_mul_f32 v[110:111], v[110:111], v[6:7] op_sel_hi:[1,0]
	v_pk_mul_f32 v[96:97], v[96:97], v[112:113]
	v_pk_mul_f32 v[98:99], v[98:99], v[114:115]
	v_pk_mul_f32 v[100:101], v[100:101], v[116:117]
	v_pk_mul_f32 v[102:103], v[102:103], v[118:119]
	v_pk_mul_f32 v[104:105], v[104:105], v[120:121]
	v_pk_mul_f32 v[106:107], v[106:107], v[122:123]
	v_pk_mul_f32 v[108:109], v[108:109], v[124:125]
	v_pk_mul_f32 v[110:111], v[110:111], v[126:127]
	v_pk_fma_f32 v[96:97], v[96:97], v[128:129], v[144:145]
	v_pk_fma_f32 v[98:99], v[98:99], v[130:131], v[146:147]
	v_pk_fma_f32 v[100:101], v[100:101], v[132:133], v[148:149]
	v_pk_fma_f32 v[102:103], v[102:103], v[134:135], v[150:151]
	v_pk_fma_f32 v[104:105], v[104:105], v[136:137], v[152:153]
	v_pk_fma_f32 v[106:107], v[106:107], v[138:139], v[154:155]
	v_pk_fma_f32 v[108:109], v[108:109], v[140:141], v[156:157]
	v_pk_fma_f32 v[110:111], v[110:111], v[142:143], v[158:159]
	v_cvt_pk_bf16_f32 v96, v96, v97
	v_cvt_pk_bf16_f32 v97, v98, v99
	v_cvt_pk_bf16_f32 v98, v100, v101
	v_cvt_pk_bf16_f32 v99, v102, v103
	v_cvt_pk_bf16_f32 v100, v104, v105
	v_cvt_pk_bf16_f32 v101, v106, v107
	v_cvt_pk_bf16_f32 v102, v108, v109
	v_cvt_pk_bf16_f32 v103, v110, v111
	s_lshl_b32 s99, s98, 11
	v_lshl_add_u32 v8, v0, 3, s99
	global_store_dwordx2 v8, v[96:97], s[94:95]
	global_store_dwordx2 v8, v[98:99], s[94:95] offset:512
	global_store_dwordx2 v8, v[100:101], s[94:95] offset:1024
	global_store_dwordx2 v8, v[102:103], s[94:95] offset:1536
	s_lshl_b32 s99, s98, 2
	v_mov_b32_e32 v9, s99
	v_mov_b32_e32 v10, 0
	v_cmp_eq_u32_e32 vcc, 0, v0
	s_and_saveexec_b64 s[98:99], vcc
	global_store_dword v9, v10, s[90:91]
	global_store_dword v9, v10, s[92:93]
	s_or_b64 exec, exec, s[98:99]
	s_waitcnt vmcnt(42)
	v_mul_f32_e32 v4, v16, v16
	v_fma_f32 v4, v17, v17, v4
	v_fma_f32 v4, v18, v18, v4
	v_fma_f32 v4, v19, v19, v4
	v_fma_f32 v4, v20, v20, v4
	v_fma_f32 v4, v21, v21, v4
	v_fma_f32 v4, v22, v22, v4
	v_fma_f32 v4, v23, v23, v4
	v_fma_f32 v4, v24, v24, v4
	v_fma_f32 v4, v25, v25, v4
	v_fma_f32 v4, v26, v26, v4
	v_fma_f32 v4, v27, v27, v4
	v_fma_f32 v4, v28, v28, v4
	v_fma_f32 v4, v29, v29, v4
	v_fma_f32 v4, v30, v30, v4
	v_fma_f32 v4, v31, v31, v4
	s_nop 1
	v_add_f32_dpp v5, v4, v4 quad_perm:[1,0,3,2] row_mask:0xf bank_mask:0xf
	s_nop 1
	v_add_f32_dpp v4, v5, v5 quad_perm:[2,3,0,1] row_mask:0xf bank_mask:0xf
	s_nop 1
	v_add_f32_dpp v5, v4, v4 row_half_mirror row_mask:0xf bank_mask:0xf
	s_nop 1
	v_add_f32_dpp v4, v5, v5 row_mirror row_mask:0xf bank_mask:0xf
	s_nop 1
	v_readlane_b32 s98, v4, 0
	v_readlane_b32 s99, v4, 16
	s_nop 3
	v_mov_b32_e32 v5, s98
	v_add_f32_e32 v5, s99, v5
	v_readlane_b32 s98, v4, 32
	v_readlane_b32 s99, v4, 48
	s_nop 3
	v_add_f32_e32 v5, s98, v5
	v_add_f32_e32 v5, s99, v5
	v_mul_f32_e32 v5, 0x3a800000, v5
	v_add_f32_e32 v5, 0x358637bd, v5
	v_rsq_f32_e32 v6, v5
	s_nop 0
	s_add_u32 s98, s97, 12
	v_pk_mul_f32 v[16:17], v[16:17], v[6:7] op_sel_hi:[1,0]
	v_pk_mul_f32 v[18:19], v[18:19], v[6:7] op_sel_hi:[1,0]
	v_pk_mul_f32 v[20:21], v[20:21], v[6:7] op_sel_hi:[1,0]
	v_pk_mul_f32 v[22:23], v[22:23], v[6:7] op_sel_hi:[1,0]
	v_pk_mul_f32 v[24:25], v[24:25], v[6:7] op_sel_hi:[1,0]
	v_pk_mul_f32 v[26:27], v[26:27], v[6:7] op_sel_hi:[1,0]
	v_pk_mul_f32 v[28:29], v[28:29], v[6:7] op_sel_hi:[1,0]
	v_pk_mul_f32 v[30:31], v[30:31], v[6:7] op_sel_hi:[1,0]
	v_pk_mul_f32 v[16:17], v[16:17], v[112:113]
	v_pk_mul_f32 v[18:19], v[18:19], v[114:115]
	v_pk_mul_f32 v[20:21], v[20:21], v[116:117]
	v_pk_mul_f32 v[22:23], v[22:23], v[118:119]
	v_pk_mul_f32 v[24:25], v[24:25], v[120:121]
	v_pk_mul_f32 v[26:27], v[26:27], v[122:123]
	v_pk_mul_f32 v[28:29], v[28:29], v[124:125]
	v_pk_mul_f32 v[30:31], v[30:31], v[126:127]
	v_pk_fma_f32 v[16:17], v[16:17], v[128:129], v[144:145]
	v_pk_fma_f32 v[18:19], v[18:19], v[130:131], v[146:147]
	v_pk_fma_f32 v[20:21], v[20:21], v[132:133], v[148:149]
	v_pk_fma_f32 v[22:23], v[22:23], v[134:135], v[150:151]
	v_pk_fma_f32 v[24:25], v[24:25], v[136:137], v[152:153]
	v_pk_fma_f32 v[26:27], v[26:27], v[138:139], v[154:155]
	v_pk_fma_f32 v[28:29], v[28:29], v[140:141], v[156:157]
	v_pk_fma_f32 v[30:31], v[30:31], v[142:143], v[158:159]
	v_cvt_pk_bf16_f32 v16, v16, v17
	v_cvt_pk_bf16_f32 v17, v18, v19
	v_cvt_pk_bf16_f32 v18, v20, v21
	v_cvt_pk_bf16_f32 v19, v22, v23
	v_cvt_pk_bf16_f32 v20, v24, v25
	v_cvt_pk_bf16_f32 v21, v26, v27
	v_cvt_pk_bf16_f32 v22, v28, v29
	v_cvt_pk_bf16_f32 v23, v30, v31
	s_lshl_b32 s99, s98, 11
	v_lshl_add_u32 v8, v0, 3, s99
	global_store_dwordx2 v8, v[16:17], s[94:95]
	global_store_dwordx2 v8, v[18:19], s[94:95] offset:512
	global_store_dwordx2 v8, v[20:21], s[94:95] offset:1024
	global_store_dwordx2 v8, v[22:23], s[94:95] offset:1536
	s_lshl_b32 s99, s98, 2
	v_mov_b32_e32 v9, s99
	v_mov_b32_e32 v10, 0
	v_cmp_eq_u32_e32 vcc, 0, v0
	s_and_saveexec_b64 s[98:99], vcc
	global_store_dword v9, v10, s[90:91]
	global_store_dword v9, v10, s[92:93]
	s_or_b64 exec, exec, s[98:99]
	s_waitcnt vmcnt(38)
	v_mul_f32_e32 v4, v32, v32
	v_fma_f32 v4, v33, v33, v4
	v_fma_f32 v4, v34, v34, v4
	v_fma_f32 v4, v35, v35, v4
	v_fma_f32 v4, v36, v36, v4
	v_fma_f32 v4, v37, v37, v4
	v_fma_f32 v4, v38, v38, v4
	v_fma_f32 v4, v39, v39, v4
	v_fma_f32 v4, v40, v40, v4
	v_fma_f32 v4, v41, v41, v4
	v_fma_f32 v4, v42, v42, v4
	v_fma_f32 v4, v43, v43, v4
	v_fma_f32 v4, v44, v44, v4
	v_fma_f32 v4, v45, v45, v4
	v_fma_f32 v4, v46, v46, v4
	v_fma_f32 v4, v47, v47, v4
	s_nop 1
	v_add_f32_dpp v5, v4, v4 quad_perm:[1,0,3,2] row_mask:0xf bank_mask:0xf
	s_nop 1
	v_add_f32_dpp v4, v5, v5 quad_perm:[2,3,0,1] row_mask:0xf bank_mask:0xf
	s_nop 1
	v_add_f32_dpp v5, v4, v4 row_half_mirror row_mask:0xf bank_mask:0xf
	s_nop 1
	v_add_f32_dpp v4, v5, v5 row_mirror row_mask:0xf bank_mask:0xf
	s_nop 1
	v_readlane_b32 s98, v4, 0
	v_readlane_b32 s99, v4, 16
	s_nop 3
	v_mov_b32_e32 v5, s98
	v_add_f32_e32 v5, s99, v5
	v_readlane_b32 s98, v4, 32
	v_readlane_b32 s99, v4, 48
	s_nop 3
	v_add_f32_e32 v5, s98, v5
	v_add_f32_e32 v5, s99, v5
	v_mul_f32_e32 v5, 0x3a800000, v5
	v_add_f32_e32 v5, 0x358637bd, v5
	v_rsq_f32_e32 v6, v5
	s_nop 0
	s_add_u32 s98, s97, 13
	v_pk_mul_f32 v[32:33], v[32:33], v[6:7] op_sel_hi:[1,0]
	v_pk_mul_f32 v[34:35], v[34:35], v[6:7] op_sel_hi:[1,0]
	v_pk_mul_f32 v[36:37], v[36:37], v[6:7] op_sel_hi:[1,0]
	v_pk_mul_f32 v[38:39], v[38:39], v[6:7] op_sel_hi:[1,0]
	v_pk_mul_f32 v[40:41], v[40:41], v[6:7] op_sel_hi:[1,0]
	v_pk_mul_f32 v[42:43], v[42:43], v[6:7] op_sel_hi:[1,0]
	v_pk_mul_f32 v[44:45], v[44:45], v[6:7] op_sel_hi:[1,0]
	v_pk_mul_f32 v[46:47], v[46:47], v[6:7] op_sel_hi:[1,0]
	v_pk_mul_f32 v[32:33], v[32:33], v[112:113]
	v_pk_mul_f32 v[34:35], v[34:35], v[114:115]
	v_pk_mul_f32 v[36:37], v[36:37], v[116:117]
	v_pk_mul_f32 v[38:39], v[38:39], v[118:119]
	v_pk_mul_f32 v[40:41], v[40:41], v[120:121]
	v_pk_mul_f32 v[42:43], v[42:43], v[122:123]
	v_pk_mul_f32 v[44:45], v[44:45], v[124:125]
	v_pk_mul_f32 v[46:47], v[46:47], v[126:127]
	v_pk_fma_f32 v[32:33], v[32:33], v[128:129], v[144:145]
	v_pk_fma_f32 v[34:35], v[34:35], v[130:131], v[146:147]
	v_pk_fma_f32 v[36:37], v[36:37], v[132:133], v[148:149]
	v_pk_fma_f32 v[38:39], v[38:39], v[134:135], v[150:151]
	v_pk_fma_f32 v[40:41], v[40:41], v[136:137], v[152:153]
	v_pk_fma_f32 v[42:43], v[42:43], v[138:139], v[154:155]
	v_pk_fma_f32 v[44:45], v[44:45], v[140:141], v[156:157]
	v_pk_fma_f32 v[46:47], v[46:47], v[142:143], v[158:159]
	v_cvt_pk_bf16_f32 v32, v32, v33
	v_cvt_pk_bf16_f32 v33, v34, v35
	v_cvt_pk_bf16_f32 v34, v36, v37
	v_cvt_pk_bf16_f32 v35, v38, v39
	v_cvt_pk_bf16_f32 v36, v40, v41
	v_cvt_pk_bf16_f32 v37, v42, v43
	v_cvt_pk_bf16_f32 v38, v44, v45
	v_cvt_pk_bf16_f32 v39, v46, v47
	s_lshl_b32 s99, s98, 11
	v_lshl_add_u32 v8, v0, 3, s99
	global_store_dwordx2 v8, v[32:33], s[94:95]
	global_store_dwordx2 v8, v[34:35], s[94:95] offset:512
	global_store_dwordx2 v8, v[36:37], s[94:95] offset:1024
	global_store_dwordx2 v8, v[38:39], s[94:95] offset:1536
	s_lshl_b32 s99, s98, 2
	v_mov_b32_e32 v9, s99
	v_mov_b32_e32 v10, 0
	v_cmp_eq_u32_e32 vcc, 0, v0
	s_and_saveexec_b64 s[98:99], vcc
	global_store_dword v9, v10, s[90:91]
	global_store_dword v9, v10, s[92:93]
	s_or_b64 exec, exec, s[98:99]
	s_waitcnt vmcnt(34)
	v_mul_f32_e32 v4, v48, v48
	v_fma_f32 v4, v49, v49, v4
	v_fma_f32 v4, v50, v50, v4
	v_fma_f32 v4, v51, v51, v4
	v_fma_f32 v4, v52, v52, v4
	v_fma_f32 v4, v53, v53, v4
	v_fma_f32 v4, v54, v54, v4
	v_fma_f32 v4, v55, v55, v4
	v_fma_f32 v4, v56, v56, v4
	v_fma_f32 v4, v57, v57, v4
	v_fma_f32 v4, v58, v58, v4
	v_fma_f32 v4, v59, v59, v4
	v_fma_f32 v4, v60, v60, v4
	v_fma_f32 v4, v61, v61, v4
	v_fma_f32 v4, v62, v62, v4
	v_fma_f32 v4, v63, v63, v4
	s_nop 1
	v_add_f32_dpp v5, v4, v4 quad_perm:[1,0,3,2] row_mask:0xf bank_mask:0xf
	s_nop 1
	v_add_f32_dpp v4, v5, v5 quad_perm:[2,3,0,1] row_mask:0xf bank_mask:0xf
	s_nop 1
	v_add_f32_dpp v5, v4, v4 row_half_mirror row_mask:0xf bank_mask:0xf
	s_nop 1
	v_add_f32_dpp v4, v5, v5 row_mirror row_mask:0xf bank_mask:0xf
	s_nop 1
	v_readlane_b32 s98, v4, 0
	v_readlane_b32 s99, v4, 16
	s_nop 3
	v_mov_b32_e32 v5, s98
	v_add_f32_e32 v5, s99, v5
	v_readlane_b32 s98, v4, 32
	v_readlane_b32 s99, v4, 48
	s_nop 3
	v_add_f32_e32 v5, s98, v5
	v_add_f32_e32 v5, s99, v5
	v_mul_f32_e32 v5, 0x3a800000, v5
	v_add_f32_e32 v5, 0x358637bd, v5
	v_rsq_f32_e32 v6, v5
	s_nop 0
	s_add_u32 s98, s97, 14
	v_pk_mul_f32 v[48:49], v[48:49], v[6:7] op_sel_hi:[1,0]
	v_pk_mul_f32 v[50:51], v[50:51], v[6:7] op_sel_hi:[1,0]
	v_pk_mul_f32 v[52:53], v[52:53], v[6:7] op_sel_hi:[1,0]
	v_pk_mul_f32 v[54:55], v[54:55], v[6:7] op_sel_hi:[1,0]
	v_pk_mul_f32 v[56:57], v[56:57], v[6:7] op_sel_hi:[1,0]
	v_pk_mul_f32 v[58:59], v[58:59], v[6:7] op_sel_hi:[1,0]
	v_pk_mul_f32 v[60:61], v[60:61], v[6:7] op_sel_hi:[1,0]
	v_pk_mul_f32 v[62:63], v[62:63], v[6:7] op_sel_hi:[1,0]
	v_pk_mul_f32 v[48:49], v[48:49], v[112:113]
	v_pk_mul_f32 v[50:51], v[50:51], v[114:115]
	v_pk_mul_f32 v[52:53], v[52:53], v[116:117]
	v_pk_mul_f32 v[54:55], v[54:55], v[118:119]
	v_pk_mul_f32 v[56:57], v[56:57], v[120:121]
	v_pk_mul_f32 v[58:59], v[58:59], v[122:123]
	v_pk_mul_f32 v[60:61], v[60:61], v[124:125]
	v_pk_mul_f32 v[62:63], v[62:63], v[126:127]
	v_pk_fma_f32 v[48:49], v[48:49], v[128:129], v[144:145]
	v_pk_fma_f32 v[50:51], v[50:51], v[130:131], v[146:147]
	v_pk_fma_f32 v[52:53], v[52:53], v[132:133], v[148:149]
	v_pk_fma_f32 v[54:55], v[54:55], v[134:135], v[150:151]
	v_pk_fma_f32 v[56:57], v[56:57], v[136:137], v[152:153]
	v_pk_fma_f32 v[58:59], v[58:59], v[138:139], v[154:155]
	v_pk_fma_f32 v[60:61], v[60:61], v[140:141], v[156:157]
	v_pk_fma_f32 v[62:63], v[62:63], v[142:143], v[158:159]
	v_cvt_pk_bf16_f32 v48, v48, v49
	v_cvt_pk_bf16_f32 v49, v50, v51
	v_cvt_pk_bf16_f32 v50, v52, v53
	v_cvt_pk_bf16_f32 v51, v54, v55
	v_cvt_pk_bf16_f32 v52, v56, v57
	v_cvt_pk_bf16_f32 v53, v58, v59
	v_cvt_pk_bf16_f32 v54, v60, v61
	v_cvt_pk_bf16_f32 v55, v62, v63
	s_lshl_b32 s99, s98, 11
	v_lshl_add_u32 v8, v0, 3, s99
	global_store_dwordx2 v8, v[48:49], s[94:95]
	global_store_dwordx2 v8, v[50:51], s[94:95] offset:512
	global_store_dwordx2 v8, v[52:53], s[94:95] offset:1024
	global_store_dwordx2 v8, v[54:55], s[94:95] offset:1536
	s_lshl_b32 s99, s98, 2
	v_mov_b32_e32 v9, s99
	v_mov_b32_e32 v10, 0
	v_cmp_eq_u32_e32 vcc, 0, v0
	s_and_saveexec_b64 s[98:99], vcc
	global_store_dword v9, v10, s[90:91]
	global_store_dword v9, v10, s[92:93]
	s_or_b64 exec, exec, s[98:99]
	s_waitcnt vmcnt(30)
	v_mul_f32_e32 v4, v64, v64
	v_fma_f32 v4, v65, v65, v4
	v_fma_f32 v4, v66, v66, v4
	v_fma_f32 v4, v67, v67, v4
	v_fma_f32 v4, v68, v68, v4
	v_fma_f32 v4, v69, v69, v4
	v_fma_f32 v4, v70, v70, v4
	v_fma_f32 v4, v71, v71, v4
	v_fma_f32 v4, v72, v72, v4
	v_fma_f32 v4, v73, v73, v4
	v_fma_f32 v4, v74, v74, v4
	v_fma_f32 v4, v75, v75, v4
	v_fma_f32 v4, v76, v76, v4
	v_fma_f32 v4, v77, v77, v4
	v_fma_f32 v4, v78, v78, v4
	v_fma_f32 v4, v79, v79, v4
	s_nop 1
	v_add_f32_dpp v5, v4, v4 quad_perm:[1,0,3,2] row_mask:0xf bank_mask:0xf
	s_nop 1
	v_add_f32_dpp v4, v5, v5 quad_perm:[2,3,0,1] row_mask:0xf bank_mask:0xf
	s_nop 1
	v_add_f32_dpp v5, v4, v4 row_half_mirror row_mask:0xf bank_mask:0xf
	s_nop 1
	v_add_f32_dpp v4, v5, v5 row_mirror row_mask:0xf bank_mask:0xf
	s_nop 1
	v_readlane_b32 s98, v4, 0
	v_readlane_b32 s99, v4, 16
	s_nop 3
	v_mov_b32_e32 v5, s98
	v_add_f32_e32 v5, s99, v5
	v_readlane_b32 s98, v4, 32
	v_readlane_b32 s99, v4, 48
	s_nop 3
	v_add_f32_e32 v5, s98, v5
	v_add_f32_e32 v5, s99, v5
	v_mul_f32_e32 v5, 0x3a800000, v5
	v_add_f32_e32 v5, 0x358637bd, v5
	v_rsq_f32_e32 v6, v5
	s_nop 0
	s_add_u32 s98, s97, 15
	v_pk_mul_f32 v[64:65], v[64:65], v[6:7] op_sel_hi:[1,0]
	v_pk_mul_f32 v[66:67], v[66:67], v[6:7] op_sel_hi:[1,0]
	v_pk_mul_f32 v[68:69], v[68:69], v[6:7] op_sel_hi:[1,0]
	v_pk_mul_f32 v[70:71], v[70:71], v[6:7] op_sel_hi:[1,0]
	v_pk_mul_f32 v[72:73], v[72:73], v[6:7] op_sel_hi:[1,0]
	v_pk_mul_f32 v[74:75], v[74:75], v[6:7] op_sel_hi:[1,0]
	v_pk_mul_f32 v[76:77], v[76:77], v[6:7] op_sel_hi:[1,0]
	v_pk_mul_f32 v[78:79], v[78:79], v[6:7] op_sel_hi:[1,0]
	v_pk_mul_f32 v[64:65], v[64:65], v[112:113]
	v_pk_mul_f32 v[66:67], v[66:67], v[114:115]
	v_pk_mul_f32 v[68:69], v[68:69], v[116:117]
	v_pk_mul_f32 v[70:71], v[70:71], v[118:119]
	v_pk_mul_f32 v[72:73], v[72:73], v[120:121]
	v_pk_mul_f32 v[74:75], v[74:75], v[122:123]
	v_pk_mul_f32 v[76:77], v[76:77], v[124:125]
	v_pk_mul_f32 v[78:79], v[78:79], v[126:127]
	v_pk_fma_f32 v[64:65], v[64:65], v[128:129], v[144:145]
	v_pk_fma_f32 v[66:67], v[66:67], v[130:131], v[146:147]
	v_pk_fma_f32 v[68:69], v[68:69], v[132:133], v[148:149]
	v_pk_fma_f32 v[70:71], v[70:71], v[134:135], v[150:151]
	v_pk_fma_f32 v[72:73], v[72:73], v[136:137], v[152:153]
	v_pk_fma_f32 v[74:75], v[74:75], v[138:139], v[154:155]
	v_pk_fma_f32 v[76:77], v[76:77], v[140:141], v[156:157]
	v_pk_fma_f32 v[78:79], v[78:79], v[142:143], v[158:159]
	v_cvt_pk_bf16_f32 v64, v64, v65
	v_cvt_pk_bf16_f32 v65, v66, v67
	v_cvt_pk_bf16_f32 v66, v68, v69
	v_cvt_pk_bf16_f32 v67, v70, v71
	v_cvt_pk_bf16_f32 v68, v72, v73
	v_cvt_pk_bf16_f32 v69, v74, v75
	v_cvt_pk_bf16_f32 v70, v76, v77
	v_cvt_pk_bf16_f32 v71, v78, v79
	s_lshl_b32 s99, s98, 11
	v_lshl_add_u32 v8, v0, 3, s99
	global_store_dwordx2 v8, v[64:65], s[94:95]
	global_store_dwordx2 v8, v[66:67], s[94:95] offset:512
	global_store_dwordx2 v8, v[68:69], s[94:95] offset:1024
	global_store_dwordx2 v8, v[70:71], s[94:95] offset:1536
	s_lshl_b32 s99, s98, 2
	v_mov_b32_e32 v9, s99
	v_mov_b32_e32 v10, 0
	v_cmp_eq_u32_e32 vcc, 0, v0
	s_and_saveexec_b64 s[98:99], vcc
	global_store_dword v9, v10, s[90:91]
	global_store_dword v9, v10, s[92:93]
	s_or_b64 exec, exec, s[98:99]
	s_waitcnt vmcnt(0)

.LBB0_1397:
	s_cmp_gt_i32 s44, 6
	s_waitcnt lgkmcnt(0)
	s_cselect_b64 s[2:3], -1, 0
	s_cmp_lt_i32 s45, 7
	s_cselect_b64 s[4:5], -1, 0
	s_or_b64 s[2:3], s[2:3], s[4:5]
	s_and_b64 vcc, exec, s[2:3]
	s_cbranch_vccnz .LBB0_1457
	s_lshl_b32 s96, s22, 3
	s_lshr_b32 s97, s70, 6
	s_add_u32 s96, s96, s97
	s_lshl_b32 s97, s96, 4
	s_cmpk_ge_u32 s97, 0x8000
	s_cbranch_scc1 .Lnp6_done
	s_load_dwordx2 s[88:89], s[0:1], 0xb8
	s_load_dwordx2 s[90:91], s[0:1], 0x18
	s_load_dwordx2 s[92:93], s[0:1], 0x140
	s_load_dwordx2 s[94:95], s[0:1], 0x158
	v_mbcnt_hi_u32_b32 v0, -1, v210
	v_lshlrev_b32_e32 v1, 4, v0
	s_waitcnt lgkmcnt(0)
	s_add_u32 s90, s90, 4096
	s_addc_u32 s91, s91, 0
	global_load_dwordx4 v[112:115], v1, s[90:91] nt
	global_load_dwordx4 v[116:119], v1, s[90:91] offset:1024 nt
	global_load_dwordx4 v[120:123], v1, s[90:91] offset:2048 nt
	global_load_dwordx4 v[124:127], v1, s[90:91] offset:3072 nt
	s_lshr_b32 s98, s97, 12
	s_add_u32 s98, s98, 8
	s_mul_i32 s98, s98, 0x3000
	s_add_u32 s92, s92, s98
	s_addc_u32 s93, s93, 0
	global_load_dwordx4 v[144:147], v1, s[92:93] nt
	global_load_dwordx4 v[148:151], v1, s[92:93] offset:1024 nt
	global_load_dwordx4 v[152:155], v1, s[92:93] offset:2048 nt
	global_load_dwordx4 v[156:159], v1, s[92:93] offset:3072 nt
	s_add_u32 s92, s92, 0x1000
	s_addc_u32 s93, s93, 0
	global_load_dwordx4 v[128:131], v1, s[92:93] nt
	global_load_dwordx4 v[132:135], v1, s[92:93] offset:1024 nt
	global_load_dwordx4 v[136:139], v1, s[92:93] offset:2048 nt
	global_load_dwordx4 v[140:143], v1, s[92:93] offset:3072 nt
	s_load_dwordx2 s[90:91], s[0:1], 0x210
	s_load_dwordx2 s[92:93], s[0:1], 0x218
	s_waitcnt vmcnt(0) lgkmcnt(0)
	v_pk_add_f32 v[128:129], v[128:129], 1.0 op_sel_hi:[1,0]
	v_pk_add_f32 v[130:131], v[130:131], 1.0 op_sel_hi:[1,0]
	v_pk_add_f32 v[132:133], v[132:133], 1.0 op_sel_hi:[1,0]
	v_pk_add_f32 v[134:135], v[134:135], 1.0 op_sel_hi:[1,0]
	v_pk_add_f32 v[136:137], v[136:137], 1.0 op_sel_hi:[1,0]
	v_pk_add_f32 v[138:139], v[138:139], 1.0 op_sel_hi:[1,0]
	v_pk_add_f32 v[140:141], v[140:141], 1.0 op_sel_hi:[1,0]
	v_pk_add_f32 v[142:143], v[142:143], 1.0 op_sel_hi:[1,0]
	s_add_u32 s98, s97, 0
	s_lshl_b32 s98, s98, 12
	v_add_u32_e32 v3, s98, v1
	global_load_dwordx4 v[16:19], v3, s[88:89] nt
	global_load_dwordx4 v[20:23], v3, s[88:89] offset:1024 nt
	global_load_dwordx4 v[24:27], v3, s[88:89] offset:2048 nt
	global_load_dwordx4 v[28:31], v3, s[88:89] offset:3072 nt
	s_add_u32 s98, s97, 1
	s_lshl_b32 s98, s98, 12
	v_add_u32_e32 v3, s98, v1
	global_load_dwordx4 v[32:35], v3, s[88:89] nt
	global_load_dwordx4 v[36:39], v3, s[88:89] offset:1024 nt
	global_load_dwordx4 v[40:43], v3, s[88:89] offset:2048 nt
	global_load_dwordx4 v[44:47], v3, s[88:89] offset:3072 nt
	s_add_u32 s98, s97, 2
	s_lshl_b32 s98, s98, 12
	v_add_u32_e32 v3, s98, v1
	global_load_dwordx4 v[48:51], v3, s[88:89] nt
	global_load_dwordx4 v[52:55], v3, s[88:89] offset:1024 nt
	global_load_dwordx4 v[56:59], v3, s[88:89] offset:2048 nt
	global_load_dwordx4 v[60:63], v3, s[88:89] offset:3072 nt
	s_add_u32 s98, s97, 3
	s_lshl_b32 s98, s98, 12
	v_add_u32_e32 v3, s98, v1
	global_load_dwordx4 v[64:67], v3, s[88:89] nt
	global_load_dwordx4 v[68:71], v3, s[88:89] offset:1024 nt
	global_load_dwordx4 v[72:75], v3, s[88:89] offset:2048 nt
	global_load_dwordx4 v[76:79], v3, s[88:89] offset:3072 nt
	s_add_u32 s98, s97, 4
	s_lshl_b32 s98, s98, 12
	v_add_u32_e32 v3, s98, v1
	global_load_dwordx4 v[80:83], v3, s[88:89] nt
	global_load_dwordx4 v[84:87], v3, s[88:89] offset:1024 nt
	global_load_dwordx4 v[88:91], v3, s[88:89] offset:2048 nt
	global_load_dwordx4 v[92:95], v3, s[88:89] offset:3072 nt
	s_add_u32 s98, s97, 5
	s_lshl_b32 s98, s98, 12
	v_add_u32_e32 v3, s98, v1
	global_load_dwordx4 v[96:99], v3, s[88:89] nt
	global_load_dwordx4 v[100:103], v3, s[88:89] offset:1024 nt
	global_load_dwordx4 v[104:107], v3, s[88:89] offset:2048 nt
	global_load_dwordx4 v[108:111], v3, s[88:89] offset:3072 nt
	s_waitcnt vmcnt(20)
	v_mul_f32_e32 v4, v16, v16
	v_fma_f32 v4, v17, v17, v4
	v_fma_f32 v4, v18, v18, v4
	v_fma_f32 v4, v19, v19, v4
	v_fma_f32 v4, v20, v20, v4
	v_fma_f32 v4, v21, v21, v4
	v_fma_f32 v4, v22, v22, v4
	v_fma_f32 v4, v23, v23, v4
	v_fma_f32 v4, v24, v24, v4
	v_fma_f32 v4, v25, v25, v4
	v_fma_f32 v4, v26, v26, v4
	v_fma_f32 v4, v27, v27, v4
	v_fma_f32 v4, v28, v28, v4
	v_fma_f32 v4, v29, v29, v4
	v_fma_f32 v4, v30, v30, v4
	v_fma_f32 v4, v31, v31, v4
	s_nop 1
	v_add_f32_dpp v5, v4, v4 quad_perm:[1,0,3,2] row_mask:0xf bank_mask:0xf
	s_nop 1
	v_add_f32_dpp v4, v5, v5 quad_perm:[2,3,0,1] row_mask:0xf bank_mask:0xf
	s_nop 1
	v_add_f32_dpp v5, v4, v4 row_half_mirror row_mask:0xf bank_mask:0xf
	s_nop 1
	v_add_f32_dpp v4, v5, v5 row_mirror row_mask:0xf bank_mask:0xf
	s_nop 1
	v_readlane_b32 s98, v4, 0
	v_readlane_b32 s99, v4, 16
	s_nop 3
	v_mov_b32_e32 v5, s98
	v_add_f32_e32 v5, s99, v5
	v_readlane_b32 s98, v4, 32
	v_readlane_b32 s99, v4, 48
	s_nop 3
	v_add_f32_e32 v5, s98, v5
	v_add_f32_e32 v5, s99, v5
	v_mul_f32_e32 v5, 0x3a800000, v5
	v_add_f32_e32 v5, 0x358637bd, v5
	v_rsq_f32_e32 v6, v5
	s_nop 0
	s_add_u32 s98, s97, 0
	v_pk_mul_f32 v[16:17], v[16:17], v[6:7] op_sel_hi:[1,0]
	v_pk_mul_f32 v[18:19], v[18:19], v[6:7] op_sel_hi:[1,0]
	v_pk_mul_f32 v[20:21], v[20:21], v[6:7] op_sel_hi:[1,0]
	v_pk_mul_f32 v[22:23], v[22:23], v[6:7] op_sel_hi:[1,0]
	v_pk_mul_f32 v[24:25], v[24:25], v[6:7] op_sel_hi:[1,0]
	v_pk_mul_f32 v[26:27], v[26:27], v[6:7] op_sel_hi:[1,0]
	v_pk_mul_f32 v[28:29], v[28:29], v[6:7] op_sel_hi:[1,0]
	v_pk_mul_f32 v[30:31], v[30:31], v[6:7] op_sel_hi:[1,0]
	v_pk_mul_f32 v[16:17], v[16:17], v[112:113]
	v_pk_mul_f32 v[18:19], v[18:19], v[114:115]
	v_pk_mul_f32 v[20:21], v[20:21], v[116:117]
	v_pk_mul_f32 v[22:23], v[22:23], v[118:119]
	v_pk_mul_f32 v[24:25], v[24:25], v[120:121]
	v_pk_mul_f32 v[26:27], v[26:27], v[122:123]
	v_pk_mul_f32 v[28:29], v[28:29], v[124:125]
	v_pk_mul_f32 v[30:31], v[30:31], v[126:127]
	v_pk_fma_f32 v[16:17], v[16:17], v[128:129], v[144:145]
	v_pk_fma_f32 v[18:19], v[18:19], v[130:131], v[146:147]
	v_pk_fma_f32 v[20:21], v[20:21], v[132:133], v[148:149]
	v_pk_fma_f32 v[22:23], v[22:23], v[134:135], v[150:151]
	v_pk_fma_f32 v[24:25], v[24:25], v[136:137], v[152:153]
	v_pk_fma_f32 v[26:27], v[26:27], v[138:139], v[154:155]
	v_pk_fma_f32 v[28:29], v[28:29], v[140:141], v[156:157]
	v_pk_fma_f32 v[30:31], v[30:31], v[142:143], v[158:159]
	v_cvt_pk_bf16_f32 v16, v16, v17
	v_cvt_pk_bf16_f32 v17, v18, v19
	v_cvt_pk_bf16_f32 v18, v20, v21
	v_cvt_pk_bf16_f32 v19, v22, v23
	v_cvt_pk_bf16_f32 v20, v24, v25
	v_cvt_pk_bf16_f32 v21, v26, v27
	v_cvt_pk_bf16_f32 v22, v28, v29
	v_cvt_pk_bf16_f32 v23, v30, v31
	s_lshl_b32 s99, s98, 11
	v_lshl_add_u32 v8, v0, 3, s99
	global_store_dwordx2 v8, v[16:17], s[94:95]
	global_store_dwordx2 v8, v[18:19], s[94:95] offset:512
	global_store_dwordx2 v8, v[20:21], s[94:95] offset:1024
	global_store_dwordx2 v8, v[22:23], s[94:95] offset:1536
	s_lshl_b32 s99, s98, 2
	v_mov_b32_e32 v9, s99
	v_mov_b32_e32 v10, 0
	v_cmp_eq_u32_e32 vcc, 0, v0
	s_and_saveexec_b64 s[98:99], vcc
	global_store_dword v9, v10, s[90:91]
	global_store_dword v9, v10, s[92:93]
	s_or_b64 exec, exec, s[98:99]
	s_add_u32 s98, s97, 6
	s_lshl_b32 s98, s98, 12
	v_add_u32_e32 v3, s98, v1
	global_load_dwordx4 v[16:19], v3, s[88:89] nt
	global_load_dwordx4 v[20:23], v3, s[88:89] offset:1024 nt
	global_load_dwordx4 v[24:27], v3, s[88:89] offset:2048 nt
	global_load_dwordx4 v[28:31], v3, s[88:89] offset:3072 nt
	s_waitcnt vmcnt(26)
	v_mul_f32_e32 v4, v32, v32
	v_fma_f32 v4, v33, v33, v4
	v_fma_f32 v4, v34, v34, v4
	v_fma_f32 v4, v35, v35, v4
	v_fma_f32 v4, v36, v36, v4
	v_fma_f32 v4, v37, v37, v4
	v_fma_f32 v4, v38, v38, v4
	v_fma_f32 v4, v39, v39, v4
	v_fma_f32 v4, v40, v40, v4
	v_fma_f32 v4, v41, v41, v4
	v_fma_f32 v4, v42, v42, v4
	v_fma_f32 v4, v43, v43, v4
	v_fma_f32 v4, v44, v44, v4
	v_fma_f32 v4, v45, v45, v4
	v_fma_f32 v4, v46, v46, v4
	v_fma_f32 v4, v47, v47, v4
	s_nop 1
	v_add_f32_dpp v5, v4, v4 quad_perm:[1,0,3,2] row_mask:0xf bank_mask:0xf
	s_nop 1
	v_add_f32_dpp v4, v5, v5 quad_perm:[2,3,0,1] row_mask:0xf bank_mask:0xf
	s_nop 1
	v_add_f32_dpp v5, v4, v4 row_half_mirror row_mask:0xf bank_mask:0xf
	s_nop 1
	v_add_f32_dpp v4, v5, v5 row_mirror row_mask:0xf bank_mask:0xf
	s_nop 1
	v_readlane_b32 s98, v4, 0
	v_readlane_b32 s99, v4, 16
	s_nop 3
	v_mov_b32_e32 v5, s98
	v_add_f32_e32 v5, s99, v5
	v_readlane_b32 s98, v4, 32
	v_readlane_b32 s99, v4, 48
	s_nop 3
	v_add_f32_e32 v5, s98, v5
	v_add_f32_e32 v5, s99, v5
	v_mul_f32_e32 v5, 0x3a800000, v5
	v_add_f32_e32 v5, 0x358637bd, v5
	v_rsq_f32_e32 v6, v5
	s_nop 0
	s_add_u32 s98, s97, 1
	v_pk_mul_f32 v[32:33], v[32:33], v[6:7] op_sel_hi:[1,0]
	v_pk_mul_f32 v[34:35], v[34:35], v[6:7] op_sel_hi:[1,0]
	v_pk_mul_f32 v[36:37], v[36:37], v[6:7] op_sel_hi:[1,0]
	v_pk_mul_f32 v[38:39], v[38:39], v[6:7] op_sel_hi:[1,0]
	v_pk_mul_f32 v[40:41], v[40:41], v[6:7] op_sel_hi:[1,0]
	v_pk_mul_f32 v[42:43], v[42:43], v[6:7] op_sel_hi:[1,0]
	v_pk_mul_f32 v[44:45], v[44:45], v[6:7] op_sel_hi:[1,0]
	v_pk_mul_f32 v[46:47], v[46:47], v[6:7] op_sel_hi:[1,0]
	v_pk_mul_f32 v[32:33], v[32:33], v[112:113]
	v_pk_mul_f32 v[34:35], v[34:35], v[114:115]
	v_pk_mul_f32 v[36:37], v[36:37], v[116:117]
	v_pk_mul_f32 v[38:39], v[38:39], v[118:119]
	v_pk_mul_f32 v[40:41], v[40:41], v[120:121]
	v_pk_mul_f32 v[42:43], v[42:43], v[122:123]
	v_pk_mul_f32 v[44:45], v[44:45], v[124:125]
	v_pk_mul_f32 v[46:47], v[46:47], v[126:127]
	v_pk_fma_f32 v[32:33], v[32:33], v[128:129], v[144:145]
	v_pk_fma_f32 v[34:35], v[34:35], v[130:131], v[146:147]
	v_pk_fma_f32 v[36:37], v[36:37], v[132:133], v[148:149]
	v_pk_fma_f32 v[38:39], v[38:39], v[134:135], v[150:151]
	v_pk_fma_f32 v[40:41], v[40:41], v[136:137], v[152:153]
	v_pk_fma_f32 v[42:43], v[42:43], v[138:139], v[154:155]
	v_pk_fma_f32 v[44:45], v[44:45], v[140:141], v[156:157]
	v_pk_fma_f32 v[46:47], v[46:47], v[142:143], v[158:159]
	v_cvt_pk_bf16_f32 v32, v32, v33
	v_cvt_pk_bf16_f32 v33, v34, v35
	v_cvt_pk_bf16_f32 v34, v36, v37
	v_cvt_pk_bf16_f32 v35, v38, v39
	v_cvt_pk_bf16_f32 v36, v40, v41
	v_cvt_pk_bf16_f32 v37, v42, v43
	v_cvt_pk_bf16_f32 v38, v44, v45
	v_cvt_pk_bf16_f32 v39, v46, v47
	s_lshl_b32 s99, s98, 11
	v_lshl_add_u32 v8, v0, 3, s99
	global_store_dwordx2 v8, v[32:33], s[94:95]
	global_store_dwordx2 v8, v[34:35], s[94:95] offset:512
	global_store_dwordx2 v8, v[36:37], s[94:95] offset:1024
	global_store_dwordx2 v8, v[38:39], s[94:95] offset:1536
	s_lshl_b32 s99, s98, 2
	v_mov_b32_e32 v9, s99
	v_mov_b32_e32 v10, 0
	v_cmp_eq_u32_e32 vcc, 0, v0
	s_and_saveexec_b64 s[98:99], vcc
	global_store_dword v9, v10, s[90:91]
	global_store_dword v9, v10, s[92:93]
	s_or_b64 exec, exec, s[98:99]
	s_add_u32 s98, s97, 7
	s_lshl_b32 s98, s98, 12
	v_add_u32_e32 v3, s98, v1
	global_load_dwordx4 v[32:35], v3, s[88:89] nt
	global_load_dwordx4 v[36:39], v3, s[88:89] offset:1024 nt
	global_load_dwordx4 v[40:43], v3, s[88:89] offset:2048 nt
	global_load_dwordx4 v[44:47], v3, s[88:89] offset:3072 nt
	s_waitcnt vmcnt(32)
	v_mul_f32_e32 v4, v48, v48
	v_fma_f32 v4, v49, v49, v4
	v_fma_f32 v4, v50, v50, v4
	v_fma_f32 v4, v51, v51, v4
	v_fma_f32 v4, v52, v52, v4
	v_fma_f32 v4, v53, v53, v4
	v_fma_f32 v4, v54, v54, v4
	v_fma_f32 v4, v55, v55, v4
	v_fma_f32 v4, v56, v56, v4
	v_fma_f32 v4, v57, v57, v4
	v_fma_f32 v4, v58, v58, v4
	v_fma_f32 v4, v59, v59, v4
	v_fma_f32 v4, v60, v60, v4
	v_fma_f32 v4, v61, v61, v4
	v_fma_f32 v4, v62, v62, v4
	v_fma_f32 v4, v63, v63, v4
	s_nop 1
	v_add_f32_dpp v5, v4, v4 quad_perm:[1,0,3,2] row_mask:0xf bank_mask:0xf
	s_nop 1
	v_add_f32_dpp v4, v5, v5 quad_perm:[2,3,0,1] row_mask:0xf bank_mask:0xf
	s_nop 1
	v_add_f32_dpp v5, v4, v4 row_half_mirror row_mask:0xf bank_mask:0xf
	s_nop 1
	v_add_f32_dpp v4, v5, v5 row_mirror row_mask:0xf bank_mask:0xf
	s_nop 1
	v_readlane_b32 s98, v4, 0
	v_readlane_b32 s99, v4, 16
	s_nop 3
	v_mov_b32_e32 v5, s98
	v_add_f32_e32 v5, s99, v5
	v_readlane_b32 s98, v4, 32
	v_readlane_b32 s99, v4, 48
	s_nop 3
	v_add_f32_e32 v5, s98, v5
	v_add_f32_e32 v5, s99, v5
	v_mul_f32_e32 v5, 0x3a800000, v5
	v_add_f32_e32 v5, 0x358637bd, v5
	v_rsq_f32_e32 v6, v5
	s_nop 0
	s_add_u32 s98, s97, 2
	v_pk_mul_f32 v[48:49], v[48:49], v[6:7] op_sel_hi:[1,0]
	v_pk_mul_f32 v[50:51], v[50:51], v[6:7] op_sel_hi:[1,0]
	v_pk_mul_f32 v[52:53], v[52:53], v[6:7] op_sel_hi:[1,0]
	v_pk_mul_f32 v[54:55], v[54:55], v[6:7] op_sel_hi:[1,0]
	v_pk_mul_f32 v[56:57], v[56:57], v[6:7] op_sel_hi:[1,0]
	v_pk_mul_f32 v[58:59], v[58:59], v[6:7] op_sel_hi:[1,0]
	v_pk_mul_f32 v[60:61], v[60:61], v[6:7] op_sel_hi:[1,0]
	v_pk_mul_f32 v[62:63], v[62:63], v[6:7] op_sel_hi:[1,0]
	v_pk_mul_f32 v[48:49], v[48:49], v[112:113]
	v_pk_mul_f32 v[50:51], v[50:51], v[114:115]
	v_pk_mul_f32 v[52:53], v[52:53], v[116:117]
	v_pk_mul_f32 v[54:55], v[54:55], v[118:119]
	v_pk_mul_f32 v[56:57], v[56:57], v[120:121]
	v_pk_mul_f32 v[58:59], v[58:59], v[122:123]
	v_pk_mul_f32 v[60:61], v[60:61], v[124:125]
	v_pk_mul_f32 v[62:63], v[62:63], v[126:127]
	v_pk_fma_f32 v[48:49], v[48:49], v[128:129], v[144:145]
	v_pk_fma_f32 v[50:51], v[50:51], v[130:131], v[146:147]
	v_pk_fma_f32 v[52:53], v[52:53], v[132:133], v[148:149]
	v_pk_fma_f32 v[54:55], v[54:55], v[134:135], v[150:151]
	v_pk_fma_f32 v[56:57], v[56:57], v[136:137], v[152:153]
	v_pk_fma_f32 v[58:59], v[58:59], v[138:139], v[154:155]
	v_pk_fma_f32 v[60:61], v[60:61], v[140:141], v[156:157]
	v_pk_fma_f32 v[62:63], v[62:63], v[142:143], v[158:159]
	v_cvt_pk_bf16_f32 v48, v48, v49
	v_cvt_pk_bf16_f32 v49, v50, v51
	v_cvt_pk_bf16_f32 v50, v52, v53
	v_cvt_pk_bf16_f32 v51, v54, v55
	v_cvt_pk_bf16_f32 v52, v56, v57
	v_cvt_pk_bf16_f32 v53, v58, v59
	v_cvt_pk_bf16_f32 v54, v60, v61
	v_cvt_pk_bf16_f32 v55, v62, v63
	s_lshl_b32 s99, s98, 11
	v_lshl_add_u32 v8, v0, 3, s99
	global_store_dwordx2 v8, v[48:49], s[94:95]
	global_store_dwordx2 v8, v[50:51], s[94:95] offset:512
	global_store_dwordx2 v8, v[52:53], s[94:95] offset:1024
	global_store_dwordx2 v8, v[54:55], s[94:95] offset:1536
	s_lshl_b32 s99, s98, 2
	v_mov_b32_e32 v9, s99
	v_mov_b32_e32 v10, 0
	v_cmp_eq_u32_e32 vcc, 0, v0
	s_and_saveexec_b64 s[98:99], vcc
	global_store_dword v9, v10, s[90:91]
	global_store_dword v9, v10, s[92:93]
	s_or_b64 exec, exec, s[98:99]
	s_add_u32 s98, s97, 8
	s_lshl_b32 s98, s98, 12
	v_add_u32_e32 v3, s98, v1
	global_load_dwordx4 v[48:51], v3, s[88:89] nt
	global_load_dwordx4 v[52:55], v3, s[88:89] offset:1024 nt
	global_load_dwordx4 v[56:59], v3, s[88:89] offset:2048 nt
	global_load_dwordx4 v[60:63], v3, s[88:89] offset:3072 nt
	s_waitcnt vmcnt(38)
	v_mul_f32_e32 v4, v64, v64
	v_fma_f32 v4, v65, v65, v4
	v_fma_f32 v4, v66, v66, v4
	v_fma_f32 v4, v67, v67, v4
	v_fma_f32 v4, v68, v68, v4
	v_fma_f32 v4, v69, v69, v4
	v_fma_f32 v4, v70, v70, v4
	v_fma_f32 v4, v71, v71, v4
	v_fma_f32 v4, v72, v72, v4
	v_fma_f32 v4, v73, v73, v4
	v_fma_f32 v4, v74, v74, v4
	v_fma_f32 v4, v75, v75, v4
	v_fma_f32 v4, v76, v76, v4
	v_fma_f32 v4, v77, v77, v4
	v_fma_f32 v4, v78, v78, v4
	v_fma_f32 v4, v79, v79, v4
	s_nop 1
	v_add_f32_dpp v5, v4, v4 quad_perm:[1,0,3,2] row_mask:0xf bank_mask:0xf
	s_nop 1
	v_add_f32_dpp v4, v5, v5 quad_perm:[2,3,0,1] row_mask:0xf bank_mask:0xf
	s_nop 1
	v_add_f32_dpp v5, v4, v4 row_half_mirror row_mask:0xf bank_mask:0xf
	s_nop 1
	v_add_f32_dpp v4, v5, v5 row_mirror row_mask:0xf bank_mask:0xf
	s_nop 1
	v_readlane_b32 s98, v4, 0
	v_readlane_b32 s99, v4, 16
	s_nop 3
	v_mov_b32_e32 v5, s98
	v_add_f32_e32 v5, s99, v5
	v_readlane_b32 s98, v4, 32
	v_readlane_b32 s99, v4, 48
	s_nop 3
	v_add_f32_e32 v5, s98, v5
	v_add_f32_e32 v5, s99, v5
	v_mul_f32_e32 v5, 0x3a800000, v5
	v_add_f32_e32 v5, 0x358637bd, v5
	v_rsq_f32_e32 v6, v5
	s_nop 0
	s_add_u32 s98, s97, 3
	v_pk_mul_f32 v[64:65], v[64:65], v[6:7] op_sel_hi:[1,0]
	v_pk_mul_f32 v[66:67], v[66:67], v[6:7] op_sel_hi:[1,0]
	v_pk_mul_f32 v[68:69], v[68:69], v[6:7] op_sel_hi:[1,0]
	v_pk_mul_f32 v[70:71], v[70:71], v[6:7] op_sel_hi:[1,0]
	v_pk_mul_f32 v[72:73], v[72:73], v[6:7] op_sel_hi:[1,0]
	v_pk_mul_f32 v[74:75], v[74:75], v[6:7] op_sel_hi:[1,0]
	v_pk_mul_f32 v[76:77], v[76:77], v[6:7] op_sel_hi:[1,0]
	v_pk_mul_f32 v[78:79], v[78:79], v[6:7] op_sel_hi:[1,0]
	v_pk_mul_f32 v[64:65], v[64:65], v[112:113]
	v_pk_mul_f32 v[66:67], v[66:67], v[114:115]
	v_pk_mul_f32 v[68:69], v[68:69], v[116:117]
	v_pk_mul_f32 v[70:71], v[70:71], v[118:119]
	v_pk_mul_f32 v[72:73], v[72:73], v[120:121]
	v_pk_mul_f32 v[74:75], v[74:75], v[122:123]
	v_pk_mul_f32 v[76:77], v[76:77], v[124:125]
	v_pk_mul_f32 v[78:79], v[78:79], v[126:127]
	v_pk_fma_f32 v[64:65], v[64:65], v[128:129], v[144:145]
	v_pk_fma_f32 v[66:67], v[66:67], v[130:131], v[146:147]
	v_pk_fma_f32 v[68:69], v[68:69], v[132:133], v[148:149]
	v_pk_fma_f32 v[70:71], v[70:71], v[134:135], v[150:151]
	v_pk_fma_f32 v[72:73], v[72:73], v[136:137], v[152:153]
	v_pk_fma_f32 v[74:75], v[74:75], v[138:139], v[154:155]
	v_pk_fma_f32 v[76:77], v[76:77], v[140:141], v[156:157]
	v_pk_fma_f32 v[78:79], v[78:79], v[142:143], v[158:159]
	v_cvt_pk_bf16_f32 v64, v64, v65
	v_cvt_pk_bf16_f32 v65, v66, v67
	v_cvt_pk_bf16_f32 v66, v68, v69
	v_cvt_pk_bf16_f32 v67, v70, v71
	v_cvt_pk_bf16_f32 v68, v72, v73
	v_cvt_pk_bf16_f32 v69, v74, v75
	v_cvt_pk_bf16_f32 v70, v76, v77
	v_cvt_pk_bf16_f32 v71, v78, v79
	s_lshl_b32 s99, s98, 11
	v_lshl_add_u32 v8, v0, 3, s99
	global_store_dwordx2 v8, v[64:65], s[94:95]
	global_store_dwordx2 v8, v[66:67], s[94:95] offset:512
	global_store_dwordx2 v8, v[68:69], s[94:95] offset:1024
	global_store_dwordx2 v8, v[70:71], s[94:95] offset:1536
	s_lshl_b32 s99, s98, 2
	v_mov_b32_e32 v9, s99
	v_mov_b32_e32 v10, 0
	v_cmp_eq_u32_e32 vcc, 0, v0
	s_and_saveexec_b64 s[98:99], vcc
	global_store_dword v9, v10, s[90:91]
	global_store_dword v9, v10, s[92:93]
	s_or_b64 exec, exec, s[98:99]
	s_add_u32 s98, s97, 9
	s_lshl_b32 s98, s98, 12
	v_add_u32_e32 v3, s98, v1
	global_load_dwordx4 v[64:67], v3, s[88:89] nt
	global_load_dwordx4 v[68:71], v3, s[88:89] offset:1024 nt
	global_load_dwordx4 v[72:75], v3, s[88:89] offset:2048 nt
	global_load_dwordx4 v[76:79], v3, s[88:89] offset:3072 nt
	s_waitcnt vmcnt(44)
	v_mul_f32_e32 v4, v80, v80
	v_fma_f32 v4, v81, v81, v4
	v_fma_f32 v4, v82, v82, v4
	v_fma_f32 v4, v83, v83, v4
	v_fma_f32 v4, v84, v84, v4
	v_fma_f32 v4, v85, v85, v4
	v_fma_f32 v4, v86, v86, v4
	v_fma_f32 v4, v87, v87, v4
	v_fma_f32 v4, v88, v88, v4
	v_fma_f32 v4, v89, v89, v4
	v_fma_f32 v4, v90, v90, v4
	v_fma_f32 v4, v91, v91, v4
	v_fma_f32 v4, v92, v92, v4
	v_fma_f32 v4, v93, v93, v4
	v_fma_f32 v4, v94, v94, v4
	v_fma_f32 v4, v95, v95, v4
	s_nop 1
	v_add_f32_dpp v5, v4, v4 quad_perm:[1,0,3,2] row_mask:0xf bank_mask:0xf
	s_nop 1
	v_add_f32_dpp v4, v5, v5 quad_perm:[2,3,0,1] row_mask:0xf bank_mask:0xf
	s_nop 1
	v_add_f32_dpp v5, v4, v4 row_half_mirror row_mask:0xf bank_mask:0xf
	s_nop 1
	v_add_f32_dpp v4, v5, v5 row_mirror row_mask:0xf bank_mask:0xf
	s_nop 1
	v_readlane_b32 s98, v4, 0
	v_readlane_b32 s99, v4, 16
	s_nop 3
	v_mov_b32_e32 v5, s98
	v_add_f32_e32 v5, s99, v5
	v_readlane_b32 s98, v4, 32
	v_readlane_b32 s99, v4, 48
	s_nop 3
	v_add_f32_e32 v5, s98, v5
	v_add_f32_e32 v5, s99, v5
	v_mul_f32_e32 v5, 0x3a800000, v5
	v_add_f32_e32 v5, 0x358637bd, v5
	v_rsq_f32_e32 v6, v5
	s_nop 0
	s_add_u32 s98, s97, 4
	v_pk_mul_f32 v[80:81], v[80:81], v[6:7] op_sel_hi:[1,0]
	v_pk_mul_f32 v[82:83], v[82:83], v[6:7] op_sel_hi:[1,0]
	v_pk_mul_f32 v[84:85], v[84:85], v[6:7] op_sel_hi:[1,0]
	v_pk_mul_f32 v[86:87], v[86:87], v[6:7] op_sel_hi:[1,0]
	v_pk_mul_f32 v[88:89], v[88:89], v[6:7] op_sel_hi:[1,0]
	v_pk_mul_f32 v[90:91], v[90:91], v[6:7] op_sel_hi:[1,0]
	v_pk_mul_f32 v[92:93], v[92:93], v[6:7] op_sel_hi:[1,0]
	v_pk_mul_f32 v[94:95], v[94:95], v[6:7] op_sel_hi:[1,0]
	v_pk_mul_f32 v[80:81], v[80:81], v[112:113]
	v_pk_mul_f32 v[82:83], v[82:83], v[114:115]
	v_pk_mul_f32 v[84:85], v[84:85], v[116:117]
	v_pk_mul_f32 v[86:87], v[86:87], v[118:119]
	v_pk_mul_f32 v[88:89], v[88:89], v[120:121]
	v_pk_mul_f32 v[90:91], v[90:91], v[122:123]
	v_pk_mul_f32 v[92:93], v[92:93], v[124:125]
	v_pk_mul_f32 v[94:95], v[94:95], v[126:127]
	v_pk_fma_f32 v[80:81], v[80:81], v[128:129], v[144:145]
	v_pk_fma_f32 v[82:83], v[82:83], v[130:131], v[146:147]
	v_pk_fma_f32 v[84:85], v[84:85], v[132:133], v[148:149]
	v_pk_fma_f32 v[86:87], v[86:87], v[134:135], v[150:151]
	v_pk_fma_f32 v[88:89], v[88:89], v[136:137], v[152:153]
	v_pk_fma_f32 v[90:91], v[90:91], v[138:139], v[154:155]
	v_pk_fma_f32 v[92:93], v[92:93], v[140:141], v[156:157]
	v_pk_fma_f32 v[94:95], v[94:95], v[142:143], v[158:159]
	v_cvt_pk_bf16_f32 v80, v80, v81
	v_cvt_pk_bf16_f32 v81, v82, v83
	v_cvt_pk_bf16_f32 v82, v84, v85
	v_cvt_pk_bf16_f32 v83, v86, v87
	v_cvt_pk_bf16_f32 v84, v88, v89
	v_cvt_pk_bf16_f32 v85, v90, v91
	v_cvt_pk_bf16_f32 v86, v92, v93
	v_cvt_pk_bf16_f32 v87, v94, v95
	s_lshl_b32 s99, s98, 11
	v_lshl_add_u32 v8, v0, 3, s99
	global_store_dwordx2 v8, v[80:81], s[94:95]
	global_store_dwordx2 v8, v[82:83], s[94:95] offset:512
	global_store_dwordx2 v8, v[84:85], s[94:95] offset:1024
	global_store_dwordx2 v8, v[86:87], s[94:95] offset:1536
	s_lshl_b32 s99, s98, 2
	v_mov_b32_e32 v9, s99
	v_mov_b32_e32 v10, 0
	v_cmp_eq_u32_e32 vcc, 0, v0
	s_and_saveexec_b64 s[98:99], vcc
	global_store_dword v9, v10, s[90:91]
	global_store_dword v9, v10, s[92:93]
	s_or_b64 exec, exec, s[98:99]
	s_add_u32 s98, s97, 10
	s_lshl_b32 s98, s98, 12
	v_add_u32_e32 v3, s98, v1
	global_load_dwordx4 v[80:83], v3, s[88:89] nt
	global_load_dwordx4 v[84:87], v3, s[88:89] offset:1024 nt
	global_load_dwordx4 v[88:91], v3, s[88:89] offset:2048 nt
	global_load_dwordx4 v[92:95], v3, s[88:89] offset:3072 nt
	s_waitcnt vmcnt(50)
	v_mul_f32_e32 v4, v96, v96
	v_fma_f32 v4, v97, v97, v4
	v_fma_f32 v4, v98, v98, v4
	v_fma_f32 v4, v99, v99, v4
	v_fma_f32 v4, v100, v100, v4
	v_fma_f32 v4, v101, v101, v4
	v_fma_f32 v4, v102, v102, v4
	v_fma_f32 v4, v103, v103, v4
	v_fma_f32 v4, v104, v104, v4
	v_fma_f32 v4, v105, v105, v4
	v_fma_f32 v4, v106, v106, v4
	v_fma_f32 v4, v107, v107, v4
	v_fma_f32 v4, v108, v108, v4
	v_fma_f32 v4, v109, v109, v4
	v_fma_f32 v4, v110, v110, v4
	v_fma_f32 v4, v111, v111, v4
	s_nop 1
	v_add_f32_dpp v5, v4, v4 quad_perm:[1,0,3,2] row_mask:0xf bank_mask:0xf
	s_nop 1
	v_add_f32_dpp v4, v5, v5 quad_perm:[2,3,0,1] row_mask:0xf bank_mask:0xf
	s_nop 1
	v_add_f32_dpp v5, v4, v4 row_half_mirror row_mask:0xf bank_mask:0xf
	s_nop 1
	v_add_f32_dpp v4, v5, v5 row_mirror row_mask:0xf bank_mask:0xf
	s_nop 1
	v_readlane_b32 s98, v4, 0
	v_readlane_b32 s99, v4, 16
	s_nop 3
	v_mov_b32_e32 v5, s98
	v_add_f32_e32 v5, s99, v5
	v_readlane_b32 s98, v4, 32
	v_readlane_b32 s99, v4, 48
	s_nop 3
	v_add_f32_e32 v5, s98, v5
	v_add_f32_e32 v5, s99, v5
	v_mul_f32_e32 v5, 0x3a800000, v5
	v_add_f32_e32 v5, 0x358637bd, v5
	v_rsq_f32_e32 v6, v5
	s_nop 0
	s_add_u32 s98, s97, 5
	v_pk_mul_f32 v[96:97], v[96:97], v[6:7] op_sel_hi:[1,0]
	v_pk_mul_f32 v[98:99], v[98:99], v[6:7] op_sel_hi:[1,0]
	v_pk_mul_f32 v[100:101], v[100:101], v[6:7] op_sel_hi:[1,0]
	v_pk_mul_f32 v[102:103], v[102:103], v[6:7] op_sel_hi:[1,0]
	v_pk_mul_f32 v[104:105], v[104:105], v[6:7] op_sel_hi:[1,0]
	v_pk_mul_f32 v[106:107], v[106:107], v[6:7] op_sel_hi:[1,0]
	v_pk_mul_f32 v[108:109], v[108:109], v[6:7] op_sel_hi:[1,0]
	v_pk_mul_f32 v[110:111], v[110:111], v[6:7] op_sel_hi:[1,0]
	v_pk_mul_f32 v[96:97], v[96:97], v[112:113]
	v_pk_mul_f32 v[98:99], v[98:99], v[114:115]
	v_pk_mul_f32 v[100:101], v[100:101], v[116:117]
	v_pk_mul_f32 v[102:103], v[102:103], v[118:119]
	v_pk_mul_f32 v[104:105], v[104:105], v[120:121]
	v_pk_mul_f32 v[106:107], v[106:107], v[122:123]
	v_pk_mul_f32 v[108:109], v[108:109], v[124:125]
	v_pk_mul_f32 v[110:111], v[110:111], v[126:127]
	v_pk_fma_f32 v[96:97], v[96:97], v[128:129], v[144:145]
	v_pk_fma_f32 v[98:99], v[98:99], v[130:131], v[146:147]
	v_pk_fma_f32 v[100:101], v[100:101], v[132:133], v[148:149]
	v_pk_fma_f32 v[102:103], v[102:103], v[134:135], v[150:151]
	v_pk_fma_f32 v[104:105], v[104:105], v[136:137], v[152:153]
	v_pk_fma_f32 v[106:107], v[106:107], v[138:139], v[154:155]
	v_pk_fma_f32 v[108:109], v[108:109], v[140:141], v[156:157]
	v_pk_fma_f32 v[110:111], v[110:111], v[142:143], v[158:159]
	v_cvt_pk_bf16_f32 v96, v96, v97
	v_cvt_pk_bf16_f32 v97, v98, v99
	v_cvt_pk_bf16_f32 v98, v100, v101
	v_cvt_pk_bf16_f32 v99, v102, v103
	v_cvt_pk_bf16_f32 v100, v104, v105
	v_cvt_pk_bf16_f32 v101, v106, v107
	v_cvt_pk_bf16_f32 v102, v108, v109
	v_cvt_pk_bf16_f32 v103, v110, v111
	s_lshl_b32 s99, s98, 11
	v_lshl_add_u32 v8, v0, 3, s99
	global_store_dwordx2 v8, v[96:97], s[94:95]
	global_store_dwordx2 v8, v[98:99], s[94:95] offset:512
	global_store_dwordx2 v8, v[100:101], s[94:95] offset:1024
	global_store_dwordx2 v8, v[102:103], s[94:95] offset:1536
	s_lshl_b32 s99, s98, 2
	v_mov_b32_e32 v9, s99
	v_mov_b32_e32 v10, 0
	v_cmp_eq_u32_e32 vcc, 0, v0
	s_and_saveexec_b64 s[98:99], vcc
	global_store_dword v9, v10, s[90:91]
	global_store_dword v9, v10, s[92:93]
	s_or_b64 exec, exec, s[98:99]
	s_add_u32 s98, s97, 11
	s_lshl_b32 s98, s98, 12
	v_add_u32_e32 v3, s98, v1
	global_load_dwordx4 v[96:99], v3, s[88:89] nt
	global_load_dwordx4 v[100:103], v3, s[88:89] offset:1024 nt
	global_load_dwordx4 v[104:107], v3, s[88:89] offset:2048 nt
	global_load_dwordx4 v[108:111], v3, s[88:89] offset:3072 nt
	s_waitcnt vmcnt(50)
	v_mul_f32_e32 v4, v16, v16
	v_fma_f32 v4, v17, v17, v4
	v_fma_f32 v4, v18, v18, v4
	v_fma_f32 v4, v19, v19, v4
	v_fma_f32 v4, v20, v20, v4
	v_fma_f32 v4, v21, v21, v4
	v_fma_f32 v4, v22, v22, v4
	v_fma_f32 v4, v23, v23, v4
	v_fma_f32 v4, v24, v24, v4
	v_fma_f32 v4, v25, v25, v4
	v_fma_f32 v4, v26, v26, v4
	v_fma_f32 v4, v27, v27, v4
	v_fma_f32 v4, v28, v28, v4
	v_fma_f32 v4, v29, v29, v4
	v_fma_f32 v4, v30, v30, v4
	v_fma_f32 v4, v31, v31, v4
	s_nop 1
	v_add_f32_dpp v5, v4, v4 quad_perm:[1,0,3,2] row_mask:0xf bank_mask:0xf
	s_nop 1
	v_add_f32_dpp v4, v5, v5 quad_perm:[2,3,0,1] row_mask:0xf bank_mask:0xf
	s_nop 1
	v_add_f32_dpp v5, v4, v4 row_half_mirror row_mask:0xf bank_mask:0xf
	s_nop 1
	v_add_f32_dpp v4, v5, v5 row_mirror row_mask:0xf bank_mask:0xf
	s_nop 1
	v_readlane_b32 s98, v4, 0
	v_readlane_b32 s99, v4, 16
	s_nop 3
	v_mov_b32_e32 v5, s98
	v_add_f32_e32 v5, s99, v5
	v_readlane_b32 s98, v4, 32
	v_readlane_b32 s99, v4, 48
	s_nop 3
	v_add_f32_e32 v5, s98, v5
	v_add_f32_e32 v5, s99, v5
	v_mul_f32_e32 v5, 0x3a800000, v5
	v_add_f32_e32 v5, 0x358637bd, v5
	v_rsq_f32_e32 v6, v5
	s_nop 0
	s_add_u32 s98, s97, 6
	v_pk_mul_f32 v[16:17], v[16:17], v[6:7] op_sel_hi:[1,0]
	v_pk_mul_f32 v[18:19], v[18:19], v[6:7] op_sel_hi:[1,0]
	v_pk_mul_f32 v[20:21], v[20:21], v[6:7] op_sel_hi:[1,0]
	v_pk_mul_f32 v[22:23], v[22:23], v[6:7] op_sel_hi:[1,0]
	v_pk_mul_f32 v[24:25], v[24:25], v[6:7] op_sel_hi:[1,0]
	v_pk_mul_f32 v[26:27], v[26:27], v[6:7] op_sel_hi:[1,0]
	v_pk_mul_f32 v[28:29], v[28:29], v[6:7] op_sel_hi:[1,0]
	v_pk_mul_f32 v[30:31], v[30:31], v[6:7] op_sel_hi:[1,0]
	v_pk_mul_f32 v[16:17], v[16:17], v[112:113]
	v_pk_mul_f32 v[18:19], v[18:19], v[114:115]
	v_pk_mul_f32 v[20:21], v[20:21], v[116:117]
	v_pk_mul_f32 v[22:23], v[22:23], v[118:119]
	v_pk_mul_f32 v[24:25], v[24:25], v[120:121]
	v_pk_mul_f32 v[26:27], v[26:27], v[122:123]
	v_pk_mul_f32 v[28:29], v[28:29], v[124:125]
	v_pk_mul_f32 v[30:31], v[30:31], v[126:127]
	v_pk_fma_f32 v[16:17], v[16:17], v[128:129], v[144:145]
	v_pk_fma_f32 v[18:19], v[18:19], v[130:131], v[146:147]
	v_pk_fma_f32 v[20:21], v[20:21], v[132:133], v[148:149]
	v_pk_fma_f32 v[22:23], v[22:23], v[134:135], v[150:151]
	v_pk_fma_f32 v[24:25], v[24:25], v[136:137], v[152:153]
	v_pk_fma_f32 v[26:27], v[26:27], v[138:139], v[154:155]
	v_pk_fma_f32 v[28:29], v[28:29], v[140:141], v[156:157]
	v_pk_fma_f32 v[30:31], v[30:31], v[142:143], v[158:159]
	v_cvt_pk_bf16_f32 v16, v16, v17
	v_cvt_pk_bf16_f32 v17, v18, v19
	v_cvt_pk_bf16_f32 v18, v20, v21
	v_cvt_pk_bf16_f32 v19, v22, v23
	v_cvt_pk_bf16_f32 v20, v24, v25
	v_cvt_pk_bf16_f32 v21, v26, v27
	v_cvt_pk_bf16_f32 v22, v28, v29
	v_cvt_pk_bf16_f32 v23, v30, v31
	s_lshl_b32 s99, s98, 11
	v_lshl_add_u32 v8, v0, 3, s99
	global_store_dwordx2 v8, v[16:17], s[94:95]
	global_store_dwordx2 v8, v[18:19], s[94:95] offset:512
	global_store_dwordx2 v8, v[20:21], s[94:95] offset:1024
	global_store_dwordx2 v8, v[22:23], s[94:95] offset:1536
	s_lshl_b32 s99, s98, 2
	v_mov_b32_e32 v9, s99
	v_mov_b32_e32 v10, 0
	v_cmp_eq_u32_e32 vcc, 0, v0
	s_and_saveexec_b64 s[98:99], vcc
	global_store_dword v9, v10, s[90:91]
	global_store_dword v9, v10, s[92:93]
	s_or_b64 exec, exec, s[98:99]
	s_add_u32 s98, s97, 12
	s_lshl_b32 s98, s98, 12
	v_add_u32_e32 v3, s98, v1
	global_load_dwordx4 v[16:19], v3, s[88:89] nt
	global_load_dwordx4 v[20:23], v3, s[88:89] offset:1024 nt
	global_load_dwordx4 v[24:27], v3, s[88:89] offset:2048 nt
	global_load_dwordx4 v[28:31], v3, s[88:89] offset:3072 nt
	s_waitcnt vmcnt(50)
	v_mul_f32_e32 v4, v32, v32
	v_fma_f32 v4, v33, v33, v4
	v_fma_f32 v4, v34, v34, v4
	v_fma_f32 v4, v35, v35, v4
	v_fma_f32 v4, v36, v36, v4
	v_fma_f32 v4, v37, v37, v4
	v_fma_f32 v4, v38, v38, v4
	v_fma_f32 v4, v39, v39, v4
	v_fma_f32 v4, v40, v40, v4
	v_fma_f32 v4, v41, v41, v4
	v_fma_f32 v4, v42, v42, v4
	v_fma_f32 v4, v43, v43, v4
	v_fma_f32 v4, v44, v44, v4
	v_fma_f32 v4, v45, v45, v4
	v_fma_f32 v4, v46, v46, v4
	v_fma_f32 v4, v47, v47, v4
	s_nop 1
	v_add_f32_dpp v5, v4, v4 quad_perm:[1,0,3,2] row_mask:0xf bank_mask:0xf
	s_nop 1
	v_add_f32_dpp v4, v5, v5 quad_perm:[2,3,0,1] row_mask:0xf bank_mask:0xf
	s_nop 1
	v_add_f32_dpp v5, v4, v4 row_half_mirror row_mask:0xf bank_mask:0xf
	s_nop 1
	v_add_f32_dpp v4, v5, v5 row_mirror row_mask:0xf bank_mask:0xf
	s_nop 1
	v_readlane_b32 s98, v4, 0
	v_readlane_b32 s99, v4, 16
	s_nop 3
	v_mov_b32_e32 v5, s98
	v_add_f32_e32 v5, s99, v5
	v_readlane_b32 s98, v4, 32
	v_readlane_b32 s99, v4, 48
	s_nop 3
	v_add_f32_e32 v5, s98, v5
	v_add_f32_e32 v5, s99, v5
	v_mul_f32_e32 v5, 0x3a800000, v5
	v_add_f32_e32 v5, 0x358637bd, v5
	v_rsq_f32_e32 v6, v5
	s_nop 0
	s_add_u32 s98, s97, 7
	v_pk_mul_f32 v[32:33], v[32:33], v[6:7] op_sel_hi:[1,0]
	v_pk_mul_f32 v[34:35], v[34:35], v[6:7] op_sel_hi:[1,0]
	v_pk_mul_f32 v[36:37], v[36:37], v[6:7] op_sel_hi:[1,0]
	v_pk_mul_f32 v[38:39], v[38:39], v[6:7] op_sel_hi:[1,0]
	v_pk_mul_f32 v[40:41], v[40:41], v[6:7] op_sel_hi:[1,0]
	v_pk_mul_f32 v[42:43], v[42:43], v[6:7] op_sel_hi:[1,0]
	v_pk_mul_f32 v[44:45], v[44:45], v[6:7] op_sel_hi:[1,0]
	v_pk_mul_f32 v[46:47], v[46:47], v[6:7] op_sel_hi:[1,0]
	v_pk_mul_f32 v[32:33], v[32:33], v[112:113]
	v_pk_mul_f32 v[34:35], v[34:35], v[114:115]
	v_pk_mul_f32 v[36:37], v[36:37], v[116:117]
	v_pk_mul_f32 v[38:39], v[38:39], v[118:119]
	v_pk_mul_f32 v[40:41], v[40:41], v[120:121]
	v_pk_mul_f32 v[42:43], v[42:43], v[122:123]
	v_pk_mul_f32 v[44:45], v[44:45], v[124:125]
	v_pk_mul_f32 v[46:47], v[46:47], v[126:127]
	v_pk_fma_f32 v[32:33], v[32:33], v[128:129], v[144:145]
	v_pk_fma_f32 v[34:35], v[34:35], v[130:131], v[146:147]
	v_pk_fma_f32 v[36:37], v[36:37], v[132:133], v[148:149]
	v_pk_fma_f32 v[38:39], v[38:39], v[134:135], v[150:151]
	v_pk_fma_f32 v[40:41], v[40:41], v[136:137], v[152:153]
	v_pk_fma_f32 v[42:43], v[42:43], v[138:139], v[154:155]
	v_pk_fma_f32 v[44:45], v[44:45], v[140:141], v[156:157]
	v_pk_fma_f32 v[46:47], v[46:47], v[142:143], v[158:159]
	v_cvt_pk_bf16_f32 v32, v32, v33
	v_cvt_pk_bf16_f32 v33, v34, v35
	v_cvt_pk_bf16_f32 v34, v36, v37
	v_cvt_pk_bf16_f32 v35, v38, v39
	v_cvt_pk_bf16_f32 v36, v40, v41
	v_cvt_pk_bf16_f32 v37, v42, v43
	v_cvt_pk_bf16_f32 v38, v44, v45
	v_cvt_pk_bf16_f32 v39, v46, v47
	s_lshl_b32 s99, s98, 11
	v_lshl_add_u32 v8, v0, 3, s99
	global_store_dwordx2 v8, v[32:33], s[94:95]
	global_store_dwordx2 v8, v[34:35], s[94:95] offset:512
	global_store_dwordx2 v8, v[36:37], s[94:95] offset:1024
	global_store_dwordx2 v8, v[38:39], s[94:95] offset:1536
	s_lshl_b32 s99, s98, 2
	v_mov_b32_e32 v9, s99
	v_mov_b32_e32 v10, 0
	v_cmp_eq_u32_e32 vcc, 0, v0
	s_and_saveexec_b64 s[98:99], vcc
	global_store_dword v9, v10, s[90:91]
	global_store_dword v9, v10, s[92:93]
	s_or_b64 exec, exec, s[98:99]
	s_add_u32 s98, s97, 13
	s_lshl_b32 s98, s98, 12
	v_add_u32_e32 v3, s98, v1
	global_load_dwordx4 v[32:35], v3, s[88:89] nt
	global_load_dwordx4 v[36:39], v3, s[88:89] offset:1024 nt
	global_load_dwordx4 v[40:43], v3, s[88:89] offset:2048 nt
	global_load_dwordx4 v[44:47], v3, s[88:89] offset:3072 nt
	s_waitcnt vmcnt(50)
	v_mul_f32_e32 v4, v48, v48
	v_fma_f32 v4, v49, v49, v4
	v_fma_f32 v4, v50, v50, v4
	v_fma_f32 v4, v51, v51, v4
	v_fma_f32 v4, v52, v52, v4
	v_fma_f32 v4, v53, v53, v4
	v_fma_f32 v4, v54, v54, v4
	v_fma_f32 v4, v55, v55, v4
	v_fma_f32 v4, v56, v56, v4
	v_fma_f32 v4, v57, v57, v4
	v_fma_f32 v4, v58, v58, v4
	v_fma_f32 v4, v59, v59, v4
	v_fma_f32 v4, v60, v60, v4
	v_fma_f32 v4, v61, v61, v4
	v_fma_f32 v4, v62, v62, v4
	v_fma_f32 v4, v63, v63, v4
	s_nop 1
	v_add_f32_dpp v5, v4, v4 quad_perm:[1,0,3,2] row_mask:0xf bank_mask:0xf
	s_nop 1
	v_add_f32_dpp v4, v5, v5 quad_perm:[2,3,0,1] row_mask:0xf bank_mask:0xf
	s_nop 1
	v_add_f32_dpp v5, v4, v4 row_half_mirror row_mask:0xf bank_mask:0xf
	s_nop 1
	v_add_f32_dpp v4, v5, v5 row_mirror row_mask:0xf bank_mask:0xf
	s_nop 1
	v_readlane_b32 s98, v4, 0
	v_readlane_b32 s99, v4, 16
	s_nop 3
	v_mov_b32_e32 v5, s98
	v_add_f32_e32 v5, s99, v5
	v_readlane_b32 s98, v4, 32
	v_readlane_b32 s99, v4, 48
	s_nop 3
	v_add_f32_e32 v5, s98, v5
	v_add_f32_e32 v5, s99, v5
	v_mul_f32_e32 v5, 0x3a800000, v5
	v_add_f32_e32 v5, 0x358637bd, v5
	v_rsq_f32_e32 v6, v5
	s_nop 0
	s_add_u32 s98, s97, 8
	v_pk_mul_f32 v[48:49], v[48:49], v[6:7] op_sel_hi:[1,0]
	v_pk_mul_f32 v[50:51], v[50:51], v[6:7] op_sel_hi:[1,0]
	v_pk_mul_f32 v[52:53], v[52:53], v[6:7] op_sel_hi:[1,0]
	v_pk_mul_f32 v[54:55], v[54:55], v[6:7] op_sel_hi:[1,0]
	v_pk_mul_f32 v[56:57], v[56:57], v[6:7] op_sel_hi:[1,0]
	v_pk_mul_f32 v[58:59], v[58:59], v[6:7] op_sel_hi:[1,0]
	v_pk_mul_f32 v[60:61], v[60:61], v[6:7] op_sel_hi:[1,0]
	v_pk_mul_f32 v[62:63], v[62:63], v[6:7] op_sel_hi:[1,0]
	v_pk_mul_f32 v[48:49], v[48:49], v[112:113]
	v_pk_mul_f32 v[50:51], v[50:51], v[114:115]
	v_pk_mul_f32 v[52:53], v[52:53], v[116:117]
	v_pk_mul_f32 v[54:55], v[54:55], v[118:119]
	v_pk_mul_f32 v[56:57], v[56:57], v[120:121]
	v_pk_mul_f32 v[58:59], v[58:59], v[122:123]
	v_pk_mul_f32 v[60:61], v[60:61], v[124:125]
	v_pk_mul_f32 v[62:63], v[62:63], v[126:127]
	v_pk_fma_f32 v[48:49], v[48:49], v[128:129], v[144:145]
	v_pk_fma_f32 v[50:51], v[50:51], v[130:131], v[146:147]
	v_pk_fma_f32 v[52:53], v[52:53], v[132:133], v[148:149]
	v_pk_fma_f32 v[54:55], v[54:55], v[134:135], v[150:151]
	v_pk_fma_f32 v[56:57], v[56:57], v[136:137], v[152:153]
	v_pk_fma_f32 v[58:59], v[58:59], v[138:139], v[154:155]
	v_pk_fma_f32 v[60:61], v[60:61], v[140:141], v[156:157]
	v_pk_fma_f32 v[62:63], v[62:63], v[142:143], v[158:159]
	v_cvt_pk_bf16_f32 v48, v48, v49
	v_cvt_pk_bf16_f32 v49, v50, v51
	v_cvt_pk_bf16_f32 v50, v52, v53
	v_cvt_pk_bf16_f32 v51, v54, v55
	v_cvt_pk_bf16_f32 v52, v56, v57
	v_cvt_pk_bf16_f32 v53, v58, v59
	v_cvt_pk_bf16_f32 v54, v60, v61
	v_cvt_pk_bf16_f32 v55, v62, v63
	s_lshl_b32 s99, s98, 11
	v_lshl_add_u32 v8, v0, 3, s99
	global_store_dwordx2 v8, v[48:49], s[94:95]
	global_store_dwordx2 v8, v[50:51], s[94:95] offset:512
	global_store_dwordx2 v8, v[52:53], s[94:95] offset:1024
	global_store_dwordx2 v8, v[54:55], s[94:95] offset:1536
	s_lshl_b32 s99, s98, 2
	v_mov_b32_e32 v9, s99
	v_mov_b32_e32 v10, 0
	v_cmp_eq_u32_e32 vcc, 0, v0
	s_and_saveexec_b64 s[98:99], vcc
	global_store_dword v9, v10, s[90:91]
	global_store_dword v9, v10, s[92:93]
	s_or_b64 exec, exec, s[98:99]
	s_add_u32 s98, s97, 14
	s_lshl_b32 s98, s98, 12
	v_add_u32_e32 v3, s98, v1
	global_load_dwordx4 v[48:51], v3, s[88:89] nt
	global_load_dwordx4 v[52:55], v3, s[88:89] offset:1024 nt
	global_load_dwordx4 v[56:59], v3, s[88:89] offset:2048 nt
	global_load_dwordx4 v[60:63], v3, s[88:89] offset:3072 nt
	s_waitcnt vmcnt(50)
	v_mul_f32_e32 v4, v64, v64
	v_fma_f32 v4, v65, v65, v4
	v_fma_f32 v4, v66, v66, v4
	v_fma_f32 v4, v67, v67, v4
	v_fma_f32 v4, v68, v68, v4
	v_fma_f32 v4, v69, v69, v4
	v_fma_f32 v4, v70, v70, v4
	v_fma_f32 v4, v71, v71, v4
	v_fma_f32 v4, v72, v72, v4
	v_fma_f32 v4, v73, v73, v4
	v_fma_f32 v4, v74, v74, v4
	v_fma_f32 v4, v75, v75, v4
	v_fma_f32 v4, v76, v76, v4
	v_fma_f32 v4, v77, v77, v4
	v_fma_f32 v4, v78, v78, v4
	v_fma_f32 v4, v79, v79, v4
	s_nop 1
	v_add_f32_dpp v5, v4, v4 quad_perm:[1,0,3,2] row_mask:0xf bank_mask:0xf
	s_nop 1
	v_add_f32_dpp v4, v5, v5 quad_perm:[2,3,0,1] row_mask:0xf bank_mask:0xf
	s_nop 1
	v_add_f32_dpp v5, v4, v4 row_half_mirror row_mask:0xf bank_mask:0xf
	s_nop 1
	v_add_f32_dpp v4, v5, v5 row_mirror row_mask:0xf bank_mask:0xf
	s_nop 1
	v_readlane_b32 s98, v4, 0
	v_readlane_b32 s99, v4, 16
	s_nop 3
	v_mov_b32_e32 v5, s98
	v_add_f32_e32 v5, s99, v5
	v_readlane_b32 s98, v4, 32
	v_readlane_b32 s99, v4, 48
	s_nop 3
	v_add_f32_e32 v5, s98, v5
	v_add_f32_e32 v5, s99, v5
	v_mul_f32_e32 v5, 0x3a800000, v5
	v_add_f32_e32 v5, 0x358637bd, v5
	v_rsq_f32_e32 v6, v5
	s_nop 0
	s_add_u32 s98, s97, 9
	v_pk_mul_f32 v[64:65], v[64:65], v[6:7] op_sel_hi:[1,0]
	v_pk_mul_f32 v[66:67], v[66:67], v[6:7] op_sel_hi:[1,0]
	v_pk_mul_f32 v[68:69], v[68:69], v[6:7] op_sel_hi:[1,0]
	v_pk_mul_f32 v[70:71], v[70:71], v[6:7] op_sel_hi:[1,0]
	v_pk_mul_f32 v[72:73], v[72:73], v[6:7] op_sel_hi:[1,0]
	v_pk_mul_f32 v[74:75], v[74:75], v[6:7] op_sel_hi:[1,0]
	v_pk_mul_f32 v[76:77], v[76:77], v[6:7] op_sel_hi:[1,0]
	v_pk_mul_f32 v[78:79], v[78:79], v[6:7] op_sel_hi:[1,0]
	v_pk_mul_f32 v[64:65], v[64:65], v[112:113]
	v_pk_mul_f32 v[66:67], v[66:67], v[114:115]
	v_pk_mul_f32 v[68:69], v[68:69], v[116:117]
	v_pk_mul_f32 v[70:71], v[70:71], v[118:119]
	v_pk_mul_f32 v[72:73], v[72:73], v[120:121]
	v_pk_mul_f32 v[74:75], v[74:75], v[122:123]
	v_pk_mul_f32 v[76:77], v[76:77], v[124:125]
	v_pk_mul_f32 v[78:79], v[78:79], v[126:127]
	v_pk_fma_f32 v[64:65], v[64:65], v[128:129], v[144:145]
	v_pk_fma_f32 v[66:67], v[66:67], v[130:131], v[146:147]
	v_pk_fma_f32 v[68:69], v[68:69], v[132:133], v[148:149]
	v_pk_fma_f32 v[70:71], v[70:71], v[134:135], v[150:151]
	v_pk_fma_f32 v[72:73], v[72:73], v[136:137], v[152:153]
	v_pk_fma_f32 v[74:75], v[74:75], v[138:139], v[154:155]
	v_pk_fma_f32 v[76:77], v[76:77], v[140:141], v[156:157]
	v_pk_fma_f32 v[78:79], v[78:79], v[142:143], v[158:159]
	v_cvt_pk_bf16_f32 v64, v64, v65
	v_cvt_pk_bf16_f32 v65, v66, v67
	v_cvt_pk_bf16_f32 v66, v68, v69
	v_cvt_pk_bf16_f32 v67, v70, v71
	v_cvt_pk_bf16_f32 v68, v72, v73
	v_cvt_pk_bf16_f32 v69, v74, v75
	v_cvt_pk_bf16_f32 v70, v76, v77
	v_cvt_pk_bf16_f32 v71, v78, v79
	s_lshl_b32 s99, s98, 11
	v_lshl_add_u32 v8, v0, 3, s99
	global_store_dwordx2 v8, v[64:65], s[94:95]
	global_store_dwordx2 v8, v[66:67], s[94:95] offset:512
	global_store_dwordx2 v8, v[68:69], s[94:95] offset:1024
	global_store_dwordx2 v8, v[70:71], s[94:95] offset:1536
	s_lshl_b32 s99, s98, 2
	v_mov_b32_e32 v9, s99
	v_mov_b32_e32 v10, 0
	v_cmp_eq_u32_e32 vcc, 0, v0
	s_and_saveexec_b64 s[98:99], vcc
	global_store_dword v9, v10, s[90:91]
	global_store_dword v9, v10, s[92:93]
	s_or_b64 exec, exec, s[98:99]
	s_add_u32 s98, s97, 15
	s_lshl_b32 s98, s98, 12
	v_add_u32_e32 v3, s98, v1
	global_load_dwordx4 v[64:67], v3, s[88:89] nt
	global_load_dwordx4 v[68:71], v3, s[88:89] offset:1024 nt
	global_load_dwordx4 v[72:75], v3, s[88:89] offset:2048 nt
	global_load_dwordx4 v[76:79], v3, s[88:89] offset:3072 nt
	s_waitcnt vmcnt(50)
	v_mul_f32_e32 v4, v80, v80
	v_fma_f32 v4, v81, v81, v4
	v_fma_f32 v4, v82, v82, v4
	v_fma_f32 v4, v83, v83, v4
	v_fma_f32 v4, v84, v84, v4
	v_fma_f32 v4, v85, v85, v4
	v_fma_f32 v4, v86, v86, v4
	v_fma_f32 v4, v87, v87, v4
	v_fma_f32 v4, v88, v88, v4
	v_fma_f32 v4, v89, v89, v4
	v_fma_f32 v4, v90, v90, v4
	v_fma_f32 v4, v91, v91, v4
	v_fma_f32 v4, v92, v92, v4
	v_fma_f32 v4, v93, v93, v4
	v_fma_f32 v4, v94, v94, v4
	v_fma_f32 v4, v95, v95, v4
	s_nop 1
	v_add_f32_dpp v5, v4, v4 quad_perm:[1,0,3,2] row_mask:0xf bank_mask:0xf
	s_nop 1
	v_add_f32_dpp v4, v5, v5 quad_perm:[2,3,0,1] row_mask:0xf bank_mask:0xf
	s_nop 1
	v_add_f32_dpp v5, v4, v4 row_half_mirror row_mask:0xf bank_mask:0xf
	s_nop 1
	v_add_f32_dpp v4, v5, v5 row_mirror row_mask:0xf bank_mask:0xf
	s_nop 1
	v_readlane_b32 s98, v4, 0
	v_readlane_b32 s99, v4, 16
	s_nop 3
	v_mov_b32_e32 v5, s98
	v_add_f32_e32 v5, s99, v5
	v_readlane_b32 s98, v4, 32
	v_readlane_b32 s99, v4, 48
	s_nop 3
	v_add_f32_e32 v5, s98, v5
	v_add_f32_e32 v5, s99, v5
	v_mul_f32_e32 v5, 0x3a800000, v5
	v_add_f32_e32 v5, 0x358637bd, v5
	v_rsq_f32_e32 v6, v5
	s_nop 0
	s_add_u32 s98, s97, 10
	v_pk_mul_f32 v[80:81], v[80:81], v[6:7] op_sel_hi:[1,0]
	v_pk_mul_f32 v[82:83], v[82:83], v[6:7] op_sel_hi:[1,0]
	v_pk_mul_f32 v[84:85], v[84:85], v[6:7] op_sel_hi:[1,0]
	v_pk_mul_f32 v[86:87], v[86:87], v[6:7] op_sel_hi:[1,0]
	v_pk_mul_f32 v[88:89], v[88:89], v[6:7] op_sel_hi:[1,0]
	v_pk_mul_f32 v[90:91], v[90:91], v[6:7] op_sel_hi:[1,0]
	v_pk_mul_f32 v[92:93], v[92:93], v[6:7] op_sel_hi:[1,0]
	v_pk_mul_f32 v[94:95], v[94:95], v[6:7] op_sel_hi:[1,0]
	v_pk_mul_f32 v[80:81], v[80:81], v[112:113]
	v_pk_mul_f32 v[82:83], v[82:83], v[114:115]
	v_pk_mul_f32 v[84:85], v[84:85], v[116:117]
	v_pk_mul_f32 v[86:87], v[86:87], v[118:119]
	v_pk_mul_f32 v[88:89], v[88:89], v[120:121]
	v_pk_mul_f32 v[90:91], v[90:91], v[122:123]
	v_pk_mul_f32 v[92:93], v[92:93], v[124:125]
	v_pk_mul_f32 v[94:95], v[94:95], v[126:127]
	v_pk_fma_f32 v[80:81], v[80:81], v[128:129], v[144:145]
	v_pk_fma_f32 v[82:83], v[82:83], v[130:131], v[146:147]
	v_pk_fma_f32 v[84:85], v[84:85], v[132:133], v[148:149]
	v_pk_fma_f32 v[86:87], v[86:87], v[134:135], v[150:151]
	v_pk_fma_f32 v[88:89], v[88:89], v[136:137], v[152:153]
	v_pk_fma_f32 v[90:91], v[90:91], v[138:139], v[154:155]
	v_pk_fma_f32 v[92:93], v[92:93], v[140:141], v[156:157]
	v_pk_fma_f32 v[94:95], v[94:95], v[142:143], v[158:159]
	v_cvt_pk_bf16_f32 v80, v80, v81
	v_cvt_pk_bf16_f32 v81, v82, v83
	v_cvt_pk_bf16_f32 v82, v84, v85
	v_cvt_pk_bf16_f32 v83, v86, v87
	v_cvt_pk_bf16_f32 v84, v88, v89
	v_cvt_pk_bf16_f32 v85, v90, v91
	v_cvt_pk_bf16_f32 v86, v92, v93
	v_cvt_pk_bf16_f32 v87, v94, v95
	s_lshl_b32 s99, s98, 11
	v_lshl_add_u32 v8, v0, 3, s99
	global_store_dwordx2 v8, v[80:81], s[94:95]
	global_store_dwordx2 v8, v[82:83], s[94:95] offset:512
	global_store_dwordx2 v8, v[84:85], s[94:95] offset:1024
	global_store_dwordx2 v8, v[86:87], s[94:95] offset:1536
	s_lshl_b32 s99, s98, 2
	v_mov_b32_e32 v9, s99
	v_mov_b32_e32 v10, 0
	v_cmp_eq_u32_e32 vcc, 0, v0
	s_and_saveexec_b64 s[98:99], vcc
	global_store_dword v9, v10, s[90:91]
	global_store_dword v9, v10, s[92:93]
	s_or_b64 exec, exec, s[98:99]
	s_waitcnt vmcnt(46)
	v_mul_f32_e32 v4, v96, v96
	v_fma_f32 v4, v97, v97, v4
	v_fma_f32 v4, v98, v98, v4
	v_fma_f32 v4, v99, v99, v4
	v_fma_f32 v4, v100, v100, v4
	v_fma_f32 v4, v101, v101, v4
	v_fma_f32 v4, v102, v102, v4
	v_fma_f32 v4, v103, v103, v4
	v_fma_f32 v4, v104, v104, v4
	v_fma_f32 v4, v105, v105, v4
	v_fma_f32 v4, v106, v106, v4
	v_fma_f32 v4, v107, v107, v4
	v_fma_f32 v4, v108, v108, v4
	v_fma_f32 v4, v109, v109, v4
	v_fma_f32 v4, v110, v110, v4
	v_fma_f32 v4, v111, v111, v4
	s_nop 1
	v_add_f32_dpp v5, v4, v4 quad_perm:[1,0,3,2] row_mask:0xf bank_mask:0xf
	s_nop 1
	v_add_f32_dpp v4, v5, v5 quad_perm:[2,3,0,1] row_mask:0xf bank_mask:0xf
	s_nop 1
	v_add_f32_dpp v5, v4, v4 row_half_mirror row_mask:0xf bank_mask:0xf
	s_nop 1
	v_add_f32_dpp v4, v5, v5 row_mirror row_mask:0xf bank_mask:0xf
	s_nop 1
	v_readlane_b32 s98, v4, 0
	v_readlane_b32 s99, v4, 16
	s_nop 3
	v_mov_b32_e32 v5, s98
	v_add_f32_e32 v5, s99, v5
	v_readlane_b32 s98, v4, 32
	v_readlane_b32 s99, v4, 48
	s_nop 3
	v_add_f32_e32 v5, s98, v5
	v_add_f32_e32 v5, s99, v5
	v_mul_f32_e32 v5, 0x3a800000, v5
	v_add_f32_e32 v5, 0x358637bd, v5
	v_rsq_f32_e32 v6, v5
	s_nop 0
	s_add_u32 s98, s97, 11
	v_pk_mul_f32 v[96:97], v[96:97], v[6:7] op_sel_hi:[1,0]
	v_pk_mul_f32 v[98:99], v[98:99], v[6:7] op_sel_hi:[1,0]
	v_pk_mul_f32 v[100:101], v[100:101], v[6:7] op_sel_hi:[1,0]
	v_pk_mul_f32 v[102:103], v[102:103], v[6:7] op_sel_hi:[1,0]
	v_pk_mul_f32 v[104:105], v[104:105], v[6:7] op_sel_hi:[1,0]
	v_pk_mul_f32 v[106:107], v[106:107], v[6:7] op_sel_hi:[1,0]
	v_pk_mul_f32 v[108:109], v[108:109], v[6:7] op_sel_hi:[1,0]
	v_pk_mul_f32 v[110:111], v[110:111], v[6:7] op_sel_hi:[1,0]
	v_pk_mul_f32 v[96:97], v[96:97], v[112:113]
	v_pk_mul_f32 v[98:99], v[98:99], v[114:115]
	v_pk_mul_f32 v[100:101], v[100:101], v[116:117]
	v_pk_mul_f32 v[102:103], v[102:103], v[118:119]
	v_pk_mul_f32 v[104:105], v[104:105], v[120:121]
	v_pk_mul_f32 v[106:107], v[106:107], v[122:123]
	v_pk_mul_f32 v[108:109], v[108:109], v[124:125]
	v_pk_mul_f32 v[110:111], v[110:111], v[126:127]
	v_pk_fma_f32 v[96:97], v[96:97], v[128:129], v[144:145]
	v_pk_fma_f32 v[98:99], v[98:99], v[130:131], v[146:147]
	v_pk_fma_f32 v[100:101], v[100:101], v[132:133], v[148:149]
	v_pk_fma_f32 v[102:103], v[102:103], v[134:135], v[150:151]
	v_pk_fma_f32 v[104:105], v[104:105], v[136:137], v[152:153]
	v_pk_fma_f32 v[106:107], v[106:107], v[138:139], v[154:155]
	v_pk_fma_f32 v[108:109], v[108:109], v[140:141], v[156:157]
	v_pk_fma_f32 v[110:111], v[110:111], v[142:143], v[158:159]
	v_cvt_pk_bf16_f32 v96, v96, v97
	v_cvt_pk_bf16_f32 v97, v98, v99
	v_cvt_pk_bf16_f32 v98, v100, v101
	v_cvt_pk_bf16_f32 v99, v102, v103
	v_cvt_pk_bf16_f32 v100, v104, v105
	v_cvt_pk_bf16_f32 v101, v106, v107
	v_cvt_pk_bf16_f32 v102, v108, v109
	v_cvt_pk_bf16_f32 v103, v110, v111
	s_lshl_b32 s99, s98, 11
	v_lshl_add_u32 v8, v0, 3, s99
	global_store_dwordx2 v8, v[96:97], s[94:95]
	global_store_dwordx2 v8, v[98:99], s[94:95] offset:512
	global_store_dwordx2 v8, v[100:101], s[94:95] offset:1024
	global_store_dwordx2 v8, v[102:103], s[94:95] offset:1536
	s_lshl_b32 s99, s98, 2
	v_mov_b32_e32 v9, s99
	v_mov_b32_e32 v10, 0
	v_cmp_eq_u32_e32 vcc, 0, v0
	s_and_saveexec_b64 s[98:99], vcc
	global_store_dword v9, v10, s[90:91]
	global_store_dword v9, v10, s[92:93]
	s_or_b64 exec, exec, s[98:99]
	s_waitcnt vmcnt(42)
	v_mul_f32_e32 v4, v16, v16
	v_fma_f32 v4, v17, v17, v4
	v_fma_f32 v4, v18, v18, v4
	v_fma_f32 v4, v19, v19, v4
	v_fma_f32 v4, v20, v20, v4
	v_fma_f32 v4, v21, v21, v4
	v_fma_f32 v4, v22, v22, v4
	v_fma_f32 v4, v23, v23, v4
	v_fma_f32 v4, v24, v24, v4
	v_fma_f32 v4, v25, v25, v4
	v_fma_f32 v4, v26, v26, v4
	v_fma_f32 v4, v27, v27, v4
	v_fma_f32 v4, v28, v28, v4
	v_fma_f32 v4, v29, v29, v4
	v_fma_f32 v4, v30, v30, v4
	v_fma_f32 v4, v31, v31, v4
	s_nop 1
	v_add_f32_dpp v5, v4, v4 quad_perm:[1,0,3,2] row_mask:0xf bank_mask:0xf
	s_nop 1
	v_add_f32_dpp v4, v5, v5 quad_perm:[2,3,0,1] row_mask:0xf bank_mask:0xf
	s_nop 1
	v_add_f32_dpp v5, v4, v4 row_half_mirror row_mask:0xf bank_mask:0xf
	s_nop 1
	v_add_f32_dpp v4, v5, v5 row_mirror row_mask:0xf bank_mask:0xf
	s_nop 1
	v_readlane_b32 s98, v4, 0
	v_readlane_b32 s99, v4, 16
	s_nop 3
	v_mov_b32_e32 v5, s98
	v_add_f32_e32 v5, s99, v5
	v_readlane_b32 s98, v4, 32
	v_readlane_b32 s99, v4, 48
	s_nop 3
	v_add_f32_e32 v5, s98, v5
	v_add_f32_e32 v5, s99, v5
	v_mul_f32_e32 v5, 0x3a800000, v5
	v_add_f32_e32 v5, 0x358637bd, v5
	v_rsq_f32_e32 v6, v5
	s_nop 0
	s_add_u32 s98, s97, 12
	v_pk_mul_f32 v[16:17], v[16:17], v[6:7] op_sel_hi:[1,0]
	v_pk_mul_f32 v[18:19], v[18:19], v[6:7] op_sel_hi:[1,0]
	v_pk_mul_f32 v[20:21], v[20:21], v[6:7] op_sel_hi:[1,0]
	v_pk_mul_f32 v[22:23], v[22:23], v[6:7] op_sel_hi:[1,0]
	v_pk_mul_f32 v[24:25], v[24:25], v[6:7] op_sel_hi:[1,0]
	v_pk_mul_f32 v[26:27], v[26:27], v[6:7] op_sel_hi:[1,0]
	v_pk_mul_f32 v[28:29], v[28:29], v[6:7] op_sel_hi:[1,0]
	v_pk_mul_f32 v[30:31], v[30:31], v[6:7] op_sel_hi:[1,0]
	v_pk_mul_f32 v[16:17], v[16:17], v[112:113]
	v_pk_mul_f32 v[18:19], v[18:19], v[114:115]
	v_pk_mul_f32 v[20:21], v[20:21], v[116:117]
	v_pk_mul_f32 v[22:23], v[22:23], v[118:119]
	v_pk_mul_f32 v[24:25], v[24:25], v[120:121]
	v_pk_mul_f32 v[26:27], v[26:27], v[122:123]
	v_pk_mul_f32 v[28:29], v[28:29], v[124:125]
	v_pk_mul_f32 v[30:31], v[30:31], v[126:127]
	v_pk_fma_f32 v[16:17], v[16:17], v[128:129], v[144:145]
	v_pk_fma_f32 v[18:19], v[18:19], v[130:131], v[146:147]
	v_pk_fma_f32 v[20:21], v[20:21], v[132:133], v[148:149]
	v_pk_fma_f32 v[22:23], v[22:23], v[134:135], v[150:151]
	v_pk_fma_f32 v[24:25], v[24:25], v[136:137], v[152:153]
	v_pk_fma_f32 v[26:27], v[26:27], v[138:139], v[154:155]
	v_pk_fma_f32 v[28:29], v[28:29], v[140:141], v[156:157]
	v_pk_fma_f32 v[30:31], v[30:31], v[142:143], v[158:159]
	v_cvt_pk_bf16_f32 v16, v16, v17
	v_cvt_pk_bf16_f32 v17, v18, v19
	v_cvt_pk_bf16_f32 v18, v20, v21
	v_cvt_pk_bf16_f32 v19, v22, v23
	v_cvt_pk_bf16_f32 v20, v24, v25
	v_cvt_pk_bf16_f32 v21, v26, v27
	v_cvt_pk_bf16_f32 v22, v28, v29
	v_cvt_pk_bf16_f32 v23, v30, v31
	s_lshl_b32 s99, s98, 11
	v_lshl_add_u32 v8, v0, 3, s99
	global_store_dwordx2 v8, v[16:17], s[94:95]
	global_store_dwordx2 v8, v[18:19], s[94:95] offset:512
	global_store_dwordx2 v8, v[20:21], s[94:95] offset:1024
	global_store_dwordx2 v8, v[22:23], s[94:95] offset:1536
	s_lshl_b32 s99, s98, 2
	v_mov_b32_e32 v9, s99
	v_mov_b32_e32 v10, 0
	v_cmp_eq_u32_e32 vcc, 0, v0
	s_and_saveexec_b64 s[98:99], vcc
	global_store_dword v9, v10, s[90:91]
	global_store_dword v9, v10, s[92:93]
	s_or_b64 exec, exec, s[98:99]
	s_waitcnt vmcnt(38)
	v_mul_f32_e32 v4, v32, v32
	v_fma_f32 v4, v33, v33, v4
	v_fma_f32 v4, v34, v34, v4
	v_fma_f32 v4, v35, v35, v4
	v_fma_f32 v4, v36, v36, v4
	v_fma_f32 v4, v37, v37, v4
	v_fma_f32 v4, v38, v38, v4
	v_fma_f32 v4, v39, v39, v4
	v_fma_f32 v4, v40, v40, v4
	v_fma_f32 v4, v41, v41, v4
	v_fma_f32 v4, v42, v42, v4
	v_fma_f32 v4, v43, v43, v4
	v_fma_f32 v4, v44, v44, v4
	v_fma_f32 v4, v45, v45, v4
	v_fma_f32 v4, v46, v46, v4
	v_fma_f32 v4, v47, v47, v4
	s_nop 1
	v_add_f32_dpp v5, v4, v4 quad_perm:[1,0,3,2] row_mask:0xf bank_mask:0xf
	s_nop 1
	v_add_f32_dpp v4, v5, v5 quad_perm:[2,3,0,1] row_mask:0xf bank_mask:0xf
	s_nop 1
	v_add_f32_dpp v5, v4, v4 row_half_mirror row_mask:0xf bank_mask:0xf
	s_nop 1
	v_add_f32_dpp v4, v5, v5 row_mirror row_mask:0xf bank_mask:0xf
	s_nop 1
	v_readlane_b32 s98, v4, 0
	v_readlane_b32 s99, v4, 16
	s_nop 3
	v_mov_b32_e32 v5, s98
	v_add_f32_e32 v5, s99, v5
	v_readlane_b32 s98, v4, 32
	v_readlane_b32 s99, v4, 48
	s_nop 3
	v_add_f32_e32 v5, s98, v5
	v_add_f32_e32 v5, s99, v5
	v_mul_f32_e32 v5, 0x3a800000, v5
	v_add_f32_e32 v5, 0x358637bd, v5
	v_rsq_f32_e32 v6, v5
	s_nop 0
	s_add_u32 s98, s97, 13
	v_pk_mul_f32 v[32:33], v[32:33], v[6:7] op_sel_hi:[1,0]
	v_pk_mul_f32 v[34:35], v[34:35], v[6:7] op_sel_hi:[1,0]
	v_pk_mul_f32 v[36:37], v[36:37], v[6:7] op_sel_hi:[1,0]
	v_pk_mul_f32 v[38:39], v[38:39], v[6:7] op_sel_hi:[1,0]
	v_pk_mul_f32 v[40:41], v[40:41], v[6:7] op_sel_hi:[1,0]
	v_pk_mul_f32 v[42:43], v[42:43], v[6:7] op_sel_hi:[1,0]
	v_pk_mul_f32 v[44:45], v[44:45], v[6:7] op_sel_hi:[1,0]
	v_pk_mul_f32 v[46:47], v[46:47], v[6:7] op_sel_hi:[1,0]
	v_pk_mul_f32 v[32:33], v[32:33], v[112:113]
	v_pk_mul_f32 v[34:35], v[34:35], v[114:115]
	v_pk_mul_f32 v[36:37], v[36:37], v[116:117]
	v_pk_mul_f32 v[38:39], v[38:39], v[118:119]
	v_pk_mul_f32 v[40:41], v[40:41], v[120:121]
	v_pk_mul_f32 v[42:43], v[42:43], v[122:123]
	v_pk_mul_f32 v[44:45], v[44:45], v[124:125]
	v_pk_mul_f32 v[46:47], v[46:47], v[126:127]
	v_pk_fma_f32 v[32:33], v[32:33], v[128:129], v[144:145]
	v_pk_fma_f32 v[34:35], v[34:35], v[130:131], v[146:147]
	v_pk_fma_f32 v[36:37], v[36:37], v[132:133], v[148:149]
	v_pk_fma_f32 v[38:39], v[38:39], v[134:135], v[150:151]
	v_pk_fma_f32 v[40:41], v[40:41], v[136:137], v[152:153]
	v_pk_fma_f32 v[42:43], v[42:43], v[138:139], v[154:155]
	v_pk_fma_f32 v[44:45], v[44:45], v[140:141], v[156:157]
	v_pk_fma_f32 v[46:47], v[46:47], v[142:143], v[158:159]
	v_cvt_pk_bf16_f32 v32, v32, v33
	v_cvt_pk_bf16_f32 v33, v34, v35
	v_cvt_pk_bf16_f32 v34, v36, v37
	v_cvt_pk_bf16_f32 v35, v38, v39
	v_cvt_pk_bf16_f32 v36, v40, v41
	v_cvt_pk_bf16_f32 v37, v42, v43
	v_cvt_pk_bf16_f32 v38, v44, v45
	v_cvt_pk_bf16_f32 v39, v46, v47
	s_lshl_b32 s99, s98, 11
	v_lshl_add_u32 v8, v0, 3, s99
	global_store_dwordx2 v8, v[32:33], s[94:95]
	global_store_dwordx2 v8, v[34:35], s[94:95] offset:512
	global_store_dwordx2 v8, v[36:37], s[94:95] offset:1024
	global_store_dwordx2 v8, v[38:39], s[94:95] offset:1536
	s_lshl_b32 s99, s98, 2
	v_mov_b32_e32 v9, s99
	v_mov_b32_e32 v10, 0
	v_cmp_eq_u32_e32 vcc, 0, v0
	s_and_saveexec_b64 s[98:99], vcc
	global_store_dword v9, v10, s[90:91]
	global_store_dword v9, v10, s[92:93]
	s_or_b64 exec, exec, s[98:99]
	s_waitcnt vmcnt(34)
	v_mul_f32_e32 v4, v48, v48
	v_fma_f32 v4, v49, v49, v4
	v_fma_f32 v4, v50, v50, v4
	v_fma_f32 v4, v51, v51, v4
	v_fma_f32 v4, v52, v52, v4
	v_fma_f32 v4, v53, v53, v4
	v_fma_f32 v4, v54, v54, v4
	v_fma_f32 v4, v55, v55, v4
	v_fma_f32 v4, v56, v56, v4
	v_fma_f32 v4, v57, v57, v4
	v_fma_f32 v4, v58, v58, v4
	v_fma_f32 v4, v59, v59, v4
	v_fma_f32 v4, v60, v60, v4
	v_fma_f32 v4, v61, v61, v4
	v_fma_f32 v4, v62, v62, v4
	v_fma_f32 v4, v63, v63, v4
	s_nop 1
	v_add_f32_dpp v5, v4, v4 quad_perm:[1,0,3,2] row_mask:0xf bank_mask:0xf
	s_nop 1
	v_add_f32_dpp v4, v5, v5 quad_perm:[2,3,0,1] row_mask:0xf bank_mask:0xf
	s_nop 1
	v_add_f32_dpp v5, v4, v4 row_half_mirror row_mask:0xf bank_mask:0xf
	s_nop 1
	v_add_f32_dpp v4, v5, v5 row_mirror row_mask:0xf bank_mask:0xf
	s_nop 1
	v_readlane_b32 s98, v4, 0
	v_readlane_b32 s99, v4, 16
	s_nop 3
	v_mov_b32_e32 v5, s98
	v_add_f32_e32 v5, s99, v5
	v_readlane_b32 s98, v4, 32
	v_readlane_b32 s99, v4, 48
	s_nop 3
	v_add_f32_e32 v5, s98, v5
	v_add_f32_e32 v5, s99, v5
	v_mul_f32_e32 v5, 0x3a800000, v5
	v_add_f32_e32 v5, 0x358637bd, v5
	v_rsq_f32_e32 v6, v5
	s_nop 0
	s_add_u32 s98, s97, 14
	v_pk_mul_f32 v[48:49], v[48:49], v[6:7] op_sel_hi:[1,0]
	v_pk_mul_f32 v[50:51], v[50:51], v[6:7] op_sel_hi:[1,0]
	v_pk_mul_f32 v[52:53], v[52:53], v[6:7] op_sel_hi:[1,0]
	v_pk_mul_f32 v[54:55], v[54:55], v[6:7] op_sel_hi:[1,0]
	v_pk_mul_f32 v[56:57], v[56:57], v[6:7] op_sel_hi:[1,0]
	v_pk_mul_f32 v[58:59], v[58:59], v[6:7] op_sel_hi:[1,0]
	v_pk_mul_f32 v[60:61], v[60:61], v[6:7] op_sel_hi:[1,0]
	v_pk_mul_f32 v[62:63], v[62:63], v[6:7] op_sel_hi:[1,0]
	v_pk_mul_f32 v[48:49], v[48:49], v[112:113]
	v_pk_mul_f32 v[50:51], v[50:51], v[114:115]
	v_pk_mul_f32 v[52:53], v[52:53], v[116:117]
	v_pk_mul_f32 v[54:55], v[54:55], v[118:119]
	v_pk_mul_f32 v[56:57], v[56:57], v[120:121]
	v_pk_mul_f32 v[58:59], v[58:59], v[122:123]
	v_pk_mul_f32 v[60:61], v[60:61], v[124:125]
	v_pk_mul_f32 v[62:63], v[62:63], v[126:127]
	v_pk_fma_f32 v[48:49], v[48:49], v[128:129], v[144:145]
	v_pk_fma_f32 v[50:51], v[50:51], v[130:131], v[146:147]
	v_pk_fma_f32 v[52:53], v[52:53], v[132:133], v[148:149]
	v_pk_fma_f32 v[54:55], v[54:55], v[134:135], v[150:151]
	v_pk_fma_f32 v[56:57], v[56:57], v[136:137], v[152:153]
	v_pk_fma_f32 v[58:59], v[58:59], v[138:139], v[154:155]
	v_pk_fma_f32 v[60:61], v[60:61], v[140:141], v[156:157]
	v_pk_fma_f32 v[62:63], v[62:63], v[142:143], v[158:159]
	v_cvt_pk_bf16_f32 v48, v48, v49
	v_cvt_pk_bf16_f32 v49, v50, v51
	v_cvt_pk_bf16_f32 v50, v52, v53
	v_cvt_pk_bf16_f32 v51, v54, v55
	v_cvt_pk_bf16_f32 v52, v56, v57
	v_cvt_pk_bf16_f32 v53, v58, v59
	v_cvt_pk_bf16_f32 v54, v60, v61
	v_cvt_pk_bf16_f32 v55, v62, v63
	s_lshl_b32 s99, s98, 11
	v_lshl_add_u32 v8, v0, 3, s99
	global_store_dwordx2 v8, v[48:49], s[94:95]
	global_store_dwordx2 v8, v[50:51], s[94:95] offset:512
	global_store_dwordx2 v8, v[52:53], s[94:95] offset:1024
	global_store_dwordx2 v8, v[54:55], s[94:95] offset:1536
	s_lshl_b32 s99, s98, 2
	v_mov_b32_e32 v9, s99
	v_mov_b32_e32 v10, 0
	v_cmp_eq_u32_e32 vcc, 0, v0
	s_and_saveexec_b64 s[98:99], vcc
	global_store_dword v9, v10, s[90:91]
	global_store_dword v9, v10, s[92:93]
	s_or_b64 exec, exec, s[98:99]
	s_waitcnt vmcnt(30)
	v_mul_f32_e32 v4, v64, v64
	v_fma_f32 v4, v65, v65, v4
	v_fma_f32 v4, v66, v66, v4
	v_fma_f32 v4, v67, v67, v4
	v_fma_f32 v4, v68, v68, v4
	v_fma_f32 v4, v69, v69, v4
	v_fma_f32 v4, v70, v70, v4
	v_fma_f32 v4, v71, v71, v4
	v_fma_f32 v4, v72, v72, v4
	v_fma_f32 v4, v73, v73, v4
	v_fma_f32 v4, v74, v74, v4
	v_fma_f32 v4, v75, v75, v4
	v_fma_f32 v4, v76, v76, v4
	v_fma_f32 v4, v77, v77, v4
	v_fma_f32 v4, v78, v78, v4
	v_fma_f32 v4, v79, v79, v4
	s_nop 1
	v_add_f32_dpp v5, v4, v4 quad_perm:[1,0,3,2] row_mask:0xf bank_mask:0xf
	s_nop 1
	v_add_f32_dpp v4, v5, v5 quad_perm:[2,3,0,1] row_mask:0xf bank_mask:0xf
	s_nop 1
	v_add_f32_dpp v5, v4, v4 row_half_mirror row_mask:0xf bank_mask:0xf
	s_nop 1
	v_add_f32_dpp v4, v5, v5 row_mirror row_mask:0xf bank_mask:0xf
	s_nop 1
	v_readlane_b32 s98, v4, 0
	v_readlane_b32 s99, v4, 16
	s_nop 3
	v_mov_b32_e32 v5, s98
	v_add_f32_e32 v5, s99, v5
	v_readlane_b32 s98, v4, 32
	v_readlane_b32 s99, v4, 48
	s_nop 3
	v_add_f32_e32 v5, s98, v5
	v_add_f32_e32 v5, s99, v5
	v_mul_f32_e32 v5, 0x3a800000, v5
	v_add_f32_e32 v5, 0x358637bd, v5
	v_rsq_f32_e32 v6, v5
	s_nop 0
	s_add_u32 s98, s97, 15
	v_pk_mul_f32 v[64:65], v[64:65], v[6:7] op_sel_hi:[1,0]
	v_pk_mul_f32 v[66:67], v[66:67], v[6:7] op_sel_hi:[1,0]
	v_pk_mul_f32 v[68:69], v[68:69], v[6:7] op_sel_hi:[1,0]
	v_pk_mul_f32 v[70:71], v[70:71], v[6:7] op_sel_hi:[1,0]
	v_pk_mul_f32 v[72:73], v[72:73], v[6:7] op_sel_hi:[1,0]
	v_pk_mul_f32 v[74:75], v[74:75], v[6:7] op_sel_hi:[1,0]
	v_pk_mul_f32 v[76:77], v[76:77], v[6:7] op_sel_hi:[1,0]
	v_pk_mul_f32 v[78:79], v[78:79], v[6:7] op_sel_hi:[1,0]
	v_pk_mul_f32 v[64:65], v[64:65], v[112:113]
	v_pk_mul_f32 v[66:67], v[66:67], v[114:115]
	v_pk_mul_f32 v[68:69], v[68:69], v[116:117]
	v_pk_mul_f32 v[70:71], v[70:71], v[118:119]
	v_pk_mul_f32 v[72:73], v[72:73], v[120:121]
	v_pk_mul_f32 v[74:75], v[74:75], v[122:123]
	v_pk_mul_f32 v[76:77], v[76:77], v[124:125]
	v_pk_mul_f32 v[78:79], v[78:79], v[126:127]
	v_pk_fma_f32 v[64:65], v[64:65], v[128:129], v[144:145]
	v_pk_fma_f32 v[66:67], v[66:67], v[130:131], v[146:147]
	v_pk_fma_f32 v[68:69], v[68:69], v[132:133], v[148:149]
	v_pk_fma_f32 v[70:71], v[70:71], v[134:135], v[150:151]
	v_pk_fma_f32 v[72:73], v[72:73], v[136:137], v[152:153]
	v_pk_fma_f32 v[74:75], v[74:75], v[138:139], v[154:155]
	v_pk_fma_f32 v[76:77], v[76:77], v[140:141], v[156:157]
	v_pk_fma_f32 v[78:79], v[78:79], v[142:143], v[158:159]
	v_cvt_pk_bf16_f32 v64, v64, v65
	v_cvt_pk_bf16_f32 v65, v66, v67
	v_cvt_pk_bf16_f32 v66, v68, v69
	v_cvt_pk_bf16_f32 v67, v70, v71
	v_cvt_pk_bf16_f32 v68, v72, v73
	v_cvt_pk_bf16_f32 v69, v74, v75
	v_cvt_pk_bf16_f32 v70, v76, v77
	v_cvt_pk_bf16_f32 v71, v78, v79
	s_lshl_b32 s99, s98, 11
	v_lshl_add_u32 v8, v0, 3, s99
	global_store_dwordx2 v8, v[64:65], s[94:95]
	global_store_dwordx2 v8, v[66:67], s[94:95] offset:512
	global_store_dwordx2 v8, v[68:69], s[94:95] offset:1024
	global_store_dwordx2 v8, v[70:71], s[94:95] offset:1536
	s_lshl_b32 s99, s98, 2
	v_mov_b32_e32 v9, s99
	v_mov_b32_e32 v10, 0
	v_cmp_eq_u32_e32 vcc, 0, v0
	s_and_saveexec_b64 s[98:99], vcc
	global_store_dword v9, v10, s[90:91]
	global_store_dword v9, v10, s[92:93]
	s_or_b64 exec, exec, s[98:99]
	s_waitcnt vmcnt(0)

.LBB0_2341:
	s_cmp_gt_i32 s44, 10
	s_waitcnt lgkmcnt(0)
	s_cselect_b64 s[2:3], -1, 0
	s_cmp_lt_i32 s45, 11
	s_cselect_b64 s[4:5], -1, 0
	s_or_b64 s[2:3], s[2:3], s[4:5]
	s_and_b64 vcc, exec, s[2:3]
	s_cbranch_vccnz .LBB0_2401
	s_lshl_b32 s96, s22, 3
	s_lshr_b32 s97, s70, 6
	s_add_u32 s96, s96, s97
	s_lshl_b32 s97, s96, 4
	s_cmpk_ge_u32 s97, 0x8000
	s_cbranch_scc1 .Lnp10_done
	s_load_dwordx2 s[88:89], s[0:1], 0xb8
	s_load_dwordx2 s[90:91], s[0:1], 0x18
	s_load_dwordx2 s[92:93], s[0:1], 0x140
	s_load_dwordx2 s[94:95], s[0:1], 0x158
	v_mbcnt_hi_u32_b32 v0, -1, v210
	v_lshlrev_b32_e32 v1, 4, v0
	s_waitcnt lgkmcnt(0)
	s_add_u32 s90, s90, 8192
	s_addc_u32 s91, s91, 0
	global_load_dwordx4 v[112:115], v1, s[90:91] nt
	global_load_dwordx4 v[116:119], v1, s[90:91] offset:1024 nt
	global_load_dwordx4 v[120:123], v1, s[90:91] offset:2048 nt
	global_load_dwordx4 v[124:127], v1, s[90:91] offset:3072 nt
	s_lshr_b32 s98, s97, 12
	s_add_u32 s98, s98, 16
	s_mul_i32 s98, s98, 0x3000
	s_add_u32 s92, s92, s98
	s_addc_u32 s93, s93, 0
	global_load_dwordx4 v[144:147], v1, s[92:93] nt
	global_load_dwordx4 v[148:151], v1, s[92:93] offset:1024 nt
	global_load_dwordx4 v[152:155], v1, s[92:93] offset:2048 nt
	global_load_dwordx4 v[156:159], v1, s[92:93] offset:3072 nt
	s_add_u32 s92, s92, 0x1000
	s_addc_u32 s93, s93, 0
	global_load_dwordx4 v[128:131], v1, s[92:93] nt
	global_load_dwordx4 v[132:135], v1, s[92:93] offset:1024 nt
	global_load_dwordx4 v[136:139], v1, s[92:93] offset:2048 nt
	global_load_dwordx4 v[140:143], v1, s[92:93] offset:3072 nt
	s_load_dwordx2 s[90:91], s[0:1], 0x210
	s_load_dwordx2 s[92:93], s[0:1], 0x218
	s_waitcnt vmcnt(0) lgkmcnt(0)
	v_pk_add_f32 v[128:129], v[128:129], 1.0 op_sel_hi:[1,0]
	v_pk_add_f32 v[130:131], v[130:131], 1.0 op_sel_hi:[1,0]
	v_pk_add_f32 v[132:133], v[132:133], 1.0 op_sel_hi:[1,0]
	v_pk_add_f32 v[134:135], v[134:135], 1.0 op_sel_hi:[1,0]
	v_pk_add_f32 v[136:137], v[136:137], 1.0 op_sel_hi:[1,0]
	v_pk_add_f32 v[138:139], v[138:139], 1.0 op_sel_hi:[1,0]
	v_pk_add_f32 v[140:141], v[140:141], 1.0 op_sel_hi:[1,0]
	v_pk_add_f32 v[142:143], v[142:143], 1.0 op_sel_hi:[1,0]
	s_add_u32 s98, s97, 0
	s_lshl_b32 s98, s98, 12
	v_add_u32_e32 v3, s98, v1
	global_load_dwordx4 v[16:19], v3, s[88:89] nt
	global_load_dwordx4 v[20:23], v3, s[88:89] offset:1024 nt
	global_load_dwordx4 v[24:27], v3, s[88:89] offset:2048 nt
	global_load_dwordx4 v[28:31], v3, s[88:89] offset:3072 nt
	s_add_u32 s98, s97, 1
	s_lshl_b32 s98, s98, 12
	v_add_u32_e32 v3, s98, v1
	global_load_dwordx4 v[32:35], v3, s[88:89] nt
	global_load_dwordx4 v[36:39], v3, s[88:89] offset:1024 nt
	global_load_dwordx4 v[40:43], v3, s[88:89] offset:2048 nt
	global_load_dwordx4 v[44:47], v3, s[88:89] offset:3072 nt
	s_add_u32 s98, s97, 2
	s_lshl_b32 s98, s98, 12
	v_add_u32_e32 v3, s98, v1
	global_load_dwordx4 v[48:51], v3, s[88:89] nt
	global_load_dwordx4 v[52:55], v3, s[88:89] offset:1024 nt
	global_load_dwordx4 v[56:59], v3, s[88:89] offset:2048 nt
	global_load_dwordx4 v[60:63], v3, s[88:89] offset:3072 nt
	s_add_u32 s98, s97, 3
	s_lshl_b32 s98, s98, 12
	v_add_u32_e32 v3, s98, v1
	global_load_dwordx4 v[64:67], v3, s[88:89] nt
	global_load_dwordx4 v[68:71], v3, s[88:89] offset:1024 nt
	global_load_dwordx4 v[72:75], v3, s[88:89] offset:2048 nt
	global_load_dwordx4 v[76:79], v3, s[88:89] offset:3072 nt
	s_add_u32 s98, s97, 4
	s_lshl_b32 s98, s98, 12
	v_add_u32_e32 v3, s98, v1
	global_load_dwordx4 v[80:83], v3, s[88:89] nt
	global_load_dwordx4 v[84:87], v3, s[88:89] offset:1024 nt
	global_load_dwordx4 v[88:91], v3, s[88:89] offset:2048 nt
	global_load_dwordx4 v[92:95], v3, s[88:89] offset:3072 nt
	s_add_u32 s98, s97, 5
	s_lshl_b32 s98, s98, 12
	v_add_u32_e32 v3, s98, v1
	global_load_dwordx4 v[96:99], v3, s[88:89] nt
	global_load_dwordx4 v[100:103], v3, s[88:89] offset:1024 nt
	global_load_dwordx4 v[104:107], v3, s[88:89] offset:2048 nt
	global_load_dwordx4 v[108:111], v3, s[88:89] offset:3072 nt
	s_waitcnt vmcnt(20)
	v_mul_f32_e32 v4, v16, v16
	v_fma_f32 v4, v17, v17, v4
	v_fma_f32 v4, v18, v18, v4
	v_fma_f32 v4, v19, v19, v4
	v_fma_f32 v4, v20, v20, v4
	v_fma_f32 v4, v21, v21, v4
	v_fma_f32 v4, v22, v22, v4
	v_fma_f32 v4, v23, v23, v4
	v_fma_f32 v4, v24, v24, v4
	v_fma_f32 v4, v25, v25, v4
	v_fma_f32 v4, v26, v26, v4
	v_fma_f32 v4, v27, v27, v4
	v_fma_f32 v4, v28, v28, v4
	v_fma_f32 v4, v29, v29, v4
	v_fma_f32 v4, v30, v30, v4
	v_fma_f32 v4, v31, v31, v4
	s_nop 1
	v_add_f32_dpp v5, v4, v4 quad_perm:[1,0,3,2] row_mask:0xf bank_mask:0xf
	s_nop 1
	v_add_f32_dpp v4, v5, v5 quad_perm:[2,3,0,1] row_mask:0xf bank_mask:0xf
	s_nop 1
	v_add_f32_dpp v5, v4, v4 row_half_mirror row_mask:0xf bank_mask:0xf
	s_nop 1
	v_add_f32_dpp v4, v5, v5 row_mirror row_mask:0xf bank_mask:0xf
	s_nop 1
	v_readlane_b32 s98, v4, 0
	v_readlane_b32 s99, v4, 16
	s_nop 3
	v_mov_b32_e32 v5, s98
	v_add_f32_e32 v5, s99, v5
	v_readlane_b32 s98, v4, 32
	v_readlane_b32 s99, v4, 48
	s_nop 3
	v_add_f32_e32 v5, s98, v5
	v_add_f32_e32 v5, s99, v5
	v_mul_f32_e32 v5, 0x3a800000, v5
	v_add_f32_e32 v5, 0x358637bd, v5
	v_rsq_f32_e32 v6, v5
	s_nop 0
	s_add_u32 s98, s97, 0
	v_pk_mul_f32 v[16:17], v[16:17], v[6:7] op_sel_hi:[1,0]
	v_pk_mul_f32 v[18:19], v[18:19], v[6:7] op_sel_hi:[1,0]
	v_pk_mul_f32 v[20:21], v[20:21], v[6:7] op_sel_hi:[1,0]
	v_pk_mul_f32 v[22:23], v[22:23], v[6:7] op_sel_hi:[1,0]
	v_pk_mul_f32 v[24:25], v[24:25], v[6:7] op_sel_hi:[1,0]
	v_pk_mul_f32 v[26:27], v[26:27], v[6:7] op_sel_hi:[1,0]
	v_pk_mul_f32 v[28:29], v[28:29], v[6:7] op_sel_hi:[1,0]
	v_pk_mul_f32 v[30:31], v[30:31], v[6:7] op_sel_hi:[1,0]
	v_pk_mul_f32 v[16:17], v[16:17], v[112:113]
	v_pk_mul_f32 v[18:19], v[18:19], v[114:115]
	v_pk_mul_f32 v[20:21], v[20:21], v[116:117]
	v_pk_mul_f32 v[22:23], v[22:23], v[118:119]
	v_pk_mul_f32 v[24:25], v[24:25], v[120:121]
	v_pk_mul_f32 v[26:27], v[26:27], v[122:123]
	v_pk_mul_f32 v[28:29], v[28:29], v[124:125]
	v_pk_mul_f32 v[30:31], v[30:31], v[126:127]
	v_pk_fma_f32 v[16:17], v[16:17], v[128:129], v[144:145]
	v_pk_fma_f32 v[18:19], v[18:19], v[130:131], v[146:147]
	v_pk_fma_f32 v[20:21], v[20:21], v[132:133], v[148:149]
	v_pk_fma_f32 v[22:23], v[22:23], v[134:135], v[150:151]
	v_pk_fma_f32 v[24:25], v[24:25], v[136:137], v[152:153]
	v_pk_fma_f32 v[26:27], v[26:27], v[138:139], v[154:155]
	v_pk_fma_f32 v[28:29], v[28:29], v[140:141], v[156:157]
	v_pk_fma_f32 v[30:31], v[30:31], v[142:143], v[158:159]
	v_cvt_pk_bf16_f32 v16, v16, v17
	v_cvt_pk_bf16_f32 v17, v18, v19
	v_cvt_pk_bf16_f32 v18, v20, v21
	v_cvt_pk_bf16_f32 v19, v22, v23
	v_cvt_pk_bf16_f32 v20, v24, v25
	v_cvt_pk_bf16_f32 v21, v26, v27
	v_cvt_pk_bf16_f32 v22, v28, v29
	v_cvt_pk_bf16_f32 v23, v30, v31
	s_lshl_b32 s99, s98, 11
	v_lshl_add_u32 v8, v0, 3, s99
	global_store_dwordx2 v8, v[16:17], s[94:95]
	global_store_dwordx2 v8, v[18:19], s[94:95] offset:512
	global_store_dwordx2 v8, v[20:21], s[94:95] offset:1024
	global_store_dwordx2 v8, v[22:23], s[94:95] offset:1536
	s_lshl_b32 s99, s98, 2
	v_mov_b32_e32 v9, s99
	v_mov_b32_e32 v10, 0
	v_cmp_eq_u32_e32 vcc, 0, v0
	s_and_saveexec_b64 s[98:99], vcc
	global_store_dword v9, v10, s[90:91]
	global_store_dword v9, v10, s[92:93]
	s_or_b64 exec, exec, s[98:99]
	s_add_u32 s98, s97, 6
	s_lshl_b32 s98, s98, 12
	v_add_u32_e32 v3, s98, v1
	global_load_dwordx4 v[16:19], v3, s[88:89] nt
	global_load_dwordx4 v[20:23], v3, s[88:89] offset:1024 nt
	global_load_dwordx4 v[24:27], v3, s[88:89] offset:2048 nt
	global_load_dwordx4 v[28:31], v3, s[88:89] offset:3072 nt
	s_waitcnt vmcnt(26)
	v_mul_f32_e32 v4, v32, v32
	v_fma_f32 v4, v33, v33, v4
	v_fma_f32 v4, v34, v34, v4
	v_fma_f32 v4, v35, v35, v4
	v_fma_f32 v4, v36, v36, v4
	v_fma_f32 v4, v37, v37, v4
	v_fma_f32 v4, v38, v38, v4
	v_fma_f32 v4, v39, v39, v4
	v_fma_f32 v4, v40, v40, v4
	v_fma_f32 v4, v41, v41, v4
	v_fma_f32 v4, v42, v42, v4
	v_fma_f32 v4, v43, v43, v4
	v_fma_f32 v4, v44, v44, v4
	v_fma_f32 v4, v45, v45, v4
	v_fma_f32 v4, v46, v46, v4
	v_fma_f32 v4, v47, v47, v4
	s_nop 1
	v_add_f32_dpp v5, v4, v4 quad_perm:[1,0,3,2] row_mask:0xf bank_mask:0xf
	s_nop 1
	v_add_f32_dpp v4, v5, v5 quad_perm:[2,3,0,1] row_mask:0xf bank_mask:0xf
	s_nop 1
	v_add_f32_dpp v5, v4, v4 row_half_mirror row_mask:0xf bank_mask:0xf
	s_nop 1
	v_add_f32_dpp v4, v5, v5 row_mirror row_mask:0xf bank_mask:0xf
	s_nop 1
	v_readlane_b32 s98, v4, 0
	v_readlane_b32 s99, v4, 16
	s_nop 3
	v_mov_b32_e32 v5, s98
	v_add_f32_e32 v5, s99, v5
	v_readlane_b32 s98, v4, 32
	v_readlane_b32 s99, v4, 48
	s_nop 3
	v_add_f32_e32 v5, s98, v5
	v_add_f32_e32 v5, s99, v5
	v_mul_f32_e32 v5, 0x3a800000, v5
	v_add_f32_e32 v5, 0x358637bd, v5
	v_rsq_f32_e32 v6, v5
	s_nop 0
	s_add_u32 s98, s97, 1
	v_pk_mul_f32 v[32:33], v[32:33], v[6:7] op_sel_hi:[1,0]
	v_pk_mul_f32 v[34:35], v[34:35], v[6:7] op_sel_hi:[1,0]
	v_pk_mul_f32 v[36:37], v[36:37], v[6:7] op_sel_hi:[1,0]
	v_pk_mul_f32 v[38:39], v[38:39], v[6:7] op_sel_hi:[1,0]
	v_pk_mul_f32 v[40:41], v[40:41], v[6:7] op_sel_hi:[1,0]
	v_pk_mul_f32 v[42:43], v[42:43], v[6:7] op_sel_hi:[1,0]
	v_pk_mul_f32 v[44:45], v[44:45], v[6:7] op_sel_hi:[1,0]
	v_pk_mul_f32 v[46:47], v[46:47], v[6:7] op_sel_hi:[1,0]
	v_pk_mul_f32 v[32:33], v[32:33], v[112:113]
	v_pk_mul_f32 v[34:35], v[34:35], v[114:115]
	v_pk_mul_f32 v[36:37], v[36:37], v[116:117]
	v_pk_mul_f32 v[38:39], v[38:39], v[118:119]
	v_pk_mul_f32 v[40:41], v[40:41], v[120:121]
	v_pk_mul_f32 v[42:43], v[42:43], v[122:123]
	v_pk_mul_f32 v[44:45], v[44:45], v[124:125]
	v_pk_mul_f32 v[46:47], v[46:47], v[126:127]
	v_pk_fma_f32 v[32:33], v[32:33], v[128:129], v[144:145]
	v_pk_fma_f32 v[34:35], v[34:35], v[130:131], v[146:147]
	v_pk_fma_f32 v[36:37], v[36:37], v[132:133], v[148:149]
	v_pk_fma_f32 v[38:39], v[38:39], v[134:135], v[150:151]
	v_pk_fma_f32 v[40:41], v[40:41], v[136:137], v[152:153]
	v_pk_fma_f32 v[42:43], v[42:43], v[138:139], v[154:155]
	v_pk_fma_f32 v[44:45], v[44:45], v[140:141], v[156:157]
	v_pk_fma_f32 v[46:47], v[46:47], v[142:143], v[158:159]
	v_cvt_pk_bf16_f32 v32, v32, v33
	v_cvt_pk_bf16_f32 v33, v34, v35
	v_cvt_pk_bf16_f32 v34, v36, v37
	v_cvt_pk_bf16_f32 v35, v38, v39
	v_cvt_pk_bf16_f32 v36, v40, v41
	v_cvt_pk_bf16_f32 v37, v42, v43
	v_cvt_pk_bf16_f32 v38, v44, v45
	v_cvt_pk_bf16_f32 v39, v46, v47
	s_lshl_b32 s99, s98, 11
	v_lshl_add_u32 v8, v0, 3, s99
	global_store_dwordx2 v8, v[32:33], s[94:95]
	global_store_dwordx2 v8, v[34:35], s[94:95] offset:512
	global_store_dwordx2 v8, v[36:37], s[94:95] offset:1024
	global_store_dwordx2 v8, v[38:39], s[94:95] offset:1536
	s_lshl_b32 s99, s98, 2
	v_mov_b32_e32 v9, s99
	v_mov_b32_e32 v10, 0
	v_cmp_eq_u32_e32 vcc, 0, v0
	s_and_saveexec_b64 s[98:99], vcc
	global_store_dword v9, v10, s[90:91]
	global_store_dword v9, v10, s[92:93]
	s_or_b64 exec, exec, s[98:99]
	s_add_u32 s98, s97, 7
	s_lshl_b32 s98, s98, 12
	v_add_u32_e32 v3, s98, v1
	global_load_dwordx4 v[32:35], v3, s[88:89] nt
	global_load_dwordx4 v[36:39], v3, s[88:89] offset:1024 nt
	global_load_dwordx4 v[40:43], v3, s[88:89] offset:2048 nt
	global_load_dwordx4 v[44:47], v3, s[88:89] offset:3072 nt
	s_waitcnt vmcnt(32)
	v_mul_f32_e32 v4, v48, v48
	v_fma_f32 v4, v49, v49, v4
	v_fma_f32 v4, v50, v50, v4
	v_fma_f32 v4, v51, v51, v4
	v_fma_f32 v4, v52, v52, v4
	v_fma_f32 v4, v53, v53, v4
	v_fma_f32 v4, v54, v54, v4
	v_fma_f32 v4, v55, v55, v4
	v_fma_f32 v4, v56, v56, v4
	v_fma_f32 v4, v57, v57, v4
	v_fma_f32 v4, v58, v58, v4
	v_fma_f32 v4, v59, v59, v4
	v_fma_f32 v4, v60, v60, v4
	v_fma_f32 v4, v61, v61, v4
	v_fma_f32 v4, v62, v62, v4
	v_fma_f32 v4, v63, v63, v4
	s_nop 1
	v_add_f32_dpp v5, v4, v4 quad_perm:[1,0,3,2] row_mask:0xf bank_mask:0xf
	s_nop 1
	v_add_f32_dpp v4, v5, v5 quad_perm:[2,3,0,1] row_mask:0xf bank_mask:0xf
	s_nop 1
	v_add_f32_dpp v5, v4, v4 row_half_mirror row_mask:0xf bank_mask:0xf
	s_nop 1
	v_add_f32_dpp v4, v5, v5 row_mirror row_mask:0xf bank_mask:0xf
	s_nop 1
	v_readlane_b32 s98, v4, 0
	v_readlane_b32 s99, v4, 16
	s_nop 3
	v_mov_b32_e32 v5, s98
	v_add_f32_e32 v5, s99, v5
	v_readlane_b32 s98, v4, 32
	v_readlane_b32 s99, v4, 48
	s_nop 3
	v_add_f32_e32 v5, s98, v5
	v_add_f32_e32 v5, s99, v5
	v_mul_f32_e32 v5, 0x3a800000, v5
	v_add_f32_e32 v5, 0x358637bd, v5
	v_rsq_f32_e32 v6, v5
	s_nop 0
	s_add_u32 s98, s97, 2
	v_pk_mul_f32 v[48:49], v[48:49], v[6:7] op_sel_hi:[1,0]
	v_pk_mul_f32 v[50:51], v[50:51], v[6:7] op_sel_hi:[1,0]
	v_pk_mul_f32 v[52:53], v[52:53], v[6:7] op_sel_hi:[1,0]
	v_pk_mul_f32 v[54:55], v[54:55], v[6:7] op_sel_hi:[1,0]
	v_pk_mul_f32 v[56:57], v[56:57], v[6:7] op_sel_hi:[1,0]
	v_pk_mul_f32 v[58:59], v[58:59], v[6:7] op_sel_hi:[1,0]
	v_pk_mul_f32 v[60:61], v[60:61], v[6:7] op_sel_hi:[1,0]
	v_pk_mul_f32 v[62:63], v[62:63], v[6:7] op_sel_hi:[1,0]
	v_pk_mul_f32 v[48:49], v[48:49], v[112:113]
	v_pk_mul_f32 v[50:51], v[50:51], v[114:115]
	v_pk_mul_f32 v[52:53], v[52:53], v[116:117]
	v_pk_mul_f32 v[54:55], v[54:55], v[118:119]
	v_pk_mul_f32 v[56:57], v[56:57], v[120:121]
	v_pk_mul_f32 v[58:59], v[58:59], v[122:123]
	v_pk_mul_f32 v[60:61], v[60:61], v[124:125]
	v_pk_mul_f32 v[62:63], v[62:63], v[126:127]
	v_pk_fma_f32 v[48:49], v[48:49], v[128:129], v[144:145]
	v_pk_fma_f32 v[50:51], v[50:51], v[130:131], v[146:147]
	v_pk_fma_f32 v[52:53], v[52:53], v[132:133], v[148:149]
	v_pk_fma_f32 v[54:55], v[54:55], v[134:135], v[150:151]
	v_pk_fma_f32 v[56:57], v[56:57], v[136:137], v[152:153]
	v_pk_fma_f32 v[58:59], v[58:59], v[138:139], v[154:155]
	v_pk_fma_f32 v[60:61], v[60:61], v[140:141], v[156:157]
	v_pk_fma_f32 v[62:63], v[62:63], v[142:143], v[158:159]
	v_cvt_pk_bf16_f32 v48, v48, v49
	v_cvt_pk_bf16_f32 v49, v50, v51
	v_cvt_pk_bf16_f32 v50, v52, v53
	v_cvt_pk_bf16_f32 v51, v54, v55
	v_cvt_pk_bf16_f32 v52, v56, v57
	v_cvt_pk_bf16_f32 v53, v58, v59
	v_cvt_pk_bf16_f32 v54, v60, v61
	v_cvt_pk_bf16_f32 v55, v62, v63
	s_lshl_b32 s99, s98, 11
	v_lshl_add_u32 v8, v0, 3, s99
	global_store_dwordx2 v8, v[48:49], s[94:95]
	global_store_dwordx2 v8, v[50:51], s[94:95] offset:512
	global_store_dwordx2 v8, v[52:53], s[94:95] offset:1024
	global_store_dwordx2 v8, v[54:55], s[94:95] offset:1536
	s_lshl_b32 s99, s98, 2
	v_mov_b32_e32 v9, s99
	v_mov_b32_e32 v10, 0
	v_cmp_eq_u32_e32 vcc, 0, v0
	s_and_saveexec_b64 s[98:99], vcc
	global_store_dword v9, v10, s[90:91]
	global_store_dword v9, v10, s[92:93]
	s_or_b64 exec, exec, s[98:99]
	s_add_u32 s98, s97, 8
	s_lshl_b32 s98, s98, 12
	v_add_u32_e32 v3, s98, v1
	global_load_dwordx4 v[48:51], v3, s[88:89] nt
	global_load_dwordx4 v[52:55], v3, s[88:89] offset:1024 nt
	global_load_dwordx4 v[56:59], v3, s[88:89] offset:2048 nt
	global_load_dwordx4 v[60:63], v3, s[88:89] offset:3072 nt
	s_waitcnt vmcnt(38)
	v_mul_f32_e32 v4, v64, v64
	v_fma_f32 v4, v65, v65, v4
	v_fma_f32 v4, v66, v66, v4
	v_fma_f32 v4, v67, v67, v4
	v_fma_f32 v4, v68, v68, v4
	v_fma_f32 v4, v69, v69, v4
	v_fma_f32 v4, v70, v70, v4
	v_fma_f32 v4, v71, v71, v4
	v_fma_f32 v4, v72, v72, v4
	v_fma_f32 v4, v73, v73, v4
	v_fma_f32 v4, v74, v74, v4
	v_fma_f32 v4, v75, v75, v4
	v_fma_f32 v4, v76, v76, v4
	v_fma_f32 v4, v77, v77, v4
	v_fma_f32 v4, v78, v78, v4
	v_fma_f32 v4, v79, v79, v4
	s_nop 1
	v_add_f32_dpp v5, v4, v4 quad_perm:[1,0,3,2] row_mask:0xf bank_mask:0xf
	s_nop 1
	v_add_f32_dpp v4, v5, v5 quad_perm:[2,3,0,1] row_mask:0xf bank_mask:0xf
	s_nop 1
	v_add_f32_dpp v5, v4, v4 row_half_mirror row_mask:0xf bank_mask:0xf
	s_nop 1
	v_add_f32_dpp v4, v5, v5 row_mirror row_mask:0xf bank_mask:0xf
	s_nop 1
	v_readlane_b32 s98, v4, 0
	v_readlane_b32 s99, v4, 16
	s_nop 3
	v_mov_b32_e32 v5, s98
	v_add_f32_e32 v5, s99, v5
	v_readlane_b32 s98, v4, 32
	v_readlane_b32 s99, v4, 48
	s_nop 3
	v_add_f32_e32 v5, s98, v5
	v_add_f32_e32 v5, s99, v5
	v_mul_f32_e32 v5, 0x3a800000, v5
	v_add_f32_e32 v5, 0x358637bd, v5
	v_rsq_f32_e32 v6, v5
	s_nop 0
	s_add_u32 s98, s97, 3
	v_pk_mul_f32 v[64:65], v[64:65], v[6:7] op_sel_hi:[1,0]
	v_pk_mul_f32 v[66:67], v[66:67], v[6:7] op_sel_hi:[1,0]
	v_pk_mul_f32 v[68:69], v[68:69], v[6:7] op_sel_hi:[1,0]
	v_pk_mul_f32 v[70:71], v[70:71], v[6:7] op_sel_hi:[1,0]
	v_pk_mul_f32 v[72:73], v[72:73], v[6:7] op_sel_hi:[1,0]
	v_pk_mul_f32 v[74:75], v[74:75], v[6:7] op_sel_hi:[1,0]
	v_pk_mul_f32 v[76:77], v[76:77], v[6:7] op_sel_hi:[1,0]
	v_pk_mul_f32 v[78:79], v[78:79], v[6:7] op_sel_hi:[1,0]
	v_pk_mul_f32 v[64:65], v[64:65], v[112:113]
	v_pk_mul_f32 v[66:67], v[66:67], v[114:115]
	v_pk_mul_f32 v[68:69], v[68:69], v[116:117]
	v_pk_mul_f32 v[70:71], v[70:71], v[118:119]
	v_pk_mul_f32 v[72:73], v[72:73], v[120:121]
	v_pk_mul_f32 v[74:75], v[74:75], v[122:123]
	v_pk_mul_f32 v[76:77], v[76:77], v[124:125]
	v_pk_mul_f32 v[78:79], v[78:79], v[126:127]
	v_pk_fma_f32 v[64:65], v[64:65], v[128:129], v[144:145]
	v_pk_fma_f32 v[66:67], v[66:67], v[130:131], v[146:147]
	v_pk_fma_f32 v[68:69], v[68:69], v[132:133], v[148:149]
	v_pk_fma_f32 v[70:71], v[70:71], v[134:135], v[150:151]
	v_pk_fma_f32 v[72:73], v[72:73], v[136:137], v[152:153]
	v_pk_fma_f32 v[74:75], v[74:75], v[138:139], v[154:155]
	v_pk_fma_f32 v[76:77], v[76:77], v[140:141], v[156:157]
	v_pk_fma_f32 v[78:79], v[78:79], v[142:143], v[158:159]
	v_cvt_pk_bf16_f32 v64, v64, v65
	v_cvt_pk_bf16_f32 v65, v66, v67
	v_cvt_pk_bf16_f32 v66, v68, v69
	v_cvt_pk_bf16_f32 v67, v70, v71
	v_cvt_pk_bf16_f32 v68, v72, v73
	v_cvt_pk_bf16_f32 v69, v74, v75
	v_cvt_pk_bf16_f32 v70, v76, v77
	v_cvt_pk_bf16_f32 v71, v78, v79
	s_lshl_b32 s99, s98, 11
	v_lshl_add_u32 v8, v0, 3, s99
	global_store_dwordx2 v8, v[64:65], s[94:95]
	global_store_dwordx2 v8, v[66:67], s[94:95] offset:512
	global_store_dwordx2 v8, v[68:69], s[94:95] offset:1024
	global_store_dwordx2 v8, v[70:71], s[94:95] offset:1536
	s_lshl_b32 s99, s98, 2
	v_mov_b32_e32 v9, s99
	v_mov_b32_e32 v10, 0
	v_cmp_eq_u32_e32 vcc, 0, v0
	s_and_saveexec_b64 s[98:99], vcc
	global_store_dword v9, v10, s[90:91]
	global_store_dword v9, v10, s[92:93]
	s_or_b64 exec, exec, s[98:99]
	s_add_u32 s98, s97, 9
	s_lshl_b32 s98, s98, 12
	v_add_u32_e32 v3, s98, v1
	global_load_dwordx4 v[64:67], v3, s[88:89] nt
	global_load_dwordx4 v[68:71], v3, s[88:89] offset:1024 nt
	global_load_dwordx4 v[72:75], v3, s[88:89] offset:2048 nt
	global_load_dwordx4 v[76:79], v3, s[88:89] offset:3072 nt
	s_waitcnt vmcnt(44)
	v_mul_f32_e32 v4, v80, v80
	v_fma_f32 v4, v81, v81, v4
	v_fma_f32 v4, v82, v82, v4
	v_fma_f32 v4, v83, v83, v4
	v_fma_f32 v4, v84, v84, v4
	v_fma_f32 v4, v85, v85, v4
	v_fma_f32 v4, v86, v86, v4
	v_fma_f32 v4, v87, v87, v4
	v_fma_f32 v4, v88, v88, v4
	v_fma_f32 v4, v89, v89, v4
	v_fma_f32 v4, v90, v90, v4
	v_fma_f32 v4, v91, v91, v4
	v_fma_f32 v4, v92, v92, v4
	v_fma_f32 v4, v93, v93, v4
	v_fma_f32 v4, v94, v94, v4
	v_fma_f32 v4, v95, v95, v4
	s_nop 1
	v_add_f32_dpp v5, v4, v4 quad_perm:[1,0,3,2] row_mask:0xf bank_mask:0xf
	s_nop 1
	v_add_f32_dpp v4, v5, v5 quad_perm:[2,3,0,1] row_mask:0xf bank_mask:0xf
	s_nop 1
	v_add_f32_dpp v5, v4, v4 row_half_mirror row_mask:0xf bank_mask:0xf
	s_nop 1
	v_add_f32_dpp v4, v5, v5 row_mirror row_mask:0xf bank_mask:0xf
	s_nop 1
	v_readlane_b32 s98, v4, 0
	v_readlane_b32 s99, v4, 16
	s_nop 3
	v_mov_b32_e32 v5, s98
	v_add_f32_e32 v5, s99, v5
	v_readlane_b32 s98, v4, 32
	v_readlane_b32 s99, v4, 48
	s_nop 3
	v_add_f32_e32 v5, s98, v5
	v_add_f32_e32 v5, s99, v5
	v_mul_f32_e32 v5, 0x3a800000, v5
	v_add_f32_e32 v5, 0x358637bd, v5
	v_rsq_f32_e32 v6, v5
	s_nop 0
	s_add_u32 s98, s97, 4
	v_pk_mul_f32 v[80:81], v[80:81], v[6:7] op_sel_hi:[1,0]
	v_pk_mul_f32 v[82:83], v[82:83], v[6:7] op_sel_hi:[1,0]
	v_pk_mul_f32 v[84:85], v[84:85], v[6:7] op_sel_hi:[1,0]
	v_pk_mul_f32 v[86:87], v[86:87], v[6:7] op_sel_hi:[1,0]
	v_pk_mul_f32 v[88:89], v[88:89], v[6:7] op_sel_hi:[1,0]
	v_pk_mul_f32 v[90:91], v[90:91], v[6:7] op_sel_hi:[1,0]
	v_pk_mul_f32 v[92:93], v[92:93], v[6:7] op_sel_hi:[1,0]
	v_pk_mul_f32 v[94:95], v[94:95], v[6:7] op_sel_hi:[1,0]
	v_pk_mul_f32 v[80:81], v[80:81], v[112:113]
	v_pk_mul_f32 v[82:83], v[82:83], v[114:115]
	v_pk_mul_f32 v[84:85], v[84:85], v[116:117]
	v_pk_mul_f32 v[86:87], v[86:87], v[118:119]
	v_pk_mul_f32 v[88:89], v[88:89], v[120:121]
	v_pk_mul_f32 v[90:91], v[90:91], v[122:123]
	v_pk_mul_f32 v[92:93], v[92:93], v[124:125]
	v_pk_mul_f32 v[94:95], v[94:95], v[126:127]
	v_pk_fma_f32 v[80:81], v[80:81], v[128:129], v[144:145]
	v_pk_fma_f32 v[82:83], v[82:83], v[130:131], v[146:147]
	v_pk_fma_f32 v[84:85], v[84:85], v[132:133], v[148:149]
	v_pk_fma_f32 v[86:87], v[86:87], v[134:135], v[150:151]
	v_pk_fma_f32 v[88:89], v[88:89], v[136:137], v[152:153]
	v_pk_fma_f32 v[90:91], v[90:91], v[138:139], v[154:155]
	v_pk_fma_f32 v[92:93], v[92:93], v[140:141], v[156:157]
	v_pk_fma_f32 v[94:95], v[94:95], v[142:143], v[158:159]
	v_cvt_pk_bf16_f32 v80, v80, v81
	v_cvt_pk_bf16_f32 v81, v82, v83
	v_cvt_pk_bf16_f32 v82, v84, v85
	v_cvt_pk_bf16_f32 v83, v86, v87
	v_cvt_pk_bf16_f32 v84, v88, v89
	v_cvt_pk_bf16_f32 v85, v90, v91
	v_cvt_pk_bf16_f32 v86, v92, v93
	v_cvt_pk_bf16_f32 v87, v94, v95
	s_lshl_b32 s99, s98, 11
	v_lshl_add_u32 v8, v0, 3, s99
	global_store_dwordx2 v8, v[80:81], s[94:95]
	global_store_dwordx2 v8, v[82:83], s[94:95] offset:512
	global_store_dwordx2 v8, v[84:85], s[94:95] offset:1024
	global_store_dwordx2 v8, v[86:87], s[94:95] offset:1536
	s_lshl_b32 s99, s98, 2
	v_mov_b32_e32 v9, s99
	v_mov_b32_e32 v10, 0
	v_cmp_eq_u32_e32 vcc, 0, v0
	s_and_saveexec_b64 s[98:99], vcc
	global_store_dword v9, v10, s[90:91]
	global_store_dword v9, v10, s[92:93]
	s_or_b64 exec, exec, s[98:99]
	s_add_u32 s98, s97, 10
	s_lshl_b32 s98, s98, 12
	v_add_u32_e32 v3, s98, v1
	global_load_dwordx4 v[80:83], v3, s[88:89] nt
	global_load_dwordx4 v[84:87], v3, s[88:89] offset:1024 nt
	global_load_dwordx4 v[88:91], v3, s[88:89] offset:2048 nt
	global_load_dwordx4 v[92:95], v3, s[88:89] offset:3072 nt
	s_waitcnt vmcnt(50)
	v_mul_f32_e32 v4, v96, v96
	v_fma_f32 v4, v97, v97, v4
	v_fma_f32 v4, v98, v98, v4
	v_fma_f32 v4, v99, v99, v4
	v_fma_f32 v4, v100, v100, v4
	v_fma_f32 v4, v101, v101, v4
	v_fma_f32 v4, v102, v102, v4
	v_fma_f32 v4, v103, v103, v4
	v_fma_f32 v4, v104, v104, v4
	v_fma_f32 v4, v105, v105, v4
	v_fma_f32 v4, v106, v106, v4
	v_fma_f32 v4, v107, v107, v4
	v_fma_f32 v4, v108, v108, v4
	v_fma_f32 v4, v109, v109, v4
	v_fma_f32 v4, v110, v110, v4
	v_fma_f32 v4, v111, v111, v4
	s_nop 1
	v_add_f32_dpp v5, v4, v4 quad_perm:[1,0,3,2] row_mask:0xf bank_mask:0xf
	s_nop 1
	v_add_f32_dpp v4, v5, v5 quad_perm:[2,3,0,1] row_mask:0xf bank_mask:0xf
	s_nop 1
	v_add_f32_dpp v5, v4, v4 row_half_mirror row_mask:0xf bank_mask:0xf
	s_nop 1
	v_add_f32_dpp v4, v5, v5 row_mirror row_mask:0xf bank_mask:0xf
	s_nop 1
	v_readlane_b32 s98, v4, 0
	v_readlane_b32 s99, v4, 16
	s_nop 3
	v_mov_b32_e32 v5, s98
	v_add_f32_e32 v5, s99, v5
	v_readlane_b32 s98, v4, 32
	v_readlane_b32 s99, v4, 48
	s_nop 3
	v_add_f32_e32 v5, s98, v5
	v_add_f32_e32 v5, s99, v5
	v_mul_f32_e32 v5, 0x3a800000, v5
	v_add_f32_e32 v5, 0x358637bd, v5
	v_rsq_f32_e32 v6, v5
	s_nop 0
	s_add_u32 s98, s97, 5
	v_pk_mul_f32 v[96:97], v[96:97], v[6:7] op_sel_hi:[1,0]
	v_pk_mul_f32 v[98:99], v[98:99], v[6:7] op_sel_hi:[1,0]
	v_pk_mul_f32 v[100:101], v[100:101], v[6:7] op_sel_hi:[1,0]
	v_pk_mul_f32 v[102:103], v[102:103], v[6:7] op_sel_hi:[1,0]
	v_pk_mul_f32 v[104:105], v[104:105], v[6:7] op_sel_hi:[1,0]
	v_pk_mul_f32 v[106:107], v[106:107], v[6:7] op_sel_hi:[1,0]
	v_pk_mul_f32 v[108:109], v[108:109], v[6:7] op_sel_hi:[1,0]
	v_pk_mul_f32 v[110:111], v[110:111], v[6:7] op_sel_hi:[1,0]
	v_pk_mul_f32 v[96:97], v[96:97], v[112:113]
	v_pk_mul_f32 v[98:99], v[98:99], v[114:115]
	v_pk_mul_f32 v[100:101], v[100:101], v[116:117]
	v_pk_mul_f32 v[102:103], v[102:103], v[118:119]
	v_pk_mul_f32 v[104:105], v[104:105], v[120:121]
	v_pk_mul_f32 v[106:107], v[106:107], v[122:123]
	v_pk_mul_f32 v[108:109], v[108:109], v[124:125]
	v_pk_mul_f32 v[110:111], v[110:111], v[126:127]
	v_pk_fma_f32 v[96:97], v[96:97], v[128:129], v[144:145]
	v_pk_fma_f32 v[98:99], v[98:99], v[130:131], v[146:147]
	v_pk_fma_f32 v[100:101], v[100:101], v[132:133], v[148:149]
	v_pk_fma_f32 v[102:103], v[102:103], v[134:135], v[150:151]
	v_pk_fma_f32 v[104:105], v[104:105], v[136:137], v[152:153]
	v_pk_fma_f32 v[106:107], v[106:107], v[138:139], v[154:155]
	v_pk_fma_f32 v[108:109], v[108:109], v[140:141], v[156:157]
	v_pk_fma_f32 v[110:111], v[110:111], v[142:143], v[158:159]
	v_cvt_pk_bf16_f32 v96, v96, v97
	v_cvt_pk_bf16_f32 v97, v98, v99
	v_cvt_pk_bf16_f32 v98, v100, v101
	v_cvt_pk_bf16_f32 v99, v102, v103
	v_cvt_pk_bf16_f32 v100, v104, v105
	v_cvt_pk_bf16_f32 v101, v106, v107
	v_cvt_pk_bf16_f32 v102, v108, v109
	v_cvt_pk_bf16_f32 v103, v110, v111
	s_lshl_b32 s99, s98, 11
	v_lshl_add_u32 v8, v0, 3, s99
	global_store_dwordx2 v8, v[96:97], s[94:95]
	global_store_dwordx2 v8, v[98:99], s[94:95] offset:512
	global_store_dwordx2 v8, v[100:101], s[94:95] offset:1024
	global_store_dwordx2 v8, v[102:103], s[94:95] offset:1536
	s_lshl_b32 s99, s98, 2
	v_mov_b32_e32 v9, s99
	v_mov_b32_e32 v10, 0
	v_cmp_eq_u32_e32 vcc, 0, v0
	s_and_saveexec_b64 s[98:99], vcc
	global_store_dword v9, v10, s[90:91]
	global_store_dword v9, v10, s[92:93]
	s_or_b64 exec, exec, s[98:99]
	s_add_u32 s98, s97, 11
	s_lshl_b32 s98, s98, 12
	v_add_u32_e32 v3, s98, v1
	global_load_dwordx4 v[96:99], v3, s[88:89] nt
	global_load_dwordx4 v[100:103], v3, s[88:89] offset:1024 nt
	global_load_dwordx4 v[104:107], v3, s[88:89] offset:2048 nt
	global_load_dwordx4 v[108:111], v3, s[88:89] offset:3072 nt
	s_waitcnt vmcnt(50)
	v_mul_f32_e32 v4, v16, v16
	v_fma_f32 v4, v17, v17, v4
	v_fma_f32 v4, v18, v18, v4
	v_fma_f32 v4, v19, v19, v4
	v_fma_f32 v4, v20, v20, v4
	v_fma_f32 v4, v21, v21, v4
	v_fma_f32 v4, v22, v22, v4
	v_fma_f32 v4, v23, v23, v4
	v_fma_f32 v4, v24, v24, v4
	v_fma_f32 v4, v25, v25, v4
	v_fma_f32 v4, v26, v26, v4
	v_fma_f32 v4, v27, v27, v4
	v_fma_f32 v4, v28, v28, v4
	v_fma_f32 v4, v29, v29, v4
	v_fma_f32 v4, v30, v30, v4
	v_fma_f32 v4, v31, v31, v4
	s_nop 1
	v_add_f32_dpp v5, v4, v4 quad_perm:[1,0,3,2] row_mask:0xf bank_mask:0xf
	s_nop 1
	v_add_f32_dpp v4, v5, v5 quad_perm:[2,3,0,1] row_mask:0xf bank_mask:0xf
	s_nop 1
	v_add_f32_dpp v5, v4, v4 row_half_mirror row_mask:0xf bank_mask:0xf
	s_nop 1
	v_add_f32_dpp v4, v5, v5 row_mirror row_mask:0xf bank_mask:0xf
	s_nop 1
	v_readlane_b32 s98, v4, 0
	v_readlane_b32 s99, v4, 16
	s_nop 3
	v_mov_b32_e32 v5, s98
	v_add_f32_e32 v5, s99, v5
	v_readlane_b32 s98, v4, 32
	v_readlane_b32 s99, v4, 48
	s_nop 3
	v_add_f32_e32 v5, s98, v5
	v_add_f32_e32 v5, s99, v5
	v_mul_f32_e32 v5, 0x3a800000, v5
	v_add_f32_e32 v5, 0x358637bd, v5
	v_rsq_f32_e32 v6, v5
	s_nop 0
	s_add_u32 s98, s97, 6
	v_pk_mul_f32 v[16:17], v[16:17], v[6:7] op_sel_hi:[1,0]
	v_pk_mul_f32 v[18:19], v[18:19], v[6:7] op_sel_hi:[1,0]
	v_pk_mul_f32 v[20:21], v[20:21], v[6:7] op_sel_hi:[1,0]
	v_pk_mul_f32 v[22:23], v[22:23], v[6:7] op_sel_hi:[1,0]
	v_pk_mul_f32 v[24:25], v[24:25], v[6:7] op_sel_hi:[1,0]
	v_pk_mul_f32 v[26:27], v[26:27], v[6:7] op_sel_hi:[1,0]
	v_pk_mul_f32 v[28:29], v[28:29], v[6:7] op_sel_hi:[1,0]
	v_pk_mul_f32 v[30:31], v[30:31], v[6:7] op_sel_hi:[1,0]
	v_pk_mul_f32 v[16:17], v[16:17], v[112:113]
	v_pk_mul_f32 v[18:19], v[18:19], v[114:115]
	v_pk_mul_f32 v[20:21], v[20:21], v[116:117]
	v_pk_mul_f32 v[22:23], v[22:23], v[118:119]
	v_pk_mul_f32 v[24:25], v[24:25], v[120:121]
	v_pk_mul_f32 v[26:27], v[26:27], v[122:123]
	v_pk_mul_f32 v[28:29], v[28:29], v[124:125]
	v_pk_mul_f32 v[30:31], v[30:31], v[126:127]
	v_pk_fma_f32 v[16:17], v[16:17], v[128:129], v[144:145]
	v_pk_fma_f32 v[18:19], v[18:19], v[130:131], v[146:147]
	v_pk_fma_f32 v[20:21], v[20:21], v[132:133], v[148:149]
	v_pk_fma_f32 v[22:23], v[22:23], v[134:135], v[150:151]
	v_pk_fma_f32 v[24:25], v[24:25], v[136:137], v[152:153]
	v_pk_fma_f32 v[26:27], v[26:27], v[138:139], v[154:155]
	v_pk_fma_f32 v[28:29], v[28:29], v[140:141], v[156:157]
	v_pk_fma_f32 v[30:31], v[30:31], v[142:143], v[158:159]
	v_cvt_pk_bf16_f32 v16, v16, v17
	v_cvt_pk_bf16_f32 v17, v18, v19
	v_cvt_pk_bf16_f32 v18, v20, v21
	v_cvt_pk_bf16_f32 v19, v22, v23
	v_cvt_pk_bf16_f32 v20, v24, v25
	v_cvt_pk_bf16_f32 v21, v26, v27
	v_cvt_pk_bf16_f32 v22, v28, v29
	v_cvt_pk_bf16_f32 v23, v30, v31
	s_lshl_b32 s99, s98, 11
	v_lshl_add_u32 v8, v0, 3, s99
	global_store_dwordx2 v8, v[16:17], s[94:95]
	global_store_dwordx2 v8, v[18:19], s[94:95] offset:512
	global_store_dwordx2 v8, v[20:21], s[94:95] offset:1024
	global_store_dwordx2 v8, v[22:23], s[94:95] offset:1536
	s_lshl_b32 s99, s98, 2
	v_mov_b32_e32 v9, s99
	v_mov_b32_e32 v10, 0
	v_cmp_eq_u32_e32 vcc, 0, v0
	s_and_saveexec_b64 s[98:99], vcc
	global_store_dword v9, v10, s[90:91]
	global_store_dword v9, v10, s[92:93]
	s_or_b64 exec, exec, s[98:99]
	s_add_u32 s98, s97, 12
	s_lshl_b32 s98, s98, 12
	v_add_u32_e32 v3, s98, v1
	global_load_dwordx4 v[16:19], v3, s[88:89] nt
	global_load_dwordx4 v[20:23], v3, s[88:89] offset:1024 nt
	global_load_dwordx4 v[24:27], v3, s[88:89] offset:2048 nt
	global_load_dwordx4 v[28:31], v3, s[88:89] offset:3072 nt
	s_waitcnt vmcnt(50)
	v_mul_f32_e32 v4, v32, v32
	v_fma_f32 v4, v33, v33, v4
	v_fma_f32 v4, v34, v34, v4
	v_fma_f32 v4, v35, v35, v4
	v_fma_f32 v4, v36, v36, v4
	v_fma_f32 v4, v37, v37, v4
	v_fma_f32 v4, v38, v38, v4
	v_fma_f32 v4, v39, v39, v4
	v_fma_f32 v4, v40, v40, v4
	v_fma_f32 v4, v41, v41, v4
	v_fma_f32 v4, v42, v42, v4
	v_fma_f32 v4, v43, v43, v4
	v_fma_f32 v4, v44, v44, v4
	v_fma_f32 v4, v45, v45, v4
	v_fma_f32 v4, v46, v46, v4
	v_fma_f32 v4, v47, v47, v4
	s_nop 1
	v_add_f32_dpp v5, v4, v4 quad_perm:[1,0,3,2] row_mask:0xf bank_mask:0xf
	s_nop 1
	v_add_f32_dpp v4, v5, v5 quad_perm:[2,3,0,1] row_mask:0xf bank_mask:0xf
	s_nop 1
	v_add_f32_dpp v5, v4, v4 row_half_mirror row_mask:0xf bank_mask:0xf
	s_nop 1
	v_add_f32_dpp v4, v5, v5 row_mirror row_mask:0xf bank_mask:0xf
	s_nop 1
	v_readlane_b32 s98, v4, 0
	v_readlane_b32 s99, v4, 16
	s_nop 3
	v_mov_b32_e32 v5, s98
	v_add_f32_e32 v5, s99, v5
	v_readlane_b32 s98, v4, 32
	v_readlane_b32 s99, v4, 48
	s_nop 3
	v_add_f32_e32 v5, s98, v5
	v_add_f32_e32 v5, s99, v5
	v_mul_f32_e32 v5, 0x3a800000, v5
	v_add_f32_e32 v5, 0x358637bd, v5
	v_rsq_f32_e32 v6, v5
	s_nop 0
	s_add_u32 s98, s97, 7
	v_pk_mul_f32 v[32:33], v[32:33], v[6:7] op_sel_hi:[1,0]
	v_pk_mul_f32 v[34:35], v[34:35], v[6:7] op_sel_hi:[1,0]
	v_pk_mul_f32 v[36:37], v[36:37], v[6:7] op_sel_hi:[1,0]
	v_pk_mul_f32 v[38:39], v[38:39], v[6:7] op_sel_hi:[1,0]
	v_pk_mul_f32 v[40:41], v[40:41], v[6:7] op_sel_hi:[1,0]
	v_pk_mul_f32 v[42:43], v[42:43], v[6:7] op_sel_hi:[1,0]
	v_pk_mul_f32 v[44:45], v[44:45], v[6:7] op_sel_hi:[1,0]
	v_pk_mul_f32 v[46:47], v[46:47], v[6:7] op_sel_hi:[1,0]
	v_pk_mul_f32 v[32:33], v[32:33], v[112:113]
	v_pk_mul_f32 v[34:35], v[34:35], v[114:115]
	v_pk_mul_f32 v[36:37], v[36:37], v[116:117]
	v_pk_mul_f32 v[38:39], v[38:39], v[118:119]
	v_pk_mul_f32 v[40:41], v[40:41], v[120:121]
	v_pk_mul_f32 v[42:43], v[42:43], v[122:123]
	v_pk_mul_f32 v[44:45], v[44:45], v[124:125]
	v_pk_mul_f32 v[46:47], v[46:47], v[126:127]
	v_pk_fma_f32 v[32:33], v[32:33], v[128:129], v[144:145]
	v_pk_fma_f32 v[34:35], v[34:35], v[130:131], v[146:147]
	v_pk_fma_f32 v[36:37], v[36:37], v[132:133], v[148:149]
	v_pk_fma_f32 v[38:39], v[38:39], v[134:135], v[150:151]
	v_pk_fma_f32 v[40:41], v[40:41], v[136:137], v[152:153]
	v_pk_fma_f32 v[42:43], v[42:43], v[138:139], v[154:155]
	v_pk_fma_f32 v[44:45], v[44:45], v[140:141], v[156:157]
	v_pk_fma_f32 v[46:47], v[46:47], v[142:143], v[158:159]
	v_cvt_pk_bf16_f32 v32, v32, v33
	v_cvt_pk_bf16_f32 v33, v34, v35
	v_cvt_pk_bf16_f32 v34, v36, v37
	v_cvt_pk_bf16_f32 v35, v38, v39
	v_cvt_pk_bf16_f32 v36, v40, v41
	v_cvt_pk_bf16_f32 v37, v42, v43
	v_cvt_pk_bf16_f32 v38, v44, v45
	v_cvt_pk_bf16_f32 v39, v46, v47
	s_lshl_b32 s99, s98, 11
	v_lshl_add_u32 v8, v0, 3, s99
	global_store_dwordx2 v8, v[32:33], s[94:95]
	global_store_dwordx2 v8, v[34:35], s[94:95] offset:512
	global_store_dwordx2 v8, v[36:37], s[94:95] offset:1024
	global_store_dwordx2 v8, v[38:39], s[94:95] offset:1536
	s_lshl_b32 s99, s98, 2
	v_mov_b32_e32 v9, s99
	v_mov_b32_e32 v10, 0
	v_cmp_eq_u32_e32 vcc, 0, v0
	s_and_saveexec_b64 s[98:99], vcc
	global_store_dword v9, v10, s[90:91]
	global_store_dword v9, v10, s[92:93]
	s_or_b64 exec, exec, s[98:99]
	s_add_u32 s98, s97, 13
	s_lshl_b32 s98, s98, 12
	v_add_u32_e32 v3, s98, v1
	global_load_dwordx4 v[32:35], v3, s[88:89] nt
	global_load_dwordx4 v[36:39], v3, s[88:89] offset:1024 nt
	global_load_dwordx4 v[40:43], v3, s[88:89] offset:2048 nt
	global_load_dwordx4 v[44:47], v3, s[88:89] offset:3072 nt
	s_waitcnt vmcnt(50)
	v_mul_f32_e32 v4, v48, v48
	v_fma_f32 v4, v49, v49, v4
	v_fma_f32 v4, v50, v50, v4
	v_fma_f32 v4, v51, v51, v4
	v_fma_f32 v4, v52, v52, v4
	v_fma_f32 v4, v53, v53, v4
	v_fma_f32 v4, v54, v54, v4
	v_fma_f32 v4, v55, v55, v4
	v_fma_f32 v4, v56, v56, v4
	v_fma_f32 v4, v57, v57, v4
	v_fma_f32 v4, v58, v58, v4
	v_fma_f32 v4, v59, v59, v4
	v_fma_f32 v4, v60, v60, v4
	v_fma_f32 v4, v61, v61, v4
	v_fma_f32 v4, v62, v62, v4
	v_fma_f32 v4, v63, v63, v4
	s_nop 1
	v_add_f32_dpp v5, v4, v4 quad_perm:[1,0,3,2] row_mask:0xf bank_mask:0xf
	s_nop 1
	v_add_f32_dpp v4, v5, v5 quad_perm:[2,3,0,1] row_mask:0xf bank_mask:0xf
	s_nop 1
	v_add_f32_dpp v5, v4, v4 row_half_mirror row_mask:0xf bank_mask:0xf
	s_nop 1
	v_add_f32_dpp v4, v5, v5 row_mirror row_mask:0xf bank_mask:0xf
	s_nop 1
	v_readlane_b32 s98, v4, 0
	v_readlane_b32 s99, v4, 16
	s_nop 3
	v_mov_b32_e32 v5, s98
	v_add_f32_e32 v5, s99, v5
	v_readlane_b32 s98, v4, 32
	v_readlane_b32 s99, v4, 48
	s_nop 3
	v_add_f32_e32 v5, s98, v5
	v_add_f32_e32 v5, s99, v5
	v_mul_f32_e32 v5, 0x3a800000, v5
	v_add_f32_e32 v5, 0x358637bd, v5
	v_rsq_f32_e32 v6, v5
	s_nop 0
	s_add_u32 s98, s97, 8
	v_pk_mul_f32 v[48:49], v[48:49], v[6:7] op_sel_hi:[1,0]
	v_pk_mul_f32 v[50:51], v[50:51], v[6:7] op_sel_hi:[1,0]
	v_pk_mul_f32 v[52:53], v[52:53], v[6:7] op_sel_hi:[1,0]
	v_pk_mul_f32 v[54:55], v[54:55], v[6:7] op_sel_hi:[1,0]
	v_pk_mul_f32 v[56:57], v[56:57], v[6:7] op_sel_hi:[1,0]
	v_pk_mul_f32 v[58:59], v[58:59], v[6:7] op_sel_hi:[1,0]
	v_pk_mul_f32 v[60:61], v[60:61], v[6:7] op_sel_hi:[1,0]
	v_pk_mul_f32 v[62:63], v[62:63], v[6:7] op_sel_hi:[1,0]
	v_pk_mul_f32 v[48:49], v[48:49], v[112:113]
	v_pk_mul_f32 v[50:51], v[50:51], v[114:115]
	v_pk_mul_f32 v[52:53], v[52:53], v[116:117]
	v_pk_mul_f32 v[54:55], v[54:55], v[118:119]
	v_pk_mul_f32 v[56:57], v[56:57], v[120:121]
	v_pk_mul_f32 v[58:59], v[58:59], v[122:123]
	v_pk_mul_f32 v[60:61], v[60:61], v[124:125]
	v_pk_mul_f32 v[62:63], v[62:63], v[126:127]
	v_pk_fma_f32 v[48:49], v[48:49], v[128:129], v[144:145]
	v_pk_fma_f32 v[50:51], v[50:51], v[130:131], v[146:147]
	v_pk_fma_f32 v[52:53], v[52:53], v[132:133], v[148:149]
	v_pk_fma_f32 v[54:55], v[54:55], v[134:135], v[150:151]
	v_pk_fma_f32 v[56:57], v[56:57], v[136:137], v[152:153]
	v_pk_fma_f32 v[58:59], v[58:59], v[138:139], v[154:155]
	v_pk_fma_f32 v[60:61], v[60:61], v[140:141], v[156:157]
	v_pk_fma_f32 v[62:63], v[62:63], v[142:143], v[158:159]
	v_cvt_pk_bf16_f32 v48, v48, v49
	v_cvt_pk_bf16_f32 v49, v50, v51
	v_cvt_pk_bf16_f32 v50, v52, v53
	v_cvt_pk_bf16_f32 v51, v54, v55
	v_cvt_pk_bf16_f32 v52, v56, v57
	v_cvt_pk_bf16_f32 v53, v58, v59
	v_cvt_pk_bf16_f32 v54, v60, v61
	v_cvt_pk_bf16_f32 v55, v62, v63
	s_lshl_b32 s99, s98, 11
	v_lshl_add_u32 v8, v0, 3, s99
	global_store_dwordx2 v8, v[48:49], s[94:95]
	global_store_dwordx2 v8, v[50:51], s[94:95] offset:512
	global_store_dwordx2 v8, v[52:53], s[94:95] offset:1024
	global_store_dwordx2 v8, v[54:55], s[94:95] offset:1536
	s_lshl_b32 s99, s98, 2
	v_mov_b32_e32 v9, s99
	v_mov_b32_e32 v10, 0
	v_cmp_eq_u32_e32 vcc, 0, v0
	s_and_saveexec_b64 s[98:99], vcc
	global_store_dword v9, v10, s[90:91]
	global_store_dword v9, v10, s[92:93]
	s_or_b64 exec, exec, s[98:99]
	s_add_u32 s98, s97, 14
	s_lshl_b32 s98, s98, 12
	v_add_u32_e32 v3, s98, v1
	global_load_dwordx4 v[48:51], v3, s[88:89] nt
	global_load_dwordx4 v[52:55], v3, s[88:89] offset:1024 nt
	global_load_dwordx4 v[56:59], v3, s[88:89] offset:2048 nt
	global_load_dwordx4 v[60:63], v3, s[88:89] offset:3072 nt
	s_waitcnt vmcnt(50)
	v_mul_f32_e32 v4, v64, v64
	v_fma_f32 v4, v65, v65, v4
	v_fma_f32 v4, v66, v66, v4
	v_fma_f32 v4, v67, v67, v4
	v_fma_f32 v4, v68, v68, v4
	v_fma_f32 v4, v69, v69, v4
	v_fma_f32 v4, v70, v70, v4
	v_fma_f32 v4, v71, v71, v4
	v_fma_f32 v4, v72, v72, v4
	v_fma_f32 v4, v73, v73, v4
	v_fma_f32 v4, v74, v74, v4
	v_fma_f32 v4, v75, v75, v4
	v_fma_f32 v4, v76, v76, v4
	v_fma_f32 v4, v77, v77, v4
	v_fma_f32 v4, v78, v78, v4
	v_fma_f32 v4, v79, v79, v4
	s_nop 1
	v_add_f32_dpp v5, v4, v4 quad_perm:[1,0,3,2] row_mask:0xf bank_mask:0xf
	s_nop 1
	v_add_f32_dpp v4, v5, v5 quad_perm:[2,3,0,1] row_mask:0xf bank_mask:0xf
	s_nop 1
	v_add_f32_dpp v5, v4, v4 row_half_mirror row_mask:0xf bank_mask:0xf
	s_nop 1
	v_add_f32_dpp v4, v5, v5 row_mirror row_mask:0xf bank_mask:0xf
	s_nop 1
	v_readlane_b32 s98, v4, 0
	v_readlane_b32 s99, v4, 16
	s_nop 3
	v_mov_b32_e32 v5, s98
	v_add_f32_e32 v5, s99, v5
	v_readlane_b32 s98, v4, 32
	v_readlane_b32 s99, v4, 48
	s_nop 3
	v_add_f32_e32 v5, s98, v5
	v_add_f32_e32 v5, s99, v5
	v_mul_f32_e32 v5, 0x3a800000, v5
	v_add_f32_e32 v5, 0x358637bd, v5
	v_rsq_f32_e32 v6, v5
	s_nop 0
	s_add_u32 s98, s97, 9
	v_pk_mul_f32 v[64:65], v[64:65], v[6:7] op_sel_hi:[1,0]
	v_pk_mul_f32 v[66:67], v[66:67], v[6:7] op_sel_hi:[1,0]
	v_pk_mul_f32 v[68:69], v[68:69], v[6:7] op_sel_hi:[1,0]
	v_pk_mul_f32 v[70:71], v[70:71], v[6:7] op_sel_hi:[1,0]
	v_pk_mul_f32 v[72:73], v[72:73], v[6:7] op_sel_hi:[1,0]
	v_pk_mul_f32 v[74:75], v[74:75], v[6:7] op_sel_hi:[1,0]
	v_pk_mul_f32 v[76:77], v[76:77], v[6:7] op_sel_hi:[1,0]
	v_pk_mul_f32 v[78:79], v[78:79], v[6:7] op_sel_hi:[1,0]
	v_pk_mul_f32 v[64:65], v[64:65], v[112:113]
	v_pk_mul_f32 v[66:67], v[66:67], v[114:115]
	v_pk_mul_f32 v[68:69], v[68:69], v[116:117]
	v_pk_mul_f32 v[70:71], v[70:71], v[118:119]
	v_pk_mul_f32 v[72:73], v[72:73], v[120:121]
	v_pk_mul_f32 v[74:75], v[74:75], v[122:123]
	v_pk_mul_f32 v[76:77], v[76:77], v[124:125]
	v_pk_mul_f32 v[78:79], v[78:79], v[126:127]
	v_pk_fma_f32 v[64:65], v[64:65], v[128:129], v[144:145]
	v_pk_fma_f32 v[66:67], v[66:67], v[130:131], v[146:147]
	v_pk_fma_f32 v[68:69], v[68:69], v[132:133], v[148:149]
	v_pk_fma_f32 v[70:71], v[70:71], v[134:135], v[150:151]
	v_pk_fma_f32 v[72:73], v[72:73], v[136:137], v[152:153]
	v_pk_fma_f32 v[74:75], v[74:75], v[138:139], v[154:155]
	v_pk_fma_f32 v[76:77], v[76:77], v[140:141], v[156:157]
	v_pk_fma_f32 v[78:79], v[78:79], v[142:143], v[158:159]
	v_cvt_pk_bf16_f32 v64, v64, v65
	v_cvt_pk_bf16_f32 v65, v66, v67
	v_cvt_pk_bf16_f32 v66, v68, v69
	v_cvt_pk_bf16_f32 v67, v70, v71
	v_cvt_pk_bf16_f32 v68, v72, v73
	v_cvt_pk_bf16_f32 v69, v74, v75
	v_cvt_pk_bf16_f32 v70, v76, v77
	v_cvt_pk_bf16_f32 v71, v78, v79
	s_lshl_b32 s99, s98, 11
	v_lshl_add_u32 v8, v0, 3, s99
	global_store_dwordx2 v8, v[64:65], s[94:95]
	global_store_dwordx2 v8, v[66:67], s[94:95] offset:512
	global_store_dwordx2 v8, v[68:69], s[94:95] offset:1024
	global_store_dwordx2 v8, v[70:71], s[94:95] offset:1536
	s_lshl_b32 s99, s98, 2
	v_mov_b32_e32 v9, s99
	v_mov_b32_e32 v10, 0
	v_cmp_eq_u32_e32 vcc, 0, v0
	s_and_saveexec_b64 s[98:99], vcc
	global_store_dword v9, v10, s[90:91]
	global_store_dword v9, v10, s[92:93]
	s_or_b64 exec, exec, s[98:99]
	s_add_u32 s98, s97, 15
	s_lshl_b32 s98, s98, 12
	v_add_u32_e32 v3, s98, v1
	global_load_dwordx4 v[64:67], v3, s[88:89] nt
	global_load_dwordx4 v[68:71], v3, s[88:89] offset:1024 nt
	global_load_dwordx4 v[72:75], v3, s[88:89] offset:2048 nt
	global_load_dwordx4 v[76:79], v3, s[88:89] offset:3072 nt
	s_waitcnt vmcnt(50)
	v_mul_f32_e32 v4, v80, v80
	v_fma_f32 v4, v81, v81, v4
	v_fma_f32 v4, v82, v82, v4
	v_fma_f32 v4, v83, v83, v4
	v_fma_f32 v4, v84, v84, v4
	v_fma_f32 v4, v85, v85, v4
	v_fma_f32 v4, v86, v86, v4
	v_fma_f32 v4, v87, v87, v4
	v_fma_f32 v4, v88, v88, v4
	v_fma_f32 v4, v89, v89, v4
	v_fma_f32 v4, v90, v90, v4
	v_fma_f32 v4, v91, v91, v4
	v_fma_f32 v4, v92, v92, v4
	v_fma_f32 v4, v93, v93, v4
	v_fma_f32 v4, v94, v94, v4
	v_fma_f32 v4, v95, v95, v4
	s_nop 1
	v_add_f32_dpp v5, v4, v4 quad_perm:[1,0,3,2] row_mask:0xf bank_mask:0xf
	s_nop 1
	v_add_f32_dpp v4, v5, v5 quad_perm:[2,3,0,1] row_mask:0xf bank_mask:0xf
	s_nop 1
	v_add_f32_dpp v5, v4, v4 row_half_mirror row_mask:0xf bank_mask:0xf
	s_nop 1
	v_add_f32_dpp v4, v5, v5 row_mirror row_mask:0xf bank_mask:0xf
	s_nop 1
	v_readlane_b32 s98, v4, 0
	v_readlane_b32 s99, v4, 16
	s_nop 3
	v_mov_b32_e32 v5, s98
	v_add_f32_e32 v5, s99, v5
	v_readlane_b32 s98, v4, 32
	v_readlane_b32 s99, v4, 48
	s_nop 3
	v_add_f32_e32 v5, s98, v5
	v_add_f32_e32 v5, s99, v5
	v_mul_f32_e32 v5, 0x3a800000, v5
	v_add_f32_e32 v5, 0x358637bd, v5
	v_rsq_f32_e32 v6, v5
	s_nop 0
	s_add_u32 s98, s97, 10
	v_pk_mul_f32 v[80:81], v[80:81], v[6:7] op_sel_hi:[1,0]
	v_pk_mul_f32 v[82:83], v[82:83], v[6:7] op_sel_hi:[1,0]
	v_pk_mul_f32 v[84:85], v[84:85], v[6:7] op_sel_hi:[1,0]
	v_pk_mul_f32 v[86:87], v[86:87], v[6:7] op_sel_hi:[1,0]
	v_pk_mul_f32 v[88:89], v[88:89], v[6:7] op_sel_hi:[1,0]
	v_pk_mul_f32 v[90:91], v[90:91], v[6:7] op_sel_hi:[1,0]
	v_pk_mul_f32 v[92:93], v[92:93], v[6:7] op_sel_hi:[1,0]
	v_pk_mul_f32 v[94:95], v[94:95], v[6:7] op_sel_hi:[1,0]
	v_pk_mul_f32 v[80:81], v[80:81], v[112:113]
	v_pk_mul_f32 v[82:83], v[82:83], v[114:115]
	v_pk_mul_f32 v[84:85], v[84:85], v[116:117]
	v_pk_mul_f32 v[86:87], v[86:87], v[118:119]
	v_pk_mul_f32 v[88:89], v[88:89], v[120:121]
	v_pk_mul_f32 v[90:91], v[90:91], v[122:123]
	v_pk_mul_f32 v[92:93], v[92:93], v[124:125]
	v_pk_mul_f32 v[94:95], v[94:95], v[126:127]
	v_pk_fma_f32 v[80:81], v[80:81], v[128:129], v[144:145]
	v_pk_fma_f32 v[82:83], v[82:83], v[130:131], v[146:147]
	v_pk_fma_f32 v[84:85], v[84:85], v[132:133], v[148:149]
	v_pk_fma_f32 v[86:87], v[86:87], v[134:135], v[150:151]
	v_pk_fma_f32 v[88:89], v[88:89], v[136:137], v[152:153]
	v_pk_fma_f32 v[90:91], v[90:91], v[138:139], v[154:155]
	v_pk_fma_f32 v[92:93], v[92:93], v[140:141], v[156:157]
	v_pk_fma_f32 v[94:95], v[94:95], v[142:143], v[158:159]
	v_cvt_pk_bf16_f32 v80, v80, v81
	v_cvt_pk_bf16_f32 v81, v82, v83
	v_cvt_pk_bf16_f32 v82, v84, v85
	v_cvt_pk_bf16_f32 v83, v86, v87
	v_cvt_pk_bf16_f32 v84, v88, v89
	v_cvt_pk_bf16_f32 v85, v90, v91
	v_cvt_pk_bf16_f32 v86, v92, v93
	v_cvt_pk_bf16_f32 v87, v94, v95
	s_lshl_b32 s99, s98, 11
	v_lshl_add_u32 v8, v0, 3, s99
	global_store_dwordx2 v8, v[80:81], s[94:95]
	global_store_dwordx2 v8, v[82:83], s[94:95] offset:512
	global_store_dwordx2 v8, v[84:85], s[94:95] offset:1024
	global_store_dwordx2 v8, v[86:87], s[94:95] offset:1536
	s_lshl_b32 s99, s98, 2
	v_mov_b32_e32 v9, s99
	v_mov_b32_e32 v10, 0
	v_cmp_eq_u32_e32 vcc, 0, v0
	s_and_saveexec_b64 s[98:99], vcc
	global_store_dword v9, v10, s[90:91]
	global_store_dword v9, v10, s[92:93]
	s_or_b64 exec, exec, s[98:99]
	s_waitcnt vmcnt(46)
	v_mul_f32_e32 v4, v96, v96
	v_fma_f32 v4, v97, v97, v4
	v_fma_f32 v4, v98, v98, v4
	v_fma_f32 v4, v99, v99, v4
	v_fma_f32 v4, v100, v100, v4
	v_fma_f32 v4, v101, v101, v4
	v_fma_f32 v4, v102, v102, v4
	v_fma_f32 v4, v103, v103, v4
	v_fma_f32 v4, v104, v104, v4
	v_fma_f32 v4, v105, v105, v4
	v_fma_f32 v4, v106, v106, v4
	v_fma_f32 v4, v107, v107, v4
	v_fma_f32 v4, v108, v108, v4
	v_fma_f32 v4, v109, v109, v4
	v_fma_f32 v4, v110, v110, v4
	v_fma_f32 v4, v111, v111, v4
	s_nop 1
	v_add_f32_dpp v5, v4, v4 quad_perm:[1,0,3,2] row_mask:0xf bank_mask:0xf
	s_nop 1
	v_add_f32_dpp v4, v5, v5 quad_perm:[2,3,0,1] row_mask:0xf bank_mask:0xf
	s_nop 1
	v_add_f32_dpp v5, v4, v4 row_half_mirror row_mask:0xf bank_mask:0xf
	s_nop 1
	v_add_f32_dpp v4, v5, v5 row_mirror row_mask:0xf bank_mask:0xf
	s_nop 1
	v_readlane_b32 s98, v4, 0
	v_readlane_b32 s99, v4, 16
	s_nop 3
	v_mov_b32_e32 v5, s98
	v_add_f32_e32 v5, s99, v5
	v_readlane_b32 s98, v4, 32
	v_readlane_b32 s99, v4, 48
	s_nop 3
	v_add_f32_e32 v5, s98, v5
	v_add_f32_e32 v5, s99, v5
	v_mul_f32_e32 v5, 0x3a800000, v5
	v_add_f32_e32 v5, 0x358637bd, v5
	v_rsq_f32_e32 v6, v5
	s_nop 0
	s_add_u32 s98, s97, 11
	v_pk_mul_f32 v[96:97], v[96:97], v[6:7] op_sel_hi:[1,0]
	v_pk_mul_f32 v[98:99], v[98:99], v[6:7] op_sel_hi:[1,0]
	v_pk_mul_f32 v[100:101], v[100:101], v[6:7] op_sel_hi:[1,0]
	v_pk_mul_f32 v[102:103], v[102:103], v[6:7] op_sel_hi:[1,0]
	v_pk_mul_f32 v[104:105], v[104:105], v[6:7] op_sel_hi:[1,0]
	v_pk_mul_f32 v[106:107], v[106:107], v[6:7] op_sel_hi:[1,0]
	v_pk_mul_f32 v[108:109], v[108:109], v[6:7] op_sel_hi:[1,0]
	v_pk_mul_f32 v[110:111], v[110:111], v[6:7] op_sel_hi:[1,0]
	v_pk_mul_f32 v[96:97], v[96:97], v[112:113]
	v_pk_mul_f32 v[98:99], v[98:99], v[114:115]
	v_pk_mul_f32 v[100:101], v[100:101], v[116:117]
	v_pk_mul_f32 v[102:103], v[102:103], v[118:119]
	v_pk_mul_f32 v[104:105], v[104:105], v[120:121]
	v_pk_mul_f32 v[106:107], v[106:107], v[122:123]
	v_pk_mul_f32 v[108:109], v[108:109], v[124:125]
	v_pk_mul_f32 v[110:111], v[110:111], v[126:127]
	v_pk_fma_f32 v[96:97], v[96:97], v[128:129], v[144:145]
	v_pk_fma_f32 v[98:99], v[98:99], v[130:131], v[146:147]
	v_pk_fma_f32 v[100:101], v[100:101], v[132:133], v[148:149]
	v_pk_fma_f32 v[102:103], v[102:103], v[134:135], v[150:151]
	v_pk_fma_f32 v[104:105], v[104:105], v[136:137], v[152:153]
	v_pk_fma_f32 v[106:107], v[106:107], v[138:139], v[154:155]
	v_pk_fma_f32 v[108:109], v[108:109], v[140:141], v[156:157]
	v_pk_fma_f32 v[110:111], v[110:111], v[142:143], v[158:159]
	v_cvt_pk_bf16_f32 v96, v96, v97
	v_cvt_pk_bf16_f32 v97, v98, v99
	v_cvt_pk_bf16_f32 v98, v100, v101
	v_cvt_pk_bf16_f32 v99, v102, v103
	v_cvt_pk_bf16_f32 v100, v104, v105
	v_cvt_pk_bf16_f32 v101, v106, v107
	v_cvt_pk_bf16_f32 v102, v108, v109
	v_cvt_pk_bf16_f32 v103, v110, v111
	s_lshl_b32 s99, s98, 11
	v_lshl_add_u32 v8, v0, 3, s99
	global_store_dwordx2 v8, v[96:97], s[94:95]
	global_store_dwordx2 v8, v[98:99], s[94:95] offset:512
	global_store_dwordx2 v8, v[100:101], s[94:95] offset:1024
	global_store_dwordx2 v8, v[102:103], s[94:95] offset:1536
	s_lshl_b32 s99, s98, 2
	v_mov_b32_e32 v9, s99
	v_mov_b32_e32 v10, 0
	v_cmp_eq_u32_e32 vcc, 0, v0
	s_and_saveexec_b64 s[98:99], vcc
	global_store_dword v9, v10, s[90:91]
	global_store_dword v9, v10, s[92:93]
	s_or_b64 exec, exec, s[98:99]
	s_waitcnt vmcnt(42)
	v_mul_f32_e32 v4, v16, v16
	v_fma_f32 v4, v17, v17, v4
	v_fma_f32 v4, v18, v18, v4
	v_fma_f32 v4, v19, v19, v4
	v_fma_f32 v4, v20, v20, v4
	v_fma_f32 v4, v21, v21, v4
	v_fma_f32 v4, v22, v22, v4
	v_fma_f32 v4, v23, v23, v4
	v_fma_f32 v4, v24, v24, v4
	v_fma_f32 v4, v25, v25, v4
	v_fma_f32 v4, v26, v26, v4
	v_fma_f32 v4, v27, v27, v4
	v_fma_f32 v4, v28, v28, v4
	v_fma_f32 v4, v29, v29, v4
	v_fma_f32 v4, v30, v30, v4
	v_fma_f32 v4, v31, v31, v4
	s_nop 1
	v_add_f32_dpp v5, v4, v4 quad_perm:[1,0,3,2] row_mask:0xf bank_mask:0xf
	s_nop 1
	v_add_f32_dpp v4, v5, v5 quad_perm:[2,3,0,1] row_mask:0xf bank_mask:0xf
	s_nop 1
	v_add_f32_dpp v5, v4, v4 row_half_mirror row_mask:0xf bank_mask:0xf
	s_nop 1
	v_add_f32_dpp v4, v5, v5 row_mirror row_mask:0xf bank_mask:0xf
	s_nop 1
	v_readlane_b32 s98, v4, 0
	v_readlane_b32 s99, v4, 16
	s_nop 3
	v_mov_b32_e32 v5, s98
	v_add_f32_e32 v5, s99, v5
	v_readlane_b32 s98, v4, 32
	v_readlane_b32 s99, v4, 48
	s_nop 3
	v_add_f32_e32 v5, s98, v5
	v_add_f32_e32 v5, s99, v5
	v_mul_f32_e32 v5, 0x3a800000, v5
	v_add_f32_e32 v5, 0x358637bd, v5
	v_rsq_f32_e32 v6, v5
	s_nop 0
	s_add_u32 s98, s97, 12
	v_pk_mul_f32 v[16:17], v[16:17], v[6:7] op_sel_hi:[1,0]
	v_pk_mul_f32 v[18:19], v[18:19], v[6:7] op_sel_hi:[1,0]
	v_pk_mul_f32 v[20:21], v[20:21], v[6:7] op_sel_hi:[1,0]
	v_pk_mul_f32 v[22:23], v[22:23], v[6:7] op_sel_hi:[1,0]
	v_pk_mul_f32 v[24:25], v[24:25], v[6:7] op_sel_hi:[1,0]
	v_pk_mul_f32 v[26:27], v[26:27], v[6:7] op_sel_hi:[1,0]
	v_pk_mul_f32 v[28:29], v[28:29], v[6:7] op_sel_hi:[1,0]
	v_pk_mul_f32 v[30:31], v[30:31], v[6:7] op_sel_hi:[1,0]
	v_pk_mul_f32 v[16:17], v[16:17], v[112:113]
	v_pk_mul_f32 v[18:19], v[18:19], v[114:115]
	v_pk_mul_f32 v[20:21], v[20:21], v[116:117]
	v_pk_mul_f32 v[22:23], v[22:23], v[118:119]
	v_pk_mul_f32 v[24:25], v[24:25], v[120:121]
	v_pk_mul_f32 v[26:27], v[26:27], v[122:123]
	v_pk_mul_f32 v[28:29], v[28:29], v[124:125]
	v_pk_mul_f32 v[30:31], v[30:31], v[126:127]
	v_pk_fma_f32 v[16:17], v[16:17], v[128:129], v[144:145]
	v_pk_fma_f32 v[18:19], v[18:19], v[130:131], v[146:147]
	v_pk_fma_f32 v[20:21], v[20:21], v[132:133], v[148:149]
	v_pk_fma_f32 v[22:23], v[22:23], v[134:135], v[150:151]
	v_pk_fma_f32 v[24:25], v[24:25], v[136:137], v[152:153]
	v_pk_fma_f32 v[26:27], v[26:27], v[138:139], v[154:155]
	v_pk_fma_f32 v[28:29], v[28:29], v[140:141], v[156:157]
	v_pk_fma_f32 v[30:31], v[30:31], v[142:143], v[158:159]
	v_cvt_pk_bf16_f32 v16, v16, v17
	v_cvt_pk_bf16_f32 v17, v18, v19
	v_cvt_pk_bf16_f32 v18, v20, v21
	v_cvt_pk_bf16_f32 v19, v22, v23
	v_cvt_pk_bf16_f32 v20, v24, v25
	v_cvt_pk_bf16_f32 v21, v26, v27
	v_cvt_pk_bf16_f32 v22, v28, v29
	v_cvt_pk_bf16_f32 v23, v30, v31
	s_lshl_b32 s99, s98, 11
	v_lshl_add_u32 v8, v0, 3, s99
	global_store_dwordx2 v8, v[16:17], s[94:95]
	global_store_dwordx2 v8, v[18:19], s[94:95] offset:512
	global_store_dwordx2 v8, v[20:21], s[94:95] offset:1024
	global_store_dwordx2 v8, v[22:23], s[94:95] offset:1536
	s_lshl_b32 s99, s98, 2
	v_mov_b32_e32 v9, s99
	v_mov_b32_e32 v10, 0
	v_cmp_eq_u32_e32 vcc, 0, v0
	s_and_saveexec_b64 s[98:99], vcc
	global_store_dword v9, v10, s[90:91]
	global_store_dword v9, v10, s[92:93]
	s_or_b64 exec, exec, s[98:99]
	s_waitcnt vmcnt(38)
	v_mul_f32_e32 v4, v32, v32
	v_fma_f32 v4, v33, v33, v4
	v_fma_f32 v4, v34, v34, v4
	v_fma_f32 v4, v35, v35, v4
	v_fma_f32 v4, v36, v36, v4
	v_fma_f32 v4, v37, v37, v4
	v_fma_f32 v4, v38, v38, v4
	v_fma_f32 v4, v39, v39, v4
	v_fma_f32 v4, v40, v40, v4
	v_fma_f32 v4, v41, v41, v4
	v_fma_f32 v4, v42, v42, v4
	v_fma_f32 v4, v43, v43, v4
	v_fma_f32 v4, v44, v44, v4
	v_fma_f32 v4, v45, v45, v4
	v_fma_f32 v4, v46, v46, v4
	v_fma_f32 v4, v47, v47, v4
	s_nop 1
	v_add_f32_dpp v5, v4, v4 quad_perm:[1,0,3,2] row_mask:0xf bank_mask:0xf
	s_nop 1
	v_add_f32_dpp v4, v5, v5 quad_perm:[2,3,0,1] row_mask:0xf bank_mask:0xf
	s_nop 1
	v_add_f32_dpp v5, v4, v4 row_half_mirror row_mask:0xf bank_mask:0xf
	s_nop 1
	v_add_f32_dpp v4, v5, v5 row_mirror row_mask:0xf bank_mask:0xf
	s_nop 1
	v_readlane_b32 s98, v4, 0
	v_readlane_b32 s99, v4, 16
	s_nop 3
	v_mov_b32_e32 v5, s98
	v_add_f32_e32 v5, s99, v5
	v_readlane_b32 s98, v4, 32
	v_readlane_b32 s99, v4, 48
	s_nop 3
	v_add_f32_e32 v5, s98, v5
	v_add_f32_e32 v5, s99, v5
	v_mul_f32_e32 v5, 0x3a800000, v5
	v_add_f32_e32 v5, 0x358637bd, v5
	v_rsq_f32_e32 v6, v5
	s_nop 0
	s_add_u32 s98, s97, 13
	v_pk_mul_f32 v[32:33], v[32:33], v[6:7] op_sel_hi:[1,0]
	v_pk_mul_f32 v[34:35], v[34:35], v[6:7] op_sel_hi:[1,0]
	v_pk_mul_f32 v[36:37], v[36:37], v[6:7] op_sel_hi:[1,0]
	v_pk_mul_f32 v[38:39], v[38:39], v[6:7] op_sel_hi:[1,0]
	v_pk_mul_f32 v[40:41], v[40:41], v[6:7] op_sel_hi:[1,0]
	v_pk_mul_f32 v[42:43], v[42:43], v[6:7] op_sel_hi:[1,0]
	v_pk_mul_f32 v[44:45], v[44:45], v[6:7] op_sel_hi:[1,0]
	v_pk_mul_f32 v[46:47], v[46:47], v[6:7] op_sel_hi:[1,0]
	v_pk_mul_f32 v[32:33], v[32:33], v[112:113]
	v_pk_mul_f32 v[34:35], v[34:35], v[114:115]
	v_pk_mul_f32 v[36:37], v[36:37], v[116:117]
	v_pk_mul_f32 v[38:39], v[38:39], v[118:119]
	v_pk_mul_f32 v[40:41], v[40:41], v[120:121]
	v_pk_mul_f32 v[42:43], v[42:43], v[122:123]
	v_pk_mul_f32 v[44:45], v[44:45], v[124:125]
	v_pk_mul_f32 v[46:47], v[46:47], v[126:127]
	v_pk_fma_f32 v[32:33], v[32:33], v[128:129], v[144:145]
	v_pk_fma_f32 v[34:35], v[34:35], v[130:131], v[146:147]
	v_pk_fma_f32 v[36:37], v[36:37], v[132:133], v[148:149]
	v_pk_fma_f32 v[38:39], v[38:39], v[134:135], v[150:151]
	v_pk_fma_f32 v[40:41], v[40:41], v[136:137], v[152:153]
	v_pk_fma_f32 v[42:43], v[42:43], v[138:139], v[154:155]
	v_pk_fma_f32 v[44:45], v[44:45], v[140:141], v[156:157]
	v_pk_fma_f32 v[46:47], v[46:47], v[142:143], v[158:159]
	v_cvt_pk_bf16_f32 v32, v32, v33
	v_cvt_pk_bf16_f32 v33, v34, v35
	v_cvt_pk_bf16_f32 v34, v36, v37
	v_cvt_pk_bf16_f32 v35, v38, v39
	v_cvt_pk_bf16_f32 v36, v40, v41
	v_cvt_pk_bf16_f32 v37, v42, v43
	v_cvt_pk_bf16_f32 v38, v44, v45
	v_cvt_pk_bf16_f32 v39, v46, v47
	s_lshl_b32 s99, s98, 11
	v_lshl_add_u32 v8, v0, 3, s99
	global_store_dwordx2 v8, v[32:33], s[94:95]
	global_store_dwordx2 v8, v[34:35], s[94:95] offset:512
	global_store_dwordx2 v8, v[36:37], s[94:95] offset:1024
	global_store_dwordx2 v8, v[38:39], s[94:95] offset:1536
	s_lshl_b32 s99, s98, 2
	v_mov_b32_e32 v9, s99
	v_mov_b32_e32 v10, 0
	v_cmp_eq_u32_e32 vcc, 0, v0
	s_and_saveexec_b64 s[98:99], vcc
	global_store_dword v9, v10, s[90:91]
	global_store_dword v9, v10, s[92:93]
	s_or_b64 exec, exec, s[98:99]
	s_waitcnt vmcnt(34)
	v_mul_f32_e32 v4, v48, v48
	v_fma_f32 v4, v49, v49, v4
	v_fma_f32 v4, v50, v50, v4
	v_fma_f32 v4, v51, v51, v4
	v_fma_f32 v4, v52, v52, v4
	v_fma_f32 v4, v53, v53, v4
	v_fma_f32 v4, v54, v54, v4
	v_fma_f32 v4, v55, v55, v4
	v_fma_f32 v4, v56, v56, v4
	v_fma_f32 v4, v57, v57, v4
	v_fma_f32 v4, v58, v58, v4
	v_fma_f32 v4, v59, v59, v4
	v_fma_f32 v4, v60, v60, v4
	v_fma_f32 v4, v61, v61, v4
	v_fma_f32 v4, v62, v62, v4
	v_fma_f32 v4, v63, v63, v4
	s_nop 1
	v_add_f32_dpp v5, v4, v4 quad_perm:[1,0,3,2] row_mask:0xf bank_mask:0xf
	s_nop 1
	v_add_f32_dpp v4, v5, v5 quad_perm:[2,3,0,1] row_mask:0xf bank_mask:0xf
	s_nop 1
	v_add_f32_dpp v5, v4, v4 row_half_mirror row_mask:0xf bank_mask:0xf
	s_nop 1
	v_add_f32_dpp v4, v5, v5 row_mirror row_mask:0xf bank_mask:0xf
	s_nop 1
	v_readlane_b32 s98, v4, 0
	v_readlane_b32 s99, v4, 16
	s_nop 3
	v_mov_b32_e32 v5, s98
	v_add_f32_e32 v5, s99, v5
	v_readlane_b32 s98, v4, 32
	v_readlane_b32 s99, v4, 48
	s_nop 3
	v_add_f32_e32 v5, s98, v5
	v_add_f32_e32 v5, s99, v5
	v_mul_f32_e32 v5, 0x3a800000, v5
	v_add_f32_e32 v5, 0x358637bd, v5
	v_rsq_f32_e32 v6, v5
	s_nop 0
	s_add_u32 s98, s97, 14
	v_pk_mul_f32 v[48:49], v[48:49], v[6:7] op_sel_hi:[1,0]
	v_pk_mul_f32 v[50:51], v[50:51], v[6:7] op_sel_hi:[1,0]
	v_pk_mul_f32 v[52:53], v[52:53], v[6:7] op_sel_hi:[1,0]
	v_pk_mul_f32 v[54:55], v[54:55], v[6:7] op_sel_hi:[1,0]
	v_pk_mul_f32 v[56:57], v[56:57], v[6:7] op_sel_hi:[1,0]
	v_pk_mul_f32 v[58:59], v[58:59], v[6:7] op_sel_hi:[1,0]
	v_pk_mul_f32 v[60:61], v[60:61], v[6:7] op_sel_hi:[1,0]
	v_pk_mul_f32 v[62:63], v[62:63], v[6:7] op_sel_hi:[1,0]
	v_pk_mul_f32 v[48:49], v[48:49], v[112:113]
	v_pk_mul_f32 v[50:51], v[50:51], v[114:115]
	v_pk_mul_f32 v[52:53], v[52:53], v[116:117]
	v_pk_mul_f32 v[54:55], v[54:55], v[118:119]
	v_pk_mul_f32 v[56:57], v[56:57], v[120:121]
	v_pk_mul_f32 v[58:59], v[58:59], v[122:123]
	v_pk_mul_f32 v[60:61], v[60:61], v[124:125]
	v_pk_mul_f32 v[62:63], v[62:63], v[126:127]
	v_pk_fma_f32 v[48:49], v[48:49], v[128:129], v[144:145]
	v_pk_fma_f32 v[50:51], v[50:51], v[130:131], v[146:147]
	v_pk_fma_f32 v[52:53], v[52:53], v[132:133], v[148:149]
	v_pk_fma_f32 v[54:55], v[54:55], v[134:135], v[150:151]
	v_pk_fma_f32 v[56:57], v[56:57], v[136:137], v[152:153]
	v_pk_fma_f32 v[58:59], v[58:59], v[138:139], v[154:155]
	v_pk_fma_f32 v[60:61], v[60:61], v[140:141], v[156:157]
	v_pk_fma_f32 v[62:63], v[62:63], v[142:143], v[158:159]
	v_cvt_pk_bf16_f32 v48, v48, v49
	v_cvt_pk_bf16_f32 v49, v50, v51
	v_cvt_pk_bf16_f32 v50, v52, v53
	v_cvt_pk_bf16_f32 v51, v54, v55
	v_cvt_pk_bf16_f32 v52, v56, v57
	v_cvt_pk_bf16_f32 v53, v58, v59
	v_cvt_pk_bf16_f32 v54, v60, v61
	v_cvt_pk_bf16_f32 v55, v62, v63
	s_lshl_b32 s99, s98, 11
	v_lshl_add_u32 v8, v0, 3, s99
	global_store_dwordx2 v8, v[48:49], s[94:95]
	global_store_dwordx2 v8, v[50:51], s[94:95] offset:512
	global_store_dwordx2 v8, v[52:53], s[94:95] offset:1024
	global_store_dwordx2 v8, v[54:55], s[94:95] offset:1536
	s_lshl_b32 s99, s98, 2
	v_mov_b32_e32 v9, s99
	v_mov_b32_e32 v10, 0
	v_cmp_eq_u32_e32 vcc, 0, v0
	s_and_saveexec_b64 s[98:99], vcc
	global_store_dword v9, v10, s[90:91]
	global_store_dword v9, v10, s[92:93]
	s_or_b64 exec, exec, s[98:99]
	s_waitcnt vmcnt(30)
	v_mul_f32_e32 v4, v64, v64
	v_fma_f32 v4, v65, v65, v4
	v_fma_f32 v4, v66, v66, v4
	v_fma_f32 v4, v67, v67, v4
	v_fma_f32 v4, v68, v68, v4
	v_fma_f32 v4, v69, v69, v4
	v_fma_f32 v4, v70, v70, v4
	v_fma_f32 v4, v71, v71, v4
	v_fma_f32 v4, v72, v72, v4
	v_fma_f32 v4, v73, v73, v4
	v_fma_f32 v4, v74, v74, v4
	v_fma_f32 v4, v75, v75, v4
	v_fma_f32 v4, v76, v76, v4
	v_fma_f32 v4, v77, v77, v4
	v_fma_f32 v4, v78, v78, v4
	v_fma_f32 v4, v79, v79, v4
	s_nop 1
	v_add_f32_dpp v5, v4, v4 quad_perm:[1,0,3,2] row_mask:0xf bank_mask:0xf
	s_nop 1
	v_add_f32_dpp v4, v5, v5 quad_perm:[2,3,0,1] row_mask:0xf bank_mask:0xf
	s_nop 1
	v_add_f32_dpp v5, v4, v4 row_half_mirror row_mask:0xf bank_mask:0xf
	s_nop 1
	v_add_f32_dpp v4, v5, v5 row_mirror row_mask:0xf bank_mask:0xf
	s_nop 1
	v_readlane_b32 s98, v4, 0
	v_readlane_b32 s99, v4, 16
	s_nop 3
	v_mov_b32_e32 v5, s98
	v_add_f32_e32 v5, s99, v5
	v_readlane_b32 s98, v4, 32
	v_readlane_b32 s99, v4, 48
	s_nop 3
	v_add_f32_e32 v5, s98, v5
	v_add_f32_e32 v5, s99, v5
	v_mul_f32_e32 v5, 0x3a800000, v5
	v_add_f32_e32 v5, 0x358637bd, v5
	v_rsq_f32_e32 v6, v5
	s_nop 0
	s_add_u32 s98, s97, 15
	v_pk_mul_f32 v[64:65], v[64:65], v[6:7] op_sel_hi:[1,0]
	v_pk_mul_f32 v[66:67], v[66:67], v[6:7] op_sel_hi:[1,0]
	v_pk_mul_f32 v[68:69], v[68:69], v[6:7] op_sel_hi:[1,0]
	v_pk_mul_f32 v[70:71], v[70:71], v[6:7] op_sel_hi:[1,0]
	v_pk_mul_f32 v[72:73], v[72:73], v[6:7] op_sel_hi:[1,0]
	v_pk_mul_f32 v[74:75], v[74:75], v[6:7] op_sel_hi:[1,0]
	v_pk_mul_f32 v[76:77], v[76:77], v[6:7] op_sel_hi:[1,0]
	v_pk_mul_f32 v[78:79], v[78:79], v[6:7] op_sel_hi:[1,0]
	v_pk_mul_f32 v[64:65], v[64:65], v[112:113]
	v_pk_mul_f32 v[66:67], v[66:67], v[114:115]
	v_pk_mul_f32 v[68:69], v[68:69], v[116:117]
	v_pk_mul_f32 v[70:71], v[70:71], v[118:119]
	v_pk_mul_f32 v[72:73], v[72:73], v[120:121]
	v_pk_mul_f32 v[74:75], v[74:75], v[122:123]
	v_pk_mul_f32 v[76:77], v[76:77], v[124:125]
	v_pk_mul_f32 v[78:79], v[78:79], v[126:127]
	v_pk_fma_f32 v[64:65], v[64:65], v[128:129], v[144:145]
	v_pk_fma_f32 v[66:67], v[66:67], v[130:131], v[146:147]
	v_pk_fma_f32 v[68:69], v[68:69], v[132:133], v[148:149]
	v_pk_fma_f32 v[70:71], v[70:71], v[134:135], v[150:151]
	v_pk_fma_f32 v[72:73], v[72:73], v[136:137], v[152:153]
	v_pk_fma_f32 v[74:75], v[74:75], v[138:139], v[154:155]
	v_pk_fma_f32 v[76:77], v[76:77], v[140:141], v[156:157]
	v_pk_fma_f32 v[78:79], v[78:79], v[142:143], v[158:159]
	v_cvt_pk_bf16_f32 v64, v64, v65
	v_cvt_pk_bf16_f32 v65, v66, v67
	v_cvt_pk_bf16_f32 v66, v68, v69
	v_cvt_pk_bf16_f32 v67, v70, v71
	v_cvt_pk_bf16_f32 v68, v72, v73
	v_cvt_pk_bf16_f32 v69, v74, v75
	v_cvt_pk_bf16_f32 v70, v76, v77
	v_cvt_pk_bf16_f32 v71, v78, v79
	s_lshl_b32 s99, s98, 11
	v_lshl_add_u32 v8, v0, 3, s99
	global_store_dwordx2 v8, v[64:65], s[94:95]
	global_store_dwordx2 v8, v[66:67], s[94:95] offset:512
	global_store_dwordx2 v8, v[68:69], s[94:95] offset:1024
	global_store_dwordx2 v8, v[70:71], s[94:95] offset:1536
	s_lshl_b32 s99, s98, 2
	v_mov_b32_e32 v9, s99
	v_mov_b32_e32 v10, 0
	v_cmp_eq_u32_e32 vcc, 0, v0
	s_and_saveexec_b64 s[98:99], vcc
	global_store_dword v9, v10, s[90:91]
	global_store_dword v9, v10, s[92:93]
	s_or_b64 exec, exec, s[98:99]
	s_waitcnt vmcnt(0)

.LBB0_4600:
	s_cmp_gt_i32 s44, 17
	s_cselect_b64 s[2:3], -1, 0
	s_cmp_lt_i32 s45, 18
	s_cselect_b64 s[4:5], -1, 0
	s_or_b64 s[2:3], s[2:3], s[4:5]
	s_and_b64 vcc, exec, s[2:3]
	s_cbranch_vccnz .LBB0_4660
	s_lshl_b32 s96, s22, 3
	s_lshr_b32 s97, s70, 6
	s_add_u32 s96, s96, s97
	s_lshl_b32 s97, s96, 4
	s_cmpk_ge_u32 s97, 0x8000
	s_cbranch_scc1 .Lnp17_done
	s_load_dwordx2 s[88:89], s[0:1], 0xb8
	s_load_dwordx2 s[90:91], s[0:1], 0x18
	s_load_dwordx2 s[92:93], s[0:1], 0x140
	s_load_dwordx2 s[94:95], s[0:1], 0x158
	v_mbcnt_hi_u32_b32 v0, -1, v210
	v_lshlrev_b32_e32 v1, 4, v0
	s_waitcnt lgkmcnt(0)
	s_add_u32 s90, s90, 12288
	s_addc_u32 s91, s91, 0
	global_load_dwordx4 v[112:115], v1, s[90:91] nt
	global_load_dwordx4 v[116:119], v1, s[90:91] offset:1024 nt
	global_load_dwordx4 v[120:123], v1, s[90:91] offset:2048 nt
	global_load_dwordx4 v[124:127], v1, s[90:91] offset:3072 nt
	s_lshr_b32 s98, s97, 12
	s_add_u32 s98, s98, 24
	s_mul_i32 s98, s98, 0x3000
	s_add_u32 s92, s92, s98
	s_addc_u32 s93, s93, 0
	global_load_dwordx4 v[144:147], v1, s[92:93] nt
	global_load_dwordx4 v[148:151], v1, s[92:93] offset:1024 nt
	global_load_dwordx4 v[152:155], v1, s[92:93] offset:2048 nt
	global_load_dwordx4 v[156:159], v1, s[92:93] offset:3072 nt
	s_add_u32 s92, s92, 0x1000
	s_addc_u32 s93, s93, 0
	global_load_dwordx4 v[128:131], v1, s[92:93] nt
	global_load_dwordx4 v[132:135], v1, s[92:93] offset:1024 nt
	global_load_dwordx4 v[136:139], v1, s[92:93] offset:2048 nt
	global_load_dwordx4 v[140:143], v1, s[92:93] offset:3072 nt
	s_load_dwordx2 s[90:91], s[0:1], 0x210
	s_load_dwordx2 s[92:93], s[0:1], 0x218
	s_waitcnt vmcnt(0) lgkmcnt(0)
	v_pk_add_f32 v[128:129], v[128:129], 1.0 op_sel_hi:[1,0]
	v_pk_add_f32 v[130:131], v[130:131], 1.0 op_sel_hi:[1,0]
	v_pk_add_f32 v[132:133], v[132:133], 1.0 op_sel_hi:[1,0]
	v_pk_add_f32 v[134:135], v[134:135], 1.0 op_sel_hi:[1,0]
	v_pk_add_f32 v[136:137], v[136:137], 1.0 op_sel_hi:[1,0]
	v_pk_add_f32 v[138:139], v[138:139], 1.0 op_sel_hi:[1,0]
	v_pk_add_f32 v[140:141], v[140:141], 1.0 op_sel_hi:[1,0]
	v_pk_add_f32 v[142:143], v[142:143], 1.0 op_sel_hi:[1,0]
	s_add_u32 s98, s97, 0
	s_lshl_b32 s98, s98, 12
	v_add_u32_e32 v3, s98, v1
	global_load_dwordx4 v[16:19], v3, s[88:89] nt
	global_load_dwordx4 v[20:23], v3, s[88:89] offset:1024 nt
	global_load_dwordx4 v[24:27], v3, s[88:89] offset:2048 nt
	global_load_dwordx4 v[28:31], v3, s[88:89] offset:3072 nt
	s_add_u32 s98, s97, 1
	s_lshl_b32 s98, s98, 12
	v_add_u32_e32 v3, s98, v1
	global_load_dwordx4 v[32:35], v3, s[88:89] nt
	global_load_dwordx4 v[36:39], v3, s[88:89] offset:1024 nt
	global_load_dwordx4 v[40:43], v3, s[88:89] offset:2048 nt
	global_load_dwordx4 v[44:47], v3, s[88:89] offset:3072 nt
	s_add_u32 s98, s97, 2
	s_lshl_b32 s98, s98, 12
	v_add_u32_e32 v3, s98, v1
	global_load_dwordx4 v[48:51], v3, s[88:89] nt
	global_load_dwordx4 v[52:55], v3, s[88:89] offset:1024 nt
	global_load_dwordx4 v[56:59], v3, s[88:89] offset:2048 nt
	global_load_dwordx4 v[60:63], v3, s[88:89] offset:3072 nt
	s_add_u32 s98, s97, 3
	s_lshl_b32 s98, s98, 12
	v_add_u32_e32 v3, s98, v1
	global_load_dwordx4 v[64:67], v3, s[88:89] nt
	global_load_dwordx4 v[68:71], v3, s[88:89] offset:1024 nt
	global_load_dwordx4 v[72:75], v3, s[88:89] offset:2048 nt
	global_load_dwordx4 v[76:79], v3, s[88:89] offset:3072 nt
	s_add_u32 s98, s97, 4
	s_lshl_b32 s98, s98, 12
	v_add_u32_e32 v3, s98, v1
	global_load_dwordx4 v[80:83], v3, s[88:89] nt
	global_load_dwordx4 v[84:87], v3, s[88:89] offset:1024 nt
	global_load_dwordx4 v[88:91], v3, s[88:89] offset:2048 nt
	global_load_dwordx4 v[92:95], v3, s[88:89] offset:3072 nt
	s_add_u32 s98, s97, 5
	s_lshl_b32 s98, s98, 12
	v_add_u32_e32 v3, s98, v1
	global_load_dwordx4 v[96:99], v3, s[88:89] nt
	global_load_dwordx4 v[100:103], v3, s[88:89] offset:1024 nt
	global_load_dwordx4 v[104:107], v3, s[88:89] offset:2048 nt
	global_load_dwordx4 v[108:111], v3, s[88:89] offset:3072 nt
	s_waitcnt vmcnt(20)
	v_mul_f32_e32 v4, v16, v16
	v_fma_f32 v4, v17, v17, v4
	v_fma_f32 v4, v18, v18, v4
	v_fma_f32 v4, v19, v19, v4
	v_fma_f32 v4, v20, v20, v4
	v_fma_f32 v4, v21, v21, v4
	v_fma_f32 v4, v22, v22, v4
	v_fma_f32 v4, v23, v23, v4
	v_fma_f32 v4, v24, v24, v4
	v_fma_f32 v4, v25, v25, v4
	v_fma_f32 v4, v26, v26, v4
	v_fma_f32 v4, v27, v27, v4
	v_fma_f32 v4, v28, v28, v4
	v_fma_f32 v4, v29, v29, v4
	v_fma_f32 v4, v30, v30, v4
	v_fma_f32 v4, v31, v31, v4
	s_nop 1
	v_add_f32_dpp v5, v4, v4 quad_perm:[1,0,3,2] row_mask:0xf bank_mask:0xf
	s_nop 1
	v_add_f32_dpp v4, v5, v5 quad_perm:[2,3,0,1] row_mask:0xf bank_mask:0xf
	s_nop 1
	v_add_f32_dpp v5, v4, v4 row_half_mirror row_mask:0xf bank_mask:0xf
	s_nop 1
	v_add_f32_dpp v4, v5, v5 row_mirror row_mask:0xf bank_mask:0xf
	s_nop 1
	v_readlane_b32 s98, v4, 0
	v_readlane_b32 s99, v4, 16
	s_nop 3
	v_mov_b32_e32 v5, s98
	v_add_f32_e32 v5, s99, v5
	v_readlane_b32 s98, v4, 32
	v_readlane_b32 s99, v4, 48
	s_nop 3
	v_add_f32_e32 v5, s98, v5
	v_add_f32_e32 v5, s99, v5
	v_mul_f32_e32 v5, 0x3a800000, v5
	v_add_f32_e32 v5, 0x358637bd, v5
	v_rsq_f32_e32 v6, v5
	s_nop 0
	s_add_u32 s98, s97, 0
	v_pk_mul_f32 v[16:17], v[16:17], v[6:7] op_sel_hi:[1,0]
	v_pk_mul_f32 v[18:19], v[18:19], v[6:7] op_sel_hi:[1,0]
	v_pk_mul_f32 v[20:21], v[20:21], v[6:7] op_sel_hi:[1,0]
	v_pk_mul_f32 v[22:23], v[22:23], v[6:7] op_sel_hi:[1,0]
	v_pk_mul_f32 v[24:25], v[24:25], v[6:7] op_sel_hi:[1,0]
	v_pk_mul_f32 v[26:27], v[26:27], v[6:7] op_sel_hi:[1,0]
	v_pk_mul_f32 v[28:29], v[28:29], v[6:7] op_sel_hi:[1,0]
	v_pk_mul_f32 v[30:31], v[30:31], v[6:7] op_sel_hi:[1,0]
	v_pk_mul_f32 v[16:17], v[16:17], v[112:113]
	v_pk_mul_f32 v[18:19], v[18:19], v[114:115]
	v_pk_mul_f32 v[20:21], v[20:21], v[116:117]
	v_pk_mul_f32 v[22:23], v[22:23], v[118:119]
	v_pk_mul_f32 v[24:25], v[24:25], v[120:121]
	v_pk_mul_f32 v[26:27], v[26:27], v[122:123]
	v_pk_mul_f32 v[28:29], v[28:29], v[124:125]
	v_pk_mul_f32 v[30:31], v[30:31], v[126:127]
	v_pk_fma_f32 v[16:17], v[16:17], v[128:129], v[144:145]
	v_pk_fma_f32 v[18:19], v[18:19], v[130:131], v[146:147]
	v_pk_fma_f32 v[20:21], v[20:21], v[132:133], v[148:149]
	v_pk_fma_f32 v[22:23], v[22:23], v[134:135], v[150:151]
	v_pk_fma_f32 v[24:25], v[24:25], v[136:137], v[152:153]
	v_pk_fma_f32 v[26:27], v[26:27], v[138:139], v[154:155]
	v_pk_fma_f32 v[28:29], v[28:29], v[140:141], v[156:157]
	v_pk_fma_f32 v[30:31], v[30:31], v[142:143], v[158:159]
	v_cvt_pk_bf16_f32 v16, v16, v17
	v_cvt_pk_bf16_f32 v17, v18, v19
	v_cvt_pk_bf16_f32 v18, v20, v21
	v_cvt_pk_bf16_f32 v19, v22, v23
	v_cvt_pk_bf16_f32 v20, v24, v25
	v_cvt_pk_bf16_f32 v21, v26, v27
	v_cvt_pk_bf16_f32 v22, v28, v29
	v_cvt_pk_bf16_f32 v23, v30, v31
	s_lshl_b32 s99, s98, 11
	v_lshl_add_u32 v8, v0, 3, s99
	global_store_dwordx2 v8, v[16:17], s[94:95]
	global_store_dwordx2 v8, v[18:19], s[94:95] offset:512
	global_store_dwordx2 v8, v[20:21], s[94:95] offset:1024
	global_store_dwordx2 v8, v[22:23], s[94:95] offset:1536
	s_lshl_b32 s99, s98, 2
	v_mov_b32_e32 v9, s99
	v_mov_b32_e32 v10, 0
	v_cmp_eq_u32_e32 vcc, 0, v0
	s_and_saveexec_b64 s[98:99], vcc
	global_store_dword v9, v10, s[90:91]
	global_store_dword v9, v10, s[92:93]
	s_or_b64 exec, exec, s[98:99]
	s_add_u32 s98, s97, 6
	s_lshl_b32 s98, s98, 12
	v_add_u32_e32 v3, s98, v1
	global_load_dwordx4 v[16:19], v3, s[88:89] nt
	global_load_dwordx4 v[20:23], v3, s[88:89] offset:1024 nt
	global_load_dwordx4 v[24:27], v3, s[88:89] offset:2048 nt
	global_load_dwordx4 v[28:31], v3, s[88:89] offset:3072 nt
	s_waitcnt vmcnt(26)
	v_mul_f32_e32 v4, v32, v32
	v_fma_f32 v4, v33, v33, v4
	v_fma_f32 v4, v34, v34, v4
	v_fma_f32 v4, v35, v35, v4
	v_fma_f32 v4, v36, v36, v4
	v_fma_f32 v4, v37, v37, v4
	v_fma_f32 v4, v38, v38, v4
	v_fma_f32 v4, v39, v39, v4
	v_fma_f32 v4, v40, v40, v4
	v_fma_f32 v4, v41, v41, v4
	v_fma_f32 v4, v42, v42, v4
	v_fma_f32 v4, v43, v43, v4
	v_fma_f32 v4, v44, v44, v4
	v_fma_f32 v4, v45, v45, v4
	v_fma_f32 v4, v46, v46, v4
	v_fma_f32 v4, v47, v47, v4
	s_nop 1
	v_add_f32_dpp v5, v4, v4 quad_perm:[1,0,3,2] row_mask:0xf bank_mask:0xf
	s_nop 1
	v_add_f32_dpp v4, v5, v5 quad_perm:[2,3,0,1] row_mask:0xf bank_mask:0xf
	s_nop 1
	v_add_f32_dpp v5, v4, v4 row_half_mirror row_mask:0xf bank_mask:0xf
	s_nop 1
	v_add_f32_dpp v4, v5, v5 row_mirror row_mask:0xf bank_mask:0xf
	s_nop 1
	v_readlane_b32 s98, v4, 0
	v_readlane_b32 s99, v4, 16
	s_nop 3
	v_mov_b32_e32 v5, s98
	v_add_f32_e32 v5, s99, v5
	v_readlane_b32 s98, v4, 32
	v_readlane_b32 s99, v4, 48
	s_nop 3
	v_add_f32_e32 v5, s98, v5
	v_add_f32_e32 v5, s99, v5
	v_mul_f32_e32 v5, 0x3a800000, v5
	v_add_f32_e32 v5, 0x358637bd, v5
	v_rsq_f32_e32 v6, v5
	s_nop 0
	s_add_u32 s98, s97, 1
	v_pk_mul_f32 v[32:33], v[32:33], v[6:7] op_sel_hi:[1,0]
	v_pk_mul_f32 v[34:35], v[34:35], v[6:7] op_sel_hi:[1,0]
	v_pk_mul_f32 v[36:37], v[36:37], v[6:7] op_sel_hi:[1,0]
	v_pk_mul_f32 v[38:39], v[38:39], v[6:7] op_sel_hi:[1,0]
	v_pk_mul_f32 v[40:41], v[40:41], v[6:7] op_sel_hi:[1,0]
	v_pk_mul_f32 v[42:43], v[42:43], v[6:7] op_sel_hi:[1,0]
	v_pk_mul_f32 v[44:45], v[44:45], v[6:7] op_sel_hi:[1,0]
	v_pk_mul_f32 v[46:47], v[46:47], v[6:7] op_sel_hi:[1,0]
	v_pk_mul_f32 v[32:33], v[32:33], v[112:113]
	v_pk_mul_f32 v[34:35], v[34:35], v[114:115]
	v_pk_mul_f32 v[36:37], v[36:37], v[116:117]
	v_pk_mul_f32 v[38:39], v[38:39], v[118:119]
	v_pk_mul_f32 v[40:41], v[40:41], v[120:121]
	v_pk_mul_f32 v[42:43], v[42:43], v[122:123]
	v_pk_mul_f32 v[44:45], v[44:45], v[124:125]
	v_pk_mul_f32 v[46:47], v[46:47], v[126:127]
	v_pk_fma_f32 v[32:33], v[32:33], v[128:129], v[144:145]
	v_pk_fma_f32 v[34:35], v[34:35], v[130:131], v[146:147]
	v_pk_fma_f32 v[36:37], v[36:37], v[132:133], v[148:149]
	v_pk_fma_f32 v[38:39], v[38:39], v[134:135], v[150:151]
	v_pk_fma_f32 v[40:41], v[40:41], v[136:137], v[152:153]
	v_pk_fma_f32 v[42:43], v[42:43], v[138:139], v[154:155]
	v_pk_fma_f32 v[44:45], v[44:45], v[140:141], v[156:157]
	v_pk_fma_f32 v[46:47], v[46:47], v[142:143], v[158:159]
	v_cvt_pk_bf16_f32 v32, v32, v33
	v_cvt_pk_bf16_f32 v33, v34, v35
	v_cvt_pk_bf16_f32 v34, v36, v37
	v_cvt_pk_bf16_f32 v35, v38, v39
	v_cvt_pk_bf16_f32 v36, v40, v41
	v_cvt_pk_bf16_f32 v37, v42, v43
	v_cvt_pk_bf16_f32 v38, v44, v45
	v_cvt_pk_bf16_f32 v39, v46, v47
	s_lshl_b32 s99, s98, 11
	v_lshl_add_u32 v8, v0, 3, s99
	global_store_dwordx2 v8, v[32:33], s[94:95]
	global_store_dwordx2 v8, v[34:35], s[94:95] offset:512
	global_store_dwordx2 v8, v[36:37], s[94:95] offset:1024
	global_store_dwordx2 v8, v[38:39], s[94:95] offset:1536
	s_lshl_b32 s99, s98, 2
	v_mov_b32_e32 v9, s99
	v_mov_b32_e32 v10, 0
	v_cmp_eq_u32_e32 vcc, 0, v0
	s_and_saveexec_b64 s[98:99], vcc
	global_store_dword v9, v10, s[90:91]
	global_store_dword v9, v10, s[92:93]
	s_or_b64 exec, exec, s[98:99]
	s_add_u32 s98, s97, 7
	s_lshl_b32 s98, s98, 12
	v_add_u32_e32 v3, s98, v1
	global_load_dwordx4 v[32:35], v3, s[88:89] nt
	global_load_dwordx4 v[36:39], v3, s[88:89] offset:1024 nt
	global_load_dwordx4 v[40:43], v3, s[88:89] offset:2048 nt
	global_load_dwordx4 v[44:47], v3, s[88:89] offset:3072 nt
	s_waitcnt vmcnt(32)
	v_mul_f32_e32 v4, v48, v48
	v_fma_f32 v4, v49, v49, v4
	v_fma_f32 v4, v50, v50, v4
	v_fma_f32 v4, v51, v51, v4
	v_fma_f32 v4, v52, v52, v4
	v_fma_f32 v4, v53, v53, v4
	v_fma_f32 v4, v54, v54, v4
	v_fma_f32 v4, v55, v55, v4
	v_fma_f32 v4, v56, v56, v4
	v_fma_f32 v4, v57, v57, v4
	v_fma_f32 v4, v58, v58, v4
	v_fma_f32 v4, v59, v59, v4
	v_fma_f32 v4, v60, v60, v4
	v_fma_f32 v4, v61, v61, v4
	v_fma_f32 v4, v62, v62, v4
	v_fma_f32 v4, v63, v63, v4
	s_nop 1
	v_add_f32_dpp v5, v4, v4 quad_perm:[1,0,3,2] row_mask:0xf bank_mask:0xf
	s_nop 1
	v_add_f32_dpp v4, v5, v5 quad_perm:[2,3,0,1] row_mask:0xf bank_mask:0xf
	s_nop 1
	v_add_f32_dpp v5, v4, v4 row_half_mirror row_mask:0xf bank_mask:0xf
	s_nop 1
	v_add_f32_dpp v4, v5, v5 row_mirror row_mask:0xf bank_mask:0xf
	s_nop 1
	v_readlane_b32 s98, v4, 0
	v_readlane_b32 s99, v4, 16
	s_nop 3
	v_mov_b32_e32 v5, s98
	v_add_f32_e32 v5, s99, v5
	v_readlane_b32 s98, v4, 32
	v_readlane_b32 s99, v4, 48
	s_nop 3
	v_add_f32_e32 v5, s98, v5
	v_add_f32_e32 v5, s99, v5
	v_mul_f32_e32 v5, 0x3a800000, v5
	v_add_f32_e32 v5, 0x358637bd, v5
	v_rsq_f32_e32 v6, v5
	s_nop 0
	s_add_u32 s98, s97, 2
	v_pk_mul_f32 v[48:49], v[48:49], v[6:7] op_sel_hi:[1,0]
	v_pk_mul_f32 v[50:51], v[50:51], v[6:7] op_sel_hi:[1,0]
	v_pk_mul_f32 v[52:53], v[52:53], v[6:7] op_sel_hi:[1,0]
	v_pk_mul_f32 v[54:55], v[54:55], v[6:7] op_sel_hi:[1,0]
	v_pk_mul_f32 v[56:57], v[56:57], v[6:7] op_sel_hi:[1,0]
	v_pk_mul_f32 v[58:59], v[58:59], v[6:7] op_sel_hi:[1,0]
	v_pk_mul_f32 v[60:61], v[60:61], v[6:7] op_sel_hi:[1,0]
	v_pk_mul_f32 v[62:63], v[62:63], v[6:7] op_sel_hi:[1,0]
	v_pk_mul_f32 v[48:49], v[48:49], v[112:113]
	v_pk_mul_f32 v[50:51], v[50:51], v[114:115]
	v_pk_mul_f32 v[52:53], v[52:53], v[116:117]
	v_pk_mul_f32 v[54:55], v[54:55], v[118:119]
	v_pk_mul_f32 v[56:57], v[56:57], v[120:121]
	v_pk_mul_f32 v[58:59], v[58:59], v[122:123]
	v_pk_mul_f32 v[60:61], v[60:61], v[124:125]
	v_pk_mul_f32 v[62:63], v[62:63], v[126:127]
	v_pk_fma_f32 v[48:49], v[48:49], v[128:129], v[144:145]
	v_pk_fma_f32 v[50:51], v[50:51], v[130:131], v[146:147]
	v_pk_fma_f32 v[52:53], v[52:53], v[132:133], v[148:149]
	v_pk_fma_f32 v[54:55], v[54:55], v[134:135], v[150:151]
	v_pk_fma_f32 v[56:57], v[56:57], v[136:137], v[152:153]
	v_pk_fma_f32 v[58:59], v[58:59], v[138:139], v[154:155]
	v_pk_fma_f32 v[60:61], v[60:61], v[140:141], v[156:157]
	v_pk_fma_f32 v[62:63], v[62:63], v[142:143], v[158:159]
	v_cvt_pk_bf16_f32 v48, v48, v49
	v_cvt_pk_bf16_f32 v49, v50, v51
	v_cvt_pk_bf16_f32 v50, v52, v53
	v_cvt_pk_bf16_f32 v51, v54, v55
	v_cvt_pk_bf16_f32 v52, v56, v57
	v_cvt_pk_bf16_f32 v53, v58, v59
	v_cvt_pk_bf16_f32 v54, v60, v61
	v_cvt_pk_bf16_f32 v55, v62, v63
	s_lshl_b32 s99, s98, 11
	v_lshl_add_u32 v8, v0, 3, s99
	global_store_dwordx2 v8, v[48:49], s[94:95]
	global_store_dwordx2 v8, v[50:51], s[94:95] offset:512
	global_store_dwordx2 v8, v[52:53], s[94:95] offset:1024
	global_store_dwordx2 v8, v[54:55], s[94:95] offset:1536
	s_lshl_b32 s99, s98, 2
	v_mov_b32_e32 v9, s99
	v_mov_b32_e32 v10, 0
	v_cmp_eq_u32_e32 vcc, 0, v0
	s_and_saveexec_b64 s[98:99], vcc
	global_store_dword v9, v10, s[90:91]
	global_store_dword v9, v10, s[92:93]
	s_or_b64 exec, exec, s[98:99]
	s_add_u32 s98, s97, 8
	s_lshl_b32 s98, s98, 12
	v_add_u32_e32 v3, s98, v1
	global_load_dwordx4 v[48:51], v3, s[88:89] nt
	global_load_dwordx4 v[52:55], v3, s[88:89] offset:1024 nt
	global_load_dwordx4 v[56:59], v3, s[88:89] offset:2048 nt
	global_load_dwordx4 v[60:63], v3, s[88:89] offset:3072 nt
	s_waitcnt vmcnt(38)
	v_mul_f32_e32 v4, v64, v64
	v_fma_f32 v4, v65, v65, v4
	v_fma_f32 v4, v66, v66, v4
	v_fma_f32 v4, v67, v67, v4
	v_fma_f32 v4, v68, v68, v4
	v_fma_f32 v4, v69, v69, v4
	v_fma_f32 v4, v70, v70, v4
	v_fma_f32 v4, v71, v71, v4
	v_fma_f32 v4, v72, v72, v4
	v_fma_f32 v4, v73, v73, v4
	v_fma_f32 v4, v74, v74, v4
	v_fma_f32 v4, v75, v75, v4
	v_fma_f32 v4, v76, v76, v4
	v_fma_f32 v4, v77, v77, v4
	v_fma_f32 v4, v78, v78, v4
	v_fma_f32 v4, v79, v79, v4
	s_nop 1
	v_add_f32_dpp v5, v4, v4 quad_perm:[1,0,3,2] row_mask:0xf bank_mask:0xf
	s_nop 1
	v_add_f32_dpp v4, v5, v5 quad_perm:[2,3,0,1] row_mask:0xf bank_mask:0xf
	s_nop 1
	v_add_f32_dpp v5, v4, v4 row_half_mirror row_mask:0xf bank_mask:0xf
	s_nop 1
	v_add_f32_dpp v4, v5, v5 row_mirror row_mask:0xf bank_mask:0xf
	s_nop 1
	v_readlane_b32 s98, v4, 0
	v_readlane_b32 s99, v4, 16
	s_nop 3
	v_mov_b32_e32 v5, s98
	v_add_f32_e32 v5, s99, v5
	v_readlane_b32 s98, v4, 32
	v_readlane_b32 s99, v4, 48
	s_nop 3
	v_add_f32_e32 v5, s98, v5
	v_add_f32_e32 v5, s99, v5
	v_mul_f32_e32 v5, 0x3a800000, v5
	v_add_f32_e32 v5, 0x358637bd, v5
	v_rsq_f32_e32 v6, v5
	s_nop 0
	s_add_u32 s98, s97, 3
	v_pk_mul_f32 v[64:65], v[64:65], v[6:7] op_sel_hi:[1,0]
	v_pk_mul_f32 v[66:67], v[66:67], v[6:7] op_sel_hi:[1,0]
	v_pk_mul_f32 v[68:69], v[68:69], v[6:7] op_sel_hi:[1,0]
	v_pk_mul_f32 v[70:71], v[70:71], v[6:7] op_sel_hi:[1,0]
	v_pk_mul_f32 v[72:73], v[72:73], v[6:7] op_sel_hi:[1,0]
	v_pk_mul_f32 v[74:75], v[74:75], v[6:7] op_sel_hi:[1,0]
	v_pk_mul_f32 v[76:77], v[76:77], v[6:7] op_sel_hi:[1,0]
	v_pk_mul_f32 v[78:79], v[78:79], v[6:7] op_sel_hi:[1,0]
	v_pk_mul_f32 v[64:65], v[64:65], v[112:113]
	v_pk_mul_f32 v[66:67], v[66:67], v[114:115]
	v_pk_mul_f32 v[68:69], v[68:69], v[116:117]
	v_pk_mul_f32 v[70:71], v[70:71], v[118:119]
	v_pk_mul_f32 v[72:73], v[72:73], v[120:121]
	v_pk_mul_f32 v[74:75], v[74:75], v[122:123]
	v_pk_mul_f32 v[76:77], v[76:77], v[124:125]
	v_pk_mul_f32 v[78:79], v[78:79], v[126:127]
	v_pk_fma_f32 v[64:65], v[64:65], v[128:129], v[144:145]
	v_pk_fma_f32 v[66:67], v[66:67], v[130:131], v[146:147]
	v_pk_fma_f32 v[68:69], v[68:69], v[132:133], v[148:149]
	v_pk_fma_f32 v[70:71], v[70:71], v[134:135], v[150:151]
	v_pk_fma_f32 v[72:73], v[72:73], v[136:137], v[152:153]
	v_pk_fma_f32 v[74:75], v[74:75], v[138:139], v[154:155]
	v_pk_fma_f32 v[76:77], v[76:77], v[140:141], v[156:157]
	v_pk_fma_f32 v[78:79], v[78:79], v[142:143], v[158:159]
	v_cvt_pk_bf16_f32 v64, v64, v65
	v_cvt_pk_bf16_f32 v65, v66, v67
	v_cvt_pk_bf16_f32 v66, v68, v69
	v_cvt_pk_bf16_f32 v67, v70, v71
	v_cvt_pk_bf16_f32 v68, v72, v73
	v_cvt_pk_bf16_f32 v69, v74, v75
	v_cvt_pk_bf16_f32 v70, v76, v77
	v_cvt_pk_bf16_f32 v71, v78, v79
	s_lshl_b32 s99, s98, 11
	v_lshl_add_u32 v8, v0, 3, s99
	global_store_dwordx2 v8, v[64:65], s[94:95]
	global_store_dwordx2 v8, v[66:67], s[94:95] offset:512
	global_store_dwordx2 v8, v[68:69], s[94:95] offset:1024
	global_store_dwordx2 v8, v[70:71], s[94:95] offset:1536
	s_lshl_b32 s99, s98, 2
	v_mov_b32_e32 v9, s99
	v_mov_b32_e32 v10, 0
	v_cmp_eq_u32_e32 vcc, 0, v0
	s_and_saveexec_b64 s[98:99], vcc
	global_store_dword v9, v10, s[90:91]
	global_store_dword v9, v10, s[92:93]
	s_or_b64 exec, exec, s[98:99]
	s_add_u32 s98, s97, 9
	s_lshl_b32 s98, s98, 12
	v_add_u32_e32 v3, s98, v1
	global_load_dwordx4 v[64:67], v3, s[88:89] nt
	global_load_dwordx4 v[68:71], v3, s[88:89] offset:1024 nt
	global_load_dwordx4 v[72:75], v3, s[88:89] offset:2048 nt
	global_load_dwordx4 v[76:79], v3, s[88:89] offset:3072 nt
	s_waitcnt vmcnt(44)
	v_mul_f32_e32 v4, v80, v80
	v_fma_f32 v4, v81, v81, v4
	v_fma_f32 v4, v82, v82, v4
	v_fma_f32 v4, v83, v83, v4
	v_fma_f32 v4, v84, v84, v4
	v_fma_f32 v4, v85, v85, v4
	v_fma_f32 v4, v86, v86, v4
	v_fma_f32 v4, v87, v87, v4
	v_fma_f32 v4, v88, v88, v4
	v_fma_f32 v4, v89, v89, v4
	v_fma_f32 v4, v90, v90, v4
	v_fma_f32 v4, v91, v91, v4
	v_fma_f32 v4, v92, v92, v4
	v_fma_f32 v4, v93, v93, v4
	v_fma_f32 v4, v94, v94, v4
	v_fma_f32 v4, v95, v95, v4
	s_nop 1
	v_add_f32_dpp v5, v4, v4 quad_perm:[1,0,3,2] row_mask:0xf bank_mask:0xf
	s_nop 1
	v_add_f32_dpp v4, v5, v5 quad_perm:[2,3,0,1] row_mask:0xf bank_mask:0xf
	s_nop 1
	v_add_f32_dpp v5, v4, v4 row_half_mirror row_mask:0xf bank_mask:0xf
	s_nop 1
	v_add_f32_dpp v4, v5, v5 row_mirror row_mask:0xf bank_mask:0xf
	s_nop 1
	v_readlane_b32 s98, v4, 0
	v_readlane_b32 s99, v4, 16
	s_nop 3
	v_mov_b32_e32 v5, s98
	v_add_f32_e32 v5, s99, v5
	v_readlane_b32 s98, v4, 32
	v_readlane_b32 s99, v4, 48
	s_nop 3
	v_add_f32_e32 v5, s98, v5
	v_add_f32_e32 v5, s99, v5
	v_mul_f32_e32 v5, 0x3a800000, v5
	v_add_f32_e32 v5, 0x358637bd, v5
	v_rsq_f32_e32 v6, v5
	s_nop 0
	s_add_u32 s98, s97, 4
	v_pk_mul_f32 v[80:81], v[80:81], v[6:7] op_sel_hi:[1,0]
	v_pk_mul_f32 v[82:83], v[82:83], v[6:7] op_sel_hi:[1,0]
	v_pk_mul_f32 v[84:85], v[84:85], v[6:7] op_sel_hi:[1,0]
	v_pk_mul_f32 v[86:87], v[86:87], v[6:7] op_sel_hi:[1,0]
	v_pk_mul_f32 v[88:89], v[88:89], v[6:7] op_sel_hi:[1,0]
	v_pk_mul_f32 v[90:91], v[90:91], v[6:7] op_sel_hi:[1,0]
	v_pk_mul_f32 v[92:93], v[92:93], v[6:7] op_sel_hi:[1,0]
	v_pk_mul_f32 v[94:95], v[94:95], v[6:7] op_sel_hi:[1,0]
	v_pk_mul_f32 v[80:81], v[80:81], v[112:113]
	v_pk_mul_f32 v[82:83], v[82:83], v[114:115]
	v_pk_mul_f32 v[84:85], v[84:85], v[116:117]
	v_pk_mul_f32 v[86:87], v[86:87], v[118:119]
	v_pk_mul_f32 v[88:89], v[88:89], v[120:121]
	v_pk_mul_f32 v[90:91], v[90:91], v[122:123]
	v_pk_mul_f32 v[92:93], v[92:93], v[124:125]
	v_pk_mul_f32 v[94:95], v[94:95], v[126:127]
	v_pk_fma_f32 v[80:81], v[80:81], v[128:129], v[144:145]
	v_pk_fma_f32 v[82:83], v[82:83], v[130:131], v[146:147]
	v_pk_fma_f32 v[84:85], v[84:85], v[132:133], v[148:149]
	v_pk_fma_f32 v[86:87], v[86:87], v[134:135], v[150:151]
	v_pk_fma_f32 v[88:89], v[88:89], v[136:137], v[152:153]
	v_pk_fma_f32 v[90:91], v[90:91], v[138:139], v[154:155]
	v_pk_fma_f32 v[92:93], v[92:93], v[140:141], v[156:157]
	v_pk_fma_f32 v[94:95], v[94:95], v[142:143], v[158:159]
	v_cvt_pk_bf16_f32 v80, v80, v81
	v_cvt_pk_bf16_f32 v81, v82, v83
	v_cvt_pk_bf16_f32 v82, v84, v85
	v_cvt_pk_bf16_f32 v83, v86, v87
	v_cvt_pk_bf16_f32 v84, v88, v89
	v_cvt_pk_bf16_f32 v85, v90, v91
	v_cvt_pk_bf16_f32 v86, v92, v93
	v_cvt_pk_bf16_f32 v87, v94, v95
	s_lshl_b32 s99, s98, 11
	v_lshl_add_u32 v8, v0, 3, s99
	global_store_dwordx2 v8, v[80:81], s[94:95]
	global_store_dwordx2 v8, v[82:83], s[94:95] offset:512
	global_store_dwordx2 v8, v[84:85], s[94:95] offset:1024
	global_store_dwordx2 v8, v[86:87], s[94:95] offset:1536
	s_lshl_b32 s99, s98, 2
	v_mov_b32_e32 v9, s99
	v_mov_b32_e32 v10, 0
	v_cmp_eq_u32_e32 vcc, 0, v0
	s_and_saveexec_b64 s[98:99], vcc
	global_store_dword v9, v10, s[90:91]
	global_store_dword v9, v10, s[92:93]
	s_or_b64 exec, exec, s[98:99]
	s_add_u32 s98, s97, 10
	s_lshl_b32 s98, s98, 12
	v_add_u32_e32 v3, s98, v1
	global_load_dwordx4 v[80:83], v3, s[88:89] nt
	global_load_dwordx4 v[84:87], v3, s[88:89] offset:1024 nt
	global_load_dwordx4 v[88:91], v3, s[88:89] offset:2048 nt
	global_load_dwordx4 v[92:95], v3, s[88:89] offset:3072 nt
	s_waitcnt vmcnt(50)
	v_mul_f32_e32 v4, v96, v96
	v_fma_f32 v4, v97, v97, v4
	v_fma_f32 v4, v98, v98, v4
	v_fma_f32 v4, v99, v99, v4
	v_fma_f32 v4, v100, v100, v4
	v_fma_f32 v4, v101, v101, v4
	v_fma_f32 v4, v102, v102, v4
	v_fma_f32 v4, v103, v103, v4
	v_fma_f32 v4, v104, v104, v4
	v_fma_f32 v4, v105, v105, v4
	v_fma_f32 v4, v106, v106, v4
	v_fma_f32 v4, v107, v107, v4
	v_fma_f32 v4, v108, v108, v4
	v_fma_f32 v4, v109, v109, v4
	v_fma_f32 v4, v110, v110, v4
	v_fma_f32 v4, v111, v111, v4
	s_nop 1
	v_add_f32_dpp v5, v4, v4 quad_perm:[1,0,3,2] row_mask:0xf bank_mask:0xf
	s_nop 1
	v_add_f32_dpp v4, v5, v5 quad_perm:[2,3,0,1] row_mask:0xf bank_mask:0xf
	s_nop 1
	v_add_f32_dpp v5, v4, v4 row_half_mirror row_mask:0xf bank_mask:0xf
	s_nop 1
	v_add_f32_dpp v4, v5, v5 row_mirror row_mask:0xf bank_mask:0xf
	s_nop 1
	v_readlane_b32 s98, v4, 0
	v_readlane_b32 s99, v4, 16
	s_nop 3
	v_mov_b32_e32 v5, s98
	v_add_f32_e32 v5, s99, v5
	v_readlane_b32 s98, v4, 32
	v_readlane_b32 s99, v4, 48
	s_nop 3
	v_add_f32_e32 v5, s98, v5
	v_add_f32_e32 v5, s99, v5
	v_mul_f32_e32 v5, 0x3a800000, v5
	v_add_f32_e32 v5, 0x358637bd, v5
	v_rsq_f32_e32 v6, v5
	s_nop 0
	s_add_u32 s98, s97, 5
	v_pk_mul_f32 v[96:97], v[96:97], v[6:7] op_sel_hi:[1,0]
	v_pk_mul_f32 v[98:99], v[98:99], v[6:7] op_sel_hi:[1,0]
	v_pk_mul_f32 v[100:101], v[100:101], v[6:7] op_sel_hi:[1,0]
	v_pk_mul_f32 v[102:103], v[102:103], v[6:7] op_sel_hi:[1,0]
	v_pk_mul_f32 v[104:105], v[104:105], v[6:7] op_sel_hi:[1,0]
	v_pk_mul_f32 v[106:107], v[106:107], v[6:7] op_sel_hi:[1,0]
	v_pk_mul_f32 v[108:109], v[108:109], v[6:7] op_sel_hi:[1,0]
	v_pk_mul_f32 v[110:111], v[110:111], v[6:7] op_sel_hi:[1,0]
	v_pk_mul_f32 v[96:97], v[96:97], v[112:113]
	v_pk_mul_f32 v[98:99], v[98:99], v[114:115]
	v_pk_mul_f32 v[100:101], v[100:101], v[116:117]
	v_pk_mul_f32 v[102:103], v[102:103], v[118:119]
	v_pk_mul_f32 v[104:105], v[104:105], v[120:121]
	v_pk_mul_f32 v[106:107], v[106:107], v[122:123]
	v_pk_mul_f32 v[108:109], v[108:109], v[124:125]
	v_pk_mul_f32 v[110:111], v[110:111], v[126:127]
	v_pk_fma_f32 v[96:97], v[96:97], v[128:129], v[144:145]
	v_pk_fma_f32 v[98:99], v[98:99], v[130:131], v[146:147]
	v_pk_fma_f32 v[100:101], v[100:101], v[132:133], v[148:149]
	v_pk_fma_f32 v[102:103], v[102:103], v[134:135], v[150:151]
	v_pk_fma_f32 v[104:105], v[104:105], v[136:137], v[152:153]
	v_pk_fma_f32 v[106:107], v[106:107], v[138:139], v[154:155]
	v_pk_fma_f32 v[108:109], v[108:109], v[140:141], v[156:157]
	v_pk_fma_f32 v[110:111], v[110:111], v[142:143], v[158:159]
	v_cvt_pk_bf16_f32 v96, v96, v97
	v_cvt_pk_bf16_f32 v97, v98, v99
	v_cvt_pk_bf16_f32 v98, v100, v101
	v_cvt_pk_bf16_f32 v99, v102, v103
	v_cvt_pk_bf16_f32 v100, v104, v105
	v_cvt_pk_bf16_f32 v101, v106, v107
	v_cvt_pk_bf16_f32 v102, v108, v109
	v_cvt_pk_bf16_f32 v103, v110, v111
	s_lshl_b32 s99, s98, 11
	v_lshl_add_u32 v8, v0, 3, s99
	global_store_dwordx2 v8, v[96:97], s[94:95]
	global_store_dwordx2 v8, v[98:99], s[94:95] offset:512
	global_store_dwordx2 v8, v[100:101], s[94:95] offset:1024
	global_store_dwordx2 v8, v[102:103], s[94:95] offset:1536
	s_lshl_b32 s99, s98, 2
	v_mov_b32_e32 v9, s99
	v_mov_b32_e32 v10, 0
	v_cmp_eq_u32_e32 vcc, 0, v0
	s_and_saveexec_b64 s[98:99], vcc
	global_store_dword v9, v10, s[90:91]
	global_store_dword v9, v10, s[92:93]
	s_or_b64 exec, exec, s[98:99]
	s_add_u32 s98, s97, 11
	s_lshl_b32 s98, s98, 12
	v_add_u32_e32 v3, s98, v1
	global_load_dwordx4 v[96:99], v3, s[88:89] nt
	global_load_dwordx4 v[100:103], v3, s[88:89] offset:1024 nt
	global_load_dwordx4 v[104:107], v3, s[88:89] offset:2048 nt
	global_load_dwordx4 v[108:111], v3, s[88:89] offset:3072 nt
	s_waitcnt vmcnt(50)
	v_mul_f32_e32 v4, v16, v16
	v_fma_f32 v4, v17, v17, v4
	v_fma_f32 v4, v18, v18, v4
	v_fma_f32 v4, v19, v19, v4
	v_fma_f32 v4, v20, v20, v4
	v_fma_f32 v4, v21, v21, v4
	v_fma_f32 v4, v22, v22, v4
	v_fma_f32 v4, v23, v23, v4
	v_fma_f32 v4, v24, v24, v4
	v_fma_f32 v4, v25, v25, v4
	v_fma_f32 v4, v26, v26, v4
	v_fma_f32 v4, v27, v27, v4
	v_fma_f32 v4, v28, v28, v4
	v_fma_f32 v4, v29, v29, v4
	v_fma_f32 v4, v30, v30, v4
	v_fma_f32 v4, v31, v31, v4
	s_nop 1
	v_add_f32_dpp v5, v4, v4 quad_perm:[1,0,3,2] row_mask:0xf bank_mask:0xf
	s_nop 1
	v_add_f32_dpp v4, v5, v5 quad_perm:[2,3,0,1] row_mask:0xf bank_mask:0xf
	s_nop 1
	v_add_f32_dpp v5, v4, v4 row_half_mirror row_mask:0xf bank_mask:0xf
	s_nop 1
	v_add_f32_dpp v4, v5, v5 row_mirror row_mask:0xf bank_mask:0xf
	s_nop 1
	v_readlane_b32 s98, v4, 0
	v_readlane_b32 s99, v4, 16
	s_nop 3
	v_mov_b32_e32 v5, s98
	v_add_f32_e32 v5, s99, v5
	v_readlane_b32 s98, v4, 32
	v_readlane_b32 s99, v4, 48
	s_nop 3
	v_add_f32_e32 v5, s98, v5
	v_add_f32_e32 v5, s99, v5
	v_mul_f32_e32 v5, 0x3a800000, v5
	v_add_f32_e32 v5, 0x358637bd, v5
	v_rsq_f32_e32 v6, v5
	s_nop 0
	s_add_u32 s98, s97, 6
	v_pk_mul_f32 v[16:17], v[16:17], v[6:7] op_sel_hi:[1,0]
	v_pk_mul_f32 v[18:19], v[18:19], v[6:7] op_sel_hi:[1,0]
	v_pk_mul_f32 v[20:21], v[20:21], v[6:7] op_sel_hi:[1,0]
	v_pk_mul_f32 v[22:23], v[22:23], v[6:7] op_sel_hi:[1,0]
	v_pk_mul_f32 v[24:25], v[24:25], v[6:7] op_sel_hi:[1,0]
	v_pk_mul_f32 v[26:27], v[26:27], v[6:7] op_sel_hi:[1,0]
	v_pk_mul_f32 v[28:29], v[28:29], v[6:7] op_sel_hi:[1,0]
	v_pk_mul_f32 v[30:31], v[30:31], v[6:7] op_sel_hi:[1,0]
	v_pk_mul_f32 v[16:17], v[16:17], v[112:113]
	v_pk_mul_f32 v[18:19], v[18:19], v[114:115]
	v_pk_mul_f32 v[20:21], v[20:21], v[116:117]
	v_pk_mul_f32 v[22:23], v[22:23], v[118:119]
	v_pk_mul_f32 v[24:25], v[24:25], v[120:121]
	v_pk_mul_f32 v[26:27], v[26:27], v[122:123]
	v_pk_mul_f32 v[28:29], v[28:29], v[124:125]
	v_pk_mul_f32 v[30:31], v[30:31], v[126:127]
	v_pk_fma_f32 v[16:17], v[16:17], v[128:129], v[144:145]
	v_pk_fma_f32 v[18:19], v[18:19], v[130:131], v[146:147]
	v_pk_fma_f32 v[20:21], v[20:21], v[132:133], v[148:149]
	v_pk_fma_f32 v[22:23], v[22:23], v[134:135], v[150:151]
	v_pk_fma_f32 v[24:25], v[24:25], v[136:137], v[152:153]
	v_pk_fma_f32 v[26:27], v[26:27], v[138:139], v[154:155]
	v_pk_fma_f32 v[28:29], v[28:29], v[140:141], v[156:157]
	v_pk_fma_f32 v[30:31], v[30:31], v[142:143], v[158:159]
	v_cvt_pk_bf16_f32 v16, v16, v17
	v_cvt_pk_bf16_f32 v17, v18, v19
	v_cvt_pk_bf16_f32 v18, v20, v21
	v_cvt_pk_bf16_f32 v19, v22, v23
	v_cvt_pk_bf16_f32 v20, v24, v25
	v_cvt_pk_bf16_f32 v21, v26, v27
	v_cvt_pk_bf16_f32 v22, v28, v29
	v_cvt_pk_bf16_f32 v23, v30, v31
	s_lshl_b32 s99, s98, 11
	v_lshl_add_u32 v8, v0, 3, s99
	global_store_dwordx2 v8, v[16:17], s[94:95]
	global_store_dwordx2 v8, v[18:19], s[94:95] offset:512
	global_store_dwordx2 v8, v[20:21], s[94:95] offset:1024
	global_store_dwordx2 v8, v[22:23], s[94:95] offset:1536
	s_lshl_b32 s99, s98, 2
	v_mov_b32_e32 v9, s99
	v_mov_b32_e32 v10, 0
	v_cmp_eq_u32_e32 vcc, 0, v0
	s_and_saveexec_b64 s[98:99], vcc
	global_store_dword v9, v10, s[90:91]
	global_store_dword v9, v10, s[92:93]
	s_or_b64 exec, exec, s[98:99]
	s_add_u32 s98, s97, 12
	s_lshl_b32 s98, s98, 12
	v_add_u32_e32 v3, s98, v1
	global_load_dwordx4 v[16:19], v3, s[88:89] nt
	global_load_dwordx4 v[20:23], v3, s[88:89] offset:1024 nt
	global_load_dwordx4 v[24:27], v3, s[88:89] offset:2048 nt
	global_load_dwordx4 v[28:31], v3, s[88:89] offset:3072 nt
	s_waitcnt vmcnt(50)
	v_mul_f32_e32 v4, v32, v32
	v_fma_f32 v4, v33, v33, v4
	v_fma_f32 v4, v34, v34, v4
	v_fma_f32 v4, v35, v35, v4
	v_fma_f32 v4, v36, v36, v4
	v_fma_f32 v4, v37, v37, v4
	v_fma_f32 v4, v38, v38, v4
	v_fma_f32 v4, v39, v39, v4
	v_fma_f32 v4, v40, v40, v4
	v_fma_f32 v4, v41, v41, v4
	v_fma_f32 v4, v42, v42, v4
	v_fma_f32 v4, v43, v43, v4
	v_fma_f32 v4, v44, v44, v4
	v_fma_f32 v4, v45, v45, v4
	v_fma_f32 v4, v46, v46, v4
	v_fma_f32 v4, v47, v47, v4
	s_nop 1
	v_add_f32_dpp v5, v4, v4 quad_perm:[1,0,3,2] row_mask:0xf bank_mask:0xf
	s_nop 1
	v_add_f32_dpp v4, v5, v5 quad_perm:[2,3,0,1] row_mask:0xf bank_mask:0xf
	s_nop 1
	v_add_f32_dpp v5, v4, v4 row_half_mirror row_mask:0xf bank_mask:0xf
	s_nop 1
	v_add_f32_dpp v4, v5, v5 row_mirror row_mask:0xf bank_mask:0xf
	s_nop 1
	v_readlane_b32 s98, v4, 0
	v_readlane_b32 s99, v4, 16
	s_nop 3
	v_mov_b32_e32 v5, s98
	v_add_f32_e32 v5, s99, v5
	v_readlane_b32 s98, v4, 32
	v_readlane_b32 s99, v4, 48
	s_nop 3
	v_add_f32_e32 v5, s98, v5
	v_add_f32_e32 v5, s99, v5
	v_mul_f32_e32 v5, 0x3a800000, v5
	v_add_f32_e32 v5, 0x358637bd, v5
	v_rsq_f32_e32 v6, v5
	s_nop 0
	s_add_u32 s98, s97, 7
	v_pk_mul_f32 v[32:33], v[32:33], v[6:7] op_sel_hi:[1,0]
	v_pk_mul_f32 v[34:35], v[34:35], v[6:7] op_sel_hi:[1,0]
	v_pk_mul_f32 v[36:37], v[36:37], v[6:7] op_sel_hi:[1,0]
	v_pk_mul_f32 v[38:39], v[38:39], v[6:7] op_sel_hi:[1,0]
	v_pk_mul_f32 v[40:41], v[40:41], v[6:7] op_sel_hi:[1,0]
	v_pk_mul_f32 v[42:43], v[42:43], v[6:7] op_sel_hi:[1,0]
	v_pk_mul_f32 v[44:45], v[44:45], v[6:7] op_sel_hi:[1,0]
	v_pk_mul_f32 v[46:47], v[46:47], v[6:7] op_sel_hi:[1,0]
	v_pk_mul_f32 v[32:33], v[32:33], v[112:113]
	v_pk_mul_f32 v[34:35], v[34:35], v[114:115]
	v_pk_mul_f32 v[36:37], v[36:37], v[116:117]
	v_pk_mul_f32 v[38:39], v[38:39], v[118:119]
	v_pk_mul_f32 v[40:41], v[40:41], v[120:121]
	v_pk_mul_f32 v[42:43], v[42:43], v[122:123]
	v_pk_mul_f32 v[44:45], v[44:45], v[124:125]
	v_pk_mul_f32 v[46:47], v[46:47], v[126:127]
	v_pk_fma_f32 v[32:33], v[32:33], v[128:129], v[144:145]
	v_pk_fma_f32 v[34:35], v[34:35], v[130:131], v[146:147]
	v_pk_fma_f32 v[36:37], v[36:37], v[132:133], v[148:149]
	v_pk_fma_f32 v[38:39], v[38:39], v[134:135], v[150:151]
	v_pk_fma_f32 v[40:41], v[40:41], v[136:137], v[152:153]
	v_pk_fma_f32 v[42:43], v[42:43], v[138:139], v[154:155]
	v_pk_fma_f32 v[44:45], v[44:45], v[140:141], v[156:157]
	v_pk_fma_f32 v[46:47], v[46:47], v[142:143], v[158:159]
	v_cvt_pk_bf16_f32 v32, v32, v33
	v_cvt_pk_bf16_f32 v33, v34, v35
	v_cvt_pk_bf16_f32 v34, v36, v37
	v_cvt_pk_bf16_f32 v35, v38, v39
	v_cvt_pk_bf16_f32 v36, v40, v41
	v_cvt_pk_bf16_f32 v37, v42, v43
	v_cvt_pk_bf16_f32 v38, v44, v45
	v_cvt_pk_bf16_f32 v39, v46, v47
	s_lshl_b32 s99, s98, 11
	v_lshl_add_u32 v8, v0, 3, s99
	global_store_dwordx2 v8, v[32:33], s[94:95]
	global_store_dwordx2 v8, v[34:35], s[94:95] offset:512
	global_store_dwordx2 v8, v[36:37], s[94:95] offset:1024
	global_store_dwordx2 v8, v[38:39], s[94:95] offset:1536
	s_lshl_b32 s99, s98, 2
	v_mov_b32_e32 v9, s99
	v_mov_b32_e32 v10, 0
	v_cmp_eq_u32_e32 vcc, 0, v0
	s_and_saveexec_b64 s[98:99], vcc
	global_store_dword v9, v10, s[90:91]
	global_store_dword v9, v10, s[92:93]
	s_or_b64 exec, exec, s[98:99]
	s_add_u32 s98, s97, 13
	s_lshl_b32 s98, s98, 12
	v_add_u32_e32 v3, s98, v1
	global_load_dwordx4 v[32:35], v3, s[88:89] nt
	global_load_dwordx4 v[36:39], v3, s[88:89] offset:1024 nt
	global_load_dwordx4 v[40:43], v3, s[88:89] offset:2048 nt
	global_load_dwordx4 v[44:47], v3, s[88:89] offset:3072 nt
	s_waitcnt vmcnt(50)
	v_mul_f32_e32 v4, v48, v48
	v_fma_f32 v4, v49, v49, v4
	v_fma_f32 v4, v50, v50, v4
	v_fma_f32 v4, v51, v51, v4
	v_fma_f32 v4, v52, v52, v4
	v_fma_f32 v4, v53, v53, v4
	v_fma_f32 v4, v54, v54, v4
	v_fma_f32 v4, v55, v55, v4
	v_fma_f32 v4, v56, v56, v4
	v_fma_f32 v4, v57, v57, v4
	v_fma_f32 v4, v58, v58, v4
	v_fma_f32 v4, v59, v59, v4
	v_fma_f32 v4, v60, v60, v4
	v_fma_f32 v4, v61, v61, v4
	v_fma_f32 v4, v62, v62, v4
	v_fma_f32 v4, v63, v63, v4
	s_nop 1
	v_add_f32_dpp v5, v4, v4 quad_perm:[1,0,3,2] row_mask:0xf bank_mask:0xf
	s_nop 1
	v_add_f32_dpp v4, v5, v5 quad_perm:[2,3,0,1] row_mask:0xf bank_mask:0xf
	s_nop 1
	v_add_f32_dpp v5, v4, v4 row_half_mirror row_mask:0xf bank_mask:0xf
	s_nop 1
	v_add_f32_dpp v4, v5, v5 row_mirror row_mask:0xf bank_mask:0xf
	s_nop 1
	v_readlane_b32 s98, v4, 0
	v_readlane_b32 s99, v4, 16
	s_nop 3
	v_mov_b32_e32 v5, s98
	v_add_f32_e32 v5, s99, v5
	v_readlane_b32 s98, v4, 32
	v_readlane_b32 s99, v4, 48
	s_nop 3
	v_add_f32_e32 v5, s98, v5
	v_add_f32_e32 v5, s99, v5
	v_mul_f32_e32 v5, 0x3a800000, v5
	v_add_f32_e32 v5, 0x358637bd, v5
	v_rsq_f32_e32 v6, v5
	s_nop 0
	s_add_u32 s98, s97, 8
	v_pk_mul_f32 v[48:49], v[48:49], v[6:7] op_sel_hi:[1,0]
	v_pk_mul_f32 v[50:51], v[50:51], v[6:7] op_sel_hi:[1,0]
	v_pk_mul_f32 v[52:53], v[52:53], v[6:7] op_sel_hi:[1,0]
	v_pk_mul_f32 v[54:55], v[54:55], v[6:7] op_sel_hi:[1,0]
	v_pk_mul_f32 v[56:57], v[56:57], v[6:7] op_sel_hi:[1,0]
	v_pk_mul_f32 v[58:59], v[58:59], v[6:7] op_sel_hi:[1,0]
	v_pk_mul_f32 v[60:61], v[60:61], v[6:7] op_sel_hi:[1,0]
	v_pk_mul_f32 v[62:63], v[62:63], v[6:7] op_sel_hi:[1,0]
	v_pk_mul_f32 v[48:49], v[48:49], v[112:113]
	v_pk_mul_f32 v[50:51], v[50:51], v[114:115]
	v_pk_mul_f32 v[52:53], v[52:53], v[116:117]
	v_pk_mul_f32 v[54:55], v[54:55], v[118:119]
	v_pk_mul_f32 v[56:57], v[56:57], v[120:121]
	v_pk_mul_f32 v[58:59], v[58:59], v[122:123]
	v_pk_mul_f32 v[60:61], v[60:61], v[124:125]
	v_pk_mul_f32 v[62:63], v[62:63], v[126:127]
	v_pk_fma_f32 v[48:49], v[48:49], v[128:129], v[144:145]
	v_pk_fma_f32 v[50:51], v[50:51], v[130:131], v[146:147]
	v_pk_fma_f32 v[52:53], v[52:53], v[132:133], v[148:149]
	v_pk_fma_f32 v[54:55], v[54:55], v[134:135], v[150:151]
	v_pk_fma_f32 v[56:57], v[56:57], v[136:137], v[152:153]
	v_pk_fma_f32 v[58:59], v[58:59], v[138:139], v[154:155]
	v_pk_fma_f32 v[60:61], v[60:61], v[140:141], v[156:157]
	v_pk_fma_f32 v[62:63], v[62:63], v[142:143], v[158:159]
	v_cvt_pk_bf16_f32 v48, v48, v49
	v_cvt_pk_bf16_f32 v49, v50, v51
	v_cvt_pk_bf16_f32 v50, v52, v53
	v_cvt_pk_bf16_f32 v51, v54, v55
	v_cvt_pk_bf16_f32 v52, v56, v57
	v_cvt_pk_bf16_f32 v53, v58, v59
	v_cvt_pk_bf16_f32 v54, v60, v61
	v_cvt_pk_bf16_f32 v55, v62, v63
	s_lshl_b32 s99, s98, 11
	v_lshl_add_u32 v8, v0, 3, s99
	global_store_dwordx2 v8, v[48:49], s[94:95]
	global_store_dwordx2 v8, v[50:51], s[94:95] offset:512
	global_store_dwordx2 v8, v[52:53], s[94:95] offset:1024
	global_store_dwordx2 v8, v[54:55], s[94:95] offset:1536
	s_lshl_b32 s99, s98, 2
	v_mov_b32_e32 v9, s99
	v_mov_b32_e32 v10, 0
	v_cmp_eq_u32_e32 vcc, 0, v0
	s_and_saveexec_b64 s[98:99], vcc
	global_store_dword v9, v10, s[90:91]
	global_store_dword v9, v10, s[92:93]
	s_or_b64 exec, exec, s[98:99]
	s_add_u32 s98, s97, 14
	s_lshl_b32 s98, s98, 12
	v_add_u32_e32 v3, s98, v1
	global_load_dwordx4 v[48:51], v3, s[88:89] nt
	global_load_dwordx4 v[52:55], v3, s[88:89] offset:1024 nt
	global_load_dwordx4 v[56:59], v3, s[88:89] offset:2048 nt
	global_load_dwordx4 v[60:63], v3, s[88:89] offset:3072 nt
	s_waitcnt vmcnt(50)
	v_mul_f32_e32 v4, v64, v64
	v_fma_f32 v4, v65, v65, v4
	v_fma_f32 v4, v66, v66, v4
	v_fma_f32 v4, v67, v67, v4
	v_fma_f32 v4, v68, v68, v4
	v_fma_f32 v4, v69, v69, v4
	v_fma_f32 v4, v70, v70, v4
	v_fma_f32 v4, v71, v71, v4
	v_fma_f32 v4, v72, v72, v4
	v_fma_f32 v4, v73, v73, v4
	v_fma_f32 v4, v74, v74, v4
	v_fma_f32 v4, v75, v75, v4
	v_fma_f32 v4, v76, v76, v4
	v_fma_f32 v4, v77, v77, v4
	v_fma_f32 v4, v78, v78, v4
	v_fma_f32 v4, v79, v79, v4
	s_nop 1
	v_add_f32_dpp v5, v4, v4 quad_perm:[1,0,3,2] row_mask:0xf bank_mask:0xf
	s_nop 1
	v_add_f32_dpp v4, v5, v5 quad_perm:[2,3,0,1] row_mask:0xf bank_mask:0xf
	s_nop 1
	v_add_f32_dpp v5, v4, v4 row_half_mirror row_mask:0xf bank_mask:0xf
	s_nop 1
	v_add_f32_dpp v4, v5, v5 row_mirror row_mask:0xf bank_mask:0xf
	s_nop 1
	v_readlane_b32 s98, v4, 0
	v_readlane_b32 s99, v4, 16
	s_nop 3
	v_mov_b32_e32 v5, s98
	v_add_f32_e32 v5, s99, v5
	v_readlane_b32 s98, v4, 32
	v_readlane_b32 s99, v4, 48
	s_nop 3
	v_add_f32_e32 v5, s98, v5
	v_add_f32_e32 v5, s99, v5
	v_mul_f32_e32 v5, 0x3a800000, v5
	v_add_f32_e32 v5, 0x358637bd, v5
	v_rsq_f32_e32 v6, v5
	s_nop 0
	s_add_u32 s98, s97, 9
	v_pk_mul_f32 v[64:65], v[64:65], v[6:7] op_sel_hi:[1,0]
	v_pk_mul_f32 v[66:67], v[66:67], v[6:7] op_sel_hi:[1,0]
	v_pk_mul_f32 v[68:69], v[68:69], v[6:7] op_sel_hi:[1,0]
	v_pk_mul_f32 v[70:71], v[70:71], v[6:7] op_sel_hi:[1,0]
	v_pk_mul_f32 v[72:73], v[72:73], v[6:7] op_sel_hi:[1,0]
	v_pk_mul_f32 v[74:75], v[74:75], v[6:7] op_sel_hi:[1,0]
	v_pk_mul_f32 v[76:77], v[76:77], v[6:7] op_sel_hi:[1,0]
	v_pk_mul_f32 v[78:79], v[78:79], v[6:7] op_sel_hi:[1,0]
	v_pk_mul_f32 v[64:65], v[64:65], v[112:113]
	v_pk_mul_f32 v[66:67], v[66:67], v[114:115]
	v_pk_mul_f32 v[68:69], v[68:69], v[116:117]
	v_pk_mul_f32 v[70:71], v[70:71], v[118:119]
	v_pk_mul_f32 v[72:73], v[72:73], v[120:121]
	v_pk_mul_f32 v[74:75], v[74:75], v[122:123]
	v_pk_mul_f32 v[76:77], v[76:77], v[124:125]
	v_pk_mul_f32 v[78:79], v[78:79], v[126:127]
	v_pk_fma_f32 v[64:65], v[64:65], v[128:129], v[144:145]
	v_pk_fma_f32 v[66:67], v[66:67], v[130:131], v[146:147]
	v_pk_fma_f32 v[68:69], v[68:69], v[132:133], v[148:149]
	v_pk_fma_f32 v[70:71], v[70:71], v[134:135], v[150:151]
	v_pk_fma_f32 v[72:73], v[72:73], v[136:137], v[152:153]
	v_pk_fma_f32 v[74:75], v[74:75], v[138:139], v[154:155]
	v_pk_fma_f32 v[76:77], v[76:77], v[140:141], v[156:157]
	v_pk_fma_f32 v[78:79], v[78:79], v[142:143], v[158:159]
	v_cvt_pk_bf16_f32 v64, v64, v65
	v_cvt_pk_bf16_f32 v65, v66, v67
	v_cvt_pk_bf16_f32 v66, v68, v69
	v_cvt_pk_bf16_f32 v67, v70, v71
	v_cvt_pk_bf16_f32 v68, v72, v73
	v_cvt_pk_bf16_f32 v69, v74, v75
	v_cvt_pk_bf16_f32 v70, v76, v77
	v_cvt_pk_bf16_f32 v71, v78, v79
	s_lshl_b32 s99, s98, 11
	v_lshl_add_u32 v8, v0, 3, s99
	global_store_dwordx2 v8, v[64:65], s[94:95]
	global_store_dwordx2 v8, v[66:67], s[94:95] offset:512
	global_store_dwordx2 v8, v[68:69], s[94:95] offset:1024
	global_store_dwordx2 v8, v[70:71], s[94:95] offset:1536
	s_lshl_b32 s99, s98, 2
	v_mov_b32_e32 v9, s99
	v_mov_b32_e32 v10, 0
	v_cmp_eq_u32_e32 vcc, 0, v0
	s_and_saveexec_b64 s[98:99], vcc
	global_store_dword v9, v10, s[90:91]
	global_store_dword v9, v10, s[92:93]
	s_or_b64 exec, exec, s[98:99]
	s_add_u32 s98, s97, 15
	s_lshl_b32 s98, s98, 12
	v_add_u32_e32 v3, s98, v1
	global_load_dwordx4 v[64:67], v3, s[88:89] nt
	global_load_dwordx4 v[68:71], v3, s[88:89] offset:1024 nt
	global_load_dwordx4 v[72:75], v3, s[88:89] offset:2048 nt
	global_load_dwordx4 v[76:79], v3, s[88:89] offset:3072 nt
	s_waitcnt vmcnt(50)
	v_mul_f32_e32 v4, v80, v80
	v_fma_f32 v4, v81, v81, v4
	v_fma_f32 v4, v82, v82, v4
	v_fma_f32 v4, v83, v83, v4
	v_fma_f32 v4, v84, v84, v4
	v_fma_f32 v4, v85, v85, v4
	v_fma_f32 v4, v86, v86, v4
	v_fma_f32 v4, v87, v87, v4
	v_fma_f32 v4, v88, v88, v4
	v_fma_f32 v4, v89, v89, v4
	v_fma_f32 v4, v90, v90, v4
	v_fma_f32 v4, v91, v91, v4
	v_fma_f32 v4, v92, v92, v4
	v_fma_f32 v4, v93, v93, v4
	v_fma_f32 v4, v94, v94, v4
	v_fma_f32 v4, v95, v95, v4
	s_nop 1
	v_add_f32_dpp v5, v4, v4 quad_perm:[1,0,3,2] row_mask:0xf bank_mask:0xf
	s_nop 1
	v_add_f32_dpp v4, v5, v5 quad_perm:[2,3,0,1] row_mask:0xf bank_mask:0xf
	s_nop 1
	v_add_f32_dpp v5, v4, v4 row_half_mirror row_mask:0xf bank_mask:0xf
	s_nop 1
	v_add_f32_dpp v4, v5, v5 row_mirror row_mask:0xf bank_mask:0xf
	s_nop 1
	v_readlane_b32 s98, v4, 0
	v_readlane_b32 s99, v4, 16
	s_nop 3
	v_mov_b32_e32 v5, s98
	v_add_f32_e32 v5, s99, v5
	v_readlane_b32 s98, v4, 32
	v_readlane_b32 s99, v4, 48
	s_nop 3
	v_add_f32_e32 v5, s98, v5
	v_add_f32_e32 v5, s99, v5
	v_mul_f32_e32 v5, 0x3a800000, v5
	v_add_f32_e32 v5, 0x358637bd, v5
	v_rsq_f32_e32 v6, v5
	s_nop 0
	s_add_u32 s98, s97, 10
	v_pk_mul_f32 v[80:81], v[80:81], v[6:7] op_sel_hi:[1,0]
	v_pk_mul_f32 v[82:83], v[82:83], v[6:7] op_sel_hi:[1,0]
	v_pk_mul_f32 v[84:85], v[84:85], v[6:7] op_sel_hi:[1,0]
	v_pk_mul_f32 v[86:87], v[86:87], v[6:7] op_sel_hi:[1,0]
	v_pk_mul_f32 v[88:89], v[88:89], v[6:7] op_sel_hi:[1,0]
	v_pk_mul_f32 v[90:91], v[90:91], v[6:7] op_sel_hi:[1,0]
	v_pk_mul_f32 v[92:93], v[92:93], v[6:7] op_sel_hi:[1,0]
	v_pk_mul_f32 v[94:95], v[94:95], v[6:7] op_sel_hi:[1,0]
	v_pk_mul_f32 v[80:81], v[80:81], v[112:113]
	v_pk_mul_f32 v[82:83], v[82:83], v[114:115]
	v_pk_mul_f32 v[84:85], v[84:85], v[116:117]
	v_pk_mul_f32 v[86:87], v[86:87], v[118:119]
	v_pk_mul_f32 v[88:89], v[88:89], v[120:121]
	v_pk_mul_f32 v[90:91], v[90:91], v[122:123]
	v_pk_mul_f32 v[92:93], v[92:93], v[124:125]
	v_pk_mul_f32 v[94:95], v[94:95], v[126:127]
	v_pk_fma_f32 v[80:81], v[80:81], v[128:129], v[144:145]
	v_pk_fma_f32 v[82:83], v[82:83], v[130:131], v[146:147]
	v_pk_fma_f32 v[84:85], v[84:85], v[132:133], v[148:149]
	v_pk_fma_f32 v[86:87], v[86:87], v[134:135], v[150:151]
	v_pk_fma_f32 v[88:89], v[88:89], v[136:137], v[152:153]
	v_pk_fma_f32 v[90:91], v[90:91], v[138:139], v[154:155]
	v_pk_fma_f32 v[92:93], v[92:93], v[140:141], v[156:157]
	v_pk_fma_f32 v[94:95], v[94:95], v[142:143], v[158:159]
	v_cvt_pk_bf16_f32 v80, v80, v81
	v_cvt_pk_bf16_f32 v81, v82, v83
	v_cvt_pk_bf16_f32 v82, v84, v85
	v_cvt_pk_bf16_f32 v83, v86, v87
	v_cvt_pk_bf16_f32 v84, v88, v89
	v_cvt_pk_bf16_f32 v85, v90, v91
	v_cvt_pk_bf16_f32 v86, v92, v93
	v_cvt_pk_bf16_f32 v87, v94, v95
	s_lshl_b32 s99, s98, 11
	v_lshl_add_u32 v8, v0, 3, s99
	global_store_dwordx2 v8, v[80:81], s[94:95]
	global_store_dwordx2 v8, v[82:83], s[94:95] offset:512
	global_store_dwordx2 v8, v[84:85], s[94:95] offset:1024
	global_store_dwordx2 v8, v[86:87], s[94:95] offset:1536
	s_lshl_b32 s99, s98, 2
	v_mov_b32_e32 v9, s99
	v_mov_b32_e32 v10, 0
	v_cmp_eq_u32_e32 vcc, 0, v0
	s_and_saveexec_b64 s[98:99], vcc
	global_store_dword v9, v10, s[90:91]
	global_store_dword v9, v10, s[92:93]
	s_or_b64 exec, exec, s[98:99]
	s_waitcnt vmcnt(46)
	v_mul_f32_e32 v4, v96, v96
	v_fma_f32 v4, v97, v97, v4
	v_fma_f32 v4, v98, v98, v4
	v_fma_f32 v4, v99, v99, v4
	v_fma_f32 v4, v100, v100, v4
	v_fma_f32 v4, v101, v101, v4
	v_fma_f32 v4, v102, v102, v4
	v_fma_f32 v4, v103, v103, v4
	v_fma_f32 v4, v104, v104, v4
	v_fma_f32 v4, v105, v105, v4
	v_fma_f32 v4, v106, v106, v4
	v_fma_f32 v4, v107, v107, v4
	v_fma_f32 v4, v108, v108, v4
	v_fma_f32 v4, v109, v109, v4
	v_fma_f32 v4, v110, v110, v4
	v_fma_f32 v4, v111, v111, v4
	s_nop 1
	v_add_f32_dpp v5, v4, v4 quad_perm:[1,0,3,2] row_mask:0xf bank_mask:0xf
	s_nop 1
	v_add_f32_dpp v4, v5, v5 quad_perm:[2,3,0,1] row_mask:0xf bank_mask:0xf
	s_nop 1
	v_add_f32_dpp v5, v4, v4 row_half_mirror row_mask:0xf bank_mask:0xf
	s_nop 1
	v_add_f32_dpp v4, v5, v5 row_mirror row_mask:0xf bank_mask:0xf
	s_nop 1
	v_readlane_b32 s98, v4, 0
	v_readlane_b32 s99, v4, 16
	s_nop 3
	v_mov_b32_e32 v5, s98
	v_add_f32_e32 v5, s99, v5
	v_readlane_b32 s98, v4, 32
	v_readlane_b32 s99, v4, 48
	s_nop 3
	v_add_f32_e32 v5, s98, v5
	v_add_f32_e32 v5, s99, v5
	v_mul_f32_e32 v5, 0x3a800000, v5
	v_add_f32_e32 v5, 0x358637bd, v5
	v_rsq_f32_e32 v6, v5
	s_nop 0
	s_add_u32 s98, s97, 11
	v_pk_mul_f32 v[96:97], v[96:97], v[6:7] op_sel_hi:[1,0]
	v_pk_mul_f32 v[98:99], v[98:99], v[6:7] op_sel_hi:[1,0]
	v_pk_mul_f32 v[100:101], v[100:101], v[6:7] op_sel_hi:[1,0]
	v_pk_mul_f32 v[102:103], v[102:103], v[6:7] op_sel_hi:[1,0]
	v_pk_mul_f32 v[104:105], v[104:105], v[6:7] op_sel_hi:[1,0]
	v_pk_mul_f32 v[106:107], v[106:107], v[6:7] op_sel_hi:[1,0]
	v_pk_mul_f32 v[108:109], v[108:109], v[6:7] op_sel_hi:[1,0]
	v_pk_mul_f32 v[110:111], v[110:111], v[6:7] op_sel_hi:[1,0]
	v_pk_mul_f32 v[96:97], v[96:97], v[112:113]
	v_pk_mul_f32 v[98:99], v[98:99], v[114:115]
	v_pk_mul_f32 v[100:101], v[100:101], v[116:117]
	v_pk_mul_f32 v[102:103], v[102:103], v[118:119]
	v_pk_mul_f32 v[104:105], v[104:105], v[120:121]
	v_pk_mul_f32 v[106:107], v[106:107], v[122:123]
	v_pk_mul_f32 v[108:109], v[108:109], v[124:125]
	v_pk_mul_f32 v[110:111], v[110:111], v[126:127]
	v_pk_fma_f32 v[96:97], v[96:97], v[128:129], v[144:145]
	v_pk_fma_f32 v[98:99], v[98:99], v[130:131], v[146:147]
	v_pk_fma_f32 v[100:101], v[100:101], v[132:133], v[148:149]
	v_pk_fma_f32 v[102:103], v[102:103], v[134:135], v[150:151]
	v_pk_fma_f32 v[104:105], v[104:105], v[136:137], v[152:153]
	v_pk_fma_f32 v[106:107], v[106:107], v[138:139], v[154:155]
	v_pk_fma_f32 v[108:109], v[108:109], v[140:141], v[156:157]
	v_pk_fma_f32 v[110:111], v[110:111], v[142:143], v[158:159]
	v_cvt_pk_bf16_f32 v96, v96, v97
	v_cvt_pk_bf16_f32 v97, v98, v99
	v_cvt_pk_bf16_f32 v98, v100, v101
	v_cvt_pk_bf16_f32 v99, v102, v103
	v_cvt_pk_bf16_f32 v100, v104, v105
	v_cvt_pk_bf16_f32 v101, v106, v107
	v_cvt_pk_bf16_f32 v102, v108, v109
	v_cvt_pk_bf16_f32 v103, v110, v111
	s_lshl_b32 s99, s98, 11
	v_lshl_add_u32 v8, v0, 3, s99
	global_store_dwordx2 v8, v[96:97], s[94:95]
	global_store_dwordx2 v8, v[98:99], s[94:95] offset:512
	global_store_dwordx2 v8, v[100:101], s[94:95] offset:1024
	global_store_dwordx2 v8, v[102:103], s[94:95] offset:1536
	s_lshl_b32 s99, s98, 2
	v_mov_b32_e32 v9, s99
	v_mov_b32_e32 v10, 0
	v_cmp_eq_u32_e32 vcc, 0, v0
	s_and_saveexec_b64 s[98:99], vcc
	global_store_dword v9, v10, s[90:91]
	global_store_dword v9, v10, s[92:93]
	s_or_b64 exec, exec, s[98:99]
	s_waitcnt vmcnt(42)
	v_mul_f32_e32 v4, v16, v16
	v_fma_f32 v4, v17, v17, v4
	v_fma_f32 v4, v18, v18, v4
	v_fma_f32 v4, v19, v19, v4
	v_fma_f32 v4, v20, v20, v4
	v_fma_f32 v4, v21, v21, v4
	v_fma_f32 v4, v22, v22, v4
	v_fma_f32 v4, v23, v23, v4
	v_fma_f32 v4, v24, v24, v4
	v_fma_f32 v4, v25, v25, v4
	v_fma_f32 v4, v26, v26, v4
	v_fma_f32 v4, v27, v27, v4
	v_fma_f32 v4, v28, v28, v4
	v_fma_f32 v4, v29, v29, v4
	v_fma_f32 v4, v30, v30, v4
	v_fma_f32 v4, v31, v31, v4
	s_nop 1
	v_add_f32_dpp v5, v4, v4 quad_perm:[1,0,3,2] row_mask:0xf bank_mask:0xf
	s_nop 1
	v_add_f32_dpp v4, v5, v5 quad_perm:[2,3,0,1] row_mask:0xf bank_mask:0xf
	s_nop 1
	v_add_f32_dpp v5, v4, v4 row_half_mirror row_mask:0xf bank_mask:0xf
	s_nop 1
	v_add_f32_dpp v4, v5, v5 row_mirror row_mask:0xf bank_mask:0xf
	s_nop 1
	v_readlane_b32 s98, v4, 0
	v_readlane_b32 s99, v4, 16
	s_nop 3
	v_mov_b32_e32 v5, s98
	v_add_f32_e32 v5, s99, v5
	v_readlane_b32 s98, v4, 32
	v_readlane_b32 s99, v4, 48
	s_nop 3
	v_add_f32_e32 v5, s98, v5
	v_add_f32_e32 v5, s99, v5
	v_mul_f32_e32 v5, 0x3a800000, v5
	v_add_f32_e32 v5, 0x358637bd, v5
	v_rsq_f32_e32 v6, v5
	s_nop 0
	s_add_u32 s98, s97, 12
	v_pk_mul_f32 v[16:17], v[16:17], v[6:7] op_sel_hi:[1,0]
	v_pk_mul_f32 v[18:19], v[18:19], v[6:7] op_sel_hi:[1,0]
	v_pk_mul_f32 v[20:21], v[20:21], v[6:7] op_sel_hi:[1,0]
	v_pk_mul_f32 v[22:23], v[22:23], v[6:7] op_sel_hi:[1,0]
	v_pk_mul_f32 v[24:25], v[24:25], v[6:7] op_sel_hi:[1,0]
	v_pk_mul_f32 v[26:27], v[26:27], v[6:7] op_sel_hi:[1,0]
	v_pk_mul_f32 v[28:29], v[28:29], v[6:7] op_sel_hi:[1,0]
	v_pk_mul_f32 v[30:31], v[30:31], v[6:7] op_sel_hi:[1,0]
	v_pk_mul_f32 v[16:17], v[16:17], v[112:113]
	v_pk_mul_f32 v[18:19], v[18:19], v[114:115]
	v_pk_mul_f32 v[20:21], v[20:21], v[116:117]
	v_pk_mul_f32 v[22:23], v[22:23], v[118:119]
	v_pk_mul_f32 v[24:25], v[24:25], v[120:121]
	v_pk_mul_f32 v[26:27], v[26:27], v[122:123]
	v_pk_mul_f32 v[28:29], v[28:29], v[124:125]
	v_pk_mul_f32 v[30:31], v[30:31], v[126:127]
	v_pk_fma_f32 v[16:17], v[16:17], v[128:129], v[144:145]
	v_pk_fma_f32 v[18:19], v[18:19], v[130:131], v[146:147]
	v_pk_fma_f32 v[20:21], v[20:21], v[132:133], v[148:149]
	v_pk_fma_f32 v[22:23], v[22:23], v[134:135], v[150:151]
	v_pk_fma_f32 v[24:25], v[24:25], v[136:137], v[152:153]
	v_pk_fma_f32 v[26:27], v[26:27], v[138:139], v[154:155]
	v_pk_fma_f32 v[28:29], v[28:29], v[140:141], v[156:157]
	v_pk_fma_f32 v[30:31], v[30:31], v[142:143], v[158:159]
	v_cvt_pk_bf16_f32 v16, v16, v17
	v_cvt_pk_bf16_f32 v17, v18, v19
	v_cvt_pk_bf16_f32 v18, v20, v21
	v_cvt_pk_bf16_f32 v19, v22, v23
	v_cvt_pk_bf16_f32 v20, v24, v25
	v_cvt_pk_bf16_f32 v21, v26, v27
	v_cvt_pk_bf16_f32 v22, v28, v29
	v_cvt_pk_bf16_f32 v23, v30, v31
	s_lshl_b32 s99, s98, 11
	v_lshl_add_u32 v8, v0, 3, s99
	global_store_dwordx2 v8, v[16:17], s[94:95]
	global_store_dwordx2 v8, v[18:19], s[94:95] offset:512
	global_store_dwordx2 v8, v[20:21], s[94:95] offset:1024
	global_store_dwordx2 v8, v[22:23], s[94:95] offset:1536
	s_lshl_b32 s99, s98, 2
	v_mov_b32_e32 v9, s99
	v_mov_b32_e32 v10, 0
	v_cmp_eq_u32_e32 vcc, 0, v0
	s_and_saveexec_b64 s[98:99], vcc
	global_store_dword v9, v10, s[90:91]
	global_store_dword v9, v10, s[92:93]
	s_or_b64 exec, exec, s[98:99]
	s_waitcnt vmcnt(38)
	v_mul_f32_e32 v4, v32, v32
	v_fma_f32 v4, v33, v33, v4
	v_fma_f32 v4, v34, v34, v4
	v_fma_f32 v4, v35, v35, v4
	v_fma_f32 v4, v36, v36, v4
	v_fma_f32 v4, v37, v37, v4
	v_fma_f32 v4, v38, v38, v4
	v_fma_f32 v4, v39, v39, v4
	v_fma_f32 v4, v40, v40, v4
	v_fma_f32 v4, v41, v41, v4
	v_fma_f32 v4, v42, v42, v4
	v_fma_f32 v4, v43, v43, v4
	v_fma_f32 v4, v44, v44, v4
	v_fma_f32 v4, v45, v45, v4
	v_fma_f32 v4, v46, v46, v4
	v_fma_f32 v4, v47, v47, v4
	s_nop 1
	v_add_f32_dpp v5, v4, v4 quad_perm:[1,0,3,2] row_mask:0xf bank_mask:0xf
	s_nop 1
	v_add_f32_dpp v4, v5, v5 quad_perm:[2,3,0,1] row_mask:0xf bank_mask:0xf
	s_nop 1
	v_add_f32_dpp v5, v4, v4 row_half_mirror row_mask:0xf bank_mask:0xf
	s_nop 1
	v_add_f32_dpp v4, v5, v5 row_mirror row_mask:0xf bank_mask:0xf
	s_nop 1
	v_readlane_b32 s98, v4, 0
	v_readlane_b32 s99, v4, 16
	s_nop 3
	v_mov_b32_e32 v5, s98
	v_add_f32_e32 v5, s99, v5
	v_readlane_b32 s98, v4, 32
	v_readlane_b32 s99, v4, 48
	s_nop 3
	v_add_f32_e32 v5, s98, v5
	v_add_f32_e32 v5, s99, v5
	v_mul_f32_e32 v5, 0x3a800000, v5
	v_add_f32_e32 v5, 0x358637bd, v5
	v_rsq_f32_e32 v6, v5
	s_nop 0
	s_add_u32 s98, s97, 13
	v_pk_mul_f32 v[32:33], v[32:33], v[6:7] op_sel_hi:[1,0]
	v_pk_mul_f32 v[34:35], v[34:35], v[6:7] op_sel_hi:[1,0]
	v_pk_mul_f32 v[36:37], v[36:37], v[6:7] op_sel_hi:[1,0]
	v_pk_mul_f32 v[38:39], v[38:39], v[6:7] op_sel_hi:[1,0]
	v_pk_mul_f32 v[40:41], v[40:41], v[6:7] op_sel_hi:[1,0]
	v_pk_mul_f32 v[42:43], v[42:43], v[6:7] op_sel_hi:[1,0]
	v_pk_mul_f32 v[44:45], v[44:45], v[6:7] op_sel_hi:[1,0]
	v_pk_mul_f32 v[46:47], v[46:47], v[6:7] op_sel_hi:[1,0]
	v_pk_mul_f32 v[32:33], v[32:33], v[112:113]
	v_pk_mul_f32 v[34:35], v[34:35], v[114:115]
	v_pk_mul_f32 v[36:37], v[36:37], v[116:117]
	v_pk_mul_f32 v[38:39], v[38:39], v[118:119]
	v_pk_mul_f32 v[40:41], v[40:41], v[120:121]
	v_pk_mul_f32 v[42:43], v[42:43], v[122:123]
	v_pk_mul_f32 v[44:45], v[44:45], v[124:125]
	v_pk_mul_f32 v[46:47], v[46:47], v[126:127]
	v_pk_fma_f32 v[32:33], v[32:33], v[128:129], v[144:145]
	v_pk_fma_f32 v[34:35], v[34:35], v[130:131], v[146:147]
	v_pk_fma_f32 v[36:37], v[36:37], v[132:133], v[148:149]
	v_pk_fma_f32 v[38:39], v[38:39], v[134:135], v[150:151]
	v_pk_fma_f32 v[40:41], v[40:41], v[136:137], v[152:153]
	v_pk_fma_f32 v[42:43], v[42:43], v[138:139], v[154:155]
	v_pk_fma_f32 v[44:45], v[44:45], v[140:141], v[156:157]
	v_pk_fma_f32 v[46:47], v[46:47], v[142:143], v[158:159]
	v_cvt_pk_bf16_f32 v32, v32, v33
	v_cvt_pk_bf16_f32 v33, v34, v35
	v_cvt_pk_bf16_f32 v34, v36, v37
	v_cvt_pk_bf16_f32 v35, v38, v39
	v_cvt_pk_bf16_f32 v36, v40, v41
	v_cvt_pk_bf16_f32 v37, v42, v43
	v_cvt_pk_bf16_f32 v38, v44, v45
	v_cvt_pk_bf16_f32 v39, v46, v47
	s_lshl_b32 s99, s98, 11
	v_lshl_add_u32 v8, v0, 3, s99
	global_store_dwordx2 v8, v[32:33], s[94:95]
	global_store_dwordx2 v8, v[34:35], s[94:95] offset:512
	global_store_dwordx2 v8, v[36:37], s[94:95] offset:1024
	global_store_dwordx2 v8, v[38:39], s[94:95] offset:1536
	s_lshl_b32 s99, s98, 2
	v_mov_b32_e32 v9, s99
	v_mov_b32_e32 v10, 0
	v_cmp_eq_u32_e32 vcc, 0, v0
	s_and_saveexec_b64 s[98:99], vcc
	global_store_dword v9, v10, s[90:91]
	global_store_dword v9, v10, s[92:93]
	s_or_b64 exec, exec, s[98:99]
	s_waitcnt vmcnt(34)
	v_mul_f32_e32 v4, v48, v48
	v_fma_f32 v4, v49, v49, v4
	v_fma_f32 v4, v50, v50, v4
	v_fma_f32 v4, v51, v51, v4
	v_fma_f32 v4, v52, v52, v4
	v_fma_f32 v4, v53, v53, v4
	v_fma_f32 v4, v54, v54, v4
	v_fma_f32 v4, v55, v55, v4
	v_fma_f32 v4, v56, v56, v4
	v_fma_f32 v4, v57, v57, v4
	v_fma_f32 v4, v58, v58, v4
	v_fma_f32 v4, v59, v59, v4
	v_fma_f32 v4, v60, v60, v4
	v_fma_f32 v4, v61, v61, v4
	v_fma_f32 v4, v62, v62, v4
	v_fma_f32 v4, v63, v63, v4
	s_nop 1
	v_add_f32_dpp v5, v4, v4 quad_perm:[1,0,3,2] row_mask:0xf bank_mask:0xf
	s_nop 1
	v_add_f32_dpp v4, v5, v5 quad_perm:[2,3,0,1] row_mask:0xf bank_mask:0xf
	s_nop 1
	v_add_f32_dpp v5, v4, v4 row_half_mirror row_mask:0xf bank_mask:0xf
	s_nop 1
	v_add_f32_dpp v4, v5, v5 row_mirror row_mask:0xf bank_mask:0xf
	s_nop 1
	v_readlane_b32 s98, v4, 0
	v_readlane_b32 s99, v4, 16
	s_nop 3
	v_mov_b32_e32 v5, s98
	v_add_f32_e32 v5, s99, v5
	v_readlane_b32 s98, v4, 32
	v_readlane_b32 s99, v4, 48
	s_nop 3
	v_add_f32_e32 v5, s98, v5
	v_add_f32_e32 v5, s99, v5
	v_mul_f32_e32 v5, 0x3a800000, v5
	v_add_f32_e32 v5, 0x358637bd, v5
	v_rsq_f32_e32 v6, v5
	s_nop 0
	s_add_u32 s98, s97, 14
	v_pk_mul_f32 v[48:49], v[48:49], v[6:7] op_sel_hi:[1,0]
	v_pk_mul_f32 v[50:51], v[50:51], v[6:7] op_sel_hi:[1,0]
	v_pk_mul_f32 v[52:53], v[52:53], v[6:7] op_sel_hi:[1,0]
	v_pk_mul_f32 v[54:55], v[54:55], v[6:7] op_sel_hi:[1,0]
	v_pk_mul_f32 v[56:57], v[56:57], v[6:7] op_sel_hi:[1,0]
	v_pk_mul_f32 v[58:59], v[58:59], v[6:7] op_sel_hi:[1,0]
	v_pk_mul_f32 v[60:61], v[60:61], v[6:7] op_sel_hi:[1,0]
	v_pk_mul_f32 v[62:63], v[62:63], v[6:7] op_sel_hi:[1,0]
	v_pk_mul_f32 v[48:49], v[48:49], v[112:113]
	v_pk_mul_f32 v[50:51], v[50:51], v[114:115]
	v_pk_mul_f32 v[52:53], v[52:53], v[116:117]
	v_pk_mul_f32 v[54:55], v[54:55], v[118:119]
	v_pk_mul_f32 v[56:57], v[56:57], v[120:121]
	v_pk_mul_f32 v[58:59], v[58:59], v[122:123]
	v_pk_mul_f32 v[60:61], v[60:61], v[124:125]
	v_pk_mul_f32 v[62:63], v[62:63], v[126:127]
	v_pk_fma_f32 v[48:49], v[48:49], v[128:129], v[144:145]
	v_pk_fma_f32 v[50:51], v[50:51], v[130:131], v[146:147]
	v_pk_fma_f32 v[52:53], v[52:53], v[132:133], v[148:149]
	v_pk_fma_f32 v[54:55], v[54:55], v[134:135], v[150:151]
	v_pk_fma_f32 v[56:57], v[56:57], v[136:137], v[152:153]
	v_pk_fma_f32 v[58:59], v[58:59], v[138:139], v[154:155]
	v_pk_fma_f32 v[60:61], v[60:61], v[140:141], v[156:157]
	v_pk_fma_f32 v[62:63], v[62:63], v[142:143], v[158:159]
	v_cvt_pk_bf16_f32 v48, v48, v49
	v_cvt_pk_bf16_f32 v49, v50, v51
	v_cvt_pk_bf16_f32 v50, v52, v53
	v_cvt_pk_bf16_f32 v51, v54, v55
	v_cvt_pk_bf16_f32 v52, v56, v57
	v_cvt_pk_bf16_f32 v53, v58, v59
	v_cvt_pk_bf16_f32 v54, v60, v61
	v_cvt_pk_bf16_f32 v55, v62, v63
	s_lshl_b32 s99, s98, 11
	v_lshl_add_u32 v8, v0, 3, s99
	global_store_dwordx2 v8, v[48:49], s[94:95]
	global_store_dwordx2 v8, v[50:51], s[94:95] offset:512
	global_store_dwordx2 v8, v[52:53], s[94:95] offset:1024
	global_store_dwordx2 v8, v[54:55], s[94:95] offset:1536
	s_lshl_b32 s99, s98, 2
	v_mov_b32_e32 v9, s99
	v_mov_b32_e32 v10, 0
	v_cmp_eq_u32_e32 vcc, 0, v0
	s_and_saveexec_b64 s[98:99], vcc
	global_store_dword v9, v10, s[90:91]
	global_store_dword v9, v10, s[92:93]
	s_or_b64 exec, exec, s[98:99]
	s_waitcnt vmcnt(30)
	v_mul_f32_e32 v4, v64, v64
	v_fma_f32 v4, v65, v65, v4
	v_fma_f32 v4, v66, v66, v4
	v_fma_f32 v4, v67, v67, v4
	v_fma_f32 v4, v68, v68, v4
	v_fma_f32 v4, v69, v69, v4
	v_fma_f32 v4, v70, v70, v4
	v_fma_f32 v4, v71, v71, v4
	v_fma_f32 v4, v72, v72, v4
	v_fma_f32 v4, v73, v73, v4
	v_fma_f32 v4, v74, v74, v4
	v_fma_f32 v4, v75, v75, v4
	v_fma_f32 v4, v76, v76, v4
	v_fma_f32 v4, v77, v77, v4
	v_fma_f32 v4, v78, v78, v4
	v_fma_f32 v4, v79, v79, v4
	s_nop 1
	v_add_f32_dpp v5, v4, v4 quad_perm:[1,0,3,2] row_mask:0xf bank_mask:0xf
	s_nop 1
	v_add_f32_dpp v4, v5, v5 quad_perm:[2,3,0,1] row_mask:0xf bank_mask:0xf
	s_nop 1
	v_add_f32_dpp v5, v4, v4 row_half_mirror row_mask:0xf bank_mask:0xf
	s_nop 1
	v_add_f32_dpp v4, v5, v5 row_mirror row_mask:0xf bank_mask:0xf
	s_nop 1
	v_readlane_b32 s98, v4, 0
	v_readlane_b32 s99, v4, 16
	s_nop 3
	v_mov_b32_e32 v5, s98
	v_add_f32_e32 v5, s99, v5
	v_readlane_b32 s98, v4, 32
	v_readlane_b32 s99, v4, 48
	s_nop 3
	v_add_f32_e32 v5, s98, v5
	v_add_f32_e32 v5, s99, v5
	v_mul_f32_e32 v5, 0x3a800000, v5
	v_add_f32_e32 v5, 0x358637bd, v5
	v_rsq_f32_e32 v6, v5
	s_nop 0
	s_add_u32 s98, s97, 15
	v_pk_mul_f32 v[64:65], v[64:65], v[6:7] op_sel_hi:[1,0]
	v_pk_mul_f32 v[66:67], v[66:67], v[6:7] op_sel_hi:[1,0]
	v_pk_mul_f32 v[68:69], v[68:69], v[6:7] op_sel_hi:[1,0]
	v_pk_mul_f32 v[70:71], v[70:71], v[6:7] op_sel_hi:[1,0]
	v_pk_mul_f32 v[72:73], v[72:73], v[6:7] op_sel_hi:[1,0]
	v_pk_mul_f32 v[74:75], v[74:75], v[6:7] op_sel_hi:[1,0]
	v_pk_mul_f32 v[76:77], v[76:77], v[6:7] op_sel_hi:[1,0]
	v_pk_mul_f32 v[78:79], v[78:79], v[6:7] op_sel_hi:[1,0]
	v_pk_mul_f32 v[64:65], v[64:65], v[112:113]
	v_pk_mul_f32 v[66:67], v[66:67], v[114:115]
	v_pk_mul_f32 v[68:69], v[68:69], v[116:117]
	v_pk_mul_f32 v[70:71], v[70:71], v[118:119]
	v_pk_mul_f32 v[72:73], v[72:73], v[120:121]
	v_pk_mul_f32 v[74:75], v[74:75], v[122:123]
	v_pk_mul_f32 v[76:77], v[76:77], v[124:125]
	v_pk_mul_f32 v[78:79], v[78:79], v[126:127]
	v_pk_fma_f32 v[64:65], v[64:65], v[128:129], v[144:145]
	v_pk_fma_f32 v[66:67], v[66:67], v[130:131], v[146:147]
	v_pk_fma_f32 v[68:69], v[68:69], v[132:133], v[148:149]
	v_pk_fma_f32 v[70:71], v[70:71], v[134:135], v[150:151]
	v_pk_fma_f32 v[72:73], v[72:73], v[136:137], v[152:153]
	v_pk_fma_f32 v[74:75], v[74:75], v[138:139], v[154:155]
	v_pk_fma_f32 v[76:77], v[76:77], v[140:141], v[156:157]
	v_pk_fma_f32 v[78:79], v[78:79], v[142:143], v[158:159]
	v_cvt_pk_bf16_f32 v64, v64, v65
	v_cvt_pk_bf16_f32 v65, v66, v67
	v_cvt_pk_bf16_f32 v66, v68, v69
	v_cvt_pk_bf16_f32 v67, v70, v71
	v_cvt_pk_bf16_f32 v68, v72, v73
	v_cvt_pk_bf16_f32 v69, v74, v75
	v_cvt_pk_bf16_f32 v70, v76, v77
	v_cvt_pk_bf16_f32 v71, v78, v79
	s_lshl_b32 s99, s98, 11
	v_lshl_add_u32 v8, v0, 3, s99
	global_store_dwordx2 v8, v[64:65], s[94:95]
	global_store_dwordx2 v8, v[66:67], s[94:95] offset:512
	global_store_dwordx2 v8, v[68:69], s[94:95] offset:1024
	global_store_dwordx2 v8, v[70:71], s[94:95] offset:1536
	s_lshl_b32 s99, s98, 2
	v_mov_b32_e32 v9, s99
	v_mov_b32_e32 v10, 0
	v_cmp_eq_u32_e32 vcc, 0, v0
	s_and_saveexec_b64 s[98:99], vcc
	global_store_dword v9, v10, s[90:91]
	global_store_dword v9, v10, s[92:93]
	s_or_b64 exec, exec, s[98:99]
	s_waitcnt vmcnt(0)

.LBB0_5762:
	s_cmp_gt_i32 s44, 22
	s_waitcnt lgkmcnt(0)
	s_cselect_b64 s[2:3], -1, 0
	s_cmp_lt_i32 s45, 23
	s_cselect_b64 s[4:5], -1, 0
	s_or_b64 s[2:3], s[2:3], s[4:5]
	s_and_b64 vcc, exec, s[2:3]
	s_cbranch_vccnz .LBB0_5820
	s_lshl_b32 s96, s22, 3
	s_lshr_b32 s97, s70, 6
	s_add_u32 s96, s96, s97
	s_lshl_b32 s97, s96, 4
	s_cmpk_ge_u32 s97, 0x8000
	s_cbranch_scc1 .Lnp22_done
	s_load_dwordx2 s[88:89], s[0:1], 0xb8
	s_load_dwordx2 s[90:91], s[0:1], 0xb0
	v_mbcnt_hi_u32_b32 v0, -1, v210
	v_lshlrev_b32_e32 v1, 4, v0
	s_waitcnt lgkmcnt(0)
	global_load_dwordx4 v[112:115], v1, s[90:91] nt
	global_load_dwordx4 v[116:119], v1, s[90:91] offset:1024 nt
	global_load_dwordx4 v[120:123], v1, s[90:91] offset:2048 nt
	global_load_dwordx4 v[124:127], v1, s[90:91] offset:3072 nt
	s_waitcnt vmcnt(0) lgkmcnt(0)
	s_add_u32 s98, s97, 0
	s_lshl_b32 s98, s98, 12
	v_add_u32_e32 v3, s98, v1
	global_load_dwordx4 v[16:19], v3, s[88:89] nt
	global_load_dwordx4 v[20:23], v3, s[88:89] offset:1024 nt
	global_load_dwordx4 v[24:27], v3, s[88:89] offset:2048 nt
	global_load_dwordx4 v[28:31], v3, s[88:89] offset:3072 nt
	s_add_u32 s98, s97, 1
	s_lshl_b32 s98, s98, 12
	v_add_u32_e32 v3, s98, v1
	global_load_dwordx4 v[32:35], v3, s[88:89] nt
	global_load_dwordx4 v[36:39], v3, s[88:89] offset:1024 nt
	global_load_dwordx4 v[40:43], v3, s[88:89] offset:2048 nt
	global_load_dwordx4 v[44:47], v3, s[88:89] offset:3072 nt
	s_add_u32 s98, s97, 2
	s_lshl_b32 s98, s98, 12
	v_add_u32_e32 v3, s98, v1
	global_load_dwordx4 v[48:51], v3, s[88:89] nt
	global_load_dwordx4 v[52:55], v3, s[88:89] offset:1024 nt
	global_load_dwordx4 v[56:59], v3, s[88:89] offset:2048 nt
	global_load_dwordx4 v[60:63], v3, s[88:89] offset:3072 nt
	s_add_u32 s98, s97, 3
	s_lshl_b32 s98, s98, 12
	v_add_u32_e32 v3, s98, v1
	global_load_dwordx4 v[64:67], v3, s[88:89] nt
	global_load_dwordx4 v[68:71], v3, s[88:89] offset:1024 nt
	global_load_dwordx4 v[72:75], v3, s[88:89] offset:2048 nt
	global_load_dwordx4 v[76:79], v3, s[88:89] offset:3072 nt
	s_add_u32 s98, s97, 4
	s_lshl_b32 s98, s98, 12
	v_add_u32_e32 v3, s98, v1
	global_load_dwordx4 v[80:83], v3, s[88:89] nt
	global_load_dwordx4 v[84:87], v3, s[88:89] offset:1024 nt
	global_load_dwordx4 v[88:91], v3, s[88:89] offset:2048 nt
	global_load_dwordx4 v[92:95], v3, s[88:89] offset:3072 nt
	s_add_u32 s98, s97, 5
	s_lshl_b32 s98, s98, 12
	v_add_u32_e32 v3, s98, v1
	global_load_dwordx4 v[96:99], v3, s[88:89] nt
	global_load_dwordx4 v[100:103], v3, s[88:89] offset:1024 nt
	global_load_dwordx4 v[104:107], v3, s[88:89] offset:2048 nt
	global_load_dwordx4 v[108:111], v3, s[88:89] offset:3072 nt
	s_waitcnt vmcnt(20)
	v_mul_f32_e32 v4, v16, v16
	v_fma_f32 v4, v17, v17, v4
	v_fma_f32 v4, v18, v18, v4
	v_fma_f32 v4, v19, v19, v4
	v_fma_f32 v4, v20, v20, v4
	v_fma_f32 v4, v21, v21, v4
	v_fma_f32 v4, v22, v22, v4
	v_fma_f32 v4, v23, v23, v4
	v_fma_f32 v4, v24, v24, v4
	v_fma_f32 v4, v25, v25, v4
	v_fma_f32 v4, v26, v26, v4
	v_fma_f32 v4, v27, v27, v4
	v_fma_f32 v4, v28, v28, v4
	v_fma_f32 v4, v29, v29, v4
	v_fma_f32 v4, v30, v30, v4
	v_fma_f32 v4, v31, v31, v4
	s_nop 1
	v_add_f32_dpp v5, v4, v4 quad_perm:[1,0,3,2] row_mask:0xf bank_mask:0xf
	s_nop 1
	v_add_f32_dpp v4, v5, v5 quad_perm:[2,3,0,1] row_mask:0xf bank_mask:0xf
	s_nop 1
	v_add_f32_dpp v5, v4, v4 row_half_mirror row_mask:0xf bank_mask:0xf
	s_nop 1
	v_add_f32_dpp v4, v5, v5 row_mirror row_mask:0xf bank_mask:0xf
	s_nop 1
	v_readlane_b32 s98, v4, 0
	v_readlane_b32 s99, v4, 16
	s_nop 3
	v_mov_b32_e32 v5, s98
	v_add_f32_e32 v5, s99, v5
	v_readlane_b32 s98, v4, 32
	v_readlane_b32 s99, v4, 48
	s_nop 3
	v_add_f32_e32 v5, s98, v5
	v_add_f32_e32 v5, s99, v5
	v_mul_f32_e32 v5, 0x3a800000, v5
	v_add_f32_e32 v5, 0x358637bd, v5
	v_rsq_f32_e32 v6, v5
	s_nop 0
	s_add_u32 s98, s97, 0
	v_pk_mul_f32 v[16:17], v[16:17], v[6:7] op_sel_hi:[1,0]
	v_pk_mul_f32 v[18:19], v[18:19], v[6:7] op_sel_hi:[1,0]
	v_pk_mul_f32 v[20:21], v[20:21], v[6:7] op_sel_hi:[1,0]
	v_pk_mul_f32 v[22:23], v[22:23], v[6:7] op_sel_hi:[1,0]
	v_pk_mul_f32 v[24:25], v[24:25], v[6:7] op_sel_hi:[1,0]
	v_pk_mul_f32 v[26:27], v[26:27], v[6:7] op_sel_hi:[1,0]
	v_pk_mul_f32 v[28:29], v[28:29], v[6:7] op_sel_hi:[1,0]
	v_pk_mul_f32 v[30:31], v[30:31], v[6:7] op_sel_hi:[1,0]
	v_pk_mul_f32 v[16:17], v[16:17], v[112:113]
	v_pk_mul_f32 v[18:19], v[18:19], v[114:115]
	v_pk_mul_f32 v[20:21], v[20:21], v[116:117]
	v_pk_mul_f32 v[22:23], v[22:23], v[118:119]
	v_pk_mul_f32 v[24:25], v[24:25], v[120:121]
	v_pk_mul_f32 v[26:27], v[26:27], v[122:123]
	v_pk_mul_f32 v[28:29], v[28:29], v[124:125]
	v_pk_mul_f32 v[30:31], v[30:31], v[126:127]
	s_lshl_b32 s99, s98, 12
	v_add_u32_e32 v8, s99, v1
	global_store_dwordx4 v8, v[16:19], s[88:89] nt
	global_store_dwordx4 v8, v[20:23], s[88:89] offset:1024 nt
	global_store_dwordx4 v8, v[24:27], s[88:89] offset:2048 nt
	global_store_dwordx4 v8, v[28:31], s[88:89] offset:3072 nt
	s_add_u32 s98, s97, 6
	s_lshl_b32 s98, s98, 12
	v_add_u32_e32 v3, s98, v1
	global_load_dwordx4 v[16:19], v3, s[88:89] nt
	global_load_dwordx4 v[20:23], v3, s[88:89] offset:1024 nt
	global_load_dwordx4 v[24:27], v3, s[88:89] offset:2048 nt
	global_load_dwordx4 v[28:31], v3, s[88:89] offset:3072 nt
	s_waitcnt vmcnt(24)
	v_mul_f32_e32 v4, v32, v32
	v_fma_f32 v4, v33, v33, v4
	v_fma_f32 v4, v34, v34, v4
	v_fma_f32 v4, v35, v35, v4
	v_fma_f32 v4, v36, v36, v4
	v_fma_f32 v4, v37, v37, v4
	v_fma_f32 v4, v38, v38, v4
	v_fma_f32 v4, v39, v39, v4
	v_fma_f32 v4, v40, v40, v4
	v_fma_f32 v4, v41, v41, v4
	v_fma_f32 v4, v42, v42, v4
	v_fma_f32 v4, v43, v43, v4
	v_fma_f32 v4, v44, v44, v4
	v_fma_f32 v4, v45, v45, v4
	v_fma_f32 v4, v46, v46, v4
	v_fma_f32 v4, v47, v47, v4
	s_nop 1
	v_add_f32_dpp v5, v4, v4 quad_perm:[1,0,3,2] row_mask:0xf bank_mask:0xf
	s_nop 1
	v_add_f32_dpp v4, v5, v5 quad_perm:[2,3,0,1] row_mask:0xf bank_mask:0xf
	s_nop 1
	v_add_f32_dpp v5, v4, v4 row_half_mirror row_mask:0xf bank_mask:0xf
	s_nop 1
	v_add_f32_dpp v4, v5, v5 row_mirror row_mask:0xf bank_mask:0xf
	s_nop 1
	v_readlane_b32 s98, v4, 0
	v_readlane_b32 s99, v4, 16
	s_nop 3
	v_mov_b32_e32 v5, s98
	v_add_f32_e32 v5, s99, v5
	v_readlane_b32 s98, v4, 32
	v_readlane_b32 s99, v4, 48
	s_nop 3
	v_add_f32_e32 v5, s98, v5
	v_add_f32_e32 v5, s99, v5
	v_mul_f32_e32 v5, 0x3a800000, v5
	v_add_f32_e32 v5, 0x358637bd, v5
	v_rsq_f32_e32 v6, v5
	s_nop 0
	s_add_u32 s98, s97, 1
	v_pk_mul_f32 v[32:33], v[32:33], v[6:7] op_sel_hi:[1,0]
	v_pk_mul_f32 v[34:35], v[34:35], v[6:7] op_sel_hi:[1,0]
	v_pk_mul_f32 v[36:37], v[36:37], v[6:7] op_sel_hi:[1,0]
	v_pk_mul_f32 v[38:39], v[38:39], v[6:7] op_sel_hi:[1,0]
	v_pk_mul_f32 v[40:41], v[40:41], v[6:7] op_sel_hi:[1,0]
	v_pk_mul_f32 v[42:43], v[42:43], v[6:7] op_sel_hi:[1,0]
	v_pk_mul_f32 v[44:45], v[44:45], v[6:7] op_sel_hi:[1,0]
	v_pk_mul_f32 v[46:47], v[46:47], v[6:7] op_sel_hi:[1,0]
	v_pk_mul_f32 v[32:33], v[32:33], v[112:113]
	v_pk_mul_f32 v[34:35], v[34:35], v[114:115]
	v_pk_mul_f32 v[36:37], v[36:37], v[116:117]
	v_pk_mul_f32 v[38:39], v[38:39], v[118:119]
	v_pk_mul_f32 v[40:41], v[40:41], v[120:121]
	v_pk_mul_f32 v[42:43], v[42:43], v[122:123]
	v_pk_mul_f32 v[44:45], v[44:45], v[124:125]
	v_pk_mul_f32 v[46:47], v[46:47], v[126:127]
	s_lshl_b32 s99, s98, 12
	v_add_u32_e32 v8, s99, v1
	global_store_dwordx4 v8, v[32:35], s[88:89] nt
	global_store_dwordx4 v8, v[36:39], s[88:89] offset:1024 nt
	global_store_dwordx4 v8, v[40:43], s[88:89] offset:2048 nt
	global_store_dwordx4 v8, v[44:47], s[88:89] offset:3072 nt
	s_add_u32 s98, s97, 7
	s_lshl_b32 s98, s98, 12
	v_add_u32_e32 v3, s98, v1
	global_load_dwordx4 v[32:35], v3, s[88:89] nt
	global_load_dwordx4 v[36:39], v3, s[88:89] offset:1024 nt
	global_load_dwordx4 v[40:43], v3, s[88:89] offset:2048 nt
	global_load_dwordx4 v[44:47], v3, s[88:89] offset:3072 nt
	s_waitcnt vmcnt(28)
	v_mul_f32_e32 v4, v48, v48
	v_fma_f32 v4, v49, v49, v4
	v_fma_f32 v4, v50, v50, v4
	v_fma_f32 v4, v51, v51, v4
	v_fma_f32 v4, v52, v52, v4
	v_fma_f32 v4, v53, v53, v4
	v_fma_f32 v4, v54, v54, v4
	v_fma_f32 v4, v55, v55, v4
	v_fma_f32 v4, v56, v56, v4
	v_fma_f32 v4, v57, v57, v4
	v_fma_f32 v4, v58, v58, v4
	v_fma_f32 v4, v59, v59, v4
	v_fma_f32 v4, v60, v60, v4
	v_fma_f32 v4, v61, v61, v4
	v_fma_f32 v4, v62, v62, v4
	v_fma_f32 v4, v63, v63, v4
	s_nop 1
	v_add_f32_dpp v5, v4, v4 quad_perm:[1,0,3,2] row_mask:0xf bank_mask:0xf
	s_nop 1
	v_add_f32_dpp v4, v5, v5 quad_perm:[2,3,0,1] row_mask:0xf bank_mask:0xf
	s_nop 1
	v_add_f32_dpp v5, v4, v4 row_half_mirror row_mask:0xf bank_mask:0xf
	s_nop 1
	v_add_f32_dpp v4, v5, v5 row_mirror row_mask:0xf bank_mask:0xf
	s_nop 1
	v_readlane_b32 s98, v4, 0
	v_readlane_b32 s99, v4, 16
	s_nop 3
	v_mov_b32_e32 v5, s98
	v_add_f32_e32 v5, s99, v5
	v_readlane_b32 s98, v4, 32
	v_readlane_b32 s99, v4, 48
	s_nop 3
	v_add_f32_e32 v5, s98, v5
	v_add_f32_e32 v5, s99, v5
	v_mul_f32_e32 v5, 0x3a800000, v5
	v_add_f32_e32 v5, 0x358637bd, v5
	v_rsq_f32_e32 v6, v5
	s_nop 0
	s_add_u32 s98, s97, 2
	v_pk_mul_f32 v[48:49], v[48:49], v[6:7] op_sel_hi:[1,0]
	v_pk_mul_f32 v[50:51], v[50:51], v[6:7] op_sel_hi:[1,0]
	v_pk_mul_f32 v[52:53], v[52:53], v[6:7] op_sel_hi:[1,0]
	v_pk_mul_f32 v[54:55], v[54:55], v[6:7] op_sel_hi:[1,0]
	v_pk_mul_f32 v[56:57], v[56:57], v[6:7] op_sel_hi:[1,0]
	v_pk_mul_f32 v[58:59], v[58:59], v[6:7] op_sel_hi:[1,0]
	v_pk_mul_f32 v[60:61], v[60:61], v[6:7] op_sel_hi:[1,0]
	v_pk_mul_f32 v[62:63], v[62:63], v[6:7] op_sel_hi:[1,0]
	v_pk_mul_f32 v[48:49], v[48:49], v[112:113]
	v_pk_mul_f32 v[50:51], v[50:51], v[114:115]
	v_pk_mul_f32 v[52:53], v[52:53], v[116:117]
	v_pk_mul_f32 v[54:55], v[54:55], v[118:119]
	v_pk_mul_f32 v[56:57], v[56:57], v[120:121]
	v_pk_mul_f32 v[58:59], v[58:59], v[122:123]
	v_pk_mul_f32 v[60:61], v[60:61], v[124:125]
	v_pk_mul_f32 v[62:63], v[62:63], v[126:127]
	s_lshl_b32 s99, s98, 12
	v_add_u32_e32 v8, s99, v1
	global_store_dwordx4 v8, v[48:51], s[88:89] nt
	global_store_dwordx4 v8, v[52:55], s[88:89] offset:1024 nt
	global_store_dwordx4 v8, v[56:59], s[88:89] offset:2048 nt
	global_store_dwordx4 v8, v[60:63], s[88:89] offset:3072 nt
	s_add_u32 s98, s97, 8
	s_lshl_b32 s98, s98, 12
	v_add_u32_e32 v3, s98, v1
	global_load_dwordx4 v[48:51], v3, s[88:89] nt
	global_load_dwordx4 v[52:55], v3, s[88:89] offset:1024 nt
	global_load_dwordx4 v[56:59], v3, s[88:89] offset:2048 nt
	global_load_dwordx4 v[60:63], v3, s[88:89] offset:3072 nt
	s_waitcnt vmcnt(32)
	v_mul_f32_e32 v4, v64, v64
	v_fma_f32 v4, v65, v65, v4
	v_fma_f32 v4, v66, v66, v4
	v_fma_f32 v4, v67, v67, v4
	v_fma_f32 v4, v68, v68, v4
	v_fma_f32 v4, v69, v69, v4
	v_fma_f32 v4, v70, v70, v4
	v_fma_f32 v4, v71, v71, v4
	v_fma_f32 v4, v72, v72, v4
	v_fma_f32 v4, v73, v73, v4
	v_fma_f32 v4, v74, v74, v4
	v_fma_f32 v4, v75, v75, v4
	v_fma_f32 v4, v76, v76, v4
	v_fma_f32 v4, v77, v77, v4
	v_fma_f32 v4, v78, v78, v4
	v_fma_f32 v4, v79, v79, v4
	s_nop 1
	v_add_f32_dpp v5, v4, v4 quad_perm:[1,0,3,2] row_mask:0xf bank_mask:0xf
	s_nop 1
	v_add_f32_dpp v4, v5, v5 quad_perm:[2,3,0,1] row_mask:0xf bank_mask:0xf
	s_nop 1
	v_add_f32_dpp v5, v4, v4 row_half_mirror row_mask:0xf bank_mask:0xf
	s_nop 1
	v_add_f32_dpp v4, v5, v5 row_mirror row_mask:0xf bank_mask:0xf
	s_nop 1
	v_readlane_b32 s98, v4, 0
	v_readlane_b32 s99, v4, 16
	s_nop 3
	v_mov_b32_e32 v5, s98
	v_add_f32_e32 v5, s99, v5
	v_readlane_b32 s98, v4, 32
	v_readlane_b32 s99, v4, 48
	s_nop 3
	v_add_f32_e32 v5, s98, v5
	v_add_f32_e32 v5, s99, v5
	v_mul_f32_e32 v5, 0x3a800000, v5
	v_add_f32_e32 v5, 0x358637bd, v5
	v_rsq_f32_e32 v6, v5
	s_nop 0
	s_add_u32 s98, s97, 3
	v_pk_mul_f32 v[64:65], v[64:65], v[6:7] op_sel_hi:[1,0]
	v_pk_mul_f32 v[66:67], v[66:67], v[6:7] op_sel_hi:[1,0]
	v_pk_mul_f32 v[68:69], v[68:69], v[6:7] op_sel_hi:[1,0]
	v_pk_mul_f32 v[70:71], v[70:71], v[6:7] op_sel_hi:[1,0]
	v_pk_mul_f32 v[72:73], v[72:73], v[6:7] op_sel_hi:[1,0]
	v_pk_mul_f32 v[74:75], v[74:75], v[6:7] op_sel_hi:[1,0]
	v_pk_mul_f32 v[76:77], v[76:77], v[6:7] op_sel_hi:[1,0]
	v_pk_mul_f32 v[78:79], v[78:79], v[6:7] op_sel_hi:[1,0]
	v_pk_mul_f32 v[64:65], v[64:65], v[112:113]
	v_pk_mul_f32 v[66:67], v[66:67], v[114:115]
	v_pk_mul_f32 v[68:69], v[68:69], v[116:117]
	v_pk_mul_f32 v[70:71], v[70:71], v[118:119]
	v_pk_mul_f32 v[72:73], v[72:73], v[120:121]
	v_pk_mul_f32 v[74:75], v[74:75], v[122:123]
	v_pk_mul_f32 v[76:77], v[76:77], v[124:125]
	v_pk_mul_f32 v[78:79], v[78:79], v[126:127]
	s_lshl_b32 s99, s98, 12
	v_add_u32_e32 v8, s99, v1
	global_store_dwordx4 v8, v[64:67], s[88:89] nt
	global_store_dwordx4 v8, v[68:71], s[88:89] offset:1024 nt
	global_store_dwordx4 v8, v[72:75], s[88:89] offset:2048 nt
	global_store_dwordx4 v8, v[76:79], s[88:89] offset:3072 nt
	s_add_u32 s98, s97, 9
	s_lshl_b32 s98, s98, 12
	v_add_u32_e32 v3, s98, v1
	global_load_dwordx4 v[64:67], v3, s[88:89] nt
	global_load_dwordx4 v[68:71], v3, s[88:89] offset:1024 nt
	global_load_dwordx4 v[72:75], v3, s[88:89] offset:2048 nt
	global_load_dwordx4 v[76:79], v3, s[88:89] offset:3072 nt
	s_waitcnt vmcnt(36)
	v_mul_f32_e32 v4, v80, v80
	v_fma_f32 v4, v81, v81, v4
	v_fma_f32 v4, v82, v82, v4
	v_fma_f32 v4, v83, v83, v4
	v_fma_f32 v4, v84, v84, v4
	v_fma_f32 v4, v85, v85, v4
	v_fma_f32 v4, v86, v86, v4
	v_fma_f32 v4, v87, v87, v4
	v_fma_f32 v4, v88, v88, v4
	v_fma_f32 v4, v89, v89, v4
	v_fma_f32 v4, v90, v90, v4
	v_fma_f32 v4, v91, v91, v4
	v_fma_f32 v4, v92, v92, v4
	v_fma_f32 v4, v93, v93, v4
	v_fma_f32 v4, v94, v94, v4
	v_fma_f32 v4, v95, v95, v4
	s_nop 1
	v_add_f32_dpp v5, v4, v4 quad_perm:[1,0,3,2] row_mask:0xf bank_mask:0xf
	s_nop 1
	v_add_f32_dpp v4, v5, v5 quad_perm:[2,3,0,1] row_mask:0xf bank_mask:0xf
	s_nop 1
	v_add_f32_dpp v5, v4, v4 row_half_mirror row_mask:0xf bank_mask:0xf
	s_nop 1
	v_add_f32_dpp v4, v5, v5 row_mirror row_mask:0xf bank_mask:0xf
	s_nop 1
	v_readlane_b32 s98, v4, 0
	v_readlane_b32 s99, v4, 16
	s_nop 3
	v_mov_b32_e32 v5, s98
	v_add_f32_e32 v5, s99, v5
	v_readlane_b32 s98, v4, 32
	v_readlane_b32 s99, v4, 48
	s_nop 3
	v_add_f32_e32 v5, s98, v5
	v_add_f32_e32 v5, s99, v5
	v_mul_f32_e32 v5, 0x3a800000, v5
	v_add_f32_e32 v5, 0x358637bd, v5
	v_rsq_f32_e32 v6, v5
	s_nop 0
	s_add_u32 s98, s97, 4
	v_pk_mul_f32 v[80:81], v[80:81], v[6:7] op_sel_hi:[1,0]
	v_pk_mul_f32 v[82:83], v[82:83], v[6:7] op_sel_hi:[1,0]
	v_pk_mul_f32 v[84:85], v[84:85], v[6:7] op_sel_hi:[1,0]
	v_pk_mul_f32 v[86:87], v[86:87], v[6:7] op_sel_hi:[1,0]
	v_pk_mul_f32 v[88:89], v[88:89], v[6:7] op_sel_hi:[1,0]
	v_pk_mul_f32 v[90:91], v[90:91], v[6:7] op_sel_hi:[1,0]
	v_pk_mul_f32 v[92:93], v[92:93], v[6:7] op_sel_hi:[1,0]
	v_pk_mul_f32 v[94:95], v[94:95], v[6:7] op_sel_hi:[1,0]
	v_pk_mul_f32 v[80:81], v[80:81], v[112:113]
	v_pk_mul_f32 v[82:83], v[82:83], v[114:115]
	v_pk_mul_f32 v[84:85], v[84:85], v[116:117]
	v_pk_mul_f32 v[86:87], v[86:87], v[118:119]
	v_pk_mul_f32 v[88:89], v[88:89], v[120:121]
	v_pk_mul_f32 v[90:91], v[90:91], v[122:123]
	v_pk_mul_f32 v[92:93], v[92:93], v[124:125]
	v_pk_mul_f32 v[94:95], v[94:95], v[126:127]
	s_lshl_b32 s99, s98, 12
	v_add_u32_e32 v8, s99, v1
	global_store_dwordx4 v8, v[80:83], s[88:89] nt
	global_store_dwordx4 v8, v[84:87], s[88:89] offset:1024 nt
	global_store_dwordx4 v8, v[88:91], s[88:89] offset:2048 nt
	global_store_dwordx4 v8, v[92:95], s[88:89] offset:3072 nt
	s_add_u32 s98, s97, 10
	s_lshl_b32 s98, s98, 12
	v_add_u32_e32 v3, s98, v1
	global_load_dwordx4 v[80:83], v3, s[88:89] nt
	global_load_dwordx4 v[84:87], v3, s[88:89] offset:1024 nt
	global_load_dwordx4 v[88:91], v3, s[88:89] offset:2048 nt
	global_load_dwordx4 v[92:95], v3, s[88:89] offset:3072 nt
	s_waitcnt vmcnt(40)
	v_mul_f32_e32 v4, v96, v96
	v_fma_f32 v4, v97, v97, v4
	v_fma_f32 v4, v98, v98, v4
	v_fma_f32 v4, v99, v99, v4
	v_fma_f32 v4, v100, v100, v4
	v_fma_f32 v4, v101, v101, v4
	v_fma_f32 v4, v102, v102, v4
	v_fma_f32 v4, v103, v103, v4
	v_fma_f32 v4, v104, v104, v4
	v_fma_f32 v4, v105, v105, v4
	v_fma_f32 v4, v106, v106, v4
	v_fma_f32 v4, v107, v107, v4
	v_fma_f32 v4, v108, v108, v4
	v_fma_f32 v4, v109, v109, v4
	v_fma_f32 v4, v110, v110, v4
	v_fma_f32 v4, v111, v111, v4
	s_nop 1
	v_add_f32_dpp v5, v4, v4 quad_perm:[1,0,3,2] row_mask:0xf bank_mask:0xf
	s_nop 1
	v_add_f32_dpp v4, v5, v5 quad_perm:[2,3,0,1] row_mask:0xf bank_mask:0xf
	s_nop 1
	v_add_f32_dpp v5, v4, v4 row_half_mirror row_mask:0xf bank_mask:0xf
	s_nop 1
	v_add_f32_dpp v4, v5, v5 row_mirror row_mask:0xf bank_mask:0xf
	s_nop 1
	v_readlane_b32 s98, v4, 0
	v_readlane_b32 s99, v4, 16
	s_nop 3
	v_mov_b32_e32 v5, s98
	v_add_f32_e32 v5, s99, v5
	v_readlane_b32 s98, v4, 32
	v_readlane_b32 s99, v4, 48
	s_nop 3
	v_add_f32_e32 v5, s98, v5
	v_add_f32_e32 v5, s99, v5
	v_mul_f32_e32 v5, 0x3a800000, v5
	v_add_f32_e32 v5, 0x358637bd, v5
	v_rsq_f32_e32 v6, v5
	s_nop 0
	s_add_u32 s98, s97, 5
	v_pk_mul_f32 v[96:97], v[96:97], v[6:7] op_sel_hi:[1,0]
	v_pk_mul_f32 v[98:99], v[98:99], v[6:7] op_sel_hi:[1,0]
	v_pk_mul_f32 v[100:101], v[100:101], v[6:7] op_sel_hi:[1,0]
	v_pk_mul_f32 v[102:103], v[102:103], v[6:7] op_sel_hi:[1,0]
	v_pk_mul_f32 v[104:105], v[104:105], v[6:7] op_sel_hi:[1,0]
	v_pk_mul_f32 v[106:107], v[106:107], v[6:7] op_sel_hi:[1,0]
	v_pk_mul_f32 v[108:109], v[108:109], v[6:7] op_sel_hi:[1,0]
	v_pk_mul_f32 v[110:111], v[110:111], v[6:7] op_sel_hi:[1,0]
	v_pk_mul_f32 v[96:97], v[96:97], v[112:113]
	v_pk_mul_f32 v[98:99], v[98:99], v[114:115]
	v_pk_mul_f32 v[100:101], v[100:101], v[116:117]
	v_pk_mul_f32 v[102:103], v[102:103], v[118:119]
	v_pk_mul_f32 v[104:105], v[104:105], v[120:121]
	v_pk_mul_f32 v[106:107], v[106:107], v[122:123]
	v_pk_mul_f32 v[108:109], v[108:109], v[124:125]
	v_pk_mul_f32 v[110:111], v[110:111], v[126:127]
	s_lshl_b32 s99, s98, 12
	v_add_u32_e32 v8, s99, v1
	global_store_dwordx4 v8, v[96:99], s[88:89] nt
	global_store_dwordx4 v8, v[100:103], s[88:89] offset:1024 nt
	global_store_dwordx4 v8, v[104:107], s[88:89] offset:2048 nt
	global_store_dwordx4 v8, v[108:111], s[88:89] offset:3072 nt
	s_add_u32 s98, s97, 11
	s_lshl_b32 s98, s98, 12
	v_add_u32_e32 v3, s98, v1
	global_load_dwordx4 v[96:99], v3, s[88:89] nt
	global_load_dwordx4 v[100:103], v3, s[88:89] offset:1024 nt
	global_load_dwordx4 v[104:107], v3, s[88:89] offset:2048 nt
	global_load_dwordx4 v[108:111], v3, s[88:89] offset:3072 nt
	s_waitcnt vmcnt(40)
	v_mul_f32_e32 v4, v16, v16
	v_fma_f32 v4, v17, v17, v4
	v_fma_f32 v4, v18, v18, v4
	v_fma_f32 v4, v19, v19, v4
	v_fma_f32 v4, v20, v20, v4
	v_fma_f32 v4, v21, v21, v4
	v_fma_f32 v4, v22, v22, v4
	v_fma_f32 v4, v23, v23, v4
	v_fma_f32 v4, v24, v24, v4
	v_fma_f32 v4, v25, v25, v4
	v_fma_f32 v4, v26, v26, v4
	v_fma_f32 v4, v27, v27, v4
	v_fma_f32 v4, v28, v28, v4
	v_fma_f32 v4, v29, v29, v4
	v_fma_f32 v4, v30, v30, v4
	v_fma_f32 v4, v31, v31, v4
	s_nop 1
	v_add_f32_dpp v5, v4, v4 quad_perm:[1,0,3,2] row_mask:0xf bank_mask:0xf
	s_nop 1
	v_add_f32_dpp v4, v5, v5 quad_perm:[2,3,0,1] row_mask:0xf bank_mask:0xf
	s_nop 1
	v_add_f32_dpp v5, v4, v4 row_half_mirror row_mask:0xf bank_mask:0xf
	s_nop 1
	v_add_f32_dpp v4, v5, v5 row_mirror row_mask:0xf bank_mask:0xf
	s_nop 1
	v_readlane_b32 s98, v4, 0
	v_readlane_b32 s99, v4, 16
	s_nop 3
	v_mov_b32_e32 v5, s98
	v_add_f32_e32 v5, s99, v5
	v_readlane_b32 s98, v4, 32
	v_readlane_b32 s99, v4, 48
	s_nop 3
	v_add_f32_e32 v5, s98, v5
	v_add_f32_e32 v5, s99, v5
	v_mul_f32_e32 v5, 0x3a800000, v5
	v_add_f32_e32 v5, 0x358637bd, v5
	v_rsq_f32_e32 v6, v5
	s_nop 0
	s_add_u32 s98, s97, 6
	v_pk_mul_f32 v[16:17], v[16:17], v[6:7] op_sel_hi:[1,0]
	v_pk_mul_f32 v[18:19], v[18:19], v[6:7] op_sel_hi:[1,0]
	v_pk_mul_f32 v[20:21], v[20:21], v[6:7] op_sel_hi:[1,0]
	v_pk_mul_f32 v[22:23], v[22:23], v[6:7] op_sel_hi:[1,0]
	v_pk_mul_f32 v[24:25], v[24:25], v[6:7] op_sel_hi:[1,0]
	v_pk_mul_f32 v[26:27], v[26:27], v[6:7] op_sel_hi:[1,0]
	v_pk_mul_f32 v[28:29], v[28:29], v[6:7] op_sel_hi:[1,0]
	v_pk_mul_f32 v[30:31], v[30:31], v[6:7] op_sel_hi:[1,0]
	v_pk_mul_f32 v[16:17], v[16:17], v[112:113]
	v_pk_mul_f32 v[18:19], v[18:19], v[114:115]
	v_pk_mul_f32 v[20:21], v[20:21], v[116:117]
	v_pk_mul_f32 v[22:23], v[22:23], v[118:119]
	v_pk_mul_f32 v[24:25], v[24:25], v[120:121]
	v_pk_mul_f32 v[26:27], v[26:27], v[122:123]
	v_pk_mul_f32 v[28:29], v[28:29], v[124:125]
	v_pk_mul_f32 v[30:31], v[30:31], v[126:127]
	s_lshl_b32 s99, s98, 12
	v_add_u32_e32 v8, s99, v1
	global_store_dwordx4 v8, v[16:19], s[88:89] nt
	global_store_dwordx4 v8, v[20:23], s[88:89] offset:1024 nt
	global_store_dwordx4 v8, v[24:27], s[88:89] offset:2048 nt
	global_store_dwordx4 v8, v[28:31], s[88:89] offset:3072 nt
	s_add_u32 s98, s97, 12
	s_lshl_b32 s98, s98, 12
	v_add_u32_e32 v3, s98, v1
	global_load_dwordx4 v[16:19], v3, s[88:89] nt
	global_load_dwordx4 v[20:23], v3, s[88:89] offset:1024 nt
	global_load_dwordx4 v[24:27], v3, s[88:89] offset:2048 nt
	global_load_dwordx4 v[28:31], v3, s[88:89] offset:3072 nt
	s_waitcnt vmcnt(40)
	v_mul_f32_e32 v4, v32, v32
	v_fma_f32 v4, v33, v33, v4
	v_fma_f32 v4, v34, v34, v4
	v_fma_f32 v4, v35, v35, v4
	v_fma_f32 v4, v36, v36, v4
	v_fma_f32 v4, v37, v37, v4
	v_fma_f32 v4, v38, v38, v4
	v_fma_f32 v4, v39, v39, v4
	v_fma_f32 v4, v40, v40, v4
	v_fma_f32 v4, v41, v41, v4
	v_fma_f32 v4, v42, v42, v4
	v_fma_f32 v4, v43, v43, v4
	v_fma_f32 v4, v44, v44, v4
	v_fma_f32 v4, v45, v45, v4
	v_fma_f32 v4, v46, v46, v4
	v_fma_f32 v4, v47, v47, v4
	s_nop 1
	v_add_f32_dpp v5, v4, v4 quad_perm:[1,0,3,2] row_mask:0xf bank_mask:0xf
	s_nop 1
	v_add_f32_dpp v4, v5, v5 quad_perm:[2,3,0,1] row_mask:0xf bank_mask:0xf
	s_nop 1
	v_add_f32_dpp v5, v4, v4 row_half_mirror row_mask:0xf bank_mask:0xf
	s_nop 1
	v_add_f32_dpp v4, v5, v5 row_mirror row_mask:0xf bank_mask:0xf
	s_nop 1
	v_readlane_b32 s98, v4, 0
	v_readlane_b32 s99, v4, 16
	s_nop 3
	v_mov_b32_e32 v5, s98
	v_add_f32_e32 v5, s99, v5
	v_readlane_b32 s98, v4, 32
	v_readlane_b32 s99, v4, 48
	s_nop 3
	v_add_f32_e32 v5, s98, v5
	v_add_f32_e32 v5, s99, v5
	v_mul_f32_e32 v5, 0x3a800000, v5
	v_add_f32_e32 v5, 0x358637bd, v5
	v_rsq_f32_e32 v6, v5
	s_nop 0
	s_add_u32 s98, s97, 7
	v_pk_mul_f32 v[32:33], v[32:33], v[6:7] op_sel_hi:[1,0]
	v_pk_mul_f32 v[34:35], v[34:35], v[6:7] op_sel_hi:[1,0]
	v_pk_mul_f32 v[36:37], v[36:37], v[6:7] op_sel_hi:[1,0]
	v_pk_mul_f32 v[38:39], v[38:39], v[6:7] op_sel_hi:[1,0]
	v_pk_mul_f32 v[40:41], v[40:41], v[6:7] op_sel_hi:[1,0]
	v_pk_mul_f32 v[42:43], v[42:43], v[6:7] op_sel_hi:[1,0]
	v_pk_mul_f32 v[44:45], v[44:45], v[6:7] op_sel_hi:[1,0]
	v_pk_mul_f32 v[46:47], v[46:47], v[6:7] op_sel_hi:[1,0]
	v_pk_mul_f32 v[32:33], v[32:33], v[112:113]
	v_pk_mul_f32 v[34:35], v[34:35], v[114:115]
	v_pk_mul_f32 v[36:37], v[36:37], v[116:117]
	v_pk_mul_f32 v[38:39], v[38:39], v[118:119]
	v_pk_mul_f32 v[40:41], v[40:41], v[120:121]
	v_pk_mul_f32 v[42:43], v[42:43], v[122:123]
	v_pk_mul_f32 v[44:45], v[44:45], v[124:125]
	v_pk_mul_f32 v[46:47], v[46:47], v[126:127]
	s_lshl_b32 s99, s98, 12
	v_add_u32_e32 v8, s99, v1
	global_store_dwordx4 v8, v[32:35], s[88:89] nt
	global_store_dwordx4 v8, v[36:39], s[88:89] offset:1024 nt
	global_store_dwordx4 v8, v[40:43], s[88:89] offset:2048 nt
	global_store_dwordx4 v8, v[44:47], s[88:89] offset:3072 nt
	s_add_u32 s98, s97, 13
	s_lshl_b32 s98, s98, 12
	v_add_u32_e32 v3, s98, v1
	global_load_dwordx4 v[32:35], v3, s[88:89] nt
	global_load_dwordx4 v[36:39], v3, s[88:89] offset:1024 nt
	global_load_dwordx4 v[40:43], v3, s[88:89] offset:2048 nt
	global_load_dwordx4 v[44:47], v3, s[88:89] offset:3072 nt
	s_waitcnt vmcnt(40)
	v_mul_f32_e32 v4, v48, v48
	v_fma_f32 v4, v49, v49, v4
	v_fma_f32 v4, v50, v50, v4
	v_fma_f32 v4, v51, v51, v4
	v_fma_f32 v4, v52, v52, v4
	v_fma_f32 v4, v53, v53, v4
	v_fma_f32 v4, v54, v54, v4
	v_fma_f32 v4, v55, v55, v4
	v_fma_f32 v4, v56, v56, v4
	v_fma_f32 v4, v57, v57, v4
	v_fma_f32 v4, v58, v58, v4
	v_fma_f32 v4, v59, v59, v4
	v_fma_f32 v4, v60, v60, v4
	v_fma_f32 v4, v61, v61, v4
	v_fma_f32 v4, v62, v62, v4
	v_fma_f32 v4, v63, v63, v4
	s_nop 1
	v_add_f32_dpp v5, v4, v4 quad_perm:[1,0,3,2] row_mask:0xf bank_mask:0xf
	s_nop 1
	v_add_f32_dpp v4, v5, v5 quad_perm:[2,3,0,1] row_mask:0xf bank_mask:0xf
	s_nop 1
	v_add_f32_dpp v5, v4, v4 row_half_mirror row_mask:0xf bank_mask:0xf
	s_nop 1
	v_add_f32_dpp v4, v5, v5 row_mirror row_mask:0xf bank_mask:0xf
	s_nop 1
	v_readlane_b32 s98, v4, 0
	v_readlane_b32 s99, v4, 16
	s_nop 3
	v_mov_b32_e32 v5, s98
	v_add_f32_e32 v5, s99, v5
	v_readlane_b32 s98, v4, 32
	v_readlane_b32 s99, v4, 48
	s_nop 3
	v_add_f32_e32 v5, s98, v5
	v_add_f32_e32 v5, s99, v5
	v_mul_f32_e32 v5, 0x3a800000, v5
	v_add_f32_e32 v5, 0x358637bd, v5
	v_rsq_f32_e32 v6, v5
	s_nop 0
	s_add_u32 s98, s97, 8
	v_pk_mul_f32 v[48:49], v[48:49], v[6:7] op_sel_hi:[1,0]
	v_pk_mul_f32 v[50:51], v[50:51], v[6:7] op_sel_hi:[1,0]
	v_pk_mul_f32 v[52:53], v[52:53], v[6:7] op_sel_hi:[1,0]
	v_pk_mul_f32 v[54:55], v[54:55], v[6:7] op_sel_hi:[1,0]
	v_pk_mul_f32 v[56:57], v[56:57], v[6:7] op_sel_hi:[1,0]
	v_pk_mul_f32 v[58:59], v[58:59], v[6:7] op_sel_hi:[1,0]
	v_pk_mul_f32 v[60:61], v[60:61], v[6:7] op_sel_hi:[1,0]
	v_pk_mul_f32 v[62:63], v[62:63], v[6:7] op_sel_hi:[1,0]
	v_pk_mul_f32 v[48:49], v[48:49], v[112:113]
	v_pk_mul_f32 v[50:51], v[50:51], v[114:115]
	v_pk_mul_f32 v[52:53], v[52:53], v[116:117]
	v_pk_mul_f32 v[54:55], v[54:55], v[118:119]
	v_pk_mul_f32 v[56:57], v[56:57], v[120:121]
	v_pk_mul_f32 v[58:59], v[58:59], v[122:123]
	v_pk_mul_f32 v[60:61], v[60:61], v[124:125]
	v_pk_mul_f32 v[62:63], v[62:63], v[126:127]
	s_lshl_b32 s99, s98, 12
	v_add_u32_e32 v8, s99, v1
	global_store_dwordx4 v8, v[48:51], s[88:89] nt
	global_store_dwordx4 v8, v[52:55], s[88:89] offset:1024 nt
	global_store_dwordx4 v8, v[56:59], s[88:89] offset:2048 nt
	global_store_dwordx4 v8, v[60:63], s[88:89] offset:3072 nt
	s_add_u32 s98, s97, 14
	s_lshl_b32 s98, s98, 12
	v_add_u32_e32 v3, s98, v1
	global_load_dwordx4 v[48:51], v3, s[88:89] nt
	global_load_dwordx4 v[52:55], v3, s[88:89] offset:1024 nt
	global_load_dwordx4 v[56:59], v3, s[88:89] offset:2048 nt
	global_load_dwordx4 v[60:63], v3, s[88:89] offset:3072 nt
	s_waitcnt vmcnt(40)
	v_mul_f32_e32 v4, v64, v64
	v_fma_f32 v4, v65, v65, v4
	v_fma_f32 v4, v66, v66, v4
	v_fma_f32 v4, v67, v67, v4
	v_fma_f32 v4, v68, v68, v4
	v_fma_f32 v4, v69, v69, v4
	v_fma_f32 v4, v70, v70, v4
	v_fma_f32 v4, v71, v71, v4
	v_fma_f32 v4, v72, v72, v4
	v_fma_f32 v4, v73, v73, v4
	v_fma_f32 v4, v74, v74, v4
	v_fma_f32 v4, v75, v75, v4
	v_fma_f32 v4, v76, v76, v4
	v_fma_f32 v4, v77, v77, v4
	v_fma_f32 v4, v78, v78, v4
	v_fma_f32 v4, v79, v79, v4
	s_nop 1
	v_add_f32_dpp v5, v4, v4 quad_perm:[1,0,3,2] row_mask:0xf bank_mask:0xf
	s_nop 1
	v_add_f32_dpp v4, v5, v5 quad_perm:[2,3,0,1] row_mask:0xf bank_mask:0xf
	s_nop 1
	v_add_f32_dpp v5, v4, v4 row_half_mirror row_mask:0xf bank_mask:0xf
	s_nop 1
	v_add_f32_dpp v4, v5, v5 row_mirror row_mask:0xf bank_mask:0xf
	s_nop 1
	v_readlane_b32 s98, v4, 0
	v_readlane_b32 s99, v4, 16
	s_nop 3
	v_mov_b32_e32 v5, s98
	v_add_f32_e32 v5, s99, v5
	v_readlane_b32 s98, v4, 32
	v_readlane_b32 s99, v4, 48
	s_nop 3
	v_add_f32_e32 v5, s98, v5
	v_add_f32_e32 v5, s99, v5
	v_mul_f32_e32 v5, 0x3a800000, v5
	v_add_f32_e32 v5, 0x358637bd, v5
	v_rsq_f32_e32 v6, v5
	s_nop 0
	s_add_u32 s98, s97, 9
	v_pk_mul_f32 v[64:65], v[64:65], v[6:7] op_sel_hi:[1,0]
	v_pk_mul_f32 v[66:67], v[66:67], v[6:7] op_sel_hi:[1,0]
	v_pk_mul_f32 v[68:69], v[68:69], v[6:7] op_sel_hi:[1,0]
	v_pk_mul_f32 v[70:71], v[70:71], v[6:7] op_sel_hi:[1,0]
	v_pk_mul_f32 v[72:73], v[72:73], v[6:7] op_sel_hi:[1,0]
	v_pk_mul_f32 v[74:75], v[74:75], v[6:7] op_sel_hi:[1,0]
	v_pk_mul_f32 v[76:77], v[76:77], v[6:7] op_sel_hi:[1,0]
	v_pk_mul_f32 v[78:79], v[78:79], v[6:7] op_sel_hi:[1,0]
	v_pk_mul_f32 v[64:65], v[64:65], v[112:113]
	v_pk_mul_f32 v[66:67], v[66:67], v[114:115]
	v_pk_mul_f32 v[68:69], v[68:69], v[116:117]
	v_pk_mul_f32 v[70:71], v[70:71], v[118:119]
	v_pk_mul_f32 v[72:73], v[72:73], v[120:121]
	v_pk_mul_f32 v[74:75], v[74:75], v[122:123]
	v_pk_mul_f32 v[76:77], v[76:77], v[124:125]
	v_pk_mul_f32 v[78:79], v[78:79], v[126:127]
	s_lshl_b32 s99, s98, 12
	v_add_u32_e32 v8, s99, v1
	global_store_dwordx4 v8, v[64:67], s[88:89] nt
	global_store_dwordx4 v8, v[68:71], s[88:89] offset:1024 nt
	global_store_dwordx4 v8, v[72:75], s[88:89] offset:2048 nt
	global_store_dwordx4 v8, v[76:79], s[88:89] offset:3072 nt
	s_add_u32 s98, s97, 15
	s_lshl_b32 s98, s98, 12
	v_add_u32_e32 v3, s98, v1
	global_load_dwordx4 v[64:67], v3, s[88:89] nt
	global_load_dwordx4 v[68:71], v3, s[88:89] offset:1024 nt
	global_load_dwordx4 v[72:75], v3, s[88:89] offset:2048 nt
	global_load_dwordx4 v[76:79], v3, s[88:89] offset:3072 nt
	s_waitcnt vmcnt(40)
	v_mul_f32_e32 v4, v80, v80
	v_fma_f32 v4, v81, v81, v4
	v_fma_f32 v4, v82, v82, v4
	v_fma_f32 v4, v83, v83, v4
	v_fma_f32 v4, v84, v84, v4
	v_fma_f32 v4, v85, v85, v4
	v_fma_f32 v4, v86, v86, v4
	v_fma_f32 v4, v87, v87, v4
	v_fma_f32 v4, v88, v88, v4
	v_fma_f32 v4, v89, v89, v4
	v_fma_f32 v4, v90, v90, v4
	v_fma_f32 v4, v91, v91, v4
	v_fma_f32 v4, v92, v92, v4
	v_fma_f32 v4, v93, v93, v4
	v_fma_f32 v4, v94, v94, v4
	v_fma_f32 v4, v95, v95, v4
	s_nop 1
	v_add_f32_dpp v5, v4, v4 quad_perm:[1,0,3,2] row_mask:0xf bank_mask:0xf
	s_nop 1
	v_add_f32_dpp v4, v5, v5 quad_perm:[2,3,0,1] row_mask:0xf bank_mask:0xf
	s_nop 1
	v_add_f32_dpp v5, v4, v4 row_half_mirror row_mask:0xf bank_mask:0xf
	s_nop 1
	v_add_f32_dpp v4, v5, v5 row_mirror row_mask:0xf bank_mask:0xf
	s_nop 1
	v_readlane_b32 s98, v4, 0
	v_readlane_b32 s99, v4, 16
	s_nop 3
	v_mov_b32_e32 v5, s98
	v_add_f32_e32 v5, s99, v5
	v_readlane_b32 s98, v4, 32
	v_readlane_b32 s99, v4, 48
	s_nop 3
	v_add_f32_e32 v5, s98, v5
	v_add_f32_e32 v5, s99, v5
	v_mul_f32_e32 v5, 0x3a800000, v5
	v_add_f32_e32 v5, 0x358637bd, v5
	v_rsq_f32_e32 v6, v5
	s_nop 0
	s_add_u32 s98, s97, 10
	v_pk_mul_f32 v[80:81], v[80:81], v[6:7] op_sel_hi:[1,0]
	v_pk_mul_f32 v[82:83], v[82:83], v[6:7] op_sel_hi:[1,0]
	v_pk_mul_f32 v[84:85], v[84:85], v[6:7] op_sel_hi:[1,0]
	v_pk_mul_f32 v[86:87], v[86:87], v[6:7] op_sel_hi:[1,0]
	v_pk_mul_f32 v[88:89], v[88:89], v[6:7] op_sel_hi:[1,0]
	v_pk_mul_f32 v[90:91], v[90:91], v[6:7] op_sel_hi:[1,0]
	v_pk_mul_f32 v[92:93], v[92:93], v[6:7] op_sel_hi:[1,0]
	v_pk_mul_f32 v[94:95], v[94:95], v[6:7] op_sel_hi:[1,0]
	v_pk_mul_f32 v[80:81], v[80:81], v[112:113]
	v_pk_mul_f32 v[82:83], v[82:83], v[114:115]
	v_pk_mul_f32 v[84:85], v[84:85], v[116:117]
	v_pk_mul_f32 v[86:87], v[86:87], v[118:119]
	v_pk_mul_f32 v[88:89], v[88:89], v[120:121]
	v_pk_mul_f32 v[90:91], v[90:91], v[122:123]
	v_pk_mul_f32 v[92:93], v[92:93], v[124:125]
	v_pk_mul_f32 v[94:95], v[94:95], v[126:127]
	s_lshl_b32 s99, s98, 12
	v_add_u32_e32 v8, s99, v1
	global_store_dwordx4 v8, v[80:83], s[88:89] nt
	global_store_dwordx4 v8, v[84:87], s[88:89] offset:1024 nt
	global_store_dwordx4 v8, v[88:91], s[88:89] offset:2048 nt
	global_store_dwordx4 v8, v[92:95], s[88:89] offset:3072 nt
	s_waitcnt vmcnt(36)
	v_mul_f32_e32 v4, v96, v96
	v_fma_f32 v4, v97, v97, v4
	v_fma_f32 v4, v98, v98, v4
	v_fma_f32 v4, v99, v99, v4
	v_fma_f32 v4, v100, v100, v4
	v_fma_f32 v4, v101, v101, v4
	v_fma_f32 v4, v102, v102, v4
	v_fma_f32 v4, v103, v103, v4
	v_fma_f32 v4, v104, v104, v4
	v_fma_f32 v4, v105, v105, v4
	v_fma_f32 v4, v106, v106, v4
	v_fma_f32 v4, v107, v107, v4
	v_fma_f32 v4, v108, v108, v4
	v_fma_f32 v4, v109, v109, v4
	v_fma_f32 v4, v110, v110, v4
	v_fma_f32 v4, v111, v111, v4
	s_nop 1
	v_add_f32_dpp v5, v4, v4 quad_perm:[1,0,3,2] row_mask:0xf bank_mask:0xf
	s_nop 1
	v_add_f32_dpp v4, v5, v5 quad_perm:[2,3,0,1] row_mask:0xf bank_mask:0xf
	s_nop 1
	v_add_f32_dpp v5, v4, v4 row_half_mirror row_mask:0xf bank_mask:0xf
	s_nop 1
	v_add_f32_dpp v4, v5, v5 row_mirror row_mask:0xf bank_mask:0xf
	s_nop 1
	v_readlane_b32 s98, v4, 0
	v_readlane_b32 s99, v4, 16
	s_nop 3
	v_mov_b32_e32 v5, s98
	v_add_f32_e32 v5, s99, v5
	v_readlane_b32 s98, v4, 32
	v_readlane_b32 s99, v4, 48
	s_nop 3
	v_add_f32_e32 v5, s98, v5
	v_add_f32_e32 v5, s99, v5
	v_mul_f32_e32 v5, 0x3a800000, v5
	v_add_f32_e32 v5, 0x358637bd, v5
	v_rsq_f32_e32 v6, v5
	s_nop 0
	s_add_u32 s98, s97, 11
	v_pk_mul_f32 v[96:97], v[96:97], v[6:7] op_sel_hi:[1,0]
	v_pk_mul_f32 v[98:99], v[98:99], v[6:7] op_sel_hi:[1,0]
	v_pk_mul_f32 v[100:101], v[100:101], v[6:7] op_sel_hi:[1,0]
	v_pk_mul_f32 v[102:103], v[102:103], v[6:7] op_sel_hi:[1,0]
	v_pk_mul_f32 v[104:105], v[104:105], v[6:7] op_sel_hi:[1,0]
	v_pk_mul_f32 v[106:107], v[106:107], v[6:7] op_sel_hi:[1,0]
	v_pk_mul_f32 v[108:109], v[108:109], v[6:7] op_sel_hi:[1,0]
	v_pk_mul_f32 v[110:111], v[110:111], v[6:7] op_sel_hi:[1,0]
	v_pk_mul_f32 v[96:97], v[96:97], v[112:113]
	v_pk_mul_f32 v[98:99], v[98:99], v[114:115]
	v_pk_mul_f32 v[100:101], v[100:101], v[116:117]
	v_pk_mul_f32 v[102:103], v[102:103], v[118:119]
	v_pk_mul_f32 v[104:105], v[104:105], v[120:121]
	v_pk_mul_f32 v[106:107], v[106:107], v[122:123]
	v_pk_mul_f32 v[108:109], v[108:109], v[124:125]
	v_pk_mul_f32 v[110:111], v[110:111], v[126:127]
	s_lshl_b32 s99, s98, 12
	v_add_u32_e32 v8, s99, v1
	global_store_dwordx4 v8, v[96:99], s[88:89] nt
	global_store_dwordx4 v8, v[100:103], s[88:89] offset:1024 nt
	global_store_dwordx4 v8, v[104:107], s[88:89] offset:2048 nt
	global_store_dwordx4 v8, v[108:111], s[88:89] offset:3072 nt
	s_waitcnt vmcnt(32)
	v_mul_f32_e32 v4, v16, v16
	v_fma_f32 v4, v17, v17, v4
	v_fma_f32 v4, v18, v18, v4
	v_fma_f32 v4, v19, v19, v4
	v_fma_f32 v4, v20, v20, v4
	v_fma_f32 v4, v21, v21, v4
	v_fma_f32 v4, v22, v22, v4
	v_fma_f32 v4, v23, v23, v4
	v_fma_f32 v4, v24, v24, v4
	v_fma_f32 v4, v25, v25, v4
	v_fma_f32 v4, v26, v26, v4
	v_fma_f32 v4, v27, v27, v4
	v_fma_f32 v4, v28, v28, v4
	v_fma_f32 v4, v29, v29, v4
	v_fma_f32 v4, v30, v30, v4
	v_fma_f32 v4, v31, v31, v4
	s_nop 1
	v_add_f32_dpp v5, v4, v4 quad_perm:[1,0,3,2] row_mask:0xf bank_mask:0xf
	s_nop 1
	v_add_f32_dpp v4, v5, v5 quad_perm:[2,3,0,1] row_mask:0xf bank_mask:0xf
	s_nop 1
	v_add_f32_dpp v5, v4, v4 row_half_mirror row_mask:0xf bank_mask:0xf
	s_nop 1
	v_add_f32_dpp v4, v5, v5 row_mirror row_mask:0xf bank_mask:0xf
	s_nop 1
	v_readlane_b32 s98, v4, 0
	v_readlane_b32 s99, v4, 16
	s_nop 3
	v_mov_b32_e32 v5, s98
	v_add_f32_e32 v5, s99, v5
	v_readlane_b32 s98, v4, 32
	v_readlane_b32 s99, v4, 48
	s_nop 3
	v_add_f32_e32 v5, s98, v5
	v_add_f32_e32 v5, s99, v5
	v_mul_f32_e32 v5, 0x3a800000, v5
	v_add_f32_e32 v5, 0x358637bd, v5
	v_rsq_f32_e32 v6, v5
	s_nop 0
	s_add_u32 s98, s97, 12
	v_pk_mul_f32 v[16:17], v[16:17], v[6:7] op_sel_hi:[1,0]
	v_pk_mul_f32 v[18:19], v[18:19], v[6:7] op_sel_hi:[1,0]
	v_pk_mul_f32 v[20:21], v[20:21], v[6:7] op_sel_hi:[1,0]
	v_pk_mul_f32 v[22:23], v[22:23], v[6:7] op_sel_hi:[1,0]
	v_pk_mul_f32 v[24:25], v[24:25], v[6:7] op_sel_hi:[1,0]
	v_pk_mul_f32 v[26:27], v[26:27], v[6:7] op_sel_hi:[1,0]
	v_pk_mul_f32 v[28:29], v[28:29], v[6:7] op_sel_hi:[1,0]
	v_pk_mul_f32 v[30:31], v[30:31], v[6:7] op_sel_hi:[1,0]
	v_pk_mul_f32 v[16:17], v[16:17], v[112:113]
	v_pk_mul_f32 v[18:19], v[18:19], v[114:115]
	v_pk_mul_f32 v[20:21], v[20:21], v[116:117]
	v_pk_mul_f32 v[22:23], v[22:23], v[118:119]
	v_pk_mul_f32 v[24:25], v[24:25], v[120:121]
	v_pk_mul_f32 v[26:27], v[26:27], v[122:123]
	v_pk_mul_f32 v[28:29], v[28:29], v[124:125]
	v_pk_mul_f32 v[30:31], v[30:31], v[126:127]
	s_lshl_b32 s99, s98, 12
	v_add_u32_e32 v8, s99, v1
	global_store_dwordx4 v8, v[16:19], s[88:89] nt
	global_store_dwordx4 v8, v[20:23], s[88:89] offset:1024 nt
	global_store_dwordx4 v8, v[24:27], s[88:89] offset:2048 nt
	global_store_dwordx4 v8, v[28:31], s[88:89] offset:3072 nt
	s_waitcnt vmcnt(28)
	v_mul_f32_e32 v4, v32, v32
	v_fma_f32 v4, v33, v33, v4
	v_fma_f32 v4, v34, v34, v4
	v_fma_f32 v4, v35, v35, v4
	v_fma_f32 v4, v36, v36, v4
	v_fma_f32 v4, v37, v37, v4
	v_fma_f32 v4, v38, v38, v4
	v_fma_f32 v4, v39, v39, v4
	v_fma_f32 v4, v40, v40, v4
	v_fma_f32 v4, v41, v41, v4
	v_fma_f32 v4, v42, v42, v4
	v_fma_f32 v4, v43, v43, v4
	v_fma_f32 v4, v44, v44, v4
	v_fma_f32 v4, v45, v45, v4
	v_fma_f32 v4, v46, v46, v4
	v_fma_f32 v4, v47, v47, v4
	s_nop 1
	v_add_f32_dpp v5, v4, v4 quad_perm:[1,0,3,2] row_mask:0xf bank_mask:0xf
	s_nop 1
	v_add_f32_dpp v4, v5, v5 quad_perm:[2,3,0,1] row_mask:0xf bank_mask:0xf
	s_nop 1
	v_add_f32_dpp v5, v4, v4 row_half_mirror row_mask:0xf bank_mask:0xf
	s_nop 1
	v_add_f32_dpp v4, v5, v5 row_mirror row_mask:0xf bank_mask:0xf
	s_nop 1
	v_readlane_b32 s98, v4, 0
	v_readlane_b32 s99, v4, 16
	s_nop 3
	v_mov_b32_e32 v5, s98
	v_add_f32_e32 v5, s99, v5
	v_readlane_b32 s98, v4, 32
	v_readlane_b32 s99, v4, 48
	s_nop 3
	v_add_f32_e32 v5, s98, v5
	v_add_f32_e32 v5, s99, v5
	v_mul_f32_e32 v5, 0x3a800000, v5
	v_add_f32_e32 v5, 0x358637bd, v5
	v_rsq_f32_e32 v6, v5
	s_nop 0
	s_add_u32 s98, s97, 13
	v_pk_mul_f32 v[32:33], v[32:33], v[6:7] op_sel_hi:[1,0]
	v_pk_mul_f32 v[34:35], v[34:35], v[6:7] op_sel_hi:[1,0]
	v_pk_mul_f32 v[36:37], v[36:37], v[6:7] op_sel_hi:[1,0]
	v_pk_mul_f32 v[38:39], v[38:39], v[6:7] op_sel_hi:[1,0]
	v_pk_mul_f32 v[40:41], v[40:41], v[6:7] op_sel_hi:[1,0]
	v_pk_mul_f32 v[42:43], v[42:43], v[6:7] op_sel_hi:[1,0]
	v_pk_mul_f32 v[44:45], v[44:45], v[6:7] op_sel_hi:[1,0]
	v_pk_mul_f32 v[46:47], v[46:47], v[6:7] op_sel_hi:[1,0]
	v_pk_mul_f32 v[32:33], v[32:33], v[112:113]
	v_pk_mul_f32 v[34:35], v[34:35], v[114:115]
	v_pk_mul_f32 v[36:37], v[36:37], v[116:117]
	v_pk_mul_f32 v[38:39], v[38:39], v[118:119]
	v_pk_mul_f32 v[40:41], v[40:41], v[120:121]
	v_pk_mul_f32 v[42:43], v[42:43], v[122:123]
	v_pk_mul_f32 v[44:45], v[44:45], v[124:125]
	v_pk_mul_f32 v[46:47], v[46:47], v[126:127]
	s_lshl_b32 s99, s98, 12
	v_add_u32_e32 v8, s99, v1
	global_store_dwordx4 v8, v[32:35], s[88:89] nt
	global_store_dwordx4 v8, v[36:39], s[88:89] offset:1024 nt
	global_store_dwordx4 v8, v[40:43], s[88:89] offset:2048 nt
	global_store_dwordx4 v8, v[44:47], s[88:89] offset:3072 nt
	s_waitcnt vmcnt(24)
	v_mul_f32_e32 v4, v48, v48
	v_fma_f32 v4, v49, v49, v4
	v_fma_f32 v4, v50, v50, v4
	v_fma_f32 v4, v51, v51, v4
	v_fma_f32 v4, v52, v52, v4
	v_fma_f32 v4, v53, v53, v4
	v_fma_f32 v4, v54, v54, v4
	v_fma_f32 v4, v55, v55, v4
	v_fma_f32 v4, v56, v56, v4
	v_fma_f32 v4, v57, v57, v4
	v_fma_f32 v4, v58, v58, v4
	v_fma_f32 v4, v59, v59, v4
	v_fma_f32 v4, v60, v60, v4
	v_fma_f32 v4, v61, v61, v4
	v_fma_f32 v4, v62, v62, v4
	v_fma_f32 v4, v63, v63, v4
	s_nop 1
	v_add_f32_dpp v5, v4, v4 quad_perm:[1,0,3,2] row_mask:0xf bank_mask:0xf
	s_nop 1
	v_add_f32_dpp v4, v5, v5 quad_perm:[2,3,0,1] row_mask:0xf bank_mask:0xf
	s_nop 1
	v_add_f32_dpp v5, v4, v4 row_half_mirror row_mask:0xf bank_mask:0xf
	s_nop 1
	v_add_f32_dpp v4, v5, v5 row_mirror row_mask:0xf bank_mask:0xf
	s_nop 1
	v_readlane_b32 s98, v4, 0
	v_readlane_b32 s99, v4, 16
	s_nop 3
	v_mov_b32_e32 v5, s98
	v_add_f32_e32 v5, s99, v5
	v_readlane_b32 s98, v4, 32
	v_readlane_b32 s99, v4, 48
	s_nop 3
	v_add_f32_e32 v5, s98, v5
	v_add_f32_e32 v5, s99, v5
	v_mul_f32_e32 v5, 0x3a800000, v5
	v_add_f32_e32 v5, 0x358637bd, v5
	v_rsq_f32_e32 v6, v5
	s_nop 0
	s_add_u32 s98, s97, 14
	v_pk_mul_f32 v[48:49], v[48:49], v[6:7] op_sel_hi:[1,0]
	v_pk_mul_f32 v[50:51], v[50:51], v[6:7] op_sel_hi:[1,0]
	v_pk_mul_f32 v[52:53], v[52:53], v[6:7] op_sel_hi:[1,0]
	v_pk_mul_f32 v[54:55], v[54:55], v[6:7] op_sel_hi:[1,0]
	v_pk_mul_f32 v[56:57], v[56:57], v[6:7] op_sel_hi:[1,0]
	v_pk_mul_f32 v[58:59], v[58:59], v[6:7] op_sel_hi:[1,0]
	v_pk_mul_f32 v[60:61], v[60:61], v[6:7] op_sel_hi:[1,0]
	v_pk_mul_f32 v[62:63], v[62:63], v[6:7] op_sel_hi:[1,0]
	v_pk_mul_f32 v[48:49], v[48:49], v[112:113]
	v_pk_mul_f32 v[50:51], v[50:51], v[114:115]
	v_pk_mul_f32 v[52:53], v[52:53], v[116:117]
	v_pk_mul_f32 v[54:55], v[54:55], v[118:119]
	v_pk_mul_f32 v[56:57], v[56:57], v[120:121]
	v_pk_mul_f32 v[58:59], v[58:59], v[122:123]
	v_pk_mul_f32 v[60:61], v[60:61], v[124:125]
	v_pk_mul_f32 v[62:63], v[62:63], v[126:127]
	s_lshl_b32 s99, s98, 12
	v_add_u32_e32 v8, s99, v1
	global_store_dwordx4 v8, v[48:51], s[88:89] nt
	global_store_dwordx4 v8, v[52:55], s[88:89] offset:1024 nt
	global_store_dwordx4 v8, v[56:59], s[88:89] offset:2048 nt
	global_store_dwordx4 v8, v[60:63], s[88:89] offset:3072 nt
	s_waitcnt vmcnt(20)
	v_mul_f32_e32 v4, v64, v64
	v_fma_f32 v4, v65, v65, v4
	v_fma_f32 v4, v66, v66, v4
	v_fma_f32 v4, v67, v67, v4
	v_fma_f32 v4, v68, v68, v4
	v_fma_f32 v4, v69, v69, v4
	v_fma_f32 v4, v70, v70, v4
	v_fma_f32 v4, v71, v71, v4
	v_fma_f32 v4, v72, v72, v4
	v_fma_f32 v4, v73, v73, v4
	v_fma_f32 v4, v74, v74, v4
	v_fma_f32 v4, v75, v75, v4
	v_fma_f32 v4, v76, v76, v4
	v_fma_f32 v4, v77, v77, v4
	v_fma_f32 v4, v78, v78, v4
	v_fma_f32 v4, v79, v79, v4
	s_nop 1
	v_add_f32_dpp v5, v4, v4 quad_perm:[1,0,3,2] row_mask:0xf bank_mask:0xf
	s_nop 1
	v_add_f32_dpp v4, v5, v5 quad_perm:[2,3,0,1] row_mask:0xf bank_mask:0xf
	s_nop 1
	v_add_f32_dpp v5, v4, v4 row_half_mirror row_mask:0xf bank_mask:0xf
	s_nop 1
	v_add_f32_dpp v4, v5, v5 row_mirror row_mask:0xf bank_mask:0xf
	s_nop 1
	v_readlane_b32 s98, v4, 0
	v_readlane_b32 s99, v4, 16
	s_nop 3
	v_mov_b32_e32 v5, s98
	v_add_f32_e32 v5, s99, v5
	v_readlane_b32 s98, v4, 32
	v_readlane_b32 s99, v4, 48
	s_nop 3
	v_add_f32_e32 v5, s98, v5
	v_add_f32_e32 v5, s99, v5
	v_mul_f32_e32 v5, 0x3a800000, v5
	v_add_f32_e32 v5, 0x358637bd, v5
	v_rsq_f32_e32 v6, v5
	s_nop 0
	s_add_u32 s98, s97, 15
	v_pk_mul_f32 v[64:65], v[64:65], v[6:7] op_sel_hi:[1,0]
	v_pk_mul_f32 v[66:67], v[66:67], v[6:7] op_sel_hi:[1,0]
	v_pk_mul_f32 v[68:69], v[68:69], v[6:7] op_sel_hi:[1,0]
	v_pk_mul_f32 v[70:71], v[70:71], v[6:7] op_sel_hi:[1,0]
	v_pk_mul_f32 v[72:73], v[72:73], v[6:7] op_sel_hi:[1,0]
	v_pk_mul_f32 v[74:75], v[74:75], v[6:7] op_sel_hi:[1,0]
	v_pk_mul_f32 v[76:77], v[76:77], v[6:7] op_sel_hi:[1,0]
	v_pk_mul_f32 v[78:79], v[78:79], v[6:7] op_sel_hi:[1,0]
	v_pk_mul_f32 v[64:65], v[64:65], v[112:113]
	v_pk_mul_f32 v[66:67], v[66:67], v[114:115]
	v_pk_mul_f32 v[68:69], v[68:69], v[116:117]
	v_pk_mul_f32 v[70:71], v[70:71], v[118:119]
	v_pk_mul_f32 v[72:73], v[72:73], v[120:121]
	v_pk_mul_f32 v[74:75], v[74:75], v[122:123]
	v_pk_mul_f32 v[76:77], v[76:77], v[124:125]
	v_pk_mul_f32 v[78:79], v[78:79], v[126:127]
	s_lshl_b32 s99, s98, 12
	v_add_u32_e32 v8, s99, v1
	global_store_dwordx4 v8, v[64:67], s[88:89] nt
	global_store_dwordx4 v8, v[68:71], s[88:89] offset:1024 nt
	global_store_dwordx4 v8, v[72:75], s[88:89] offset:2048 nt
	global_store_dwordx4 v8, v[76:79], s[88:89] offset:3072 nt
	s_waitcnt vmcnt(0)
